# speedup vs baseline: 1.0399x; 1.0121x over previous
; template <bool ABLK, class Epi>
; __device__ __forceinline__ void gemm_tile(const bf16* __restrict__ A, int lda, const bf16* __restrict__ Bt, int ldb, int K,
;                                           int brow, int bcol, bf16* shm, const Epi& epi, int wv) {
;     ...
;   int offA, offB;
;   { int r_, c_; stage_rc(tid * 16, r_, c_); offA = ABLK ? r_ * 64 + c_ : r_ * lda + c_;
;     offB = ((r_ >> 5) * 64 + (r_ & 15) * 4 + ((r_ >> 4) & 1)) * ldb + c_; }
; template <bool ABLK, class Epi>
; __device__ __forceinline__ void gemm_phase(const bf16* A, int lda, const bf16* Bt, int ldb, int M, int N, int K, char* smem, const Epi& epi, int wv) {
;   const int nM = M / BM, nN = N / BM, nwg = nM * nN;
;   __syncthreads();
;   for (int w = blockIdx.x; w < nwg; w += gridDim.x) {
;     int wgid = w;
;     { int q = nwg / NXCD, r = nwg % NXCD, xcd = wgid % NXCD, off = wgid / NXCD;
;       wgid = (xcd < r ? xcd * (q + 1) : r * (q + 1) + (xcd - r) * q) + off; }
;     const int nig = WGM * nN, gid = wgid / nig, fm = gid * WGM, gsz = min(nM - fm, WGM);
;     const int pm = fm + ((wgid % nig) % gsz), pn = (wgid % nig) / gsz;
;     gemm_tile<ABLK>(A, lda, Bt, ldb, K, pm * BM, pn * BM, (bf16*)smem, epi, wv);
.LBB0_80:
	s_or_b64 exec, exec, s[4:5]
	v_writelane_b32 v255, s36, 9
	s_mov_b32 s0, s38
	s_mov_b64 s[8:9], s[90:91]
	v_writelane_b32 v255, s37, 10
	v_writelane_b32 v255, s0, 11
	s_mov_b64 s[10:11], s[90:91]
	s_mov_b64 s[12:13], s[90:91]
	s_mov_b64 s[14:15], s[90:91]
	s_cmpk_gt_i32 s89, 0x11ff
	v_writelane_b32 v255, s1, 12
	s_barrier
	s_barrier
	s_cbranch_scc1 .LBB0_90
	s_load_dwordx2 s[16:17], s[8:9], 0xa8
	s_load_dwordx2 s[4:5], s[10:11], 0xa8
	s_load_dwordx2 s[18:19], s[12:13], 0xa8
	s_load_dwordx2 s[6:7], s[14:15], 0x30
	s_mov_b32 s26, 0xffff2000
	s_waitcnt lgkmcnt(0)
	s_add_u32 s1, s16, 0xba40000
	s_addc_u32 s3, s17, 0
	s_add_u32 s8, s18, 0x17a40000
	s_addc_u32 s9, s19, 0
	s_add_u32 s72, s16, 0xba5a000
	s_addc_u32 s73, s17, 0
	s_add_u32 s74, s4, 0x82180
	s_mov_b32 s28, 0xffff4000
	s_mov_b32 s30, 0xfff7df80
	s_movk_i32 s34, 0xdf80
	s_mov_b32 s36, 0xffff6000
	s_movk_i32 s38, 0x8000
	s_mov_b32 s40, 0xfff7ff80
	s_movk_i32 s42, 0xff80
	s_movk_i32 s44, 0xa000
	s_movk_i32 s46, 0xc000
	s_mov_b32 s48, 0xfff7e000
	s_movk_i32 s50, 0xe000
	s_mov_b32 s52, 0xfff80000
	s_movk_i32 s0, 0x241
	s_addc_u32 s75, s5, 0
	s_add_i32 s76, 0, 0x10000
	s_mov_b64 s[10:11], 0x80000
	s_mov_b64 s[12:13], 0x2000
	s_add_i32 s77, 0, 0x14000
	s_mov_b64 s[14:15], 0x4000
	s_mov_b64 s[16:17], 0x6000
	s_mov_b64 s[18:19], 0x80
	s_add_i32 s78, 0, 0x18000
	s_mov_b64 s[20:21], 0x80080
	s_mov_b64 s[22:23], 0x8000
	s_mov_b64 s[24:25], 0xa000
	s_add_i32 s79, 0, 0x1c000
	s_movk_i32 s80, 0x3c0
	s_mov_b32 s27, -1
	s_mov_b32 s29, -1
	s_mov_b32 s31, -1
	s_mov_b32 s35, -1
	s_mov_b32 s37, -1
	s_mov_b32 s39, -1
	s_mov_b32 s41, -1
	s_mov_b32 s43, -1
	s_mov_b32 s45, -1
	s_mov_b32 s47, -1
	s_mov_b32 s49, -1
	s_mov_b32 s51, -1
	s_mov_b32 s53, -1
	s_mov_b64 s[54:55], 0x10000
	s_mov_b64 s[56:57], 0x100
	s_mov_b64 s[58:59], 0xfc000
	s_mov_b64 s[60:61], 0xfe000
	s_movk_i32 s81, 0x100
	s_movk_i32 s82, 0x3000
	v_mov_b32_e32 v134, 1
	s_mov_b32 s83, s89
	v_lshlrev_b32_e32 v254, 4, v192
	s_nop 0
	v_readfirstlane_b32 s99, v254
	s_branch .LBB0_83

; #define STAGE_A(P, hf, kt) do { if constexpr (ABLK) { const bf16* _gp = A + ((long)(brow >> 8) * nt + (kt)) * 16384 + (hf) * 8192; GLDS2(_gp, 4096, offA, P); } \
;     else { const bf16* _gp = A + (long)(brow + (hf) * HALF) * lda + (long)(kt) * BK; GLDS2(_gp, 64 * (long)lda, offA, P); } } while (0)
; #define STAGE_B(P, hf, kt) do { const bf16* _gp = Bt + (long)(bcol + (hf) * 2) * ldb + (long)(kt) * BK; GLDS2(_gp, 128 * (long)ldb, offB, P); } while (0)
; #define LDA(dst, b, h) for (int m = 0; m < 4; ++m) for (int k = 0; k < 2; ++k) \
;     dst[m][k] = *reinterpret_cast<const bf16x8*>((char*)SA(b, h) + lds_byte(wr * 64 + m * 16 + fr, k * 32 + fq * 8))
; #define LDB(dst, b, h) for (int n = 0; n < 2; ++n) for (int k = 0; k < 2; ++k) \
;     dst[n][k] = *reinterpret_cast<const bf16x8*>((char*)SB(b, h) + lds_byte(wc * 32 + n * 16 + fr, k * 32 + fq * 8))
; #define MMA(ai, bj, At, Bt_) do { __builtin_amdgcn_s_setprio(1); \
;     for (int m = 0; m < 4; ++m) for (int n = 0; n < 2; ++n) for (int k = 0; k < 2; ++k) \
;       acc[ai][bj][m][n] = __builtin_amdgcn_mfma_f32_16x16x32_bf16(At[m][k], Bt_[n][k], acc[ai][bj][m][n], 0, 0, 0); \
;     __builtin_amdgcn_s_setprio(0); } while (0)
; #define WAIT_V(n) asm volatile("s_waitcnt vmcnt(" #n ")" ::: "memory")
; #define WAIT_L(n) asm volatile("s_waitcnt lgkmcnt(" #n ")" ::: "memory")
; #define BAR __builtin_amdgcn_s_barrier()
; #define SCHED __builtin_amdgcn_sched_barrier(0)
; template <bool ABLK, class Epi>
; __device__ __forceinline__ void gemm_tile(const bf16* __restrict__ A, int lda, const bf16* __restrict__ Bt, int ldb, int K,
;                                           int brow, int bcol, bf16* shm, const Epi& epi, int wv) {
;     ...
;   for (int t = 0; t < nt - 2; t += 2) {
;     LDB(B0, 0, 0); SCHED; LDA(At, 0, 0); STAGE_A(SA(1, 1), 1, t + 1);
;     WAIT_L(8); BAR; MMA(0, 0, At, B0); BAR; SCHED;
;     LDB(B1, 0, 1); STAGE_B(SB(0, 0), 0, t + 2);
;     BAR; MMA(0, 1, At, B1); BAR;
;     LDA(At, 0, 1); STAGE_A(SA(0, 0), 0, t + 2);
;     BAR; MMA(1, 0, At, B0); BAR; SCHED;
;     STAGE_B(SB(0, 1), 1, t + 2);
;     WAIT_V(6); BAR; MMA(1, 1, At, B1); BAR;
.LBB0_86:
	ds_read_b128 v[164:167], v161
	ds_read_b128 v[168:171], v161 offset:1024
	ds_read_b128 v[172:175], v161 offset:2048
	ds_read_b128 v[176:179], v161 offset:3072
	v_add_u32_e32 v162, 0xc000, v147
	v_add_u32_e32 v163, 0xe000, v147
	v_lshl_add_u64 v[198:199], v[130:131], 0, s[26:27]
	s_add_i32 m0, s99, 0xc000
	ds_read_b128 v[180:183], v143
	ds_read_b128 v[184:187], v143 offset:1024
	ds_read_b128 v[188:191], v142
	ds_read_b128 v[194:197], v142 offset:1024
	ds_read_b128 v[208:211], v141
	ds_read_b128 v[212:215], v141 offset:1024
	ds_read_b128 v[216:219], v140
	ds_read_b128 v[220:223], v140 offset:1024
	global_load_lds_dwordx4 v[198:199], off
	s_add_i32 m0, s99, 0xe000
	v_lshl_add_u64 v[198:199], v[130:131], 0, s[28:29]
	global_load_lds_dwordx4 v[198:199], off
	s_waitcnt lgkmcnt(8)
	s_barrier
	s_setprio 1
	s_waitcnt lgkmcnt(0)
	v_mfma_f32_16x16x32_bf16 v[124:127], v[180:183], v[164:167], v[124:127]
	v_mfma_f32_16x16x32_bf16 v[120:123], v[180:183], v[172:175], v[120:123]
	v_mfma_f32_16x16x32_bf16 v[116:119], v[188:191], v[164:167], v[116:119]
	v_mfma_f32_16x16x32_bf16 v[112:115], v[188:191], v[172:175], v[112:115]
	v_mfma_f32_16x16x32_bf16 v[108:111], v[208:211], v[164:167], v[108:111]
	v_mfma_f32_16x16x32_bf16 v[104:107], v[208:211], v[172:175], v[104:107]
	v_mfma_f32_16x16x32_bf16 v[100:103], v[216:219], v[164:167], v[100:103]
	v_mfma_f32_16x16x32_bf16 v[96:99], v[216:219], v[172:175], v[96:99]
	v_mfma_f32_16x16x32_bf16 v[124:127], v[184:187], v[168:171], v[124:127]
	v_mfma_f32_16x16x32_bf16 v[120:123], v[184:187], v[176:179], v[120:123]
	v_mfma_f32_16x16x32_bf16 v[116:119], v[194:197], v[168:171], v[116:119]
	v_mfma_f32_16x16x32_bf16 v[112:115], v[194:197], v[176:179], v[112:115]
	v_mfma_f32_16x16x32_bf16 v[108:111], v[212:215], v[168:171], v[108:111]
	v_mfma_f32_16x16x32_bf16 v[104:107], v[212:215], v[176:179], v[104:107]
	v_mfma_f32_16x16x32_bf16 v[100:103], v[220:223], v[168:171], v[100:103]
	v_mfma_f32_16x16x32_bf16 v[96:99], v[220:223], v[176:179], v[96:99]
	s_setprio 0
	s_barrier
	v_lshl_add_u64 v[198:199], v[132:133], 0, s[30:31]
	s_add_i32 m0, s99, 0x10000
	ds_read_b128 v[224:227], v160
	ds_read_b128 v[228:231], v160 offset:1024
	ds_read_b128 v[232:235], v160 offset:2048
	ds_read_b128 v[236:239], v160 offset:3072
	global_load_lds_dwordx4 v[198:199], off
	s_add_i32 m0, s99, 0x12000
	v_lshl_add_u64 v[198:199], v[132:133], 0, s[34:35]
	global_load_lds_dwordx4 v[198:199], off
	s_barrier
	s_setprio 1
	s_waitcnt lgkmcnt(0)
	v_mfma_f32_16x16x32_bf16 v[92:95], v[180:183], v[224:227], v[92:95]
	v_mfma_f32_16x16x32_bf16 v[88:91], v[180:183], v[232:235], v[88:91]
	v_mfma_f32_16x16x32_bf16 v[84:87], v[188:191], v[224:227], v[84:87]
	v_mfma_f32_16x16x32_bf16 v[80:83], v[188:191], v[232:235], v[80:83]
	v_mfma_f32_16x16x32_bf16 v[76:79], v[208:211], v[224:227], v[76:79]
	v_mfma_f32_16x16x32_bf16 v[72:75], v[208:211], v[232:235], v[72:75]
	v_mfma_f32_16x16x32_bf16 v[68:71], v[216:219], v[224:227], v[68:71]
	v_mfma_f32_16x16x32_bf16 v[64:67], v[216:219], v[232:235], v[64:67]
	v_mfma_f32_16x16x32_bf16 v[92:95], v[184:187], v[228:231], v[92:95]
	v_mfma_f32_16x16x32_bf16 v[88:91], v[184:187], v[236:239], v[88:91]
	v_mfma_f32_16x16x32_bf16 v[84:87], v[194:197], v[228:231], v[84:87]
	v_mfma_f32_16x16x32_bf16 v[80:83], v[194:197], v[236:239], v[80:83]
	v_mfma_f32_16x16x32_bf16 v[76:79], v[212:215], v[228:231], v[76:79]
	v_mfma_f32_16x16x32_bf16 v[72:75], v[212:215], v[236:239], v[72:75]
	v_mfma_f32_16x16x32_bf16 v[68:71], v[220:223], v[228:231], v[68:71]
	v_mfma_f32_16x16x32_bf16 v[64:67], v[220:223], v[236:239], v[64:67]
	s_setprio 0
	v_lshl_add_u64 v[198:199], v[130:131], 0, s[36:37]
	s_add_i32 m0, s99, 0x0
	s_barrier
	ds_read_b128 v[180:183], v143 offset:16384
	ds_read_b128 v[184:187], v143 offset:17408
	ds_read_b128 v[188:191], v142 offset:16384
	ds_read_b128 v[194:197], v142 offset:17408
	ds_read_b128 v[208:211], v141 offset:16384
	ds_read_b128 v[212:215], v141 offset:17408
	ds_read_b128 v[216:219], v140 offset:16384
	ds_read_b128 v[220:223], v140 offset:17408
	global_load_lds_dwordx4 v[198:199], off
	s_add_i32 m0, s99, 0x2000
	v_lshl_add_u64 v[198:199], v[130:131], 0, s[38:39]
	global_load_lds_dwordx4 v[198:199], off
	s_barrier
	s_setprio 1
	s_waitcnt lgkmcnt(0)
	v_mfma_f32_16x16x32_bf16 v[60:63], v[180:183], v[164:167], v[60:63]
	v_mfma_f32_16x16x32_bf16 v[56:59], v[180:183], v[172:175], v[56:59]
	v_mfma_f32_16x16x32_bf16 v[52:55], v[188:191], v[164:167], v[52:55]
	v_mfma_f32_16x16x32_bf16 v[48:51], v[188:191], v[172:175], v[48:51]
	v_mfma_f32_16x16x32_bf16 v[44:47], v[208:211], v[164:167], v[44:47]
	v_mfma_f32_16x16x32_bf16 v[40:43], v[208:211], v[172:175], v[40:43]
	v_mfma_f32_16x16x32_bf16 v[36:39], v[216:219], v[164:167], v[36:39]
	v_mfma_f32_16x16x32_bf16 v[32:35], v[216:219], v[172:175], v[32:35]
	v_mfma_f32_16x16x32_bf16 v[60:63], v[184:187], v[168:171], v[60:63]
	v_mfma_f32_16x16x32_bf16 v[56:59], v[184:187], v[176:179], v[56:59]
	v_mfma_f32_16x16x32_bf16 v[52:55], v[194:197], v[168:171], v[52:55]
	v_mfma_f32_16x16x32_bf16 v[48:51], v[194:197], v[176:179], v[48:51]
	v_mfma_f32_16x16x32_bf16 v[44:47], v[212:215], v[168:171], v[44:47]
	v_mfma_f32_16x16x32_bf16 v[40:43], v[212:215], v[176:179], v[40:43]
	v_mfma_f32_16x16x32_bf16 v[36:39], v[220:223], v[168:171], v[36:39]
	v_mfma_f32_16x16x32_bf16 v[32:35], v[220:223], v[176:179], v[32:35]
	s_setprio 0
	s_barrier
	s_add_i32 m0, s99, 0x14000
	v_lshl_add_u64 v[164:165], v[132:133], 0, s[40:41]
	global_load_lds_dwordx4 v[164:165], off
	s_add_i32 m0, s99, 0x16000
	v_lshl_add_u64 v[164:165], v[132:133], 0, s[42:43]
	global_load_lds_dwordx4 v[164:165], off
	s_waitcnt vmcnt(6)
	s_barrier
; #define STAGE_A(P, hf, kt) do { if constexpr (ABLK) { const bf16* _gp = A + ((long)(brow >> 8) * nt + (kt)) * 16384 + (hf) * 8192; GLDS2(_gp, 4096, offA, P); } \
;     else { const bf16* _gp = A + (long)(brow + (hf) * HALF) * lda + (long)(kt) * BK; GLDS2(_gp, 64 * (long)lda, offA, P); } } while (0)
; #define STAGE_B(P, hf, kt) do { const bf16* _gp = Bt + (long)(bcol + (hf) * 2) * ldb + (long)(kt) * BK; GLDS2(_gp, 128 * (long)ldb, offB, P); } while (0)
; #define LDA(dst, b, h) for (int m = 0; m < 4; ++m) for (int k = 0; k < 2; ++k) \
;     dst[m][k] = *reinterpret_cast<const bf16x8*>((char*)SA(b, h) + lds_byte(wr * 64 + m * 16 + fr, k * 32 + fq * 8))
; #define LDB(dst, b, h) for (int n = 0; n < 2; ++n) for (int k = 0; k < 2; ++k) \
;     dst[n][k] = *reinterpret_cast<const bf16x8*>((char*)SB(b, h) + lds_byte(wc * 32 + n * 16 + fr, k * 32 + fq * 8))
; #define MMA(ai, bj, At, Bt_) do { __builtin_amdgcn_s_setprio(1); \
;     for (int m = 0; m < 4; ++m) for (int n = 0; n < 2; ++n) for (int k = 0; k < 2; ++k) \
;       acc[ai][bj][m][n] = __builtin_amdgcn_mfma_f32_16x16x32_bf16(At[m][k], Bt_[n][k], acc[ai][bj][m][n], 0, 0, 0); \
;     __builtin_amdgcn_s_setprio(0); } while (0)
; #define WAIT_V(n) asm volatile("s_waitcnt vmcnt(" #n ")" ::: "memory")
; #define WAIT_L(n) asm volatile("s_waitcnt lgkmcnt(" #n ")" ::: "memory")
; #define BAR __builtin_amdgcn_s_barrier()
; #define SCHED __builtin_amdgcn_sched_barrier(0)
; template <bool ABLK, class Epi>
; __device__ __forceinline__ void gemm_tile(const bf16* __restrict__ A, int lda, const bf16* __restrict__ Bt, int ldb, int K,
;                                           int brow, int bcol, bf16* shm, const Epi& epi, int wv) {
;     ...
;     LDB(B0, 1, 0); SCHED; LDA(At, 1, 0); STAGE_A(SA(0, 1), 1, t + 2);
;     WAIT_L(8); BAR; MMA(0, 0, At, B0); BAR; SCHED;
;     LDB(B1, 1, 1); STAGE_B(SB(1, 0), 0, t + 3);
;     BAR; MMA(0, 1, At, B1); BAR;
;     LDA(At, 1, 1); STAGE_A(SA(1, 0), 0, t + 3);
;     BAR; MMA(1, 0, At, B0); BAR; SCHED;
;     STAGE_B(SB(1, 1), 1, t + 3);
;     WAIT_V(6); BAR; MMA(1, 1, At, B1); BAR;
	s_setprio 1
	v_mfma_f32_16x16x32_bf16 v[28:31], v[180:183], v[224:227], v[28:31]
	v_mfma_f32_16x16x32_bf16 v[24:27], v[180:183], v[232:235], v[24:27]
	v_mfma_f32_16x16x32_bf16 v[20:23], v[188:191], v[224:227], v[20:23]
	v_mfma_f32_16x16x32_bf16 v[16:19], v[188:191], v[232:235], v[16:19]
	v_mfma_f32_16x16x32_bf16 v[12:15], v[208:211], v[224:227], v[12:15]
	v_mfma_f32_16x16x32_bf16 v[8:11], v[208:211], v[232:235], v[8:11]
	v_mfma_f32_16x16x32_bf16 v[4:7], v[216:219], v[224:227], v[4:7]
	v_mfma_f32_16x16x32_bf16 v[0:3], v[216:219], v[232:235], v[0:3]
	v_mfma_f32_16x16x32_bf16 v[28:31], v[184:187], v[228:231], v[28:31]
	v_mfma_f32_16x16x32_bf16 v[24:27], v[184:187], v[236:239], v[24:27]
	v_mfma_f32_16x16x32_bf16 v[20:23], v[194:197], v[228:231], v[20:23]
	v_mfma_f32_16x16x32_bf16 v[16:19], v[194:197], v[236:239], v[16:19]
	v_mfma_f32_16x16x32_bf16 v[12:15], v[212:215], v[228:231], v[12:15]
	v_mfma_f32_16x16x32_bf16 v[8:11], v[212:215], v[236:239], v[8:11]
	v_mfma_f32_16x16x32_bf16 v[4:7], v[220:223], v[228:231], v[4:7]
	v_mfma_f32_16x16x32_bf16 v[0:3], v[220:223], v[236:239], v[0:3]
	s_setprio 0
	s_barrier
	ds_read_b128 v[164:167], v149
	ds_read_b128 v[168:171], v149 offset:1024
	ds_read_b128 v[172:175], v149 offset:2048
	ds_read_b128 v[176:179], v149 offset:3072
	v_lshl_add_u64 v[198:199], v[130:131], 0, s[44:45]
	s_add_i32 m0, s99, 0x4000
	ds_read_b128 v[180:183], v143 offset:32768
	ds_read_b128 v[184:187], v143 offset:33792
	ds_read_b128 v[188:191], v142 offset:32768
	ds_read_b128 v[194:197], v142 offset:33792
	ds_read_b128 v[208:211], v141 offset:32768
	ds_read_b128 v[212:215], v141 offset:33792
	ds_read_b128 v[216:219], v140 offset:32768
	ds_read_b128 v[220:223], v140 offset:33792
	global_load_lds_dwordx4 v[198:199], off
	s_add_i32 m0, s99, 0x6000
	v_lshl_add_u64 v[198:199], v[130:131], 0, s[46:47]
	global_load_lds_dwordx4 v[198:199], off
	s_waitcnt lgkmcnt(8)
	s_barrier
	s_setprio 1
	s_waitcnt lgkmcnt(0)
	v_mfma_f32_16x16x32_bf16 v[124:127], v[180:183], v[164:167], v[124:127]
	v_mfma_f32_16x16x32_bf16 v[120:123], v[180:183], v[172:175], v[120:123]
	v_mfma_f32_16x16x32_bf16 v[116:119], v[188:191], v[164:167], v[116:119]
	v_mfma_f32_16x16x32_bf16 v[112:115], v[188:191], v[172:175], v[112:115]
	v_mfma_f32_16x16x32_bf16 v[108:111], v[208:211], v[164:167], v[108:111]
	v_mfma_f32_16x16x32_bf16 v[104:107], v[208:211], v[172:175], v[104:107]
	v_mfma_f32_16x16x32_bf16 v[100:103], v[216:219], v[164:167], v[100:103]
	v_mfma_f32_16x16x32_bf16 v[96:99], v[216:219], v[172:175], v[96:99]
	v_mfma_f32_16x16x32_bf16 v[124:127], v[184:187], v[168:171], v[124:127]
	v_mfma_f32_16x16x32_bf16 v[120:123], v[184:187], v[176:179], v[120:123]
	v_mfma_f32_16x16x32_bf16 v[116:119], v[194:197], v[168:171], v[116:119]
	v_mfma_f32_16x16x32_bf16 v[112:115], v[194:197], v[176:179], v[112:115]
	v_mfma_f32_16x16x32_bf16 v[108:111], v[212:215], v[168:171], v[108:111]
	v_mfma_f32_16x16x32_bf16 v[104:107], v[212:215], v[176:179], v[104:107]
	v_mfma_f32_16x16x32_bf16 v[100:103], v[220:223], v[168:171], v[100:103]
	v_mfma_f32_16x16x32_bf16 v[96:99], v[220:223], v[176:179], v[96:99]
	s_setprio 0
	s_barrier
	v_lshl_add_u64 v[198:199], v[132:133], 0, s[48:49]
	s_add_i32 m0, s99, 0x18000
	ds_read_b128 v[224:227], v146
	ds_read_b128 v[228:231], v146 offset:1024
	ds_read_b128 v[232:235], v146 offset:2048
	ds_read_b128 v[236:239], v146 offset:3072
	global_load_lds_dwordx4 v[198:199], off
	s_add_i32 m0, s99, 0x1a000
	v_lshl_add_u64 v[198:199], v[132:133], 0, s[50:51]
	global_load_lds_dwordx4 v[198:199], off
	s_barrier
	s_setprio 1
	s_waitcnt lgkmcnt(0)
	v_mfma_f32_16x16x32_bf16 v[92:95], v[180:183], v[224:227], v[92:95]
	v_mfma_f32_16x16x32_bf16 v[88:91], v[180:183], v[232:235], v[88:91]
	v_mfma_f32_16x16x32_bf16 v[84:87], v[188:191], v[224:227], v[84:87]
	v_mfma_f32_16x16x32_bf16 v[80:83], v[188:191], v[232:235], v[80:83]
	v_mfma_f32_16x16x32_bf16 v[76:79], v[208:211], v[224:227], v[76:79]
	v_mfma_f32_16x16x32_bf16 v[72:75], v[208:211], v[232:235], v[72:75]
	v_mfma_f32_16x16x32_bf16 v[68:71], v[216:219], v[224:227], v[68:71]
	v_mfma_f32_16x16x32_bf16 v[64:67], v[216:219], v[232:235], v[64:67]
	v_mfma_f32_16x16x32_bf16 v[92:95], v[184:187], v[228:231], v[92:95]
	v_mfma_f32_16x16x32_bf16 v[88:91], v[184:187], v[236:239], v[88:91]
	v_mfma_f32_16x16x32_bf16 v[84:87], v[194:197], v[228:231], v[84:87]
	v_mfma_f32_16x16x32_bf16 v[80:83], v[194:197], v[236:239], v[80:83]
	v_mfma_f32_16x16x32_bf16 v[76:79], v[212:215], v[228:231], v[76:79]
	v_mfma_f32_16x16x32_bf16 v[72:75], v[212:215], v[236:239], v[72:75]
	v_mfma_f32_16x16x32_bf16 v[68:71], v[220:223], v[228:231], v[68:71]
	v_mfma_f32_16x16x32_bf16 v[64:67], v[220:223], v[236:239], v[64:67]
	s_setprio 0
	v_lshl_add_u64 v[198:199], v[130:131], 0, s[50:51]
	s_add_i32 m0, s99, 0x8000
	s_barrier
	ds_read_b128 v[180:183], v143 offset:49152
	ds_read_b128 v[184:187], v143 offset:50176
	ds_read_b128 v[188:191], v142 offset:49152
	ds_read_b128 v[194:197], v142 offset:50176
	ds_read_b128 v[208:211], v141 offset:49152
	ds_read_b128 v[212:215], v141 offset:50176
	ds_read_b128 v[216:219], v140 offset:49152
	ds_read_b128 v[220:223], v140 offset:50176
	global_load_lds_dwordx4 v[198:199], off
	s_add_i32 m0, s99, 0xa000
	s_nop 0
	global_load_lds_dwordx4 v[130:131], off
	s_barrier
; #define STAGE_A(P, hf, kt) do { if constexpr (ABLK) { const bf16* _gp = A + ((long)(brow >> 8) * nt + (kt)) * 16384 + (hf) * 8192; GLDS2(_gp, 4096, offA, P); } \
;     else { const bf16* _gp = A + (long)(brow + (hf) * HALF) * lda + (long)(kt) * BK; GLDS2(_gp, 64 * (long)lda, offA, P); } } while (0)
; #define STAGE_B(P, hf, kt) do { const bf16* _gp = Bt + (long)(bcol + (hf) * 2) * ldb + (long)(kt) * BK; GLDS2(_gp, 128 * (long)ldb, offB, P); } while (0)
; #define LDA(dst, b, h) for (int m = 0; m < 4; ++m) for (int k = 0; k < 2; ++k) \
;     dst[m][k] = *reinterpret_cast<const bf16x8*>((char*)SA(b, h) + lds_byte(wr * 64 + m * 16 + fr, k * 32 + fq * 8))
; #define LDB(dst, b, h) for (int n = 0; n < 2; ++n) for (int k = 0; k < 2; ++k) \
;     dst[n][k] = *reinterpret_cast<const bf16x8*>((char*)SB(b, h) + lds_byte(wc * 32 + n * 16 + fr, k * 32 + fq * 8))
; #define MMA(ai, bj, At, Bt_) do { __builtin_amdgcn_s_setprio(1); \
;     for (int m = 0; m < 4; ++m) for (int n = 0; n < 2; ++n) for (int k = 0; k < 2; ++k) \
;       acc[ai][bj][m][n] = __builtin_amdgcn_mfma_f32_16x16x32_bf16(At[m][k], Bt_[n][k], acc[ai][bj][m][n], 0, 0, 0); \
;     __builtin_amdgcn_s_setprio(0); } while (0)
; #define WAIT_V(n) asm volatile("s_waitcnt vmcnt(" #n ")" ::: "memory")
; #define WAIT_L(n) asm volatile("s_waitcnt lgkmcnt(" #n ")" ::: "memory")
; #define BAR __builtin_amdgcn_s_barrier()
; #define SCHED __builtin_amdgcn_sched_barrier(0)
; template <bool ABLK, class Epi>
; __device__ __forceinline__ void gemm_tile(const bf16* __restrict__ A, int lda, const bf16* __restrict__ Bt, int ldb, int K,
;                                           int brow, int bcol, bf16* shm, const Epi& epi, int wv) {
;     ...
;     BAR; MMA(1, 0, At, B0); BAR; SCHED;
;     STAGE_B(SB(1, 1), 1, t + 3);
;     WAIT_V(6); BAR; MMA(1, 1, At, B1); BAR;
;   }
;   { LDB(B0, 0, 0); LDA(At, 0, 0); STAGE_A(SA(1, 1), 1, nt - 1);
;     BAR; WAIT_L(0); MMA(0, 0, At, B0); BAR;
;     LDB(B1, 0, 1); BAR; WAIT_L(0); MMA(0, 1, At, B1); BAR;
;     LDA(At, 0, 1); WAIT_V(4); BAR; WAIT_L(0); MMA(1, 0, At, B0); MMA(1, 1, At, B1); BAR; }
	s_setprio 1
	s_waitcnt lgkmcnt(0)
	v_mfma_f32_16x16x32_bf16 v[60:63], v[180:183], v[164:167], v[60:63]
	v_mfma_f32_16x16x32_bf16 v[56:59], v[180:183], v[172:175], v[56:59]
	v_mfma_f32_16x16x32_bf16 v[52:55], v[188:191], v[164:167], v[52:55]
	v_mfma_f32_16x16x32_bf16 v[48:51], v[188:191], v[172:175], v[48:51]
	v_mfma_f32_16x16x32_bf16 v[44:47], v[208:211], v[164:167], v[44:47]
	v_mfma_f32_16x16x32_bf16 v[40:43], v[208:211], v[172:175], v[40:43]
	v_mfma_f32_16x16x32_bf16 v[36:39], v[216:219], v[164:167], v[36:39]
	v_mfma_f32_16x16x32_bf16 v[32:35], v[216:219], v[172:175], v[32:35]
	v_mfma_f32_16x16x32_bf16 v[60:63], v[184:187], v[168:171], v[60:63]
	v_mfma_f32_16x16x32_bf16 v[56:59], v[184:187], v[176:179], v[56:59]
	v_mfma_f32_16x16x32_bf16 v[52:55], v[194:197], v[168:171], v[52:55]
	v_mfma_f32_16x16x32_bf16 v[48:51], v[194:197], v[176:179], v[48:51]
	v_mfma_f32_16x16x32_bf16 v[44:47], v[212:215], v[168:171], v[44:47]
	v_mfma_f32_16x16x32_bf16 v[40:43], v[212:215], v[176:179], v[40:43]
	v_mfma_f32_16x16x32_bf16 v[36:39], v[220:223], v[168:171], v[36:39]
	v_mfma_f32_16x16x32_bf16 v[32:35], v[220:223], v[176:179], v[32:35]
	s_setprio 0
	s_barrier
	s_add_i32 m0, s99, 0x1c000
	v_lshl_add_u64 v[164:165], v[132:133], 0, s[52:53]
	global_load_lds_dwordx4 v[164:165], off
	s_add_i32 m0, s99, 0x1e000
	s_nop 0
	global_load_lds_dwordx4 v[132:133], off
	s_waitcnt vmcnt(6)
	s_barrier
	s_setprio 1
	v_mfma_f32_16x16x32_bf16 v[28:31], v[180:183], v[224:227], v[28:31]
	v_mfma_f32_16x16x32_bf16 v[24:27], v[180:183], v[232:235], v[24:27]
	v_mfma_f32_16x16x32_bf16 v[20:23], v[188:191], v[224:227], v[20:23]
	v_mfma_f32_16x16x32_bf16 v[16:19], v[188:191], v[232:235], v[16:19]
	v_mfma_f32_16x16x32_bf16 v[12:15], v[208:211], v[224:227], v[12:15]
	v_mfma_f32_16x16x32_bf16 v[8:11], v[208:211], v[232:235], v[8:11]
	v_mfma_f32_16x16x32_bf16 v[4:7], v[216:219], v[224:227], v[4:7]
	v_mfma_f32_16x16x32_bf16 v[0:3], v[216:219], v[232:235], v[0:3]
	v_mfma_f32_16x16x32_bf16 v[28:31], v[184:187], v[228:231], v[28:31]
	v_mfma_f32_16x16x32_bf16 v[24:27], v[184:187], v[236:239], v[24:27]
	v_mfma_f32_16x16x32_bf16 v[20:23], v[194:197], v[228:231], v[20:23]
	v_mfma_f32_16x16x32_bf16 v[16:19], v[194:197], v[236:239], v[16:19]
	v_mfma_f32_16x16x32_bf16 v[12:15], v[212:215], v[228:231], v[12:15]
	v_mfma_f32_16x16x32_bf16 v[8:11], v[212:215], v[236:239], v[8:11]
	v_mfma_f32_16x16x32_bf16 v[4:7], v[220:223], v[228:231], v[4:7]
	v_mfma_f32_16x16x32_bf16 v[0:3], v[220:223], v[236:239], v[0:3]
	s_setprio 0
	s_add_i32 s33, s33, 2
	v_lshl_add_u64 v[130:131], v[130:131], 0, s[54:55]
	s_cmp_lt_u32 s33, 28
	v_lshl_add_u64 v[132:133], v[132:133], 0, s[56:57]
	s_barrier
	s_cbranch_scc1 .LBB0_86
	v_readfirstlane_b32 s2, v162
	v_lshl_add_u64 v[144:145], v[128:129], 0, s[58:59]
	s_mov_b32 m0, s2
	v_readfirstlane_b32 s2, v163
	ds_read_b128 v[130:133], v161
	ds_read_b128 v[150:153], v161 offset:1024
	ds_read_b128 v[154:157], v161 offset:2048
	ds_read_b128 v[164:167], v161 offset:3072
	ds_read_b128 v[168:171], v143
	ds_read_b128 v[172:175], v143 offset:1024
	ds_read_b128 v[176:179], v142
	ds_read_b128 v[180:183], v142 offset:1024
	ds_read_b128 v[184:187], v141
	ds_read_b128 v[188:191], v141 offset:1024
	ds_read_b128 v[194:197], v140
	ds_read_b128 v[208:211], v140 offset:1024
	global_load_lds_dwordx4 v[144:145], off
	v_lshl_add_u64 v[128:129], v[128:129], 0, s[60:61]
	s_mov_b32 m0, s2
	s_nop 0
	global_load_lds_dwordx4 v[128:129], off
	s_barrier
	s_waitcnt lgkmcnt(0)
	s_setprio 1
	s_waitcnt lgkmcnt(0)
	v_mfma_f32_16x16x32_bf16 v[124:127], v[168:171], v[130:133], v[124:127]
	v_mfma_f32_16x16x32_bf16 v[120:123], v[168:171], v[154:157], v[120:123]
	v_mfma_f32_16x16x32_bf16 v[108:111], v[184:187], v[130:133], v[108:111]
	v_mfma_f32_16x16x32_bf16 v[104:107], v[184:187], v[154:157], v[104:107]
	v_mfma_f32_16x16x32_bf16 v[124:127], v[172:175], v[150:153], v[124:127]
	v_mfma_f32_16x16x32_bf16 v[120:123], v[172:175], v[164:167], v[120:123]
	v_mfma_f32_16x16x32_bf16 v[116:119], v[176:179], v[130:133], v[116:119]
	v_mfma_f32_16x16x32_bf16 v[112:115], v[176:179], v[154:157], v[112:115]
	v_mfma_f32_16x16x32_bf16 v[108:111], v[188:191], v[150:153], v[108:111]
	v_mfma_f32_16x16x32_bf16 v[104:107], v[188:191], v[164:167], v[104:107]
	v_mfma_f32_16x16x32_bf16 v[100:103], v[194:197], v[130:133], v[100:103]
	v_mfma_f32_16x16x32_bf16 v[96:99], v[194:197], v[154:157], v[96:99]
	v_mfma_f32_16x16x32_bf16 v[212:215], v[180:183], v[150:153], v[116:119]
	v_mfma_f32_16x16x32_bf16 v[216:219], v[180:183], v[164:167], v[112:115]
	v_mfma_f32_16x16x32_bf16 v[220:223], v[208:211], v[150:153], v[100:103]
	v_mfma_f32_16x16x32_bf16 v[224:227], v[208:211], v[164:167], v[96:99]
	s_setprio 0
	s_barrier
	s_nop 1
	ds_read_b128 v[96:99], v160
	ds_read_b128 v[100:103], v160 offset:1024
	ds_read_b128 v[112:115], v160 offset:2048
	ds_read_b128 v[116:119], v160 offset:3072
	s_barrier
	s_waitcnt lgkmcnt(0)
	s_setprio 1
	s_waitcnt lgkmcnt(0)
	v_mfma_f32_16x16x32_bf16 v[92:95], v[168:171], v[96:99], v[92:95]
	v_mfma_f32_16x16x32_bf16 v[88:91], v[168:171], v[112:115], v[88:91]
	v_mfma_f32_16x16x32_bf16 v[76:79], v[184:187], v[96:99], v[76:79]
	v_mfma_f32_16x16x32_bf16 v[72:75], v[184:187], v[112:115], v[72:75]
	v_mfma_f32_16x16x32_bf16 v[92:95], v[172:175], v[100:103], v[92:95]
	v_mfma_f32_16x16x32_bf16 v[88:91], v[172:175], v[116:119], v[88:91]
	v_mfma_f32_16x16x32_bf16 v[84:87], v[176:179], v[96:99], v[84:87]
	v_mfma_f32_16x16x32_bf16 v[80:83], v[176:179], v[112:115], v[80:83]
	v_mfma_f32_16x16x32_bf16 v[76:79], v[188:191], v[100:103], v[76:79]
	v_mfma_f32_16x16x32_bf16 v[72:75], v[188:191], v[116:119], v[72:75]
	v_mfma_f32_16x16x32_bf16 v[68:71], v[194:197], v[96:99], v[68:71]
	v_mfma_f32_16x16x32_bf16 v[64:67], v[194:197], v[112:115], v[64:67]
	v_mfma_f32_16x16x32_bf16 v[158:161], v[180:183], v[100:103], v[84:87]
	v_mfma_f32_16x16x32_bf16 v[168:171], v[180:183], v[116:119], v[80:83]
	v_mfma_f32_16x16x32_bf16 v[172:175], v[208:211], v[100:103], v[68:71]
	v_mfma_f32_16x16x32_bf16 v[176:179], v[208:211], v[116:119], v[64:67]
	s_setprio 0
	s_barrier
; #define LDA(dst, b, h) for (int m = 0; m < 4; ++m) for (int k = 0; k < 2; ++k) \
;     dst[m][k] = *reinterpret_cast<const bf16x8*>((char*)SA(b, h) + lds_byte(wr * 64 + m * 16 + fr, k * 32 + fq * 8))
; #define LDB(dst, b, h) for (int n = 0; n < 2; ++n) for (int k = 0; k < 2; ++k) \
;     dst[n][k] = *reinterpret_cast<const bf16x8*>((char*)SB(b, h) + lds_byte(wc * 32 + n * 16 + fr, k * 32 + fq * 8))
; #define MMA(ai, bj, At, Bt_) do { __builtin_amdgcn_s_setprio(1); \
;     for (int m = 0; m < 4; ++m) for (int n = 0; n < 2; ++n) for (int k = 0; k < 2; ++k) \
;       acc[ai][bj][m][n] = __builtin_amdgcn_mfma_f32_16x16x32_bf16(At[m][k], Bt_[n][k], acc[ai][bj][m][n], 0, 0, 0); \
;     __builtin_amdgcn_s_setprio(0); } while (0)
; #define WAIT_V(n) asm volatile("s_waitcnt vmcnt(" #n ")" ::: "memory")
; #define WAIT_L(n) asm volatile("s_waitcnt lgkmcnt(" #n ")" ::: "memory")
; #define BAR __builtin_amdgcn_s_barrier()
; template <bool ABLK, class Epi>
; __device__ __forceinline__ void gemm_tile(const bf16* __restrict__ A, int lda, const bf16* __restrict__ Bt, int ldb, int K,
;                                           int brow, int bcol, bf16* shm, const Epi& epi, int wv) {
;     ...
;     BAR; WAIT_L(0); MMA(0, 0, At, B0); BAR;
;     LDB(B1, 0, 1); BAR; WAIT_L(0); MMA(0, 1, At, B1); BAR;
;     LDA(At, 0, 1); WAIT_V(4); BAR; WAIT_L(0); MMA(1, 0, At, B0); MMA(1, 1, At, B1); BAR; }
;   { LDB(B0, 1, 0); LDA(At, 1, 0); WAIT_V(2); BAR; WAIT_L(0); MMA(0, 0, At, B0); BAR;
	s_nop 1
	ds_read_b128 v[64:67], v143 offset:16384
	ds_read_b128 v[68:71], v143 offset:17408
	ds_read_b128 v[80:83], v142 offset:16384
	ds_read_b128 v[84:87], v142 offset:17408
	ds_read_b128 v[180:183], v141 offset:16384
	ds_read_b128 v[184:187], v141 offset:17408
	ds_read_b128 v[188:191], v140 offset:16384
	ds_read_b128 v[194:197], v140 offset:17408
	s_waitcnt vmcnt(4)
	s_barrier
	s_waitcnt lgkmcnt(0)
	s_setprio 1
	s_waitcnt lgkmcnt(0)
	v_mfma_f32_16x16x32_bf16 v[60:63], v[64:67], v[130:133], v[60:63]
	v_mfma_f32_16x16x32_bf16 v[56:59], v[64:67], v[154:157], v[56:59]
	v_mfma_f32_16x16x32_bf16 v[44:47], v[180:183], v[130:133], v[44:47]
	v_mfma_f32_16x16x32_bf16 v[40:43], v[180:183], v[154:157], v[40:43]
	v_mfma_f32_16x16x32_bf16 v[60:63], v[68:71], v[150:153], v[60:63]
	v_mfma_f32_16x16x32_bf16 v[56:59], v[68:71], v[164:167], v[56:59]
	v_mfma_f32_16x16x32_bf16 v[52:55], v[80:83], v[130:133], v[52:55]
	v_mfma_f32_16x16x32_bf16 v[48:51], v[80:83], v[154:157], v[48:51]
	v_mfma_f32_16x16x32_bf16 v[44:47], v[184:187], v[150:153], v[44:47]
	v_mfma_f32_16x16x32_bf16 v[40:43], v[184:187], v[164:167], v[40:43]
	v_mfma_f32_16x16x32_bf16 v[36:39], v[188:191], v[130:133], v[36:39]
	v_mfma_f32_16x16x32_bf16 v[32:35], v[188:191], v[154:157], v[32:35]
	v_mfma_f32_16x16x32_bf16 v[208:211], v[84:87], v[150:153], v[52:55]
	v_mfma_f32_16x16x32_bf16 v[228:231], v[84:87], v[164:167], v[48:51]
	v_mfma_f32_16x16x32_bf16 v[128:131], v[194:197], v[150:153], v[36:39]
	v_mfma_f32_16x16x32_bf16 v[150:153], v[194:197], v[164:167], v[32:35]
	s_setprio 0
	s_setprio 1
	v_mfma_f32_16x16x32_bf16 v[28:31], v[64:67], v[96:99], v[28:31]
	v_mfma_f32_16x16x32_bf16 v[24:27], v[64:67], v[112:115], v[24:27]
	v_mfma_f32_16x16x32_bf16 v[12:15], v[180:183], v[96:99], v[12:15]
	v_mfma_f32_16x16x32_bf16 v[8:11], v[180:183], v[112:115], v[8:11]
	v_mfma_f32_16x16x32_bf16 v[28:31], v[68:71], v[100:103], v[28:31]
	v_mfma_f32_16x16x32_bf16 v[24:27], v[68:71], v[116:119], v[24:27]
	v_mfma_f32_16x16x32_bf16 v[20:23], v[80:83], v[96:99], v[20:23]
	v_mfma_f32_16x16x32_bf16 v[16:19], v[80:83], v[112:115], v[16:19]
	v_mfma_f32_16x16x32_bf16 v[12:15], v[184:187], v[100:103], v[12:15]
	v_mfma_f32_16x16x32_bf16 v[8:11], v[184:187], v[116:119], v[8:11]
	v_mfma_f32_16x16x32_bf16 v[4:7], v[188:191], v[96:99], v[4:7]
	v_mfma_f32_16x16x32_bf16 v[0:3], v[188:191], v[112:115], v[0:3]
	v_mfma_f32_16x16x32_bf16 v[154:157], v[84:87], v[100:103], v[20:23]
	v_mfma_f32_16x16x32_bf16 v[162:165], v[84:87], v[116:119], v[16:19]
	v_mfma_f32_16x16x32_bf16 v[180:183], v[194:197], v[100:103], v[4:7]
	v_mfma_f32_16x16x32_bf16 v[184:187], v[194:197], v[116:119], v[0:3]
	s_setprio 0
	s_barrier
	s_nop 1
	ds_read_b128 v[0:3], v149
	ds_read_b128 v[4:7], v149 offset:1024
	ds_read_b128 v[188:191], v149 offset:2048
	ds_read_b128 v[194:197], v149 offset:3072
	ds_read_b128 v[16:19], v143 offset:32768
	ds_read_b128 v[20:23], v143 offset:33792
	ds_read_b128 v[32:35], v142 offset:32768
	ds_read_b128 v[36:39], v142 offset:33792
	ds_read_b128 v[48:51], v141 offset:32768
	ds_read_b128 v[52:55], v141 offset:33792
	ds_read_b128 v[232:235], v140 offset:32768
	ds_read_b128 v[236:239], v140 offset:33792
	s_waitcnt vmcnt(2)
	s_barrier
	s_waitcnt lgkmcnt(0)
	s_setprio 1
	s_waitcnt lgkmcnt(0)
	v_mfma_f32_16x16x32_bf16 v[64:67], v[16:19], v[0:3], v[124:127]
	v_mfma_f32_16x16x32_bf16 v[112:115], v[20:23], v[4:7], v[64:67]
	v_mfma_f32_16x16x32_bf16 v[64:67], v[16:19], v[188:191], v[120:123]
	v_mfma_f32_16x16x32_bf16 v[116:119], v[20:23], v[194:197], v[64:67]
	v_mfma_f32_16x16x32_bf16 v[64:67], v[32:35], v[0:3], v[212:215]
	v_mfma_f32_16x16x32_bf16 v[96:99], v[36:39], v[4:7], v[64:67]
	v_mfma_f32_16x16x32_bf16 v[64:67], v[32:35], v[188:191], v[216:219]
	v_mfma_f32_16x16x32_bf16 v[100:103], v[36:39], v[194:197], v[64:67]
	v_mfma_f32_16x16x32_bf16 v[64:67], v[48:51], v[0:3], v[108:111]
	v_mfma_f32_16x16x32_bf16 v[80:83], v[52:55], v[4:7], v[64:67]
	v_mfma_f32_16x16x32_bf16 v[64:67], v[48:51], v[188:191], v[104:107]
	v_mfma_f32_16x16x32_bf16 v[84:87], v[52:55], v[194:197], v[64:67]
	v_mfma_f32_16x16x32_bf16 v[64:67], v[232:235], v[0:3], v[220:223]
	v_mfma_f32_16x16x32_bf16 v[68:71], v[232:235], v[188:191], v[224:227]
	v_mfma_f32_16x16x32_bf16 v[64:67], v[236:239], v[4:7], v[64:67]
	v_mfma_f32_16x16x32_bf16 v[68:71], v[236:239], v[194:197], v[68:71]
	s_setprio 0
	s_barrier
; #define LDA(dst, b, h) for (int m = 0; m < 4; ++m) for (int k = 0; k < 2; ++k) \
;     dst[m][k] = *reinterpret_cast<const bf16x8*>((char*)SA(b, h) + lds_byte(wr * 64 + m * 16 + fr, k * 32 + fq * 8))
; #define LDB(dst, b, h) for (int n = 0; n < 2; ++n) for (int k = 0; k < 2; ++k) \
;     dst[n][k] = *reinterpret_cast<const bf16x8*>((char*)SB(b, h) + lds_byte(wc * 32 + n * 16 + fr, k * 32 + fq * 8))
; #define MMA(ai, bj, At, Bt_) do { __builtin_amdgcn_s_setprio(1); \
;     for (int m = 0; m < 4; ++m) for (int n = 0; n < 2; ++n) for (int k = 0; k < 2; ++k) \
;       acc[ai][bj][m][n] = __builtin_amdgcn_mfma_f32_16x16x32_bf16(At[m][k], Bt_[n][k], acc[ai][bj][m][n], 0, 0, 0); \
;     __builtin_amdgcn_s_setprio(0); } while (0)
; #define WAIT_V(n) asm volatile("s_waitcnt vmcnt(" #n ")" ::: "memory")
; #define WAIT_L(n) asm volatile("s_waitcnt lgkmcnt(" #n ")" ::: "memory")
; #define BAR __builtin_amdgcn_s_barrier()
; template <bool ABLK, class Epi>
; __device__ __forceinline__ void gemm_tile(const bf16* __restrict__ A, int lda, const bf16* __restrict__ Bt, int ldb, int K,
;                                           int brow, int bcol, bf16* shm, const Epi& epi, int wv) {
;     ...
;   { LDB(B0, 1, 0); LDA(At, 1, 0); WAIT_V(2); BAR; WAIT_L(0); MMA(0, 0, At, B0); BAR;
;     LDB(B1, 1, 1); WAIT_V(0); BAR; WAIT_L(0); MMA(0, 1, At, B1); BAR;
;     LDA(At, 1, 1); BAR; WAIT_L(0); MMA(1, 0, At, B0); MMA(1, 1, At, B1); BAR; }
;   if (wr == 0) BAR;
	ds_read_b128 v[212:215], v146
	ds_read_b128 v[216:219], v146 offset:1024
	ds_read_b128 v[220:223], v146 offset:2048
	ds_read_b128 v[144:147], v146 offset:3072
	s_waitcnt vmcnt(0)
	s_barrier
	s_waitcnt lgkmcnt(0)
	s_setprio 1
	s_waitcnt lgkmcnt(0)
	v_mfma_f32_16x16x32_bf16 v[92:95], v[16:19], v[212:215], v[92:95]
	v_mfma_f32_16x16x32_bf16 v[16:19], v[16:19], v[220:223], v[88:91]
	v_mfma_f32_16x16x32_bf16 v[124:127], v[20:23], v[144:147], v[16:19]
	v_mfma_f32_16x16x32_bf16 v[16:19], v[32:35], v[212:215], v[158:161]
	v_mfma_f32_16x16x32_bf16 v[104:107], v[36:39], v[216:219], v[16:19]
	v_mfma_f32_16x16x32_bf16 v[16:19], v[32:35], v[220:223], v[168:171]
	v_mfma_f32_16x16x32_bf16 v[108:111], v[36:39], v[144:147], v[16:19]
	v_mfma_f32_16x16x32_bf16 v[16:19], v[48:51], v[212:215], v[76:79]
	v_mfma_f32_16x16x32_bf16 v[88:91], v[52:55], v[216:219], v[16:19]
	v_mfma_f32_16x16x32_bf16 v[16:19], v[48:51], v[220:223], v[72:75]
	v_mfma_f32_16x16x32_bf16 v[120:123], v[20:23], v[216:219], v[92:95]
	v_mfma_f32_16x16x32_bf16 v[92:95], v[52:55], v[144:147], v[16:19]
	v_mfma_f32_16x16x32_bf16 v[16:19], v[232:235], v[212:215], v[172:175]
	v_mfma_f32_16x16x32_bf16 v[72:75], v[236:239], v[216:219], v[16:19]
	v_mfma_f32_16x16x32_bf16 v[16:19], v[232:235], v[220:223], v[176:179]
	v_mfma_f32_16x16x32_bf16 v[76:79], v[236:239], v[144:147], v[16:19]
	s_setprio 0
	s_barrier
	ds_read_b128 v[158:161], v143 offset:49152
	ds_read_b128 v[166:169], v143 offset:50176
	ds_read_b128 v[170:173], v142 offset:49152
	ds_read_b128 v[174:177], v142 offset:50176
	ds_read_b128 v[224:227], v141 offset:49152
	ds_read_b128 v[232:235], v141 offset:50176
	ds_read_b128 v[236:239], v140 offset:49152
	ds_read_b128 v[140:143], v140 offset:50176
	s_barrier
	s_waitcnt lgkmcnt(0)
	s_setprio 1
	s_waitcnt lgkmcnt(0)
	v_mfma_f32_16x16x32_bf16 v[16:19], v[158:161], v[0:3], v[60:63]
	v_mfma_f32_16x16x32_bf16 v[48:51], v[166:169], v[4:7], v[16:19]
	v_mfma_f32_16x16x32_bf16 v[16:19], v[158:161], v[188:191], v[56:59]
	v_mfma_f32_16x16x32_bf16 v[52:55], v[166:169], v[194:197], v[16:19]
	v_mfma_f32_16x16x32_bf16 v[16:19], v[170:173], v[0:3], v[208:211]
	v_mfma_f32_16x16x32_bf16 v[32:35], v[174:177], v[4:7], v[16:19]
	v_mfma_f32_16x16x32_bf16 v[16:19], v[170:173], v[188:191], v[228:231]
	v_mfma_f32_16x16x32_bf16 v[36:39], v[174:177], v[194:197], v[16:19]
	v_mfma_f32_16x16x32_bf16 v[16:19], v[224:227], v[0:3], v[44:47]
	v_mfma_f32_16x16x32_bf16 v[0:3], v[236:239], v[0:3], v[128:131]
	v_mfma_f32_16x16x32_bf16 v[16:19], v[232:235], v[4:7], v[16:19]
	v_mfma_f32_16x16x32_bf16 v[20:23], v[224:227], v[188:191], v[40:43]
	v_mfma_f32_16x16x32_bf16 v[0:3], v[140:143], v[4:7], v[0:3]
	v_mfma_f32_16x16x32_bf16 v[4:7], v[236:239], v[188:191], v[150:153]
	v_mfma_f32_16x16x32_bf16 v[20:23], v[232:235], v[194:197], v[20:23]
	v_mfma_f32_16x16x32_bf16 v[4:7], v[140:143], v[194:197], v[4:7]
	s_setprio 0
	s_setprio 1
	v_mfma_f32_16x16x32_bf16 v[24:27], v[158:161], v[220:223], v[24:27]
	v_mfma_f32_16x16x32_bf16 v[60:63], v[166:169], v[144:147], v[24:27]
	v_mfma_f32_16x16x32_bf16 v[24:27], v[170:173], v[212:215], v[154:157]
	v_mfma_f32_16x16x32_bf16 v[28:31], v[158:161], v[212:215], v[28:31]
	v_mfma_f32_16x16x32_bf16 v[40:43], v[174:177], v[216:219], v[24:27]
	v_mfma_f32_16x16x32_bf16 v[24:27], v[170:173], v[220:223], v[162:165]
	v_mfma_f32_16x16x32_bf16 v[12:15], v[224:227], v[212:215], v[12:15]
	v_mfma_f32_16x16x32_bf16 v[8:11], v[224:227], v[220:223], v[8:11]
	v_mfma_f32_16x16x32_bf16 v[56:59], v[166:169], v[216:219], v[28:31]
	v_mfma_f32_16x16x32_bf16 v[44:47], v[174:177], v[144:147], v[24:27]
	v_mfma_f32_16x16x32_bf16 v[24:27], v[232:235], v[216:219], v[12:15]
	v_mfma_f32_16x16x32_bf16 v[28:31], v[232:235], v[144:147], v[8:11]
	v_mfma_f32_16x16x32_bf16 v[8:11], v[236:239], v[212:215], v[180:183]
	v_mfma_f32_16x16x32_bf16 v[12:15], v[236:239], v[220:223], v[184:187]
	v_mfma_f32_16x16x32_bf16 v[8:11], v[140:143], v[216:219], v[8:11]
	v_mfma_f32_16x16x32_bf16 v[12:15], v[140:143], v[144:147], v[12:15]
	s_setprio 0
	v_cmp_gt_u32_e32 vcc, s81, v135
	s_barrier
	s_and_saveexec_b64 s[66:67], vcc
	s_cbranch_execz .LBB0_82
	s_barrier
	s_branch .LBB0_82

; template <bool ABLK, class Epi>
; __device__ __forceinline__ void gemm_phase(const bf16* A, int lda, const bf16* Bt, int ldb, int M, int N, int K, char* smem, const Epi& epi, int wv) {
;   const int nM = M / BM, nN = N / BM, nwg = nM * nN;
;   __syncthreads();
;   for (int w = blockIdx.x; w < nwg; w += gridDim.x) {
;     int wgid = w;
;     { int q = nwg / NXCD, r = nwg % NXCD, xcd = wgid % NXCD, off = wgid / NXCD;
;       wgid = (xcd < r ? xcd * (q + 1) : r * (q + 1) + (xcd - r) * q) + off; }
;     const int nig = WGM * nN, gid = wgid / nig, fm = gid * WGM, gsz = min(nM - fm, WGM);
;     const int pm = fm + ((wgid % nig) % gsz), pn = (wgid % nig) / gsz;
;     gemm_tile<ABLK>(A, lda, Bt, ldb, K, pm * BM, pn * BM, (bf16*)smem, epi, wv);
.LBB0_364:
	s_or_b64 exec, exec, s[4:5]
	s_cmpk_lt_i32 s89, 0x600
	s_mov_b64 s[12:13], s[90:91]
	s_mov_b64 s[14:15], s[90:91]
	s_mov_b64 s[16:17], s[90:91]
	s_mov_b64 s[20:21], s[90:91]
	s_mov_b64 s[18:19], s[90:91]
	s_cselect_b64 s[6:7], -1, 0
	s_cmpk_gt_i32 s89, 0x5ff
	s_barrier
	s_barrier
	s_cbranch_scc1 .LBB0_502
	s_load_dwordx2 s[22:23], s[12:13], 0xa8
	s_load_dwordx2 s[24:25], s[14:15], 0xa8
	s_load_dwordx2 s[4:5], s[16:17], 0xa0
	s_load_dwordx2 s[8:9], s[20:21], 0x0
	s_load_dwordx2 s[10:11], s[18:19], 0x8
	s_waitcnt lgkmcnt(0)
	s_add_u32 s0, s22, 0xba40000
	s_addc_u32 s1, s23, 0
	s_add_u32 s3, s24, 0x1800000
	s_addc_u32 s68, s25, 0
	s_add_u32 s69, s22, 0xba5a000
	s_addc_u32 s70, s23, 0
	s_add_u32 s71, s24, 0x1882180
	s_addc_u32 s72, s25, 0
	s_mov_b32 s22, 0xffff2000
	s_mov_b32 s24, 0xffff4000
	s_mov_b32 s26, 0xfff7df80
	s_movk_i32 s28, 0xdf80
	s_mov_b32 s30, 0xffff6000
	s_movk_i32 s34, 0x8000
	s_mov_b32 s36, 0xfff7ff80
	s_movk_i32 s38, 0xff80
	s_movk_i32 s40, 0xa000
	s_movk_i32 s42, 0xc000
	s_mov_b32 s44, 0xfff7e000
	s_movk_i32 s46, 0xe000
	s_mov_b32 s48, 0xfff80000
	s_add_i32 s73, 0, 0x10000
	s_mov_b64 s[12:13], 0x80000
	s_add_i32 s74, 0, 0x14000
	s_mov_b64 s[14:15], 0x80
	s_add_i32 s75, 0, 0x18000
	s_mov_b64 s[16:17], 0x80080
	s_mov_b64 s[18:19], 0x8000
	s_mov_b64 s[20:21], 0xa000
	s_add_i32 s76, 0, 0x1c000
	s_movk_i32 s77, 0x3c0
	s_mov_b32 s23, -1
	s_mov_b32 s25, -1
	s_mov_b32 s27, -1
	s_mov_b32 s29, -1
	s_mov_b32 s31, -1
	s_mov_b32 s35, -1
	s_mov_b32 s37, -1
	s_mov_b32 s39, -1
	s_mov_b32 s41, -1
	s_mov_b32 s43, -1
	s_mov_b32 s45, -1
	s_mov_b32 s47, -1
	s_mov_b32 s49, -1
	s_mov_b64 s[50:51], 0x10000
	s_mov_b64 s[52:53], 0x100
	s_mov_b64 s[54:55], 0xfc000
	s_mov_b64 s[56:57], 0xfe000
	s_movk_i32 s78, 0x100
	s_movk_i32 s79, 0x3fff
	v_mov_b32_e32 v129, 0
	s_movk_i32 s80, 0x3ffe
	s_movk_i32 s81, 0x3ffd
	s_movk_i32 s82, 0x3ffc
	v_mov_b32_e32 v140, 1
	s_mov_b32 s83, s89
	v_lshlrev_b32_e32 v254, 4, v192
	s_nop 0
	v_readfirstlane_b32 s99, v254
	s_branch .LBB0_367

; #define STAGE_A(P, hf, kt) do { if constexpr (ABLK) { const bf16* _gp = A + ((long)(brow >> 8) * nt + (kt)) * 16384 + (hf) * 8192; GLDS2(_gp, 4096, offA, P); } \
;     else { const bf16* _gp = A + (long)(brow + (hf) * HALF) * lda + (long)(kt) * BK; GLDS2(_gp, 64 * (long)lda, offA, P); } } while (0)
; #define STAGE_B(P, hf, kt) do { const bf16* _gp = Bt + (long)(bcol + (hf) * 2) * ldb + (long)(kt) * BK; GLDS2(_gp, 128 * (long)ldb, offB, P); } while (0)
; #define LDA(dst, b, h) for (int m = 0; m < 4; ++m) for (int k = 0; k < 2; ++k) \
;     dst[m][k] = *reinterpret_cast<const bf16x8*>((char*)SA(b, h) + lds_byte(wr * 64 + m * 16 + fr, k * 32 + fq * 8))
; #define LDB(dst, b, h) for (int n = 0; n < 2; ++n) for (int k = 0; k < 2; ++k) \
;     dst[n][k] = *reinterpret_cast<const bf16x8*>((char*)SB(b, h) + lds_byte(wc * 32 + n * 16 + fr, k * 32 + fq * 8))
; #define MMA(ai, bj, At, Bt_) do { __builtin_amdgcn_s_setprio(1); \
;     for (int m = 0; m < 4; ++m) for (int n = 0; n < 2; ++n) for (int k = 0; k < 2; ++k) \
;       acc[ai][bj][m][n] = __builtin_amdgcn_mfma_f32_16x16x32_bf16(At[m][k], Bt_[n][k], acc[ai][bj][m][n], 0, 0, 0); \
;     __builtin_amdgcn_s_setprio(0); } while (0)
; #define WAIT_V(n) asm volatile("s_waitcnt vmcnt(" #n ")" ::: "memory")
; #define WAIT_L(n) asm volatile("s_waitcnt lgkmcnt(" #n ")" ::: "memory")
; #define BAR __builtin_amdgcn_s_barrier()
; #define SCHED __builtin_amdgcn_sched_barrier(0)
; template <bool ABLK, class Epi>
; __device__ __forceinline__ void gemm_tile(const bf16* __restrict__ A, int lda, const bf16* __restrict__ Bt, int ldb, int K,
;                                           int brow, int bcol, bf16* shm, const Epi& epi, int wv) {
;     ...
;   for (int t = 0; t < nt - 2; t += 2) {
;     LDB(B0, 0, 0); SCHED; LDA(At, 0, 0); STAGE_A(SA(1, 1), 1, t + 1);
;     WAIT_L(8); BAR; MMA(0, 0, At, B0); BAR; SCHED;
;     LDB(B1, 0, 1); STAGE_B(SB(0, 0), 0, t + 2);
;     BAR; MMA(0, 1, At, B1); BAR;
;     LDA(At, 0, 1); STAGE_A(SA(0, 0), 0, t + 2);
;     BAR; MMA(1, 0, At, B0); BAR; SCHED;
;     STAGE_B(SB(0, 1), 1, t + 2);
;     WAIT_V(6); BAR; MMA(1, 1, At, B1); BAR;
.LBB0_370:
	ds_read_b128 v[166:169], v162
	ds_read_b128 v[170:173], v162 offset:1024
	ds_read_b128 v[174:177], v162 offset:2048
	ds_read_b128 v[178:181], v162 offset:3072
	v_add_u32_e32 v163, 0xc000, v148
	v_lshl_add_u64 v[164:165], v[132:133], 0, s[22:23]
	s_add_i32 m0, s99, 0xc000
	ds_read_b128 v[182:185], v144
	ds_read_b128 v[186:189], v144 offset:1024
	ds_read_b128 v[194:197], v143
	ds_read_b128 v[202:205], v143 offset:1024
	ds_read_b128 v[208:211], v142
	ds_read_b128 v[212:215], v142 offset:1024
	ds_read_b128 v[216:219], v141
	ds_read_b128 v[220:223], v141 offset:1024
	global_load_lds_dwordx4 v[164:165], off
	v_add_u32_e32 v164, 0xe000, v148
	s_add_i32 m0, s99, 0xe000
	v_lshl_add_u64 v[190:191], v[132:133], 0, s[24:25]
	global_load_lds_dwordx4 v[190:191], off
	s_waitcnt lgkmcnt(8)
	s_barrier
	s_setprio 1
	s_waitcnt lgkmcnt(0)
	v_mfma_f32_16x16x32_bf16 v[124:127], v[182:185], v[166:169], v[124:127]
	v_mfma_f32_16x16x32_bf16 v[120:123], v[182:185], v[174:177], v[120:123]
	v_mfma_f32_16x16x32_bf16 v[116:119], v[194:197], v[166:169], v[116:119]
	v_mfma_f32_16x16x32_bf16 v[112:115], v[194:197], v[174:177], v[112:115]
	v_mfma_f32_16x16x32_bf16 v[108:111], v[208:211], v[166:169], v[108:111]
	v_mfma_f32_16x16x32_bf16 v[104:107], v[208:211], v[174:177], v[104:107]
	v_mfma_f32_16x16x32_bf16 v[100:103], v[216:219], v[166:169], v[100:103]
	v_mfma_f32_16x16x32_bf16 v[96:99], v[216:219], v[174:177], v[96:99]
	v_mfma_f32_16x16x32_bf16 v[124:127], v[186:189], v[170:173], v[124:127]
	v_mfma_f32_16x16x32_bf16 v[120:123], v[186:189], v[178:181], v[120:123]
	v_mfma_f32_16x16x32_bf16 v[116:119], v[202:205], v[170:173], v[116:119]
	v_mfma_f32_16x16x32_bf16 v[112:115], v[202:205], v[178:181], v[112:115]
	v_mfma_f32_16x16x32_bf16 v[108:111], v[212:215], v[170:173], v[108:111]
	v_mfma_f32_16x16x32_bf16 v[104:107], v[212:215], v[178:181], v[104:107]
	v_mfma_f32_16x16x32_bf16 v[100:103], v[220:223], v[170:173], v[100:103]
	v_mfma_f32_16x16x32_bf16 v[96:99], v[220:223], v[178:181], v[96:99]
	s_setprio 0
	s_barrier
	v_lshl_add_u64 v[190:191], v[134:135], 0, s[26:27]
	s_add_i32 m0, s99, 0x10000
	ds_read_b128 v[224:227], v161
	ds_read_b128 v[228:231], v161 offset:1024
	ds_read_b128 v[232:235], v161 offset:2048
	ds_read_b128 v[236:239], v161 offset:3072
	global_load_lds_dwordx4 v[190:191], off
	s_add_i32 m0, s99, 0x12000
	v_lshl_add_u64 v[190:191], v[134:135], 0, s[28:29]
	global_load_lds_dwordx4 v[190:191], off
	s_barrier
	s_setprio 1
	s_waitcnt lgkmcnt(0)
	v_mfma_f32_16x16x32_bf16 v[92:95], v[182:185], v[224:227], v[92:95]
	v_mfma_f32_16x16x32_bf16 v[88:91], v[182:185], v[232:235], v[88:91]
	v_mfma_f32_16x16x32_bf16 v[84:87], v[194:197], v[224:227], v[84:87]
	v_mfma_f32_16x16x32_bf16 v[80:83], v[194:197], v[232:235], v[80:83]
	v_mfma_f32_16x16x32_bf16 v[76:79], v[208:211], v[224:227], v[76:79]
	v_mfma_f32_16x16x32_bf16 v[72:75], v[208:211], v[232:235], v[72:75]
	v_mfma_f32_16x16x32_bf16 v[68:71], v[216:219], v[224:227], v[68:71]
	v_mfma_f32_16x16x32_bf16 v[64:67], v[216:219], v[232:235], v[64:67]
	v_mfma_f32_16x16x32_bf16 v[92:95], v[186:189], v[228:231], v[92:95]
	v_mfma_f32_16x16x32_bf16 v[88:91], v[186:189], v[236:239], v[88:91]
	v_mfma_f32_16x16x32_bf16 v[84:87], v[202:205], v[228:231], v[84:87]
	v_mfma_f32_16x16x32_bf16 v[80:83], v[202:205], v[236:239], v[80:83]
	v_mfma_f32_16x16x32_bf16 v[76:79], v[212:215], v[228:231], v[76:79]
	v_mfma_f32_16x16x32_bf16 v[72:75], v[212:215], v[236:239], v[72:75]
	v_mfma_f32_16x16x32_bf16 v[68:71], v[220:223], v[228:231], v[68:71]
	v_mfma_f32_16x16x32_bf16 v[64:67], v[220:223], v[236:239], v[64:67]
	s_setprio 0
	v_lshl_add_u64 v[190:191], v[132:133], 0, s[30:31]
	s_add_i32 m0, s99, 0x0
	s_barrier
	ds_read_b128 v[182:185], v144 offset:16384
	ds_read_b128 v[186:189], v144 offset:17408
	ds_read_b128 v[194:197], v143 offset:16384
	ds_read_b128 v[202:205], v143 offset:17408
	ds_read_b128 v[208:211], v142 offset:16384
	ds_read_b128 v[212:215], v142 offset:17408
	ds_read_b128 v[216:219], v141 offset:16384
	ds_read_b128 v[220:223], v141 offset:17408
	global_load_lds_dwordx4 v[190:191], off
	s_add_i32 m0, s99, 0x2000
	v_lshl_add_u64 v[190:191], v[132:133], 0, s[34:35]
	global_load_lds_dwordx4 v[190:191], off
	s_barrier
	s_setprio 1
	s_waitcnt lgkmcnt(0)
	v_mfma_f32_16x16x32_bf16 v[60:63], v[182:185], v[166:169], v[60:63]
	v_mfma_f32_16x16x32_bf16 v[56:59], v[182:185], v[174:177], v[56:59]
	v_mfma_f32_16x16x32_bf16 v[52:55], v[194:197], v[166:169], v[52:55]
	v_mfma_f32_16x16x32_bf16 v[48:51], v[194:197], v[174:177], v[48:51]
	v_mfma_f32_16x16x32_bf16 v[44:47], v[208:211], v[166:169], v[44:47]
	v_mfma_f32_16x16x32_bf16 v[40:43], v[208:211], v[174:177], v[40:43]
	v_mfma_f32_16x16x32_bf16 v[36:39], v[216:219], v[166:169], v[36:39]
	v_mfma_f32_16x16x32_bf16 v[32:35], v[216:219], v[174:177], v[32:35]
	v_mfma_f32_16x16x32_bf16 v[60:63], v[186:189], v[170:173], v[60:63]
	v_mfma_f32_16x16x32_bf16 v[56:59], v[186:189], v[178:181], v[56:59]
	v_mfma_f32_16x16x32_bf16 v[52:55], v[202:205], v[170:173], v[52:55]
	v_mfma_f32_16x16x32_bf16 v[48:51], v[202:205], v[178:181], v[48:51]
	v_mfma_f32_16x16x32_bf16 v[44:47], v[212:215], v[170:173], v[44:47]
	v_mfma_f32_16x16x32_bf16 v[40:43], v[212:215], v[178:181], v[40:43]
	v_mfma_f32_16x16x32_bf16 v[36:39], v[220:223], v[170:173], v[36:39]
	v_mfma_f32_16x16x32_bf16 v[32:35], v[220:223], v[178:181], v[32:35]
	s_setprio 0
	s_barrier
	s_add_i32 m0, s99, 0x14000
	v_lshl_add_u64 v[166:167], v[134:135], 0, s[36:37]
	global_load_lds_dwordx4 v[166:167], off
	s_add_i32 m0, s99, 0x16000
	v_lshl_add_u64 v[166:167], v[134:135], 0, s[38:39]
	global_load_lds_dwordx4 v[166:167], off
	s_waitcnt vmcnt(6)
	s_barrier
; #define STAGE_A(P, hf, kt) do { if constexpr (ABLK) { const bf16* _gp = A + ((long)(brow >> 8) * nt + (kt)) * 16384 + (hf) * 8192; GLDS2(_gp, 4096, offA, P); } \
;     else { const bf16* _gp = A + (long)(brow + (hf) * HALF) * lda + (long)(kt) * BK; GLDS2(_gp, 64 * (long)lda, offA, P); } } while (0)
; #define STAGE_B(P, hf, kt) do { const bf16* _gp = Bt + (long)(bcol + (hf) * 2) * ldb + (long)(kt) * BK; GLDS2(_gp, 128 * (long)ldb, offB, P); } while (0)
; #define LDA(dst, b, h) for (int m = 0; m < 4; ++m) for (int k = 0; k < 2; ++k) \
;     dst[m][k] = *reinterpret_cast<const bf16x8*>((char*)SA(b, h) + lds_byte(wr * 64 + m * 16 + fr, k * 32 + fq * 8))
; #define LDB(dst, b, h) for (int n = 0; n < 2; ++n) for (int k = 0; k < 2; ++k) \
;     dst[n][k] = *reinterpret_cast<const bf16x8*>((char*)SB(b, h) + lds_byte(wc * 32 + n * 16 + fr, k * 32 + fq * 8))
; #define MMA(ai, bj, At, Bt_) do { __builtin_amdgcn_s_setprio(1); \
;     for (int m = 0; m < 4; ++m) for (int n = 0; n < 2; ++n) for (int k = 0; k < 2; ++k) \
;       acc[ai][bj][m][n] = __builtin_amdgcn_mfma_f32_16x16x32_bf16(At[m][k], Bt_[n][k], acc[ai][bj][m][n], 0, 0, 0); \
;     __builtin_amdgcn_s_setprio(0); } while (0)
; #define WAIT_V(n) asm volatile("s_waitcnt vmcnt(" #n ")" ::: "memory")
; #define WAIT_L(n) asm volatile("s_waitcnt lgkmcnt(" #n ")" ::: "memory")
; #define BAR __builtin_amdgcn_s_barrier()
; #define SCHED __builtin_amdgcn_sched_barrier(0)
; template <bool ABLK, class Epi>
; __device__ __forceinline__ void gemm_tile(const bf16* __restrict__ A, int lda, const bf16* __restrict__ Bt, int ldb, int K,
;                                           int brow, int bcol, bf16* shm, const Epi& epi, int wv) {
;     ...
;     LDB(B0, 1, 0); SCHED; LDA(At, 1, 0); STAGE_A(SA(0, 1), 1, t + 2);
;     WAIT_L(8); BAR; MMA(0, 0, At, B0); BAR; SCHED;
;     LDB(B1, 1, 1); STAGE_B(SB(1, 0), 0, t + 3);
;     BAR; MMA(0, 1, At, B1); BAR;
;     LDA(At, 1, 1); STAGE_A(SA(1, 0), 0, t + 3);
;     BAR; MMA(1, 0, At, B0); BAR; SCHED;
;     STAGE_B(SB(1, 1), 1, t + 3);
;     WAIT_V(6); BAR; MMA(1, 1, At, B1); BAR;
	s_setprio 1
	v_mfma_f32_16x16x32_bf16 v[28:31], v[182:185], v[224:227], v[28:31]
	v_mfma_f32_16x16x32_bf16 v[24:27], v[182:185], v[232:235], v[24:27]
	v_mfma_f32_16x16x32_bf16 v[20:23], v[194:197], v[224:227], v[20:23]
	v_mfma_f32_16x16x32_bf16 v[16:19], v[194:197], v[232:235], v[16:19]
	v_mfma_f32_16x16x32_bf16 v[12:15], v[208:211], v[224:227], v[12:15]
	v_mfma_f32_16x16x32_bf16 v[8:11], v[208:211], v[232:235], v[8:11]
	v_mfma_f32_16x16x32_bf16 v[4:7], v[216:219], v[224:227], v[4:7]
	v_mfma_f32_16x16x32_bf16 v[0:3], v[216:219], v[232:235], v[0:3]
	v_mfma_f32_16x16x32_bf16 v[28:31], v[186:189], v[228:231], v[28:31]
	v_mfma_f32_16x16x32_bf16 v[24:27], v[186:189], v[236:239], v[24:27]
	v_mfma_f32_16x16x32_bf16 v[20:23], v[202:205], v[228:231], v[20:23]
	v_mfma_f32_16x16x32_bf16 v[16:19], v[202:205], v[236:239], v[16:19]
	v_mfma_f32_16x16x32_bf16 v[12:15], v[212:215], v[228:231], v[12:15]
	v_mfma_f32_16x16x32_bf16 v[8:11], v[212:215], v[236:239], v[8:11]
	v_mfma_f32_16x16x32_bf16 v[4:7], v[220:223], v[228:231], v[4:7]
	v_mfma_f32_16x16x32_bf16 v[0:3], v[220:223], v[236:239], v[0:3]
	s_setprio 0
	s_barrier
	ds_read_b128 v[166:169], v151
	ds_read_b128 v[170:173], v151 offset:1024
	ds_read_b128 v[174:177], v151 offset:2048
	ds_read_b128 v[178:181], v151 offset:3072
	v_lshl_add_u64 v[190:191], v[132:133], 0, s[40:41]
	s_add_i32 m0, s99, 0x4000
	ds_read_b128 v[182:185], v144 offset:32768
	ds_read_b128 v[186:189], v144 offset:33792
	ds_read_b128 v[194:197], v143 offset:32768
	ds_read_b128 v[202:205], v143 offset:33792
	ds_read_b128 v[208:211], v142 offset:32768
	ds_read_b128 v[212:215], v142 offset:33792
	ds_read_b128 v[216:219], v141 offset:32768
	ds_read_b128 v[220:223], v141 offset:33792
	global_load_lds_dwordx4 v[190:191], off
	s_add_i32 m0, s99, 0x6000
	v_lshl_add_u64 v[190:191], v[132:133], 0, s[42:43]
	global_load_lds_dwordx4 v[190:191], off
	s_waitcnt lgkmcnt(8)
	s_barrier
	s_setprio 1
	s_waitcnt lgkmcnt(0)
	v_mfma_f32_16x16x32_bf16 v[124:127], v[182:185], v[166:169], v[124:127]
	v_mfma_f32_16x16x32_bf16 v[120:123], v[182:185], v[174:177], v[120:123]
	v_mfma_f32_16x16x32_bf16 v[116:119], v[194:197], v[166:169], v[116:119]
	v_mfma_f32_16x16x32_bf16 v[112:115], v[194:197], v[174:177], v[112:115]
	v_mfma_f32_16x16x32_bf16 v[108:111], v[208:211], v[166:169], v[108:111]
	v_mfma_f32_16x16x32_bf16 v[104:107], v[208:211], v[174:177], v[104:107]
	v_mfma_f32_16x16x32_bf16 v[100:103], v[216:219], v[166:169], v[100:103]
	v_mfma_f32_16x16x32_bf16 v[96:99], v[216:219], v[174:177], v[96:99]
	v_mfma_f32_16x16x32_bf16 v[124:127], v[186:189], v[170:173], v[124:127]
	v_mfma_f32_16x16x32_bf16 v[120:123], v[186:189], v[178:181], v[120:123]
	v_mfma_f32_16x16x32_bf16 v[116:119], v[202:205], v[170:173], v[116:119]
	v_mfma_f32_16x16x32_bf16 v[112:115], v[202:205], v[178:181], v[112:115]
	v_mfma_f32_16x16x32_bf16 v[108:111], v[212:215], v[170:173], v[108:111]
	v_mfma_f32_16x16x32_bf16 v[104:107], v[212:215], v[178:181], v[104:107]
	v_mfma_f32_16x16x32_bf16 v[100:103], v[220:223], v[170:173], v[100:103]
	v_mfma_f32_16x16x32_bf16 v[96:99], v[220:223], v[178:181], v[96:99]
	s_setprio 0
	s_barrier
	v_lshl_add_u64 v[190:191], v[134:135], 0, s[44:45]
	s_add_i32 m0, s99, 0x18000
	ds_read_b128 v[224:227], v147
	ds_read_b128 v[228:231], v147 offset:1024
	ds_read_b128 v[232:235], v147 offset:2048
	ds_read_b128 v[236:239], v147 offset:3072
	global_load_lds_dwordx4 v[190:191], off
	s_add_i32 m0, s99, 0x1a000
	v_lshl_add_u64 v[190:191], v[134:135], 0, s[46:47]
	global_load_lds_dwordx4 v[190:191], off
	s_barrier
	s_setprio 1
	s_waitcnt lgkmcnt(0)
	v_mfma_f32_16x16x32_bf16 v[92:95], v[182:185], v[224:227], v[92:95]
	v_mfma_f32_16x16x32_bf16 v[88:91], v[182:185], v[232:235], v[88:91]
	v_mfma_f32_16x16x32_bf16 v[84:87], v[194:197], v[224:227], v[84:87]
	v_mfma_f32_16x16x32_bf16 v[80:83], v[194:197], v[232:235], v[80:83]
	v_mfma_f32_16x16x32_bf16 v[76:79], v[208:211], v[224:227], v[76:79]
	v_mfma_f32_16x16x32_bf16 v[72:75], v[208:211], v[232:235], v[72:75]
	v_mfma_f32_16x16x32_bf16 v[68:71], v[216:219], v[224:227], v[68:71]
	v_mfma_f32_16x16x32_bf16 v[64:67], v[216:219], v[232:235], v[64:67]
	v_mfma_f32_16x16x32_bf16 v[92:95], v[186:189], v[228:231], v[92:95]
	v_mfma_f32_16x16x32_bf16 v[88:91], v[186:189], v[236:239], v[88:91]
	v_mfma_f32_16x16x32_bf16 v[84:87], v[202:205], v[228:231], v[84:87]
	v_mfma_f32_16x16x32_bf16 v[80:83], v[202:205], v[236:239], v[80:83]
	v_mfma_f32_16x16x32_bf16 v[76:79], v[212:215], v[228:231], v[76:79]
	v_mfma_f32_16x16x32_bf16 v[72:75], v[212:215], v[236:239], v[72:75]
	v_mfma_f32_16x16x32_bf16 v[68:71], v[220:223], v[228:231], v[68:71]
	v_mfma_f32_16x16x32_bf16 v[64:67], v[220:223], v[236:239], v[64:67]
	s_setprio 0
	v_lshl_add_u64 v[190:191], v[132:133], 0, s[46:47]
	s_add_i32 m0, s99, 0x8000
	s_barrier
	ds_read_b128 v[182:185], v144 offset:49152
	ds_read_b128 v[186:189], v144 offset:50176
	ds_read_b128 v[194:197], v143 offset:49152
	ds_read_b128 v[202:205], v143 offset:50176
	ds_read_b128 v[208:211], v142 offset:49152
	ds_read_b128 v[212:215], v142 offset:50176
	ds_read_b128 v[216:219], v141 offset:49152
	ds_read_b128 v[220:223], v141 offset:50176
	global_load_lds_dwordx4 v[190:191], off
	s_add_i32 m0, s99, 0xa000
	s_nop 0
	global_load_lds_dwordx4 v[132:133], off
	s_barrier
; #define STAGE_A(P, hf, kt) do { if constexpr (ABLK) { const bf16* _gp = A + ((long)(brow >> 8) * nt + (kt)) * 16384 + (hf) * 8192; GLDS2(_gp, 4096, offA, P); } \
;     else { const bf16* _gp = A + (long)(brow + (hf) * HALF) * lda + (long)(kt) * BK; GLDS2(_gp, 64 * (long)lda, offA, P); } } while (0)
; #define STAGE_B(P, hf, kt) do { const bf16* _gp = Bt + (long)(bcol + (hf) * 2) * ldb + (long)(kt) * BK; GLDS2(_gp, 128 * (long)ldb, offB, P); } while (0)
; #define LDA(dst, b, h) for (int m = 0; m < 4; ++m) for (int k = 0; k < 2; ++k) \
;     dst[m][k] = *reinterpret_cast<const bf16x8*>((char*)SA(b, h) + lds_byte(wr * 64 + m * 16 + fr, k * 32 + fq * 8))
; #define LDB(dst, b, h) for (int n = 0; n < 2; ++n) for (int k = 0; k < 2; ++k) \
;     dst[n][k] = *reinterpret_cast<const bf16x8*>((char*)SB(b, h) + lds_byte(wc * 32 + n * 16 + fr, k * 32 + fq * 8))
; #define MMA(ai, bj, At, Bt_) do { __builtin_amdgcn_s_setprio(1); \
;     for (int m = 0; m < 4; ++m) for (int n = 0; n < 2; ++n) for (int k = 0; k < 2; ++k) \
;       acc[ai][bj][m][n] = __builtin_amdgcn_mfma_f32_16x16x32_bf16(At[m][k], Bt_[n][k], acc[ai][bj][m][n], 0, 0, 0); \
;     __builtin_amdgcn_s_setprio(0); } while (0)
; #define WAIT_V(n) asm volatile("s_waitcnt vmcnt(" #n ")" ::: "memory")
; #define WAIT_L(n) asm volatile("s_waitcnt lgkmcnt(" #n ")" ::: "memory")
; #define BAR __builtin_amdgcn_s_barrier()
; #define SCHED __builtin_amdgcn_sched_barrier(0)
; template <bool ABLK, class Epi>
; __device__ __forceinline__ void gemm_tile(const bf16* __restrict__ A, int lda, const bf16* __restrict__ Bt, int ldb, int K,
;                                           int brow, int bcol, bf16* shm, const Epi& epi, int wv) {
;     ...
;     BAR; MMA(1, 0, At, B0); BAR; SCHED;
;     STAGE_B(SB(1, 1), 1, t + 3);
;     WAIT_V(6); BAR; MMA(1, 1, At, B1); BAR;
;   }
;   { LDB(B0, 0, 0); LDA(At, 0, 0); STAGE_A(SA(1, 1), 1, nt - 1);
;     BAR; WAIT_L(0); MMA(0, 0, At, B0); BAR;
;     LDB(B1, 0, 1); BAR; WAIT_L(0); MMA(0, 1, At, B1); BAR;
;     LDA(At, 0, 1); WAIT_V(4); BAR; WAIT_L(0); MMA(1, 0, At, B0); MMA(1, 1, At, B1); BAR; }
	s_setprio 1
	s_waitcnt lgkmcnt(0)
	v_mfma_f32_16x16x32_bf16 v[60:63], v[182:185], v[166:169], v[60:63]
	v_mfma_f32_16x16x32_bf16 v[56:59], v[182:185], v[174:177], v[56:59]
	v_mfma_f32_16x16x32_bf16 v[52:55], v[194:197], v[166:169], v[52:55]
	v_mfma_f32_16x16x32_bf16 v[48:51], v[194:197], v[174:177], v[48:51]
	v_mfma_f32_16x16x32_bf16 v[44:47], v[208:211], v[166:169], v[44:47]
	v_mfma_f32_16x16x32_bf16 v[40:43], v[208:211], v[174:177], v[40:43]
	v_mfma_f32_16x16x32_bf16 v[36:39], v[216:219], v[166:169], v[36:39]
	v_mfma_f32_16x16x32_bf16 v[32:35], v[216:219], v[174:177], v[32:35]
	v_mfma_f32_16x16x32_bf16 v[60:63], v[186:189], v[170:173], v[60:63]
	v_mfma_f32_16x16x32_bf16 v[56:59], v[186:189], v[178:181], v[56:59]
	v_mfma_f32_16x16x32_bf16 v[52:55], v[202:205], v[170:173], v[52:55]
	v_mfma_f32_16x16x32_bf16 v[48:51], v[202:205], v[178:181], v[48:51]
	v_mfma_f32_16x16x32_bf16 v[44:47], v[212:215], v[170:173], v[44:47]
	v_mfma_f32_16x16x32_bf16 v[40:43], v[212:215], v[178:181], v[40:43]
	v_mfma_f32_16x16x32_bf16 v[36:39], v[220:223], v[170:173], v[36:39]
	v_mfma_f32_16x16x32_bf16 v[32:35], v[220:223], v[178:181], v[32:35]
	s_setprio 0
	s_barrier
	s_add_i32 m0, s99, 0x1c000
	v_lshl_add_u64 v[166:167], v[134:135], 0, s[48:49]
	global_load_lds_dwordx4 v[166:167], off
	s_add_i32 m0, s99, 0x1e000
	s_nop 0
	global_load_lds_dwordx4 v[134:135], off
	s_waitcnt vmcnt(6)
	s_barrier
	s_setprio 1
	v_mfma_f32_16x16x32_bf16 v[28:31], v[182:185], v[224:227], v[28:31]
	v_mfma_f32_16x16x32_bf16 v[24:27], v[182:185], v[232:235], v[24:27]
	v_mfma_f32_16x16x32_bf16 v[20:23], v[194:197], v[224:227], v[20:23]
	v_mfma_f32_16x16x32_bf16 v[16:19], v[194:197], v[232:235], v[16:19]
	v_mfma_f32_16x16x32_bf16 v[12:15], v[208:211], v[224:227], v[12:15]
	v_mfma_f32_16x16x32_bf16 v[8:11], v[208:211], v[232:235], v[8:11]
	v_mfma_f32_16x16x32_bf16 v[4:7], v[216:219], v[224:227], v[4:7]
	v_mfma_f32_16x16x32_bf16 v[0:3], v[216:219], v[232:235], v[0:3]
	v_mfma_f32_16x16x32_bf16 v[28:31], v[186:189], v[228:231], v[28:31]
	v_mfma_f32_16x16x32_bf16 v[24:27], v[186:189], v[236:239], v[24:27]
	v_mfma_f32_16x16x32_bf16 v[20:23], v[202:205], v[228:231], v[20:23]
	v_mfma_f32_16x16x32_bf16 v[16:19], v[202:205], v[236:239], v[16:19]
	v_mfma_f32_16x16x32_bf16 v[12:15], v[212:215], v[228:231], v[12:15]
	v_mfma_f32_16x16x32_bf16 v[8:11], v[212:215], v[236:239], v[8:11]
	v_mfma_f32_16x16x32_bf16 v[4:7], v[220:223], v[228:231], v[4:7]
	v_mfma_f32_16x16x32_bf16 v[0:3], v[220:223], v[236:239], v[0:3]
	s_setprio 0
	s_add_i32 s33, s33, 2
	v_lshl_add_u64 v[132:133], v[132:133], 0, s[50:51]
	s_cmp_lt_u32 s33, 28
	v_lshl_add_u64 v[134:135], v[134:135], 0, s[52:53]
	s_barrier
	s_cbranch_scc1 .LBB0_370
	v_readfirstlane_b32 s2, v163
	v_lshl_add_u64 v[148:149], v[130:131], 0, s[54:55]
	s_mov_b32 m0, s2
	v_readfirstlane_b32 s2, v164
	ds_read_b128 v[132:135], v162
	ds_read_b128 v[152:155], v162 offset:1024
	ds_read_b128 v[156:159], v162 offset:2048
	ds_read_b128 v[166:169], v162 offset:3072
	ds_read_b128 v[170:173], v144
	ds_read_b128 v[174:177], v144 offset:1024
	ds_read_b128 v[178:181], v143
	ds_read_b128 v[182:185], v143 offset:1024
	ds_read_b128 v[186:189], v142
	ds_read_b128 v[194:197], v142 offset:1024
	ds_read_b128 v[202:205], v141
	ds_read_b128 v[208:211], v141 offset:1024
	global_load_lds_dwordx4 v[148:149], off
	v_lshl_add_u64 v[130:131], v[130:131], 0, s[56:57]
	s_mov_b32 m0, s2
	s_nop 0
	global_load_lds_dwordx4 v[130:131], off
	s_barrier
	s_waitcnt lgkmcnt(0)
	s_setprio 1
	s_waitcnt lgkmcnt(0)
	v_mfma_f32_16x16x32_bf16 v[124:127], v[170:173], v[132:135], v[124:127]
	v_mfma_f32_16x16x32_bf16 v[120:123], v[170:173], v[156:159], v[120:123]
	v_mfma_f32_16x16x32_bf16 v[108:111], v[186:189], v[132:135], v[108:111]
	v_mfma_f32_16x16x32_bf16 v[104:107], v[186:189], v[156:159], v[104:107]
	v_mfma_f32_16x16x32_bf16 v[124:127], v[174:177], v[152:155], v[124:127]
	v_mfma_f32_16x16x32_bf16 v[120:123], v[174:177], v[166:169], v[120:123]
	v_mfma_f32_16x16x32_bf16 v[116:119], v[178:181], v[132:135], v[116:119]
	v_mfma_f32_16x16x32_bf16 v[112:115], v[178:181], v[156:159], v[112:115]
	v_mfma_f32_16x16x32_bf16 v[108:111], v[194:197], v[152:155], v[108:111]
	v_mfma_f32_16x16x32_bf16 v[104:107], v[194:197], v[166:169], v[104:107]
	v_mfma_f32_16x16x32_bf16 v[100:103], v[202:205], v[132:135], v[100:103]
	v_mfma_f32_16x16x32_bf16 v[96:99], v[202:205], v[156:159], v[96:99]
	v_mfma_f32_16x16x32_bf16 v[162:165], v[182:185], v[152:155], v[116:119]
	v_mfma_f32_16x16x32_bf16 v[212:215], v[182:185], v[166:169], v[112:115]
	v_mfma_f32_16x16x32_bf16 v[216:219], v[208:211], v[152:155], v[100:103]
	v_mfma_f32_16x16x32_bf16 v[220:223], v[208:211], v[166:169], v[96:99]
	s_setprio 0
	s_barrier
	s_nop 1
	ds_read_b128 v[96:99], v161
	ds_read_b128 v[100:103], v161 offset:1024
	ds_read_b128 v[112:115], v161 offset:2048
	ds_read_b128 v[116:119], v161 offset:3072
	s_barrier
	s_waitcnt lgkmcnt(0)
	s_setprio 1
	s_waitcnt lgkmcnt(0)
	v_mfma_f32_16x16x32_bf16 v[92:95], v[170:173], v[96:99], v[92:95]
	v_mfma_f32_16x16x32_bf16 v[88:91], v[170:173], v[112:115], v[88:91]
	v_mfma_f32_16x16x32_bf16 v[76:79], v[186:189], v[96:99], v[76:79]
	v_mfma_f32_16x16x32_bf16 v[72:75], v[186:189], v[112:115], v[72:75]
	v_mfma_f32_16x16x32_bf16 v[92:95], v[174:177], v[100:103], v[92:95]
	v_mfma_f32_16x16x32_bf16 v[88:91], v[174:177], v[116:119], v[88:91]
	v_mfma_f32_16x16x32_bf16 v[84:87], v[178:181], v[96:99], v[84:87]
	v_mfma_f32_16x16x32_bf16 v[80:83], v[178:181], v[112:115], v[80:83]
	v_mfma_f32_16x16x32_bf16 v[76:79], v[194:197], v[100:103], v[76:79]
	v_mfma_f32_16x16x32_bf16 v[72:75], v[194:197], v[116:119], v[72:75]
	v_mfma_f32_16x16x32_bf16 v[68:71], v[202:205], v[96:99], v[68:71]
	v_mfma_f32_16x16x32_bf16 v[64:67], v[202:205], v[112:115], v[64:67]
	v_mfma_f32_16x16x32_bf16 v[170:173], v[182:185], v[100:103], v[84:87]
	v_mfma_f32_16x16x32_bf16 v[174:177], v[182:185], v[116:119], v[80:83]
	v_mfma_f32_16x16x32_bf16 v[178:181], v[208:211], v[100:103], v[68:71]
	v_mfma_f32_16x16x32_bf16 v[182:185], v[208:211], v[116:119], v[64:67]
	s_setprio 0
	s_barrier
; #define LDA(dst, b, h) for (int m = 0; m < 4; ++m) for (int k = 0; k < 2; ++k) \
;     dst[m][k] = *reinterpret_cast<const bf16x8*>((char*)SA(b, h) + lds_byte(wr * 64 + m * 16 + fr, k * 32 + fq * 8))
; #define LDB(dst, b, h) for (int n = 0; n < 2; ++n) for (int k = 0; k < 2; ++k) \
;     dst[n][k] = *reinterpret_cast<const bf16x8*>((char*)SB(b, h) + lds_byte(wc * 32 + n * 16 + fr, k * 32 + fq * 8))
; #define MMA(ai, bj, At, Bt_) do { __builtin_amdgcn_s_setprio(1); \
;     for (int m = 0; m < 4; ++m) for (int n = 0; n < 2; ++n) for (int k = 0; k < 2; ++k) \
;       acc[ai][bj][m][n] = __builtin_amdgcn_mfma_f32_16x16x32_bf16(At[m][k], Bt_[n][k], acc[ai][bj][m][n], 0, 0, 0); \
;     __builtin_amdgcn_s_setprio(0); } while (0)
; #define WAIT_V(n) asm volatile("s_waitcnt vmcnt(" #n ")" ::: "memory")
; #define WAIT_L(n) asm volatile("s_waitcnt lgkmcnt(" #n ")" ::: "memory")
; #define BAR __builtin_amdgcn_s_barrier()
; template <bool ABLK, class Epi>
; __device__ __forceinline__ void gemm_tile(const bf16* __restrict__ A, int lda, const bf16* __restrict__ Bt, int ldb, int K,
;                                           int brow, int bcol, bf16* shm, const Epi& epi, int wv) {
;     ...
;     BAR; WAIT_L(0); MMA(0, 0, At, B0); BAR;
;     LDB(B1, 0, 1); BAR; WAIT_L(0); MMA(0, 1, At, B1); BAR;
;     LDA(At, 0, 1); WAIT_V(4); BAR; WAIT_L(0); MMA(1, 0, At, B0); MMA(1, 1, At, B1); BAR; }
;   { LDB(B0, 1, 0); LDA(At, 1, 0); WAIT_V(2); BAR; WAIT_L(0); MMA(0, 0, At, B0); BAR;
	s_nop 1
	ds_read_b128 v[64:67], v144 offset:16384
	ds_read_b128 v[68:71], v144 offset:17408
	ds_read_b128 v[80:83], v143 offset:16384
	ds_read_b128 v[84:87], v143 offset:17408
	ds_read_b128 v[186:189], v142 offset:16384
	ds_read_b128 v[194:197], v142 offset:17408
	ds_read_b128 v[202:205], v141 offset:16384
	ds_read_b128 v[208:211], v141 offset:17408
	s_waitcnt vmcnt(4)
	s_barrier
	s_waitcnt lgkmcnt(0)
	s_setprio 1
	s_waitcnt lgkmcnt(0)
	v_mfma_f32_16x16x32_bf16 v[60:63], v[64:67], v[132:135], v[60:63]
	v_mfma_f32_16x16x32_bf16 v[56:59], v[64:67], v[156:159], v[56:59]
	v_mfma_f32_16x16x32_bf16 v[44:47], v[186:189], v[132:135], v[44:47]
	v_mfma_f32_16x16x32_bf16 v[40:43], v[186:189], v[156:159], v[40:43]
	v_mfma_f32_16x16x32_bf16 v[60:63], v[68:71], v[152:155], v[60:63]
	v_mfma_f32_16x16x32_bf16 v[56:59], v[68:71], v[166:169], v[56:59]
	v_mfma_f32_16x16x32_bf16 v[52:55], v[80:83], v[132:135], v[52:55]
	v_mfma_f32_16x16x32_bf16 v[48:51], v[80:83], v[156:159], v[48:51]
	v_mfma_f32_16x16x32_bf16 v[44:47], v[194:197], v[152:155], v[44:47]
	v_mfma_f32_16x16x32_bf16 v[40:43], v[194:197], v[166:169], v[40:43]
	v_mfma_f32_16x16x32_bf16 v[36:39], v[202:205], v[132:135], v[36:39]
	v_mfma_f32_16x16x32_bf16 v[32:35], v[202:205], v[156:159], v[32:35]
	v_mfma_f32_16x16x32_bf16 v[224:227], v[84:87], v[152:155], v[52:55]
	v_mfma_f32_16x16x32_bf16 v[228:231], v[84:87], v[166:169], v[48:51]
	v_mfma_f32_16x16x32_bf16 v[130:133], v[208:211], v[152:155], v[36:39]
	v_mfma_f32_16x16x32_bf16 v[152:155], v[208:211], v[166:169], v[32:35]
	s_setprio 0
	s_setprio 1
	v_mfma_f32_16x16x32_bf16 v[28:31], v[64:67], v[96:99], v[28:31]
	v_mfma_f32_16x16x32_bf16 v[24:27], v[64:67], v[112:115], v[24:27]
	v_mfma_f32_16x16x32_bf16 v[12:15], v[186:189], v[96:99], v[12:15]
	v_mfma_f32_16x16x32_bf16 v[8:11], v[186:189], v[112:115], v[8:11]
	v_mfma_f32_16x16x32_bf16 v[28:31], v[68:71], v[100:103], v[28:31]
	v_mfma_f32_16x16x32_bf16 v[24:27], v[68:71], v[116:119], v[24:27]
	v_mfma_f32_16x16x32_bf16 v[20:23], v[80:83], v[96:99], v[20:23]
	v_mfma_f32_16x16x32_bf16 v[16:19], v[80:83], v[112:115], v[16:19]
	v_mfma_f32_16x16x32_bf16 v[12:15], v[194:197], v[100:103], v[12:15]
	v_mfma_f32_16x16x32_bf16 v[8:11], v[194:197], v[116:119], v[8:11]
	v_mfma_f32_16x16x32_bf16 v[4:7], v[202:205], v[96:99], v[4:7]
	v_mfma_f32_16x16x32_bf16 v[0:3], v[202:205], v[112:115], v[0:3]
	v_mfma_f32_16x16x32_bf16 v[156:159], v[84:87], v[100:103], v[20:23]
	v_mfma_f32_16x16x32_bf16 v[166:169], v[84:87], v[116:119], v[16:19]
	v_mfma_f32_16x16x32_bf16 v[186:189], v[208:211], v[100:103], v[4:7]
	v_mfma_f32_16x16x32_bf16 v[194:197], v[208:211], v[116:119], v[0:3]
	s_setprio 0
	s_barrier
	s_nop 1
	ds_read_b128 v[0:3], v151
	ds_read_b128 v[4:7], v151 offset:1024
	ds_read_b128 v[202:205], v151 offset:2048
	ds_read_b128 v[148:151], v151 offset:3072
	ds_read_b128 v[16:19], v144 offset:32768
	ds_read_b128 v[20:23], v144 offset:33792
	ds_read_b128 v[32:35], v143 offset:32768
	ds_read_b128 v[36:39], v143 offset:33792
	ds_read_b128 v[48:51], v142 offset:32768
	ds_read_b128 v[52:55], v142 offset:33792
	ds_read_b128 v[208:211], v141 offset:32768
	ds_read_b128 v[232:235], v141 offset:33792
	s_waitcnt vmcnt(2)
	s_barrier
	s_waitcnt lgkmcnt(0)
	s_setprio 1
	s_waitcnt lgkmcnt(0)
	v_mfma_f32_16x16x32_bf16 v[64:67], v[16:19], v[0:3], v[124:127]
	v_mfma_f32_16x16x32_bf16 v[116:119], v[20:23], v[4:7], v[64:67]
	v_mfma_f32_16x16x32_bf16 v[64:67], v[16:19], v[202:205], v[120:123]
	v_mfma_f32_16x16x32_bf16 v[112:115], v[20:23], v[148:151], v[64:67]
	v_mfma_f32_16x16x32_bf16 v[64:67], v[32:35], v[0:3], v[162:165]
	v_mfma_f32_16x16x32_bf16 v[100:103], v[36:39], v[4:7], v[64:67]
	v_mfma_f32_16x16x32_bf16 v[64:67], v[32:35], v[202:205], v[212:215]
	v_mfma_f32_16x16x32_bf16 v[96:99], v[36:39], v[148:151], v[64:67]
	v_mfma_f32_16x16x32_bf16 v[64:67], v[48:51], v[0:3], v[108:111]
	v_mfma_f32_16x16x32_bf16 v[84:87], v[52:55], v[4:7], v[64:67]
	v_mfma_f32_16x16x32_bf16 v[64:67], v[48:51], v[202:205], v[104:107]
	v_mfma_f32_16x16x32_bf16 v[80:83], v[52:55], v[148:151], v[64:67]
	v_mfma_f32_16x16x32_bf16 v[64:67], v[208:211], v[0:3], v[216:219]
	v_mfma_f32_16x16x32_bf16 v[68:71], v[232:235], v[4:7], v[64:67]
	v_mfma_f32_16x16x32_bf16 v[64:67], v[208:211], v[202:205], v[220:223]
	v_mfma_f32_16x16x32_bf16 v[64:67], v[232:235], v[148:151], v[64:67]
	s_setprio 0
	s_barrier
; #define LDA(dst, b, h) for (int m = 0; m < 4; ++m) for (int k = 0; k < 2; ++k) \
;     dst[m][k] = *reinterpret_cast<const bf16x8*>((char*)SA(b, h) + lds_byte(wr * 64 + m * 16 + fr, k * 32 + fq * 8))
; #define LDB(dst, b, h) for (int n = 0; n < 2; ++n) for (int k = 0; k < 2; ++k) \
;     dst[n][k] = *reinterpret_cast<const bf16x8*>((char*)SB(b, h) + lds_byte(wc * 32 + n * 16 + fr, k * 32 + fq * 8))
; #define MMA(ai, bj, At, Bt_) do { __builtin_amdgcn_s_setprio(1); \
;     for (int m = 0; m < 4; ++m) for (int n = 0; n < 2; ++n) for (int k = 0; k < 2; ++k) \
;       acc[ai][bj][m][n] = __builtin_amdgcn_mfma_f32_16x16x32_bf16(At[m][k], Bt_[n][k], acc[ai][bj][m][n], 0, 0, 0); \
;     __builtin_amdgcn_s_setprio(0); } while (0)
; #define WAIT_V(n) asm volatile("s_waitcnt vmcnt(" #n ")" ::: "memory")
; #define WAIT_L(n) asm volatile("s_waitcnt lgkmcnt(" #n ")" ::: "memory")
; #define BAR __builtin_amdgcn_s_barrier()
; template <bool ABLK, class Epi>
; __device__ __forceinline__ void gemm_tile(const bf16* __restrict__ A, int lda, const bf16* __restrict__ Bt, int ldb, int K,
;                                           int brow, int bcol, bf16* shm, const Epi& epi, int wv) {
;     ...
;     LDB(B1, 1, 1); WAIT_V(0); BAR; WAIT_L(0); MMA(0, 1, At, B1); BAR;
;     LDA(At, 1, 1); BAR; WAIT_L(0); MMA(1, 0, At, B0); MMA(1, 1, At, B1); BAR; }
;   if (wr == 0) BAR;
	ds_read_b128 v[160:163], v147
	ds_read_b128 v[212:215], v147 offset:1024
	ds_read_b128 v[216:219], v147 offset:2048
	ds_read_b128 v[220:223], v147 offset:3072
	s_waitcnt vmcnt(0)
	s_barrier
	s_waitcnt lgkmcnt(0)
	s_setprio 1
	s_waitcnt lgkmcnt(0)
	v_mfma_f32_16x16x32_bf16 v[92:95], v[16:19], v[160:163], v[92:95]
	v_mfma_f32_16x16x32_bf16 v[16:19], v[16:19], v[216:219], v[88:91]
	v_mfma_f32_16x16x32_bf16 v[120:123], v[20:23], v[220:223], v[16:19]
	v_mfma_f32_16x16x32_bf16 v[16:19], v[32:35], v[160:163], v[170:173]
	v_mfma_f32_16x16x32_bf16 v[108:111], v[36:39], v[212:215], v[16:19]
	v_mfma_f32_16x16x32_bf16 v[16:19], v[32:35], v[216:219], v[174:177]
	v_mfma_f32_16x16x32_bf16 v[104:107], v[36:39], v[220:223], v[16:19]
	v_mfma_f32_16x16x32_bf16 v[16:19], v[48:51], v[160:163], v[76:79]
	v_mfma_f32_16x16x32_bf16 v[124:127], v[20:23], v[212:215], v[92:95]
	v_mfma_f32_16x16x32_bf16 v[92:95], v[52:55], v[212:215], v[16:19]
	v_mfma_f32_16x16x32_bf16 v[16:19], v[48:51], v[216:219], v[72:75]
	v_mfma_f32_16x16x32_bf16 v[88:91], v[52:55], v[220:223], v[16:19]
	v_mfma_f32_16x16x32_bf16 v[16:19], v[208:211], v[160:163], v[178:181]
	v_mfma_f32_16x16x32_bf16 v[76:79], v[232:235], v[212:215], v[16:19]
	v_mfma_f32_16x16x32_bf16 v[16:19], v[208:211], v[216:219], v[182:185]
	v_mfma_f32_16x16x32_bf16 v[72:75], v[232:235], v[220:223], v[16:19]
	s_setprio 0
	s_barrier
	ds_read_b128 v[170:173], v144 offset:49152
	ds_read_b128 v[144:147], v144 offset:50176
	ds_read_b128 v[174:177], v143 offset:49152
	ds_read_b128 v[178:181], v143 offset:50176
	ds_read_b128 v[182:185], v142 offset:49152
	ds_read_b128 v[208:211], v142 offset:50176
	ds_read_b128 v[232:235], v141 offset:49152
	ds_read_b128 v[236:239], v141 offset:50176
	s_barrier
	s_waitcnt lgkmcnt(0)
	s_setprio 1
	s_waitcnt lgkmcnt(0)
	v_mfma_f32_16x16x32_bf16 v[16:19], v[170:173], v[0:3], v[60:63]
	v_mfma_f32_16x16x32_bf16 v[52:55], v[144:147], v[4:7], v[16:19]
	v_mfma_f32_16x16x32_bf16 v[16:19], v[170:173], v[202:205], v[56:59]
	v_mfma_f32_16x16x32_bf16 v[48:51], v[144:147], v[148:151], v[16:19]
	v_mfma_f32_16x16x32_bf16 v[16:19], v[174:177], v[0:3], v[224:227]
	v_mfma_f32_16x16x32_bf16 v[36:39], v[178:181], v[4:7], v[16:19]
	v_mfma_f32_16x16x32_bf16 v[16:19], v[174:177], v[202:205], v[228:231]
	v_mfma_f32_16x16x32_bf16 v[32:35], v[178:181], v[148:151], v[16:19]
	v_mfma_f32_16x16x32_bf16 v[16:19], v[182:185], v[0:3], v[44:47]
	v_mfma_f32_16x16x32_bf16 v[0:3], v[232:235], v[0:3], v[130:133]
	v_mfma_f32_16x16x32_bf16 v[20:23], v[208:211], v[4:7], v[16:19]
	v_mfma_f32_16x16x32_bf16 v[16:19], v[182:185], v[202:205], v[40:43]
	v_mfma_f32_16x16x32_bf16 v[4:7], v[236:239], v[4:7], v[0:3]
	v_mfma_f32_16x16x32_bf16 v[0:3], v[232:235], v[202:205], v[152:155]
	v_mfma_f32_16x16x32_bf16 v[16:19], v[208:211], v[148:151], v[16:19]
	v_mfma_f32_16x16x32_bf16 v[0:3], v[236:239], v[148:151], v[0:3]
	s_setprio 0
	s_setprio 1
	v_mfma_f32_16x16x32_bf16 v[24:27], v[170:173], v[216:219], v[24:27]
	v_mfma_f32_16x16x32_bf16 v[56:59], v[144:147], v[220:223], v[24:27]
	v_mfma_f32_16x16x32_bf16 v[24:27], v[174:177], v[160:163], v[156:159]
	v_mfma_f32_16x16x32_bf16 v[44:47], v[178:181], v[212:215], v[24:27]
	v_mfma_f32_16x16x32_bf16 v[24:27], v[174:177], v[216:219], v[166:169]
	v_mfma_f32_16x16x32_bf16 v[8:11], v[182:185], v[216:219], v[8:11]
	v_mfma_f32_16x16x32_bf16 v[28:31], v[170:173], v[160:163], v[28:31]
	v_mfma_f32_16x16x32_bf16 v[40:43], v[178:181], v[220:223], v[24:27]
	v_mfma_f32_16x16x32_bf16 v[12:15], v[182:185], v[160:163], v[12:15]
	v_mfma_f32_16x16x32_bf16 v[24:27], v[208:211], v[220:223], v[8:11]
	v_mfma_f32_16x16x32_bf16 v[8:11], v[232:235], v[160:163], v[186:189]
	v_mfma_f32_16x16x32_bf16 v[60:63], v[144:147], v[212:215], v[28:31]
	v_mfma_f32_16x16x32_bf16 v[28:31], v[208:211], v[212:215], v[12:15]
	v_mfma_f32_16x16x32_bf16 v[12:15], v[236:239], v[212:215], v[8:11]
	v_mfma_f32_16x16x32_bf16 v[8:11], v[232:235], v[216:219], v[194:197]
	v_mfma_f32_16x16x32_bf16 v[8:11], v[236:239], v[220:223], v[8:11]
	s_setprio 0
	v_cmp_gt_u32_e32 vcc, s78, v128
	s_barrier
	s_and_saveexec_b64 s[62:63], vcc
	s_cbranch_execz .LBB0_373
	s_barrier

; __device__ __forceinline__ int mytid(int wv) { return (wv << 6) | (int)__builtin_amdgcn_mbcnt_hi(~0u, __builtin_amdgcn_mbcnt_lo(~0u, 0u)); }
; template <bool ABLK, class Epi>
; __device__ __forceinline__ void gemm_tile(const bf16* __restrict__ A, int lda, const bf16* __restrict__ Bt, int ldb, int K,
;                                           int brow, int bcol, bf16* shm, const Epi& epi, int wv) {
;     ...
;   int tid = mytid(wv); asm volatile("" : "+v"(tid));
;   const int wid = tid >> 6, lane = tid & 63, wr = wid >> 2, wc = wid & 3, fr = lane & 15, fq = lane >> 4;
;   f32x4 acc[2][2][4][2] = {};
;   bf16x8 At[4][2], B0[2][2], B1[2][2];
;   const int nt = K / BK;
;   int offA, offB;
;   { int r_, c_; stage_rc(tid * 16, r_, c_); offA = ABLK ? r_ * 64 + c_ : r_ * lda + c_;
;     offB = ((r_ >> 5) * 64 + (r_ & 15) * 4 + ((r_ >> 4) & 1)) * ldb + c_; }
; template <bool ABLK, class Epi>
; __device__ __forceinline__ void gemm_phase(const bf16* A, int lda, const bf16* Bt, int ldb, int M, int N, int K, char* smem, const Epi& epi, int wv) {
;     ...
;   for (int w = blockIdx.x; w < nwg; w += gridDim.x) {
;     int wgid = w;
;     { int q = nwg / NXCD, r = nwg % NXCD, xcd = wgid % NXCD, off = wgid / NXCD;
;       wgid = (xcd < r ? xcd * (q + 1) : r * (q + 1) + (xcd - r) * q) + off; }
;     const int nig = WGM * nN, gid = wgid / nig, fm = gid * WGM, gsz = min(nM - fm, WGM);
;     const int pm = fm + ((wgid % nig) % gsz), pn = (wgid % nig) / gsz;
;     gemm_tile<ABLK>(A, lda, Bt, ldb, K, pm * BM, pn * BM, (bf16*)smem, epi, wv);
.LBB0_579:
	s_or_b64 exec, exec, s[4:5]
	s_cmpk_lt_i32 s89, 0x2100
	s_mov_b64 s[4:5], s[90:91]
	s_mov_b64 s[8:9], s[90:91]
	s_mov_b64 s[10:11], s[90:91]
	s_cselect_b64 s[28:29], -1, 0
	s_cmpk_gt_i32 s89, 0x20ff
	s_barrier
	s_barrier
	s_cbranch_scc1 .LBB0_589
	s_load_dwordx2 s[12:13], s[4:5], 0xa8
	s_load_dwordx2 s[14:15], s[8:9], 0xa8
	s_load_dwordx2 s[16:17], s[10:11], 0xa8
	s_mov_b32 s22, 0xffff2000
	s_mov_b32 s24, 0xffff4000
	s_waitcnt lgkmcnt(0)
	s_add_u32 s0, s12, 0xba40000
	s_addc_u32 s1, s13, 0
	s_add_u32 s3, s14, 0x3240000
	s_addc_u32 s70, s15, 0
	s_add_u32 s4, s16, 0x17a40000
	s_addc_u32 s5, s17, 0
	s_add_u32 s71, s12, 0xba5a000
	s_addc_u32 s72, s13, 0
	s_add_u32 s73, s14, 0x32c2180
	s_mov_b32 s26, 0xfff7df80
	s_movk_i32 s30, 0xdf80
	s_mov_b32 s34, 0xffff6000
	s_movk_i32 s36, 0x8000
	s_mov_b32 s38, 0xfff7ff80
	s_movk_i32 s40, 0xff80
	s_movk_i32 s42, 0xa000
	s_movk_i32 s44, 0xc000
	s_mov_b32 s46, 0xfff7e000
	s_movk_i32 s48, 0xe000
	s_mov_b32 s50, 0xfff80000
	s_addc_u32 s74, s15, 0
	s_add_i32 s75, 0, 0x10000
	s_mov_b64 s[8:9], 0x80000
	s_add_i32 s76, 0, 0x14000
	s_mov_b64 s[10:11], 0x4000
	s_mov_b64 s[12:13], 0x6000
	s_mov_b64 s[14:15], 0x80
	s_add_i32 s77, 0, 0x18000
	s_mov_b64 s[16:17], 0x80080
	s_mov_b64 s[18:19], 0x8000
	s_mov_b64 s[20:21], 0xa000
	s_add_i32 s78, 0, 0x1c000
	s_movk_i32 s79, 0x3c0
	s_movk_i32 s80, 0x1000
	s_mov_b32 s23, -1
	s_mov_b32 s25, -1
	s_mov_b32 s27, -1
	s_mov_b32 s31, -1
	s_mov_b32 s35, -1
	s_mov_b32 s37, -1
	s_mov_b32 s39, -1
	s_mov_b32 s41, -1
	s_mov_b32 s43, -1
	s_mov_b32 s45, -1
	s_mov_b32 s47, -1
	s_mov_b32 s49, -1
	s_mov_b32 s51, -1
	s_mov_b64 s[52:53], 0x10000
	s_mov_b64 s[54:55], 0x100
	s_mov_b64 s[56:57], 0xfc000
	s_mov_b64 s[58:59], 0xfe000
	s_movk_i32 s81, 0x100
	v_mov_b32_e32 v129, 0
	s_movk_i32 s82, 0x7c
	v_mov_b32_e32 v136, 1
	s_mov_b32 s83, s89
	v_lshlrev_b32_e32 v254, 4, v192
	s_nop 0
	v_readfirstlane_b32 s99, v254
	s_branch .LBB0_582

; #define STAGE_A(P, hf, kt) do { if constexpr (ABLK) { const bf16* _gp = A + ((long)(brow >> 8) * nt + (kt)) * 16384 + (hf) * 8192; GLDS2(_gp, 4096, offA, P); } \
;     else { const bf16* _gp = A + (long)(brow + (hf) * HALF) * lda + (long)(kt) * BK; GLDS2(_gp, 64 * (long)lda, offA, P); } } while (0)
; #define STAGE_B(P, hf, kt) do { const bf16* _gp = Bt + (long)(bcol + (hf) * 2) * ldb + (long)(kt) * BK; GLDS2(_gp, 128 * (long)ldb, offB, P); } while (0)
; #define LDA(dst, b, h) for (int m = 0; m < 4; ++m) for (int k = 0; k < 2; ++k) \
;     dst[m][k] = *reinterpret_cast<const bf16x8*>((char*)SA(b, h) + lds_byte(wr * 64 + m * 16 + fr, k * 32 + fq * 8))
; #define LDB(dst, b, h) for (int n = 0; n < 2; ++n) for (int k = 0; k < 2; ++k) \
;     dst[n][k] = *reinterpret_cast<const bf16x8*>((char*)SB(b, h) + lds_byte(wc * 32 + n * 16 + fr, k * 32 + fq * 8))
; #define MMA(ai, bj, At, Bt_) do { __builtin_amdgcn_s_setprio(1); \
;     for (int m = 0; m < 4; ++m) for (int n = 0; n < 2; ++n) for (int k = 0; k < 2; ++k) \
;       acc[ai][bj][m][n] = __builtin_amdgcn_mfma_f32_16x16x32_bf16(At[m][k], Bt_[n][k], acc[ai][bj][m][n], 0, 0, 0); \
;     __builtin_amdgcn_s_setprio(0); } while (0)
; #define WAIT_V(n) asm volatile("s_waitcnt vmcnt(" #n ")" ::: "memory")
; #define WAIT_L(n) asm volatile("s_waitcnt lgkmcnt(" #n ")" ::: "memory")
; #define BAR __builtin_amdgcn_s_barrier()
; #define SCHED __builtin_amdgcn_sched_barrier(0)
; template <bool ABLK, class Epi>
; __device__ __forceinline__ void gemm_tile(const bf16* __restrict__ A, int lda, const bf16* __restrict__ Bt, int ldb, int K,
;                                           int brow, int bcol, bf16* shm, const Epi& epi, int wv) {
;     ...
;     LDB(B0, 0, 0); SCHED; LDA(At, 0, 0); STAGE_A(SA(1, 1), 1, t + 1);
;     WAIT_L(8); BAR; MMA(0, 0, At, B0); BAR; SCHED;
;     LDB(B1, 0, 1); STAGE_B(SB(0, 0), 0, t + 2);
;     BAR; MMA(0, 1, At, B1); BAR;
;     LDA(At, 0, 1); STAGE_A(SA(0, 0), 0, t + 2);
;     BAR; MMA(1, 0, At, B0); BAR; SCHED;
;     STAGE_B(SB(0, 1), 1, t + 2);
;     WAIT_V(6); BAR; MMA(1, 1, At, B1); BAR;
.LBB0_585:
	ds_read_b128 v[166:169], v162
	ds_read_b128 v[170:173], v162 offset:1024
	ds_read_b128 v[174:177], v162 offset:2048
	ds_read_b128 v[178:181], v162 offset:3072
	v_add_u32_e32 v163, 0xc000, v148
	v_lshl_add_u64 v[164:165], v[132:133], 0, s[22:23]
	s_add_i32 m0, s99, 0xc000
	ds_read_b128 v[182:185], v144
	ds_read_b128 v[186:189], v144 offset:1024
	ds_read_b128 v[194:197], v143
	ds_read_b128 v[202:205], v143 offset:1024
	ds_read_b128 v[208:211], v142
	ds_read_b128 v[212:215], v142 offset:1024
	ds_read_b128 v[216:219], v141
	ds_read_b128 v[220:223], v141 offset:1024
	global_load_lds_dwordx4 v[164:165], off
	v_add_u32_e32 v164, 0xe000, v148
	s_add_i32 m0, s99, 0xe000
	v_lshl_add_u64 v[190:191], v[132:133], 0, s[24:25]
	global_load_lds_dwordx4 v[190:191], off
	s_waitcnt lgkmcnt(8)
	s_barrier
	s_setprio 1
	s_waitcnt lgkmcnt(0)
	v_mfma_f32_16x16x32_bf16 v[124:127], v[182:185], v[166:169], v[124:127]
	v_mfma_f32_16x16x32_bf16 v[120:123], v[182:185], v[174:177], v[120:123]
	v_mfma_f32_16x16x32_bf16 v[116:119], v[194:197], v[166:169], v[116:119]
	v_mfma_f32_16x16x32_bf16 v[112:115], v[194:197], v[174:177], v[112:115]
	v_mfma_f32_16x16x32_bf16 v[108:111], v[208:211], v[166:169], v[108:111]
	v_mfma_f32_16x16x32_bf16 v[104:107], v[208:211], v[174:177], v[104:107]
	v_mfma_f32_16x16x32_bf16 v[100:103], v[216:219], v[166:169], v[100:103]
	v_mfma_f32_16x16x32_bf16 v[96:99], v[216:219], v[174:177], v[96:99]
	v_mfma_f32_16x16x32_bf16 v[124:127], v[186:189], v[170:173], v[124:127]
	v_mfma_f32_16x16x32_bf16 v[120:123], v[186:189], v[178:181], v[120:123]
	v_mfma_f32_16x16x32_bf16 v[116:119], v[202:205], v[170:173], v[116:119]
	v_mfma_f32_16x16x32_bf16 v[112:115], v[202:205], v[178:181], v[112:115]
	v_mfma_f32_16x16x32_bf16 v[108:111], v[212:215], v[170:173], v[108:111]
	v_mfma_f32_16x16x32_bf16 v[104:107], v[212:215], v[178:181], v[104:107]
	v_mfma_f32_16x16x32_bf16 v[100:103], v[220:223], v[170:173], v[100:103]
	v_mfma_f32_16x16x32_bf16 v[96:99], v[220:223], v[178:181], v[96:99]
	s_setprio 0
	s_barrier
	v_lshl_add_u64 v[190:191], v[134:135], 0, s[26:27]
	s_add_i32 m0, s99, 0x10000
	ds_read_b128 v[224:227], v161
	ds_read_b128 v[228:231], v161 offset:1024
	ds_read_b128 v[232:235], v161 offset:2048
	ds_read_b128 v[236:239], v161 offset:3072
	global_load_lds_dwordx4 v[190:191], off
	s_add_i32 m0, s99, 0x12000
	v_lshl_add_u64 v[190:191], v[134:135], 0, s[30:31]
	global_load_lds_dwordx4 v[190:191], off
	s_barrier
	s_setprio 1
	s_waitcnt lgkmcnt(0)
	v_mfma_f32_16x16x32_bf16 v[92:95], v[182:185], v[224:227], v[92:95]
	v_mfma_f32_16x16x32_bf16 v[88:91], v[182:185], v[232:235], v[88:91]
	v_mfma_f32_16x16x32_bf16 v[84:87], v[194:197], v[224:227], v[84:87]
	v_mfma_f32_16x16x32_bf16 v[80:83], v[194:197], v[232:235], v[80:83]
	v_mfma_f32_16x16x32_bf16 v[76:79], v[208:211], v[224:227], v[76:79]
	v_mfma_f32_16x16x32_bf16 v[72:75], v[208:211], v[232:235], v[72:75]
	v_mfma_f32_16x16x32_bf16 v[68:71], v[216:219], v[224:227], v[68:71]
	v_mfma_f32_16x16x32_bf16 v[64:67], v[216:219], v[232:235], v[64:67]
	v_mfma_f32_16x16x32_bf16 v[92:95], v[186:189], v[228:231], v[92:95]
	v_mfma_f32_16x16x32_bf16 v[88:91], v[186:189], v[236:239], v[88:91]
	v_mfma_f32_16x16x32_bf16 v[84:87], v[202:205], v[228:231], v[84:87]
	v_mfma_f32_16x16x32_bf16 v[80:83], v[202:205], v[236:239], v[80:83]
	v_mfma_f32_16x16x32_bf16 v[76:79], v[212:215], v[228:231], v[76:79]
	v_mfma_f32_16x16x32_bf16 v[72:75], v[212:215], v[236:239], v[72:75]
	v_mfma_f32_16x16x32_bf16 v[68:71], v[220:223], v[228:231], v[68:71]
	v_mfma_f32_16x16x32_bf16 v[64:67], v[220:223], v[236:239], v[64:67]
	s_setprio 0
	v_lshl_add_u64 v[190:191], v[132:133], 0, s[34:35]
	s_add_i32 m0, s99, 0x0
	s_barrier
	ds_read_b128 v[182:185], v144 offset:16384
	ds_read_b128 v[186:189], v144 offset:17408
	ds_read_b128 v[194:197], v143 offset:16384
	ds_read_b128 v[202:205], v143 offset:17408
	ds_read_b128 v[208:211], v142 offset:16384
	ds_read_b128 v[212:215], v142 offset:17408
	ds_read_b128 v[216:219], v141 offset:16384
	ds_read_b128 v[220:223], v141 offset:17408
	global_load_lds_dwordx4 v[190:191], off
	s_add_i32 m0, s99, 0x2000
	v_lshl_add_u64 v[190:191], v[132:133], 0, s[36:37]
	global_load_lds_dwordx4 v[190:191], off
	s_barrier
	s_setprio 1
	s_waitcnt lgkmcnt(0)
	v_mfma_f32_16x16x32_bf16 v[60:63], v[182:185], v[166:169], v[60:63]
	v_mfma_f32_16x16x32_bf16 v[56:59], v[182:185], v[174:177], v[56:59]
	v_mfma_f32_16x16x32_bf16 v[52:55], v[194:197], v[166:169], v[52:55]
	v_mfma_f32_16x16x32_bf16 v[48:51], v[194:197], v[174:177], v[48:51]
	v_mfma_f32_16x16x32_bf16 v[44:47], v[208:211], v[166:169], v[44:47]
	v_mfma_f32_16x16x32_bf16 v[40:43], v[208:211], v[174:177], v[40:43]
	v_mfma_f32_16x16x32_bf16 v[36:39], v[216:219], v[166:169], v[36:39]
	v_mfma_f32_16x16x32_bf16 v[32:35], v[216:219], v[174:177], v[32:35]
	v_mfma_f32_16x16x32_bf16 v[60:63], v[186:189], v[170:173], v[60:63]
	v_mfma_f32_16x16x32_bf16 v[56:59], v[186:189], v[178:181], v[56:59]
	v_mfma_f32_16x16x32_bf16 v[52:55], v[202:205], v[170:173], v[52:55]
	v_mfma_f32_16x16x32_bf16 v[48:51], v[202:205], v[178:181], v[48:51]
	v_mfma_f32_16x16x32_bf16 v[44:47], v[212:215], v[170:173], v[44:47]
	v_mfma_f32_16x16x32_bf16 v[40:43], v[212:215], v[178:181], v[40:43]
	v_mfma_f32_16x16x32_bf16 v[36:39], v[220:223], v[170:173], v[36:39]
	v_mfma_f32_16x16x32_bf16 v[32:35], v[220:223], v[178:181], v[32:35]
	s_setprio 0
	s_barrier
	s_add_i32 m0, s99, 0x14000
	v_lshl_add_u64 v[166:167], v[134:135], 0, s[38:39]
	global_load_lds_dwordx4 v[166:167], off
	s_add_i32 m0, s99, 0x16000
	v_lshl_add_u64 v[166:167], v[134:135], 0, s[40:41]
	global_load_lds_dwordx4 v[166:167], off
	s_waitcnt vmcnt(6)
	s_barrier
; #define STAGE_A(P, hf, kt) do { if constexpr (ABLK) { const bf16* _gp = A + ((long)(brow >> 8) * nt + (kt)) * 16384 + (hf) * 8192; GLDS2(_gp, 4096, offA, P); } \
;     else { const bf16* _gp = A + (long)(brow + (hf) * HALF) * lda + (long)(kt) * BK; GLDS2(_gp, 64 * (long)lda, offA, P); } } while (0)
; #define STAGE_B(P, hf, kt) do { const bf16* _gp = Bt + (long)(bcol + (hf) * 2) * ldb + (long)(kt) * BK; GLDS2(_gp, 128 * (long)ldb, offB, P); } while (0)
; #define LDA(dst, b, h) for (int m = 0; m < 4; ++m) for (int k = 0; k < 2; ++k) \
;     dst[m][k] = *reinterpret_cast<const bf16x8*>((char*)SA(b, h) + lds_byte(wr * 64 + m * 16 + fr, k * 32 + fq * 8))
; #define LDB(dst, b, h) for (int n = 0; n < 2; ++n) for (int k = 0; k < 2; ++k) \
;     dst[n][k] = *reinterpret_cast<const bf16x8*>((char*)SB(b, h) + lds_byte(wc * 32 + n * 16 + fr, k * 32 + fq * 8))
; #define MMA(ai, bj, At, Bt_) do { __builtin_amdgcn_s_setprio(1); \
;     for (int m = 0; m < 4; ++m) for (int n = 0; n < 2; ++n) for (int k = 0; k < 2; ++k) \
;       acc[ai][bj][m][n] = __builtin_amdgcn_mfma_f32_16x16x32_bf16(At[m][k], Bt_[n][k], acc[ai][bj][m][n], 0, 0, 0); \
;     __builtin_amdgcn_s_setprio(0); } while (0)
; #define WAIT_V(n) asm volatile("s_waitcnt vmcnt(" #n ")" ::: "memory")
; #define WAIT_L(n) asm volatile("s_waitcnt lgkmcnt(" #n ")" ::: "memory")
; #define BAR __builtin_amdgcn_s_barrier()
; #define SCHED __builtin_amdgcn_sched_barrier(0)
; template <bool ABLK, class Epi>
; __device__ __forceinline__ void gemm_tile(const bf16* __restrict__ A, int lda, const bf16* __restrict__ Bt, int ldb, int K,
;                                           int brow, int bcol, bf16* shm, const Epi& epi, int wv) {
;     ...
;     WAIT_V(6); BAR; MMA(1, 1, At, B1); BAR;
;     LDB(B0, 1, 0); SCHED; LDA(At, 1, 0); STAGE_A(SA(0, 1), 1, t + 2);
;     WAIT_L(8); BAR; MMA(0, 0, At, B0); BAR; SCHED;
;     LDB(B1, 1, 1); STAGE_B(SB(1, 0), 0, t + 3);
;     BAR; MMA(0, 1, At, B1); BAR;
;     LDA(At, 1, 1); STAGE_A(SA(1, 0), 0, t + 3);
;     BAR; MMA(1, 0, At, B0); BAR; SCHED;
	s_setprio 1
	v_mfma_f32_16x16x32_bf16 v[28:31], v[182:185], v[224:227], v[28:31]
	v_mfma_f32_16x16x32_bf16 v[24:27], v[182:185], v[232:235], v[24:27]
	v_mfma_f32_16x16x32_bf16 v[20:23], v[194:197], v[224:227], v[20:23]
	v_mfma_f32_16x16x32_bf16 v[16:19], v[194:197], v[232:235], v[16:19]
	v_mfma_f32_16x16x32_bf16 v[12:15], v[208:211], v[224:227], v[12:15]
	v_mfma_f32_16x16x32_bf16 v[8:11], v[208:211], v[232:235], v[8:11]
	v_mfma_f32_16x16x32_bf16 v[4:7], v[216:219], v[224:227], v[4:7]
	v_mfma_f32_16x16x32_bf16 v[0:3], v[216:219], v[232:235], v[0:3]
	v_mfma_f32_16x16x32_bf16 v[28:31], v[186:189], v[228:231], v[28:31]
	v_mfma_f32_16x16x32_bf16 v[24:27], v[186:189], v[236:239], v[24:27]
	v_mfma_f32_16x16x32_bf16 v[20:23], v[202:205], v[228:231], v[20:23]
	v_mfma_f32_16x16x32_bf16 v[16:19], v[202:205], v[236:239], v[16:19]
	v_mfma_f32_16x16x32_bf16 v[12:15], v[212:215], v[228:231], v[12:15]
	v_mfma_f32_16x16x32_bf16 v[8:11], v[212:215], v[236:239], v[8:11]
	v_mfma_f32_16x16x32_bf16 v[4:7], v[220:223], v[228:231], v[4:7]
	v_mfma_f32_16x16x32_bf16 v[0:3], v[220:223], v[236:239], v[0:3]
	s_setprio 0
	s_barrier
	ds_read_b128 v[166:169], v150
	ds_read_b128 v[170:173], v150 offset:1024
	ds_read_b128 v[174:177], v150 offset:2048
	ds_read_b128 v[178:181], v150 offset:3072
	v_lshl_add_u64 v[190:191], v[132:133], 0, s[42:43]
	s_add_i32 m0, s99, 0x4000
	ds_read_b128 v[182:185], v144 offset:32768
	ds_read_b128 v[186:189], v144 offset:33792
	ds_read_b128 v[194:197], v143 offset:32768
	ds_read_b128 v[202:205], v143 offset:33792
	ds_read_b128 v[208:211], v142 offset:32768
	ds_read_b128 v[212:215], v142 offset:33792
	ds_read_b128 v[216:219], v141 offset:32768
	ds_read_b128 v[220:223], v141 offset:33792
	global_load_lds_dwordx4 v[190:191], off
	s_add_i32 m0, s99, 0x6000
	v_lshl_add_u64 v[190:191], v[132:133], 0, s[44:45]
	global_load_lds_dwordx4 v[190:191], off
	s_waitcnt lgkmcnt(8)
	s_barrier
	s_setprio 1
	s_waitcnt lgkmcnt(0)
	v_mfma_f32_16x16x32_bf16 v[124:127], v[182:185], v[166:169], v[124:127]
	v_mfma_f32_16x16x32_bf16 v[120:123], v[182:185], v[174:177], v[120:123]
	v_mfma_f32_16x16x32_bf16 v[116:119], v[194:197], v[166:169], v[116:119]
	v_mfma_f32_16x16x32_bf16 v[112:115], v[194:197], v[174:177], v[112:115]
	v_mfma_f32_16x16x32_bf16 v[108:111], v[208:211], v[166:169], v[108:111]
	v_mfma_f32_16x16x32_bf16 v[104:107], v[208:211], v[174:177], v[104:107]
	v_mfma_f32_16x16x32_bf16 v[100:103], v[216:219], v[166:169], v[100:103]
	v_mfma_f32_16x16x32_bf16 v[96:99], v[216:219], v[174:177], v[96:99]
	v_mfma_f32_16x16x32_bf16 v[124:127], v[186:189], v[170:173], v[124:127]
	v_mfma_f32_16x16x32_bf16 v[120:123], v[186:189], v[178:181], v[120:123]
	v_mfma_f32_16x16x32_bf16 v[116:119], v[202:205], v[170:173], v[116:119]
	v_mfma_f32_16x16x32_bf16 v[112:115], v[202:205], v[178:181], v[112:115]
	v_mfma_f32_16x16x32_bf16 v[108:111], v[212:215], v[170:173], v[108:111]
	v_mfma_f32_16x16x32_bf16 v[104:107], v[212:215], v[178:181], v[104:107]
	v_mfma_f32_16x16x32_bf16 v[100:103], v[220:223], v[170:173], v[100:103]
	v_mfma_f32_16x16x32_bf16 v[96:99], v[220:223], v[178:181], v[96:99]
	s_setprio 0
	s_barrier
	v_lshl_add_u64 v[190:191], v[134:135], 0, s[46:47]
	s_add_i32 m0, s99, 0x18000
	ds_read_b128 v[224:227], v147
	ds_read_b128 v[228:231], v147 offset:1024
	ds_read_b128 v[232:235], v147 offset:2048
	ds_read_b128 v[236:239], v147 offset:3072
	global_load_lds_dwordx4 v[190:191], off
	s_add_i32 m0, s99, 0x1a000
	v_lshl_add_u64 v[190:191], v[134:135], 0, s[48:49]
	global_load_lds_dwordx4 v[190:191], off
	s_barrier
	s_setprio 1
	s_waitcnt lgkmcnt(0)
	v_mfma_f32_16x16x32_bf16 v[92:95], v[182:185], v[224:227], v[92:95]
	v_mfma_f32_16x16x32_bf16 v[88:91], v[182:185], v[232:235], v[88:91]
	v_mfma_f32_16x16x32_bf16 v[84:87], v[194:197], v[224:227], v[84:87]
	v_mfma_f32_16x16x32_bf16 v[80:83], v[194:197], v[232:235], v[80:83]
	v_mfma_f32_16x16x32_bf16 v[76:79], v[208:211], v[224:227], v[76:79]
	v_mfma_f32_16x16x32_bf16 v[72:75], v[208:211], v[232:235], v[72:75]
	v_mfma_f32_16x16x32_bf16 v[68:71], v[216:219], v[224:227], v[68:71]
	v_mfma_f32_16x16x32_bf16 v[64:67], v[216:219], v[232:235], v[64:67]
	v_mfma_f32_16x16x32_bf16 v[92:95], v[186:189], v[228:231], v[92:95]
	v_mfma_f32_16x16x32_bf16 v[88:91], v[186:189], v[236:239], v[88:91]
	v_mfma_f32_16x16x32_bf16 v[84:87], v[202:205], v[228:231], v[84:87]
	v_mfma_f32_16x16x32_bf16 v[80:83], v[202:205], v[236:239], v[80:83]
	v_mfma_f32_16x16x32_bf16 v[76:79], v[212:215], v[228:231], v[76:79]
	v_mfma_f32_16x16x32_bf16 v[72:75], v[212:215], v[236:239], v[72:75]
	v_mfma_f32_16x16x32_bf16 v[68:71], v[220:223], v[228:231], v[68:71]
	v_mfma_f32_16x16x32_bf16 v[64:67], v[220:223], v[236:239], v[64:67]
	s_setprio 0
	v_lshl_add_u64 v[190:191], v[132:133], 0, s[48:49]
	s_add_i32 m0, s99, 0x8000
	s_barrier
	ds_read_b128 v[182:185], v144 offset:49152
	ds_read_b128 v[186:189], v144 offset:50176
	ds_read_b128 v[194:197], v143 offset:49152
	ds_read_b128 v[202:205], v143 offset:50176
	ds_read_b128 v[208:211], v142 offset:49152
	ds_read_b128 v[212:215], v142 offset:50176
	ds_read_b128 v[216:219], v141 offset:49152
	ds_read_b128 v[220:223], v141 offset:50176
	global_load_lds_dwordx4 v[190:191], off
	s_add_i32 m0, s99, 0xa000
	s_nop 0
	global_load_lds_dwordx4 v[132:133], off
	s_barrier
; #define STAGE_A(P, hf, kt) do { if constexpr (ABLK) { const bf16* _gp = A + ((long)(brow >> 8) * nt + (kt)) * 16384 + (hf) * 8192; GLDS2(_gp, 4096, offA, P); } \
;     else { const bf16* _gp = A + (long)(brow + (hf) * HALF) * lda + (long)(kt) * BK; GLDS2(_gp, 64 * (long)lda, offA, P); } } while (0)
; #define STAGE_B(P, hf, kt) do { const bf16* _gp = Bt + (long)(bcol + (hf) * 2) * ldb + (long)(kt) * BK; GLDS2(_gp, 128 * (long)ldb, offB, P); } while (0)
; #define LDA(dst, b, h) for (int m = 0; m < 4; ++m) for (int k = 0; k < 2; ++k) \
;     dst[m][k] = *reinterpret_cast<const bf16x8*>((char*)SA(b, h) + lds_byte(wr * 64 + m * 16 + fr, k * 32 + fq * 8))
; #define LDB(dst, b, h) for (int n = 0; n < 2; ++n) for (int k = 0; k < 2; ++k) \
;     dst[n][k] = *reinterpret_cast<const bf16x8*>((char*)SB(b, h) + lds_byte(wc * 32 + n * 16 + fr, k * 32 + fq * 8))
; #define MMA(ai, bj, At, Bt_) do { __builtin_amdgcn_s_setprio(1); \
;     for (int m = 0; m < 4; ++m) for (int n = 0; n < 2; ++n) for (int k = 0; k < 2; ++k) \
;       acc[ai][bj][m][n] = __builtin_amdgcn_mfma_f32_16x16x32_bf16(At[m][k], Bt_[n][k], acc[ai][bj][m][n], 0, 0, 0); \
;     __builtin_amdgcn_s_setprio(0); } while (0)
; #define WAIT_V(n) asm volatile("s_waitcnt vmcnt(" #n ")" ::: "memory")
; #define WAIT_L(n) asm volatile("s_waitcnt lgkmcnt(" #n ")" ::: "memory")
; #define BAR __builtin_amdgcn_s_barrier()
; #define SCHED __builtin_amdgcn_sched_barrier(0)
; template <bool ABLK, class Epi>
; __device__ __forceinline__ void gemm_tile(const bf16* __restrict__ A, int lda, const bf16* __restrict__ Bt, int ldb, int K,
;                                           int brow, int bcol, bf16* shm, const Epi& epi, int wv) {
;     ...
;     BAR; MMA(1, 0, At, B0); BAR; SCHED;
;     STAGE_B(SB(1, 1), 1, t + 3);
;     WAIT_V(6); BAR; MMA(1, 1, At, B1); BAR;
;   }
;   { LDB(B0, 0, 0); LDA(At, 0, 0); STAGE_A(SA(1, 1), 1, nt - 1);
;     BAR; WAIT_L(0); MMA(0, 0, At, B0); BAR;
;     LDB(B1, 0, 1); BAR; WAIT_L(0); MMA(0, 1, At, B1); BAR;
;     LDA(At, 0, 1); WAIT_V(4); BAR; WAIT_L(0); MMA(1, 0, At, B0); MMA(1, 1, At, B1); BAR; }
	s_setprio 1
	s_waitcnt lgkmcnt(0)
	v_mfma_f32_16x16x32_bf16 v[60:63], v[182:185], v[166:169], v[60:63]
	v_mfma_f32_16x16x32_bf16 v[56:59], v[182:185], v[174:177], v[56:59]
	v_mfma_f32_16x16x32_bf16 v[52:55], v[194:197], v[166:169], v[52:55]
	v_mfma_f32_16x16x32_bf16 v[48:51], v[194:197], v[174:177], v[48:51]
	v_mfma_f32_16x16x32_bf16 v[44:47], v[208:211], v[166:169], v[44:47]
	v_mfma_f32_16x16x32_bf16 v[40:43], v[208:211], v[174:177], v[40:43]
	v_mfma_f32_16x16x32_bf16 v[36:39], v[216:219], v[166:169], v[36:39]
	v_mfma_f32_16x16x32_bf16 v[32:35], v[216:219], v[174:177], v[32:35]
	v_mfma_f32_16x16x32_bf16 v[60:63], v[186:189], v[170:173], v[60:63]
	v_mfma_f32_16x16x32_bf16 v[56:59], v[186:189], v[178:181], v[56:59]
	v_mfma_f32_16x16x32_bf16 v[52:55], v[202:205], v[170:173], v[52:55]
	v_mfma_f32_16x16x32_bf16 v[48:51], v[202:205], v[178:181], v[48:51]
	v_mfma_f32_16x16x32_bf16 v[44:47], v[212:215], v[170:173], v[44:47]
	v_mfma_f32_16x16x32_bf16 v[40:43], v[212:215], v[178:181], v[40:43]
	v_mfma_f32_16x16x32_bf16 v[36:39], v[220:223], v[170:173], v[36:39]
	v_mfma_f32_16x16x32_bf16 v[32:35], v[220:223], v[178:181], v[32:35]
	s_setprio 0
	s_barrier
	s_add_i32 m0, s99, 0x1c000
	v_lshl_add_u64 v[166:167], v[134:135], 0, s[50:51]
	global_load_lds_dwordx4 v[166:167], off
	s_add_i32 m0, s99, 0x1e000
	s_nop 0
	global_load_lds_dwordx4 v[134:135], off
	s_waitcnt vmcnt(6)
	s_barrier
	s_setprio 1
	v_mfma_f32_16x16x32_bf16 v[28:31], v[182:185], v[224:227], v[28:31]
	v_mfma_f32_16x16x32_bf16 v[24:27], v[182:185], v[232:235], v[24:27]
	v_mfma_f32_16x16x32_bf16 v[20:23], v[194:197], v[224:227], v[20:23]
	v_mfma_f32_16x16x32_bf16 v[16:19], v[194:197], v[232:235], v[16:19]
	v_mfma_f32_16x16x32_bf16 v[12:15], v[208:211], v[224:227], v[12:15]
	v_mfma_f32_16x16x32_bf16 v[8:11], v[208:211], v[232:235], v[8:11]
	v_mfma_f32_16x16x32_bf16 v[4:7], v[216:219], v[224:227], v[4:7]
	v_mfma_f32_16x16x32_bf16 v[0:3], v[216:219], v[232:235], v[0:3]
	v_mfma_f32_16x16x32_bf16 v[28:31], v[186:189], v[228:231], v[28:31]
	v_mfma_f32_16x16x32_bf16 v[24:27], v[186:189], v[236:239], v[24:27]
	v_mfma_f32_16x16x32_bf16 v[20:23], v[202:205], v[228:231], v[20:23]
	v_mfma_f32_16x16x32_bf16 v[16:19], v[202:205], v[236:239], v[16:19]
	v_mfma_f32_16x16x32_bf16 v[12:15], v[212:215], v[228:231], v[12:15]
	v_mfma_f32_16x16x32_bf16 v[8:11], v[212:215], v[236:239], v[8:11]
	v_mfma_f32_16x16x32_bf16 v[4:7], v[220:223], v[228:231], v[4:7]
	v_mfma_f32_16x16x32_bf16 v[0:3], v[220:223], v[236:239], v[0:3]
	s_setprio 0
	s_add_i32 s33, s33, 2
	v_lshl_add_u64 v[132:133], v[132:133], 0, s[52:53]
	s_cmp_lt_u32 s33, 28
	v_lshl_add_u64 v[134:135], v[134:135], 0, s[54:55]
	s_barrier
	s_cbranch_scc1 .LBB0_585
	v_readfirstlane_b32 s2, v163
	v_lshl_add_u64 v[148:149], v[130:131], 0, s[56:57]
	s_mov_b32 m0, s2
	v_readfirstlane_b32 s2, v164
	ds_read_b128 v[132:135], v162
	ds_read_b128 v[152:155], v162 offset:1024
	ds_read_b128 v[156:159], v162 offset:2048
	ds_read_b128 v[166:169], v162 offset:3072
	ds_read_b128 v[170:173], v144
	ds_read_b128 v[174:177], v144 offset:1024
	ds_read_b128 v[178:181], v143
	ds_read_b128 v[182:185], v143 offset:1024
	ds_read_b128 v[186:189], v142
	ds_read_b128 v[194:197], v142 offset:1024
	ds_read_b128 v[202:205], v141
	ds_read_b128 v[208:211], v141 offset:1024
	global_load_lds_dwordx4 v[148:149], off
	v_lshl_add_u64 v[130:131], v[130:131], 0, s[58:59]
	s_mov_b32 m0, s2
	s_nop 0
	global_load_lds_dwordx4 v[130:131], off
	s_barrier
	s_waitcnt lgkmcnt(0)
	s_setprio 1
	s_waitcnt lgkmcnt(0)
	v_mfma_f32_16x16x32_bf16 v[124:127], v[170:173], v[132:135], v[124:127]
	v_mfma_f32_16x16x32_bf16 v[120:123], v[170:173], v[156:159], v[120:123]
	v_mfma_f32_16x16x32_bf16 v[108:111], v[186:189], v[132:135], v[108:111]
	v_mfma_f32_16x16x32_bf16 v[104:107], v[186:189], v[156:159], v[104:107]
	v_mfma_f32_16x16x32_bf16 v[124:127], v[174:177], v[152:155], v[124:127]
	v_mfma_f32_16x16x32_bf16 v[120:123], v[174:177], v[166:169], v[120:123]
	v_mfma_f32_16x16x32_bf16 v[116:119], v[178:181], v[132:135], v[116:119]
	v_mfma_f32_16x16x32_bf16 v[112:115], v[178:181], v[156:159], v[112:115]
	v_mfma_f32_16x16x32_bf16 v[108:111], v[194:197], v[152:155], v[108:111]
	v_mfma_f32_16x16x32_bf16 v[104:107], v[194:197], v[166:169], v[104:107]
	v_mfma_f32_16x16x32_bf16 v[100:103], v[202:205], v[132:135], v[100:103]
	v_mfma_f32_16x16x32_bf16 v[96:99], v[202:205], v[156:159], v[96:99]
	v_mfma_f32_16x16x32_bf16 v[162:165], v[182:185], v[152:155], v[116:119]
	v_mfma_f32_16x16x32_bf16 v[212:215], v[182:185], v[166:169], v[112:115]
	v_mfma_f32_16x16x32_bf16 v[216:219], v[208:211], v[152:155], v[100:103]
	v_mfma_f32_16x16x32_bf16 v[220:223], v[208:211], v[166:169], v[96:99]
	s_setprio 0
	s_barrier
	s_nop 1
	ds_read_b128 v[96:99], v161
	ds_read_b128 v[100:103], v161 offset:1024
	ds_read_b128 v[112:115], v161 offset:2048
	ds_read_b128 v[116:119], v161 offset:3072
	s_barrier
	s_waitcnt lgkmcnt(0)
	s_setprio 1
	s_waitcnt lgkmcnt(0)
	v_mfma_f32_16x16x32_bf16 v[92:95], v[170:173], v[96:99], v[92:95]
	v_mfma_f32_16x16x32_bf16 v[88:91], v[170:173], v[112:115], v[88:91]
	v_mfma_f32_16x16x32_bf16 v[76:79], v[186:189], v[96:99], v[76:79]
	v_mfma_f32_16x16x32_bf16 v[72:75], v[186:189], v[112:115], v[72:75]
	v_mfma_f32_16x16x32_bf16 v[92:95], v[174:177], v[100:103], v[92:95]
	v_mfma_f32_16x16x32_bf16 v[88:91], v[174:177], v[116:119], v[88:91]
	v_mfma_f32_16x16x32_bf16 v[84:87], v[178:181], v[96:99], v[84:87]
	v_mfma_f32_16x16x32_bf16 v[80:83], v[178:181], v[112:115], v[80:83]
	v_mfma_f32_16x16x32_bf16 v[76:79], v[194:197], v[100:103], v[76:79]
	v_mfma_f32_16x16x32_bf16 v[72:75], v[194:197], v[116:119], v[72:75]
	v_mfma_f32_16x16x32_bf16 v[68:71], v[202:205], v[96:99], v[68:71]
	v_mfma_f32_16x16x32_bf16 v[64:67], v[202:205], v[112:115], v[64:67]
	v_mfma_f32_16x16x32_bf16 v[170:173], v[182:185], v[100:103], v[84:87]
	v_mfma_f32_16x16x32_bf16 v[174:177], v[182:185], v[116:119], v[80:83]
	v_mfma_f32_16x16x32_bf16 v[178:181], v[208:211], v[100:103], v[68:71]
	v_mfma_f32_16x16x32_bf16 v[182:185], v[208:211], v[116:119], v[64:67]
	s_setprio 0
	s_barrier
; #define LDA(dst, b, h) for (int m = 0; m < 4; ++m) for (int k = 0; k < 2; ++k) \
;     dst[m][k] = *reinterpret_cast<const bf16x8*>((char*)SA(b, h) + lds_byte(wr * 64 + m * 16 + fr, k * 32 + fq * 8))
; #define LDB(dst, b, h) for (int n = 0; n < 2; ++n) for (int k = 0; k < 2; ++k) \
;     dst[n][k] = *reinterpret_cast<const bf16x8*>((char*)SB(b, h) + lds_byte(wc * 32 + n * 16 + fr, k * 32 + fq * 8))
; #define MMA(ai, bj, At, Bt_) do { __builtin_amdgcn_s_setprio(1); \
;     for (int m = 0; m < 4; ++m) for (int n = 0; n < 2; ++n) for (int k = 0; k < 2; ++k) \
;       acc[ai][bj][m][n] = __builtin_amdgcn_mfma_f32_16x16x32_bf16(At[m][k], Bt_[n][k], acc[ai][bj][m][n], 0, 0, 0); \
;     __builtin_amdgcn_s_setprio(0); } while (0)
; #define WAIT_V(n) asm volatile("s_waitcnt vmcnt(" #n ")" ::: "memory")
; #define WAIT_L(n) asm volatile("s_waitcnt lgkmcnt(" #n ")" ::: "memory")
; #define BAR __builtin_amdgcn_s_barrier()
; template <bool ABLK, class Epi>
; __device__ __forceinline__ void gemm_tile(const bf16* __restrict__ A, int lda, const bf16* __restrict__ Bt, int ldb, int K,
;                                           int brow, int bcol, bf16* shm, const Epi& epi, int wv) {
;     ...
;     LDB(B1, 0, 1); BAR; WAIT_L(0); MMA(0, 1, At, B1); BAR;
;     LDA(At, 0, 1); WAIT_V(4); BAR; WAIT_L(0); MMA(1, 0, At, B0); MMA(1, 1, At, B1); BAR; }
;   { LDB(B0, 1, 0); LDA(At, 1, 0); WAIT_V(2); BAR; WAIT_L(0); MMA(0, 0, At, B0); BAR;
	s_nop 1
	ds_read_b128 v[64:67], v144 offset:16384
	ds_read_b128 v[68:71], v144 offset:17408
	ds_read_b128 v[80:83], v143 offset:16384
	ds_read_b128 v[84:87], v143 offset:17408
	ds_read_b128 v[186:189], v142 offset:16384
	ds_read_b128 v[194:197], v142 offset:17408
	ds_read_b128 v[202:205], v141 offset:16384
	ds_read_b128 v[208:211], v141 offset:17408
	s_waitcnt vmcnt(4)
	s_barrier
	s_waitcnt lgkmcnt(0)
	s_setprio 1
	s_waitcnt lgkmcnt(0)
	v_mfma_f32_16x16x32_bf16 v[60:63], v[64:67], v[132:135], v[60:63]
	v_mfma_f32_16x16x32_bf16 v[56:59], v[64:67], v[156:159], v[56:59]
	v_mfma_f32_16x16x32_bf16 v[44:47], v[186:189], v[132:135], v[44:47]
	v_mfma_f32_16x16x32_bf16 v[40:43], v[186:189], v[156:159], v[40:43]
	v_mfma_f32_16x16x32_bf16 v[60:63], v[68:71], v[152:155], v[60:63]
	v_mfma_f32_16x16x32_bf16 v[56:59], v[68:71], v[166:169], v[56:59]
	v_mfma_f32_16x16x32_bf16 v[52:55], v[80:83], v[132:135], v[52:55]
	v_mfma_f32_16x16x32_bf16 v[48:51], v[80:83], v[156:159], v[48:51]
	v_mfma_f32_16x16x32_bf16 v[44:47], v[194:197], v[152:155], v[44:47]
	v_mfma_f32_16x16x32_bf16 v[40:43], v[194:197], v[166:169], v[40:43]
	v_mfma_f32_16x16x32_bf16 v[36:39], v[202:205], v[132:135], v[36:39]
	v_mfma_f32_16x16x32_bf16 v[32:35], v[202:205], v[156:159], v[32:35]
	v_mfma_f32_16x16x32_bf16 v[224:227], v[84:87], v[152:155], v[52:55]
	v_mfma_f32_16x16x32_bf16 v[228:231], v[84:87], v[166:169], v[48:51]
	v_mfma_f32_16x16x32_bf16 v[130:133], v[208:211], v[152:155], v[36:39]
	v_mfma_f32_16x16x32_bf16 v[152:155], v[208:211], v[166:169], v[32:35]
	s_setprio 0
	s_setprio 1
	v_mfma_f32_16x16x32_bf16 v[28:31], v[64:67], v[96:99], v[28:31]
	v_mfma_f32_16x16x32_bf16 v[24:27], v[64:67], v[112:115], v[24:27]
	v_mfma_f32_16x16x32_bf16 v[12:15], v[186:189], v[96:99], v[12:15]
	v_mfma_f32_16x16x32_bf16 v[8:11], v[186:189], v[112:115], v[8:11]
	v_mfma_f32_16x16x32_bf16 v[28:31], v[68:71], v[100:103], v[28:31]
	v_mfma_f32_16x16x32_bf16 v[24:27], v[68:71], v[116:119], v[24:27]
	v_mfma_f32_16x16x32_bf16 v[20:23], v[80:83], v[96:99], v[20:23]
	v_mfma_f32_16x16x32_bf16 v[16:19], v[80:83], v[112:115], v[16:19]
	v_mfma_f32_16x16x32_bf16 v[12:15], v[194:197], v[100:103], v[12:15]
	v_mfma_f32_16x16x32_bf16 v[8:11], v[194:197], v[116:119], v[8:11]
	v_mfma_f32_16x16x32_bf16 v[4:7], v[202:205], v[96:99], v[4:7]
	v_mfma_f32_16x16x32_bf16 v[0:3], v[202:205], v[112:115], v[0:3]
	v_mfma_f32_16x16x32_bf16 v[156:159], v[84:87], v[100:103], v[20:23]
	v_mfma_f32_16x16x32_bf16 v[166:169], v[84:87], v[116:119], v[16:19]
	v_mfma_f32_16x16x32_bf16 v[186:189], v[208:211], v[100:103], v[4:7]
	v_mfma_f32_16x16x32_bf16 v[194:197], v[208:211], v[116:119], v[0:3]
	s_setprio 0
	s_barrier
	s_nop 1
	ds_read_b128 v[0:3], v150
	ds_read_b128 v[4:7], v150 offset:1024
	ds_read_b128 v[202:205], v150 offset:2048
	ds_read_b128 v[148:151], v150 offset:3072
	ds_read_b128 v[16:19], v144 offset:32768
	ds_read_b128 v[20:23], v144 offset:33792
	ds_read_b128 v[32:35], v143 offset:32768
	ds_read_b128 v[36:39], v143 offset:33792
	ds_read_b128 v[48:51], v142 offset:32768
	ds_read_b128 v[52:55], v142 offset:33792
	ds_read_b128 v[208:211], v141 offset:32768
	ds_read_b128 v[232:235], v141 offset:33792
	s_waitcnt vmcnt(2)
	s_barrier
	s_waitcnt lgkmcnt(0)
	s_setprio 1
	s_waitcnt lgkmcnt(0)
	v_mfma_f32_16x16x32_bf16 v[64:67], v[16:19], v[0:3], v[124:127]
	v_mfma_f32_16x16x32_bf16 v[112:115], v[20:23], v[4:7], v[64:67]
	v_mfma_f32_16x16x32_bf16 v[64:67], v[16:19], v[202:205], v[120:123]
	v_mfma_f32_16x16x32_bf16 v[116:119], v[20:23], v[148:151], v[64:67]
	v_mfma_f32_16x16x32_bf16 v[64:67], v[32:35], v[0:3], v[162:165]
	v_mfma_f32_16x16x32_bf16 v[96:99], v[36:39], v[4:7], v[64:67]
	v_mfma_f32_16x16x32_bf16 v[64:67], v[32:35], v[202:205], v[212:215]
	v_mfma_f32_16x16x32_bf16 v[100:103], v[36:39], v[148:151], v[64:67]
	v_mfma_f32_16x16x32_bf16 v[64:67], v[48:51], v[0:3], v[108:111]
	v_mfma_f32_16x16x32_bf16 v[80:83], v[52:55], v[4:7], v[64:67]
	v_mfma_f32_16x16x32_bf16 v[64:67], v[48:51], v[202:205], v[104:107]
	v_mfma_f32_16x16x32_bf16 v[84:87], v[52:55], v[148:151], v[64:67]
	v_mfma_f32_16x16x32_bf16 v[64:67], v[208:211], v[0:3], v[216:219]
	v_mfma_f32_16x16x32_bf16 v[68:71], v[208:211], v[202:205], v[220:223]
	v_mfma_f32_16x16x32_bf16 v[64:67], v[232:235], v[4:7], v[64:67]
	v_mfma_f32_16x16x32_bf16 v[68:71], v[232:235], v[148:151], v[68:71]
	s_setprio 0
	s_barrier
; #define LDA(dst, b, h) for (int m = 0; m < 4; ++m) for (int k = 0; k < 2; ++k) \
;     dst[m][k] = *reinterpret_cast<const bf16x8*>((char*)SA(b, h) + lds_byte(wr * 64 + m * 16 + fr, k * 32 + fq * 8))
; #define LDB(dst, b, h) for (int n = 0; n < 2; ++n) for (int k = 0; k < 2; ++k) \
;     dst[n][k] = *reinterpret_cast<const bf16x8*>((char*)SB(b, h) + lds_byte(wc * 32 + n * 16 + fr, k * 32 + fq * 8))
; #define MMA(ai, bj, At, Bt_) do { __builtin_amdgcn_s_setprio(1); \
;     for (int m = 0; m < 4; ++m) for (int n = 0; n < 2; ++n) for (int k = 0; k < 2; ++k) \
;       acc[ai][bj][m][n] = __builtin_amdgcn_mfma_f32_16x16x32_bf16(At[m][k], Bt_[n][k], acc[ai][bj][m][n], 0, 0, 0); \
;     __builtin_amdgcn_s_setprio(0); } while (0)
; #define WAIT_V(n) asm volatile("s_waitcnt vmcnt(" #n ")" ::: "memory")
; #define WAIT_L(n) asm volatile("s_waitcnt lgkmcnt(" #n ")" ::: "memory")
; #define BAR __builtin_amdgcn_s_barrier()
; template <bool ABLK, class Epi>
; __device__ __forceinline__ void gemm_tile(const bf16* __restrict__ A, int lda, const bf16* __restrict__ Bt, int ldb, int K,
;                                           int brow, int bcol, bf16* shm, const Epi& epi, int wv) {
;     ...
;     LDB(B1, 1, 1); WAIT_V(0); BAR; WAIT_L(0); MMA(0, 1, At, B1); BAR;
;     LDA(At, 1, 1); BAR; WAIT_L(0); MMA(1, 0, At, B0); MMA(1, 1, At, B1); BAR; }
;   if (wr == 0) BAR;
	ds_read_b128 v[160:163], v147
	ds_read_b128 v[212:215], v147 offset:1024
	ds_read_b128 v[216:219], v147 offset:2048
	ds_read_b128 v[220:223], v147 offset:3072
	s_waitcnt vmcnt(0)
	s_barrier
	s_waitcnt lgkmcnt(0)
	s_setprio 1
	s_waitcnt lgkmcnt(0)
	v_mfma_f32_16x16x32_bf16 v[92:95], v[16:19], v[160:163], v[92:95]
	v_mfma_f32_16x16x32_bf16 v[16:19], v[16:19], v[216:219], v[88:91]
	v_mfma_f32_16x16x32_bf16 v[124:127], v[20:23], v[220:223], v[16:19]
	v_mfma_f32_16x16x32_bf16 v[16:19], v[32:35], v[160:163], v[170:173]
	v_mfma_f32_16x16x32_bf16 v[104:107], v[36:39], v[212:215], v[16:19]
	v_mfma_f32_16x16x32_bf16 v[16:19], v[32:35], v[216:219], v[174:177]
	v_mfma_f32_16x16x32_bf16 v[108:111], v[36:39], v[220:223], v[16:19]
	v_mfma_f32_16x16x32_bf16 v[16:19], v[48:51], v[160:163], v[76:79]
	v_mfma_f32_16x16x32_bf16 v[88:91], v[52:55], v[212:215], v[16:19]
	v_mfma_f32_16x16x32_bf16 v[16:19], v[48:51], v[216:219], v[72:75]
	v_mfma_f32_16x16x32_bf16 v[120:123], v[20:23], v[212:215], v[92:95]
	v_mfma_f32_16x16x32_bf16 v[92:95], v[52:55], v[220:223], v[16:19]
	v_mfma_f32_16x16x32_bf16 v[16:19], v[208:211], v[160:163], v[178:181]
	v_mfma_f32_16x16x32_bf16 v[72:75], v[232:235], v[212:215], v[16:19]
	v_mfma_f32_16x16x32_bf16 v[16:19], v[208:211], v[216:219], v[182:185]
	v_mfma_f32_16x16x32_bf16 v[76:79], v[232:235], v[220:223], v[16:19]
	s_setprio 0
	s_barrier
	ds_read_b128 v[170:173], v144 offset:49152
	ds_read_b128 v[144:147], v144 offset:50176
	ds_read_b128 v[174:177], v143 offset:49152
	ds_read_b128 v[178:181], v143 offset:50176
	ds_read_b128 v[182:185], v142 offset:49152
	ds_read_b128 v[208:211], v142 offset:50176
	ds_read_b128 v[232:235], v141 offset:49152
	ds_read_b128 v[236:239], v141 offset:50176
	s_barrier
	s_waitcnt lgkmcnt(0)
	s_setprio 1
	s_waitcnt lgkmcnt(0)
	v_mfma_f32_16x16x32_bf16 v[16:19], v[170:173], v[0:3], v[60:63]
	v_mfma_f32_16x16x32_bf16 v[48:51], v[144:147], v[4:7], v[16:19]
	v_mfma_f32_16x16x32_bf16 v[16:19], v[170:173], v[202:205], v[56:59]
	v_mfma_f32_16x16x32_bf16 v[52:55], v[144:147], v[148:151], v[16:19]
	v_mfma_f32_16x16x32_bf16 v[16:19], v[174:177], v[0:3], v[224:227]
	v_mfma_f32_16x16x32_bf16 v[32:35], v[178:181], v[4:7], v[16:19]
	v_mfma_f32_16x16x32_bf16 v[16:19], v[174:177], v[202:205], v[228:231]
	v_mfma_f32_16x16x32_bf16 v[36:39], v[178:181], v[148:151], v[16:19]
	v_mfma_f32_16x16x32_bf16 v[16:19], v[182:185], v[0:3], v[44:47]
	v_mfma_f32_16x16x32_bf16 v[0:3], v[232:235], v[0:3], v[130:133]
	v_mfma_f32_16x16x32_bf16 v[16:19], v[208:211], v[4:7], v[16:19]
	v_mfma_f32_16x16x32_bf16 v[20:23], v[182:185], v[202:205], v[40:43]
	v_mfma_f32_16x16x32_bf16 v[0:3], v[236:239], v[4:7], v[0:3]
	v_mfma_f32_16x16x32_bf16 v[4:7], v[232:235], v[202:205], v[152:155]
	v_mfma_f32_16x16x32_bf16 v[20:23], v[208:211], v[148:151], v[20:23]
	v_mfma_f32_16x16x32_bf16 v[4:7], v[236:239], v[148:151], v[4:7]
	s_setprio 0
	s_setprio 1
	v_mfma_f32_16x16x32_bf16 v[24:27], v[170:173], v[216:219], v[24:27]
	v_mfma_f32_16x16x32_bf16 v[60:63], v[144:147], v[220:223], v[24:27]
	v_mfma_f32_16x16x32_bf16 v[24:27], v[174:177], v[160:163], v[156:159]
	v_mfma_f32_16x16x32_bf16 v[28:31], v[170:173], v[160:163], v[28:31]
	v_mfma_f32_16x16x32_bf16 v[40:43], v[178:181], v[212:215], v[24:27]
	v_mfma_f32_16x16x32_bf16 v[24:27], v[174:177], v[216:219], v[166:169]
	v_mfma_f32_16x16x32_bf16 v[12:15], v[182:185], v[160:163], v[12:15]
	v_mfma_f32_16x16x32_bf16 v[8:11], v[182:185], v[216:219], v[8:11]
	v_mfma_f32_16x16x32_bf16 v[56:59], v[144:147], v[212:215], v[28:31]
	v_mfma_f32_16x16x32_bf16 v[44:47], v[178:181], v[220:223], v[24:27]
	v_mfma_f32_16x16x32_bf16 v[24:27], v[208:211], v[212:215], v[12:15]
	v_mfma_f32_16x16x32_bf16 v[28:31], v[208:211], v[220:223], v[8:11]
	v_mfma_f32_16x16x32_bf16 v[8:11], v[232:235], v[160:163], v[186:189]
	v_mfma_f32_16x16x32_bf16 v[12:15], v[232:235], v[216:219], v[194:197]
	v_mfma_f32_16x16x32_bf16 v[8:11], v[236:239], v[212:215], v[8:11]
	v_mfma_f32_16x16x32_bf16 v[12:15], v[236:239], v[220:223], v[12:15]
	s_setprio 0
	v_cmp_gt_u32_e32 vcc, s81, v128
	s_barrier
	s_and_saveexec_b64 s[64:65], vcc
	s_cbranch_execz .LBB0_581
	s_barrier
	s_branch .LBB0_581

; __device__ __forceinline__ int mytid(int wv) { return (wv << 6) | (int)__builtin_amdgcn_mbcnt_hi(~0u, __builtin_amdgcn_mbcnt_lo(~0u, 0u)); }
; template <bool ABLK, class Epi>
; __device__ __forceinline__ void gemm_tile(const bf16* __restrict__ A, int lda, const bf16* __restrict__ Bt, int ldb, int K,
;                                           int brow, int bcol, bf16* shm, const Epi& epi, int wv) {
;     ...
;   int tid = mytid(wv); asm volatile("" : "+v"(tid));
;   const int wid = tid >> 6, lane = tid & 63, wr = wid >> 2, wc = wid & 3, fr = lane & 15, fq = lane >> 4;
;   f32x4 acc[2][2][4][2] = {};
;   bf16x8 At[4][2], B0[2][2], B1[2][2];
;   const int nt = K / BK;
;   int offA, offB;
;   { int r_, c_; stage_rc(tid * 16, r_, c_); offA = ABLK ? r_ * 64 + c_ : r_ * lda + c_;
;     offB = ((r_ >> 5) * 64 + (r_ & 15) * 4 + ((r_ >> 4) & 1)) * ldb + c_; }
; template <bool ABLK, class Epi>
; __device__ __forceinline__ void gemm_phase(const bf16* A, int lda, const bf16* Bt, int ldb, int M, int N, int K, char* smem, const Epi& epi, int wv) {
;     ...
;   for (int w = blockIdx.x; w < nwg; w += gridDim.x) {
;     int wgid = w;
;     { int q = nwg / NXCD, r = nwg % NXCD, xcd = wgid % NXCD, off = wgid / NXCD;
;       wgid = (xcd < r ? xcd * (q + 1) : r * (q + 1) + (xcd - r) * q) + off; }
;     const int nig = WGM * nN, gid = wgid / nig, fm = gid * WGM, gsz = min(nM - fm, WGM);
;     const int pm = fm + ((wgid % nig) % gsz), pn = (wgid % nig) / gsz;
;     gemm_tile<ABLK>(A, lda, Bt, ldb, K, pm * BM, pn * BM, (bf16*)smem, epi, wv);
.LBB0_626:
	s_or_b64 exec, exec, s[4:5]
	v_cndmask_b32_e64 v0, 0, 1, s[6:7]
	s_mov_b64 s[8:9], s[90:91]
	s_mov_b64 s[10:11], s[90:91]
	s_mov_b64 s[12:13], s[90:91]
	v_cmp_ne_u32_e64 s[4:5], 1, v0
	s_andn2_b64 vcc, exec, s[6:7]
	s_barrier
	s_barrier
	s_cbranch_vccnz .LBB0_636
	s_load_dwordx2 s[14:15], s[8:9], 0xa8
	s_load_dwordx2 s[16:17], s[10:11], 0xa8
	s_load_dwordx2 s[6:7], s[12:13], 0xa0
	s_mov_b32 s22, 0xffff2000
	s_mov_b32 s24, 0xffff4000
	s_waitcnt lgkmcnt(0)
	s_add_u32 s1, s14, 0x17a40000
	s_addc_u32 s3, s15, 0
	s_add_u32 s66, s16, 0x8a40000
	s_addc_u32 s67, s17, 0
	s_add_u32 s68, s14, 0x17a5a000
	s_addc_u32 s69, s15, 0
	s_add_u32 s70, s16, 0x8ba5980
	s_mov_b32 s26, 0xffe9a780
	s_movk_i32 s30, 0xa780
	s_mov_b32 s34, 0xffff6000
	s_movk_i32 s36, 0x8000
	s_mov_b32 s38, 0xffe9ff80
	s_movk_i32 s40, 0xff80
	s_movk_i32 s42, 0xa000
	s_movk_i32 s44, 0xc000
	s_mov_b32 s46, 0xffe9a800
	s_movk_i32 s48, 0xa800
	s_movk_i32 s50, 0xe000
	s_mov_b32 s52, 0xffea0000
	s_movk_i32 s0, 0x1600
	s_addc_u32 s71, s17, 0
	s_add_i32 s72, 0, 0x10000
	s_add_i32 s73, 0, 0x14000
	s_mov_b64 s[8:9], 0x6000
	s_mov_b64 s[10:11], 0x80
	s_add_i32 s74, 0, 0x18000
	s_mov_b64 s[12:13], 0x160080
	s_mov_b64 s[14:15], 0x8000
	s_mov_b64 s[16:17], 0xa000
	s_mov_b64 s[18:19], 0x5880
	s_add_i32 s75, 0, 0x1c000
	s_mov_b64 s[20:21], 0x165880
	s_movk_i32 s76, 0x3c0
	s_mov_b32 s23, -1
	s_mov_b32 s25, -1
	s_mov_b32 s27, -1
	s_mov_b32 s31, -1
	s_mov_b32 s35, -1
	s_mov_b32 s37, -1
	s_mov_b32 s39, -1
	s_mov_b32 s41, -1
	s_mov_b32 s43, -1
	s_mov_b32 s45, -1
	s_mov_b32 s47, -1
	s_mov_b32 s49, -1
	s_mov_b32 s51, -1
	s_mov_b32 s53, -1
	s_mov_b64 s[54:55], 0x10000
	s_mov_b64 s[56:57], 0x100
	s_mov_b64 s[58:59], 0x2bc000
	s_mov_b64 s[60:61], 0x2be000
	s_movk_i32 s77, 0x100
	v_mov_b32_e32 v188, 1
	s_mov_b32 s78, s89
	v_lshlrev_b32_e32 v254, 4, v192
	s_nop 0
	v_readfirstlane_b32 s99, v254
	s_branch .LBB0_629

; #define STAGE_A(P, hf, kt) do { if constexpr (ABLK) { const bf16* _gp = A + ((long)(brow >> 8) * nt + (kt)) * 16384 + (hf) * 8192; GLDS2(_gp, 4096, offA, P); } \
;     else { const bf16* _gp = A + (long)(brow + (hf) * HALF) * lda + (long)(kt) * BK; GLDS2(_gp, 64 * (long)lda, offA, P); } } while (0)
; #define STAGE_B(P, hf, kt) do { const bf16* _gp = Bt + (long)(bcol + (hf) * 2) * ldb + (long)(kt) * BK; GLDS2(_gp, 128 * (long)ldb, offB, P); } while (0)
; #define LDA(dst, b, h) for (int m = 0; m < 4; ++m) for (int k = 0; k < 2; ++k) \
;     dst[m][k] = *reinterpret_cast<const bf16x8*>((char*)SA(b, h) + lds_byte(wr * 64 + m * 16 + fr, k * 32 + fq * 8))
; #define LDB(dst, b, h) for (int n = 0; n < 2; ++n) for (int k = 0; k < 2; ++k) \
;     dst[n][k] = *reinterpret_cast<const bf16x8*>((char*)SB(b, h) + lds_byte(wc * 32 + n * 16 + fr, k * 32 + fq * 8))
; #define MMA(ai, bj, At, Bt_) do { __builtin_amdgcn_s_setprio(1); \
;     for (int m = 0; m < 4; ++m) for (int n = 0; n < 2; ++n) for (int k = 0; k < 2; ++k) \
;       acc[ai][bj][m][n] = __builtin_amdgcn_mfma_f32_16x16x32_bf16(At[m][k], Bt_[n][k], acc[ai][bj][m][n], 0, 0, 0); \
;     __builtin_amdgcn_s_setprio(0); } while (0)
; #define WAIT_V(n) asm volatile("s_waitcnt vmcnt(" #n ")" ::: "memory")
; #define WAIT_L(n) asm volatile("s_waitcnt lgkmcnt(" #n ")" ::: "memory")
; #define BAR __builtin_amdgcn_s_barrier()
; #define SCHED __builtin_amdgcn_sched_barrier(0)
; template <bool ABLK, class Epi>
; __device__ __forceinline__ void gemm_tile(const bf16* __restrict__ A, int lda, const bf16* __restrict__ Bt, int ldb, int K,
;                                           int brow, int bcol, bf16* shm, const Epi& epi, int wv) {
;     ...
;     LDB(B0, 0, 0); SCHED; LDA(At, 0, 0); STAGE_A(SA(1, 1), 1, t + 1);
;     WAIT_L(8); BAR; MMA(0, 0, At, B0); BAR; SCHED;
;     LDB(B1, 0, 1); STAGE_B(SB(0, 0), 0, t + 2);
;     BAR; MMA(0, 1, At, B1); BAR;
;     LDA(At, 0, 1); STAGE_A(SA(0, 0), 0, t + 2);
;     BAR; MMA(1, 0, At, B0); BAR; SCHED;
;     STAGE_B(SB(0, 1), 1, t + 2);
;     WAIT_V(6); BAR; MMA(1, 1, At, B1); BAR;
.LBB0_632:
	ds_read_b128 v[164:167], v160
	ds_read_b128 v[168:171], v160 offset:1024
	ds_read_b128 v[172:175], v160 offset:2048
	ds_read_b128 v[176:179], v160 offset:3072
	v_add_u32_e32 v161, 0xc000, v141
	v_lshl_add_u64 v[162:163], v[130:131], 0, s[22:23]
	s_add_i32 m0, s99, 0xc000
	ds_read_b128 v[180:183], v148
	ds_read_b128 v[184:187], v148 offset:1024
	ds_read_b128 v[194:197], v147
	ds_read_b128 v[202:205], v147 offset:1024
	ds_read_b128 v[208:211], v146
	ds_read_b128 v[212:215], v146 offset:1024
	ds_read_b128 v[216:219], v145
	ds_read_b128 v[220:223], v145 offset:1024
	global_load_lds_dwordx4 v[162:163], off
	v_add_u32_e32 v162, 0xe000, v141
	s_add_i32 m0, s99, 0xe000
	v_lshl_add_u64 v[190:191], v[130:131], 0, s[24:25]
	global_load_lds_dwordx4 v[190:191], off
	s_waitcnt lgkmcnt(8)
	s_barrier
	s_setprio 1
	s_waitcnt lgkmcnt(0)
	v_mfma_f32_16x16x32_bf16 v[124:127], v[180:183], v[164:167], v[124:127]
	v_mfma_f32_16x16x32_bf16 v[120:123], v[180:183], v[172:175], v[120:123]
	v_mfma_f32_16x16x32_bf16 v[116:119], v[194:197], v[164:167], v[116:119]
	v_mfma_f32_16x16x32_bf16 v[112:115], v[194:197], v[172:175], v[112:115]
	v_mfma_f32_16x16x32_bf16 v[108:111], v[208:211], v[164:167], v[108:111]
	v_mfma_f32_16x16x32_bf16 v[104:107], v[208:211], v[172:175], v[104:107]
	v_mfma_f32_16x16x32_bf16 v[100:103], v[216:219], v[164:167], v[100:103]
	v_mfma_f32_16x16x32_bf16 v[96:99], v[216:219], v[172:175], v[96:99]
	v_mfma_f32_16x16x32_bf16 v[124:127], v[184:187], v[168:171], v[124:127]
	v_mfma_f32_16x16x32_bf16 v[120:123], v[184:187], v[176:179], v[120:123]
	v_mfma_f32_16x16x32_bf16 v[116:119], v[202:205], v[168:171], v[116:119]
	v_mfma_f32_16x16x32_bf16 v[112:115], v[202:205], v[176:179], v[112:115]
	v_mfma_f32_16x16x32_bf16 v[108:111], v[212:215], v[168:171], v[108:111]
	v_mfma_f32_16x16x32_bf16 v[104:107], v[212:215], v[176:179], v[104:107]
	v_mfma_f32_16x16x32_bf16 v[100:103], v[220:223], v[168:171], v[100:103]
	v_mfma_f32_16x16x32_bf16 v[96:99], v[220:223], v[176:179], v[96:99]
	s_setprio 0
	s_barrier
	v_lshl_add_u64 v[190:191], v[132:133], 0, s[26:27]
	s_add_i32 m0, s99, 0x10000
	ds_read_b128 v[224:227], v159
	ds_read_b128 v[228:231], v159 offset:1024
	ds_read_b128 v[232:235], v159 offset:2048
	ds_read_b128 v[236:239], v159 offset:3072
	global_load_lds_dwordx4 v[190:191], off
	s_add_i32 m0, s99, 0x12000
	v_lshl_add_u64 v[190:191], v[132:133], 0, s[30:31]
	global_load_lds_dwordx4 v[190:191], off
	s_barrier
	s_setprio 1
	s_waitcnt lgkmcnt(0)
	v_mfma_f32_16x16x32_bf16 v[92:95], v[180:183], v[224:227], v[92:95]
	v_mfma_f32_16x16x32_bf16 v[88:91], v[180:183], v[232:235], v[88:91]
	v_mfma_f32_16x16x32_bf16 v[84:87], v[194:197], v[224:227], v[84:87]
	v_mfma_f32_16x16x32_bf16 v[80:83], v[194:197], v[232:235], v[80:83]
	v_mfma_f32_16x16x32_bf16 v[76:79], v[208:211], v[224:227], v[76:79]
	v_mfma_f32_16x16x32_bf16 v[72:75], v[208:211], v[232:235], v[72:75]
	v_mfma_f32_16x16x32_bf16 v[68:71], v[216:219], v[224:227], v[68:71]
	v_mfma_f32_16x16x32_bf16 v[64:67], v[216:219], v[232:235], v[64:67]
	v_mfma_f32_16x16x32_bf16 v[92:95], v[184:187], v[228:231], v[92:95]
	v_mfma_f32_16x16x32_bf16 v[88:91], v[184:187], v[236:239], v[88:91]
	v_mfma_f32_16x16x32_bf16 v[84:87], v[202:205], v[228:231], v[84:87]
	v_mfma_f32_16x16x32_bf16 v[80:83], v[202:205], v[236:239], v[80:83]
	v_mfma_f32_16x16x32_bf16 v[76:79], v[212:215], v[228:231], v[76:79]
	v_mfma_f32_16x16x32_bf16 v[72:75], v[212:215], v[236:239], v[72:75]
	v_mfma_f32_16x16x32_bf16 v[68:71], v[220:223], v[228:231], v[68:71]
	v_mfma_f32_16x16x32_bf16 v[64:67], v[220:223], v[236:239], v[64:67]
	s_setprio 0
	v_lshl_add_u64 v[190:191], v[130:131], 0, s[34:35]
	s_add_i32 m0, s99, 0x0
	s_barrier
	ds_read_b128 v[180:183], v148 offset:16384
	ds_read_b128 v[184:187], v148 offset:17408
	ds_read_b128 v[194:197], v147 offset:16384
	ds_read_b128 v[202:205], v147 offset:17408
	ds_read_b128 v[208:211], v146 offset:16384
	ds_read_b128 v[212:215], v146 offset:17408
	ds_read_b128 v[216:219], v145 offset:16384
	ds_read_b128 v[220:223], v145 offset:17408
	global_load_lds_dwordx4 v[190:191], off
	s_add_i32 m0, s99, 0x2000
	v_lshl_add_u64 v[190:191], v[130:131], 0, s[36:37]
	global_load_lds_dwordx4 v[190:191], off
	s_barrier
	s_setprio 1
	s_waitcnt lgkmcnt(0)
	v_mfma_f32_16x16x32_bf16 v[60:63], v[180:183], v[164:167], v[60:63]
	v_mfma_f32_16x16x32_bf16 v[56:59], v[180:183], v[172:175], v[56:59]
	v_mfma_f32_16x16x32_bf16 v[52:55], v[194:197], v[164:167], v[52:55]
	v_mfma_f32_16x16x32_bf16 v[48:51], v[194:197], v[172:175], v[48:51]
	v_mfma_f32_16x16x32_bf16 v[44:47], v[208:211], v[164:167], v[44:47]
	v_mfma_f32_16x16x32_bf16 v[40:43], v[208:211], v[172:175], v[40:43]
	v_mfma_f32_16x16x32_bf16 v[36:39], v[216:219], v[164:167], v[36:39]
	v_mfma_f32_16x16x32_bf16 v[32:35], v[216:219], v[172:175], v[32:35]
	v_mfma_f32_16x16x32_bf16 v[60:63], v[184:187], v[168:171], v[60:63]
	v_mfma_f32_16x16x32_bf16 v[56:59], v[184:187], v[176:179], v[56:59]
	v_mfma_f32_16x16x32_bf16 v[52:55], v[202:205], v[168:171], v[52:55]
	v_mfma_f32_16x16x32_bf16 v[48:51], v[202:205], v[176:179], v[48:51]
	v_mfma_f32_16x16x32_bf16 v[44:47], v[212:215], v[168:171], v[44:47]
	v_mfma_f32_16x16x32_bf16 v[40:43], v[212:215], v[176:179], v[40:43]
	v_mfma_f32_16x16x32_bf16 v[36:39], v[220:223], v[168:171], v[36:39]
	v_mfma_f32_16x16x32_bf16 v[32:35], v[220:223], v[176:179], v[32:35]
	s_setprio 0
	s_barrier
	s_add_i32 m0, s99, 0x14000
	v_lshl_add_u64 v[164:165], v[132:133], 0, s[38:39]
	global_load_lds_dwordx4 v[164:165], off
	s_add_i32 m0, s99, 0x16000
	v_lshl_add_u64 v[164:165], v[132:133], 0, s[40:41]
	global_load_lds_dwordx4 v[164:165], off
	s_waitcnt vmcnt(6)
	s_barrier
; #define STAGE_A(P, hf, kt) do { if constexpr (ABLK) { const bf16* _gp = A + ((long)(brow >> 8) * nt + (kt)) * 16384 + (hf) * 8192; GLDS2(_gp, 4096, offA, P); } \
;     else { const bf16* _gp = A + (long)(brow + (hf) * HALF) * lda + (long)(kt) * BK; GLDS2(_gp, 64 * (long)lda, offA, P); } } while (0)
; #define STAGE_B(P, hf, kt) do { const bf16* _gp = Bt + (long)(bcol + (hf) * 2) * ldb + (long)(kt) * BK; GLDS2(_gp, 128 * (long)ldb, offB, P); } while (0)
; #define LDA(dst, b, h) for (int m = 0; m < 4; ++m) for (int k = 0; k < 2; ++k) \
;     dst[m][k] = *reinterpret_cast<const bf16x8*>((char*)SA(b, h) + lds_byte(wr * 64 + m * 16 + fr, k * 32 + fq * 8))
; #define LDB(dst, b, h) for (int n = 0; n < 2; ++n) for (int k = 0; k < 2; ++k) \
;     dst[n][k] = *reinterpret_cast<const bf16x8*>((char*)SB(b, h) + lds_byte(wc * 32 + n * 16 + fr, k * 32 + fq * 8))
; #define MMA(ai, bj, At, Bt_) do { __builtin_amdgcn_s_setprio(1); \
;     for (int m = 0; m < 4; ++m) for (int n = 0; n < 2; ++n) for (int k = 0; k < 2; ++k) \
;       acc[ai][bj][m][n] = __builtin_amdgcn_mfma_f32_16x16x32_bf16(At[m][k], Bt_[n][k], acc[ai][bj][m][n], 0, 0, 0); \
;     __builtin_amdgcn_s_setprio(0); } while (0)
; #define WAIT_V(n) asm volatile("s_waitcnt vmcnt(" #n ")" ::: "memory")
; #define WAIT_L(n) asm volatile("s_waitcnt lgkmcnt(" #n ")" ::: "memory")
; #define BAR __builtin_amdgcn_s_barrier()
; #define SCHED __builtin_amdgcn_sched_barrier(0)
; template <bool ABLK, class Epi>
; __device__ __forceinline__ void gemm_tile(const bf16* __restrict__ A, int lda, const bf16* __restrict__ Bt, int ldb, int K,
;                                           int brow, int bcol, bf16* shm, const Epi& epi, int wv) {
;     ...
;     WAIT_V(6); BAR; MMA(1, 1, At, B1); BAR;
;     LDB(B0, 1, 0); SCHED; LDA(At, 1, 0); STAGE_A(SA(0, 1), 1, t + 2);
;     WAIT_L(8); BAR; MMA(0, 0, At, B0); BAR; SCHED;
;     LDB(B1, 1, 1); STAGE_B(SB(1, 0), 0, t + 3);
;     BAR; MMA(0, 1, At, B1); BAR;
;     LDA(At, 1, 1); STAGE_A(SA(1, 0), 0, t + 3);
;     BAR; MMA(1, 0, At, B0); BAR; SCHED;
	s_setprio 1
	v_mfma_f32_16x16x32_bf16 v[28:31], v[180:183], v[224:227], v[28:31]
	v_mfma_f32_16x16x32_bf16 v[24:27], v[180:183], v[232:235], v[24:27]
	v_mfma_f32_16x16x32_bf16 v[20:23], v[194:197], v[224:227], v[20:23]
	v_mfma_f32_16x16x32_bf16 v[16:19], v[194:197], v[232:235], v[16:19]
	v_mfma_f32_16x16x32_bf16 v[12:15], v[208:211], v[224:227], v[12:15]
	v_mfma_f32_16x16x32_bf16 v[8:11], v[208:211], v[232:235], v[8:11]
	v_mfma_f32_16x16x32_bf16 v[4:7], v[216:219], v[224:227], v[4:7]
	v_mfma_f32_16x16x32_bf16 v[0:3], v[216:219], v[232:235], v[0:3]
	v_mfma_f32_16x16x32_bf16 v[28:31], v[184:187], v[228:231], v[28:31]
	v_mfma_f32_16x16x32_bf16 v[24:27], v[184:187], v[236:239], v[24:27]
	v_mfma_f32_16x16x32_bf16 v[20:23], v[202:205], v[228:231], v[20:23]
	v_mfma_f32_16x16x32_bf16 v[16:19], v[202:205], v[236:239], v[16:19]
	v_mfma_f32_16x16x32_bf16 v[12:15], v[212:215], v[228:231], v[12:15]
	v_mfma_f32_16x16x32_bf16 v[8:11], v[212:215], v[236:239], v[8:11]
	v_mfma_f32_16x16x32_bf16 v[4:7], v[220:223], v[228:231], v[4:7]
	v_mfma_f32_16x16x32_bf16 v[0:3], v[220:223], v[236:239], v[0:3]
	s_setprio 0
	s_barrier
	ds_read_b128 v[164:167], v149
	ds_read_b128 v[168:171], v149 offset:1024
	ds_read_b128 v[172:175], v149 offset:2048
	ds_read_b128 v[176:179], v149 offset:3072
	v_lshl_add_u64 v[190:191], v[130:131], 0, s[42:43]
	s_add_i32 m0, s99, 0x4000
	ds_read_b128 v[180:183], v148 offset:32768
	ds_read_b128 v[184:187], v148 offset:33792
	ds_read_b128 v[194:197], v147 offset:32768
	ds_read_b128 v[202:205], v147 offset:33792
	ds_read_b128 v[208:211], v146 offset:32768
	ds_read_b128 v[212:215], v146 offset:33792
	ds_read_b128 v[216:219], v145 offset:32768
	ds_read_b128 v[220:223], v145 offset:33792
	global_load_lds_dwordx4 v[190:191], off
	s_add_i32 m0, s99, 0x6000
	v_lshl_add_u64 v[190:191], v[130:131], 0, s[44:45]
	global_load_lds_dwordx4 v[190:191], off
	s_waitcnt lgkmcnt(8)
	s_barrier
	s_setprio 1
	s_waitcnt lgkmcnt(0)
	v_mfma_f32_16x16x32_bf16 v[124:127], v[180:183], v[164:167], v[124:127]
	v_mfma_f32_16x16x32_bf16 v[120:123], v[180:183], v[172:175], v[120:123]
	v_mfma_f32_16x16x32_bf16 v[116:119], v[194:197], v[164:167], v[116:119]
	v_mfma_f32_16x16x32_bf16 v[112:115], v[194:197], v[172:175], v[112:115]
	v_mfma_f32_16x16x32_bf16 v[108:111], v[208:211], v[164:167], v[108:111]
	v_mfma_f32_16x16x32_bf16 v[104:107], v[208:211], v[172:175], v[104:107]
	v_mfma_f32_16x16x32_bf16 v[100:103], v[216:219], v[164:167], v[100:103]
	v_mfma_f32_16x16x32_bf16 v[96:99], v[216:219], v[172:175], v[96:99]
	v_mfma_f32_16x16x32_bf16 v[124:127], v[184:187], v[168:171], v[124:127]
	v_mfma_f32_16x16x32_bf16 v[120:123], v[184:187], v[176:179], v[120:123]
	v_mfma_f32_16x16x32_bf16 v[116:119], v[202:205], v[168:171], v[116:119]
	v_mfma_f32_16x16x32_bf16 v[112:115], v[202:205], v[176:179], v[112:115]
	v_mfma_f32_16x16x32_bf16 v[108:111], v[212:215], v[168:171], v[108:111]
	v_mfma_f32_16x16x32_bf16 v[104:107], v[212:215], v[176:179], v[104:107]
	v_mfma_f32_16x16x32_bf16 v[100:103], v[220:223], v[168:171], v[100:103]
	v_mfma_f32_16x16x32_bf16 v[96:99], v[220:223], v[176:179], v[96:99]
	s_setprio 0
	s_barrier
	v_lshl_add_u64 v[190:191], v[132:133], 0, s[46:47]
	s_add_i32 m0, s99, 0x18000
	ds_read_b128 v[224:227], v140
	ds_read_b128 v[228:231], v140 offset:1024
	ds_read_b128 v[232:235], v140 offset:2048
	ds_read_b128 v[236:239], v140 offset:3072
	global_load_lds_dwordx4 v[190:191], off
	s_add_i32 m0, s99, 0x1a000
	v_lshl_add_u64 v[190:191], v[132:133], 0, s[48:49]
	global_load_lds_dwordx4 v[190:191], off
	s_barrier
	s_setprio 1
	s_waitcnt lgkmcnt(0)
	v_mfma_f32_16x16x32_bf16 v[92:95], v[180:183], v[224:227], v[92:95]
	v_mfma_f32_16x16x32_bf16 v[88:91], v[180:183], v[232:235], v[88:91]
	v_mfma_f32_16x16x32_bf16 v[84:87], v[194:197], v[224:227], v[84:87]
	v_mfma_f32_16x16x32_bf16 v[80:83], v[194:197], v[232:235], v[80:83]
	v_mfma_f32_16x16x32_bf16 v[76:79], v[208:211], v[224:227], v[76:79]
	v_mfma_f32_16x16x32_bf16 v[72:75], v[208:211], v[232:235], v[72:75]
	v_mfma_f32_16x16x32_bf16 v[68:71], v[216:219], v[224:227], v[68:71]
	v_mfma_f32_16x16x32_bf16 v[64:67], v[216:219], v[232:235], v[64:67]
	v_mfma_f32_16x16x32_bf16 v[92:95], v[184:187], v[228:231], v[92:95]
	v_mfma_f32_16x16x32_bf16 v[88:91], v[184:187], v[236:239], v[88:91]
	v_mfma_f32_16x16x32_bf16 v[84:87], v[202:205], v[228:231], v[84:87]
	v_mfma_f32_16x16x32_bf16 v[80:83], v[202:205], v[236:239], v[80:83]
	v_mfma_f32_16x16x32_bf16 v[76:79], v[212:215], v[228:231], v[76:79]
	v_mfma_f32_16x16x32_bf16 v[72:75], v[212:215], v[236:239], v[72:75]
	v_mfma_f32_16x16x32_bf16 v[68:71], v[220:223], v[228:231], v[68:71]
	v_mfma_f32_16x16x32_bf16 v[64:67], v[220:223], v[236:239], v[64:67]
	s_setprio 0
	v_lshl_add_u64 v[190:191], v[130:131], 0, s[50:51]
	s_add_i32 m0, s99, 0x8000
	s_barrier
	ds_read_b128 v[180:183], v148 offset:49152
	ds_read_b128 v[184:187], v148 offset:50176
	ds_read_b128 v[194:197], v147 offset:49152
	ds_read_b128 v[202:205], v147 offset:50176
	ds_read_b128 v[208:211], v146 offset:49152
	ds_read_b128 v[212:215], v146 offset:50176
	ds_read_b128 v[216:219], v145 offset:49152
	ds_read_b128 v[220:223], v145 offset:50176
	global_load_lds_dwordx4 v[190:191], off
	s_add_i32 m0, s99, 0xa000
	s_nop 0
	global_load_lds_dwordx4 v[130:131], off
	s_barrier
; #define STAGE_A(P, hf, kt) do { if constexpr (ABLK) { const bf16* _gp = A + ((long)(brow >> 8) * nt + (kt)) * 16384 + (hf) * 8192; GLDS2(_gp, 4096, offA, P); } \
;     else { const bf16* _gp = A + (long)(brow + (hf) * HALF) * lda + (long)(kt) * BK; GLDS2(_gp, 64 * (long)lda, offA, P); } } while (0)
; #define STAGE_B(P, hf, kt) do { const bf16* _gp = Bt + (long)(bcol + (hf) * 2) * ldb + (long)(kt) * BK; GLDS2(_gp, 128 * (long)ldb, offB, P); } while (0)
; #define LDA(dst, b, h) for (int m = 0; m < 4; ++m) for (int k = 0; k < 2; ++k) \
;     dst[m][k] = *reinterpret_cast<const bf16x8*>((char*)SA(b, h) + lds_byte(wr * 64 + m * 16 + fr, k * 32 + fq * 8))
; #define LDB(dst, b, h) for (int n = 0; n < 2; ++n) for (int k = 0; k < 2; ++k) \
;     dst[n][k] = *reinterpret_cast<const bf16x8*>((char*)SB(b, h) + lds_byte(wc * 32 + n * 16 + fr, k * 32 + fq * 8))
; #define MMA(ai, bj, At, Bt_) do { __builtin_amdgcn_s_setprio(1); \
;     for (int m = 0; m < 4; ++m) for (int n = 0; n < 2; ++n) for (int k = 0; k < 2; ++k) \
;       acc[ai][bj][m][n] = __builtin_amdgcn_mfma_f32_16x16x32_bf16(At[m][k], Bt_[n][k], acc[ai][bj][m][n], 0, 0, 0); \
;     __builtin_amdgcn_s_setprio(0); } while (0)
; #define WAIT_V(n) asm volatile("s_waitcnt vmcnt(" #n ")" ::: "memory")
; #define WAIT_L(n) asm volatile("s_waitcnt lgkmcnt(" #n ")" ::: "memory")
; #define BAR __builtin_amdgcn_s_barrier()
; #define SCHED __builtin_amdgcn_sched_barrier(0)
; template <bool ABLK, class Epi>
; __device__ __forceinline__ void gemm_tile(const bf16* __restrict__ A, int lda, const bf16* __restrict__ Bt, int ldb, int K,
;                                           int brow, int bcol, bf16* shm, const Epi& epi, int wv) {
;     ...
;     BAR; MMA(1, 0, At, B0); BAR; SCHED;
;     STAGE_B(SB(1, 1), 1, t + 3);
;     WAIT_V(6); BAR; MMA(1, 1, At, B1); BAR;
;   }
;   { LDB(B0, 0, 0); LDA(At, 0, 0); STAGE_A(SA(1, 1), 1, nt - 1);
;     BAR; WAIT_L(0); MMA(0, 0, At, B0); BAR;
;     LDB(B1, 0, 1); BAR; WAIT_L(0); MMA(0, 1, At, B1); BAR;
;     LDA(At, 0, 1); WAIT_V(4); BAR; WAIT_L(0); MMA(1, 0, At, B0); MMA(1, 1, At, B1); BAR; }
	s_setprio 1
	s_waitcnt lgkmcnt(0)
	v_mfma_f32_16x16x32_bf16 v[60:63], v[180:183], v[164:167], v[60:63]
	v_mfma_f32_16x16x32_bf16 v[56:59], v[180:183], v[172:175], v[56:59]
	v_mfma_f32_16x16x32_bf16 v[52:55], v[194:197], v[164:167], v[52:55]
	v_mfma_f32_16x16x32_bf16 v[48:51], v[194:197], v[172:175], v[48:51]
	v_mfma_f32_16x16x32_bf16 v[44:47], v[208:211], v[164:167], v[44:47]
	v_mfma_f32_16x16x32_bf16 v[40:43], v[208:211], v[172:175], v[40:43]
	v_mfma_f32_16x16x32_bf16 v[36:39], v[216:219], v[164:167], v[36:39]
	v_mfma_f32_16x16x32_bf16 v[32:35], v[216:219], v[172:175], v[32:35]
	v_mfma_f32_16x16x32_bf16 v[60:63], v[184:187], v[168:171], v[60:63]
	v_mfma_f32_16x16x32_bf16 v[56:59], v[184:187], v[176:179], v[56:59]
	v_mfma_f32_16x16x32_bf16 v[52:55], v[202:205], v[168:171], v[52:55]
	v_mfma_f32_16x16x32_bf16 v[48:51], v[202:205], v[176:179], v[48:51]
	v_mfma_f32_16x16x32_bf16 v[44:47], v[212:215], v[168:171], v[44:47]
	v_mfma_f32_16x16x32_bf16 v[40:43], v[212:215], v[176:179], v[40:43]
	v_mfma_f32_16x16x32_bf16 v[36:39], v[220:223], v[168:171], v[36:39]
	v_mfma_f32_16x16x32_bf16 v[32:35], v[220:223], v[176:179], v[32:35]
	s_setprio 0
	s_barrier
	s_add_i32 m0, s99, 0x1c000
	v_lshl_add_u64 v[164:165], v[132:133], 0, s[52:53]
	global_load_lds_dwordx4 v[164:165], off
	s_add_i32 m0, s99, 0x1e000
	s_nop 0
	global_load_lds_dwordx4 v[132:133], off
	s_waitcnt vmcnt(6)
	s_barrier
	s_setprio 1
	v_mfma_f32_16x16x32_bf16 v[28:31], v[180:183], v[224:227], v[28:31]
	v_mfma_f32_16x16x32_bf16 v[24:27], v[180:183], v[232:235], v[24:27]
	v_mfma_f32_16x16x32_bf16 v[20:23], v[194:197], v[224:227], v[20:23]
	v_mfma_f32_16x16x32_bf16 v[16:19], v[194:197], v[232:235], v[16:19]
	v_mfma_f32_16x16x32_bf16 v[12:15], v[208:211], v[224:227], v[12:15]
	v_mfma_f32_16x16x32_bf16 v[8:11], v[208:211], v[232:235], v[8:11]
	v_mfma_f32_16x16x32_bf16 v[4:7], v[216:219], v[224:227], v[4:7]
	v_mfma_f32_16x16x32_bf16 v[0:3], v[216:219], v[232:235], v[0:3]
	v_mfma_f32_16x16x32_bf16 v[28:31], v[184:187], v[228:231], v[28:31]
	v_mfma_f32_16x16x32_bf16 v[24:27], v[184:187], v[236:239], v[24:27]
	v_mfma_f32_16x16x32_bf16 v[20:23], v[202:205], v[228:231], v[20:23]
	v_mfma_f32_16x16x32_bf16 v[16:19], v[202:205], v[236:239], v[16:19]
	v_mfma_f32_16x16x32_bf16 v[12:15], v[212:215], v[228:231], v[12:15]
	v_mfma_f32_16x16x32_bf16 v[8:11], v[212:215], v[236:239], v[8:11]
	v_mfma_f32_16x16x32_bf16 v[4:7], v[220:223], v[228:231], v[4:7]
	v_mfma_f32_16x16x32_bf16 v[0:3], v[220:223], v[236:239], v[0:3]
	s_setprio 0
	s_add_i32 s33, s33, 2
	v_lshl_add_u64 v[130:131], v[130:131], 0, s[54:55]
	s_cmpk_lt_u32 s33, 0x54
	v_lshl_add_u64 v[132:133], v[132:133], 0, s[56:57]
	s_barrier
	s_cbranch_scc1 .LBB0_632
	v_readfirstlane_b32 s2, v161
	v_lshl_add_u64 v[134:135], v[128:129], 0, s[58:59]
	s_mov_b32 m0, s2
	v_readfirstlane_b32 s2, v162
	ds_read_b128 v[130:133], v160
	ds_read_b128 v[150:153], v160 offset:1024
	ds_read_b128 v[154:157], v160 offset:2048
	ds_read_b128 v[164:167], v160 offset:3072
	ds_read_b128 v[168:171], v148
	ds_read_b128 v[172:175], v148 offset:1024
	ds_read_b128 v[176:179], v147
	ds_read_b128 v[180:183], v147 offset:1024
	ds_read_b128 v[184:187], v146
	ds_read_b128 v[194:197], v146 offset:1024
	ds_read_b128 v[202:205], v145
	ds_read_b128 v[208:211], v145 offset:1024
	global_load_lds_dwordx4 v[134:135], off
	v_lshl_add_u64 v[128:129], v[128:129], 0, s[60:61]
	s_mov_b32 m0, s2
	s_nop 0
	global_load_lds_dwordx4 v[128:129], off
	s_barrier
	s_waitcnt lgkmcnt(0)
	s_setprio 1
	s_waitcnt lgkmcnt(0)
	v_mfma_f32_16x16x32_bf16 v[116:119], v[176:179], v[130:133], v[116:119]
	v_mfma_f32_16x16x32_bf16 v[108:111], v[184:187], v[130:133], v[108:111]
	v_mfma_f32_16x16x32_bf16 v[104:107], v[184:187], v[154:157], v[104:107]
	v_mfma_f32_16x16x32_bf16 v[100:103], v[202:205], v[130:133], v[100:103]
	v_mfma_f32_16x16x32_bf16 v[96:99], v[202:205], v[154:157], v[96:99]
	v_mfma_f32_16x16x32_bf16 v[124:127], v[168:171], v[130:133], v[124:127]
	v_mfma_f32_16x16x32_bf16 v[120:123], v[168:171], v[154:157], v[120:123]
	v_mfma_f32_16x16x32_bf16 v[116:119], v[180:183], v[150:153], v[116:119]
	v_mfma_f32_16x16x32_bf16 v[112:115], v[176:179], v[154:157], v[112:115]
	v_mfma_f32_16x16x32_bf16 v[108:111], v[194:197], v[150:153], v[108:111]
	v_mfma_f32_16x16x32_bf16 v[104:107], v[194:197], v[164:167], v[104:107]
	v_mfma_f32_16x16x32_bf16 v[100:103], v[208:211], v[150:153], v[100:103]
	v_mfma_f32_16x16x32_bf16 v[96:99], v[208:211], v[164:167], v[96:99]
	v_mfma_f32_16x16x32_bf16 v[124:127], v[172:175], v[150:153], v[124:127]
	v_mfma_f32_16x16x32_bf16 v[120:123], v[172:175], v[164:167], v[120:123]
	v_mfma_f32_16x16x32_bf16 v[160:163], v[180:183], v[164:167], v[112:115]
	s_setprio 0
	s_barrier
	s_nop 0
	ds_read_b128 v[112:115], v159
	ds_read_b128 v[212:215], v159 offset:1024
	ds_read_b128 v[216:219], v159 offset:2048
	ds_read_b128 v[220:223], v159 offset:3072
	s_barrier
	s_waitcnt lgkmcnt(0)
	s_setprio 1
	s_waitcnt lgkmcnt(0)
	v_mfma_f32_16x16x32_bf16 v[84:87], v[176:179], v[112:115], v[84:87]
	v_mfma_f32_16x16x32_bf16 v[80:83], v[176:179], v[216:219], v[80:83]
	v_mfma_f32_16x16x32_bf16 v[92:95], v[168:171], v[112:115], v[92:95]
	v_mfma_f32_16x16x32_bf16 v[88:91], v[168:171], v[216:219], v[88:91]
	v_mfma_f32_16x16x32_bf16 v[84:87], v[180:183], v[212:215], v[84:87]
	v_mfma_f32_16x16x32_bf16 v[80:83], v[180:183], v[220:223], v[80:83]
	v_mfma_f32_16x16x32_bf16 v[76:79], v[184:187], v[112:115], v[76:79]
	v_mfma_f32_16x16x32_bf16 v[72:75], v[184:187], v[216:219], v[72:75]
	v_mfma_f32_16x16x32_bf16 v[68:71], v[202:205], v[112:115], v[68:71]
	v_mfma_f32_16x16x32_bf16 v[64:67], v[202:205], v[216:219], v[64:67]
	v_mfma_f32_16x16x32_bf16 v[224:227], v[172:175], v[212:215], v[92:95]
	v_mfma_f32_16x16x32_bf16 v[168:171], v[172:175], v[220:223], v[88:91]
	v_mfma_f32_16x16x32_bf16 v[172:175], v[194:197], v[212:215], v[76:79]
	v_mfma_f32_16x16x32_bf16 v[176:179], v[194:197], v[220:223], v[72:75]
	v_mfma_f32_16x16x32_bf16 v[180:183], v[208:211], v[212:215], v[68:71]
	v_mfma_f32_16x16x32_bf16 v[184:187], v[208:211], v[220:223], v[64:67]
	s_setprio 0
	s_barrier
; #define LDA(dst, b, h) for (int m = 0; m < 4; ++m) for (int k = 0; k < 2; ++k) \
;     dst[m][k] = *reinterpret_cast<const bf16x8*>((char*)SA(b, h) + lds_byte(wr * 64 + m * 16 + fr, k * 32 + fq * 8))
; #define LDB(dst, b, h) for (int n = 0; n < 2; ++n) for (int k = 0; k < 2; ++k) \
;     dst[n][k] = *reinterpret_cast<const bf16x8*>((char*)SB(b, h) + lds_byte(wc * 32 + n * 16 + fr, k * 32 + fq * 8))
; #define MMA(ai, bj, At, Bt_) do { __builtin_amdgcn_s_setprio(1); \
;     for (int m = 0; m < 4; ++m) for (int n = 0; n < 2; ++n) for (int k = 0; k < 2; ++k) \
;       acc[ai][bj][m][n] = __builtin_amdgcn_mfma_f32_16x16x32_bf16(At[m][k], Bt_[n][k], acc[ai][bj][m][n], 0, 0, 0); \
;     __builtin_amdgcn_s_setprio(0); } while (0)
; #define WAIT_V(n) asm volatile("s_waitcnt vmcnt(" #n ")" ::: "memory")
; #define WAIT_L(n) asm volatile("s_waitcnt lgkmcnt(" #n ")" ::: "memory")
; #define BAR __builtin_amdgcn_s_barrier()
; template <bool ABLK, class Epi>
; __device__ __forceinline__ void gemm_tile(const bf16* __restrict__ A, int lda, const bf16* __restrict__ Bt, int ldb, int K,
;                                           int brow, int bcol, bf16* shm, const Epi& epi, int wv) {
;     ...
;     LDB(B1, 0, 1); BAR; WAIT_L(0); MMA(0, 1, At, B1); BAR;
;     LDA(At, 0, 1); WAIT_V(4); BAR; WAIT_L(0); MMA(1, 0, At, B0); MMA(1, 1, At, B1); BAR; }
;   { LDB(B0, 1, 0); LDA(At, 1, 0); WAIT_V(2); BAR; WAIT_L(0); MMA(0, 0, At, B0); BAR;
	s_nop 0
	ds_read_b128 v[64:67], v148 offset:16384
	ds_read_b128 v[68:71], v148 offset:17408
	ds_read_b128 v[72:75], v147 offset:16384
	ds_read_b128 v[76:79], v147 offset:17408
	ds_read_b128 v[88:91], v146 offset:16384
	ds_read_b128 v[92:95], v146 offset:17408
	ds_read_b128 v[194:197], v145 offset:16384
	ds_read_b128 v[202:205], v145 offset:17408
	s_waitcnt vmcnt(4)
	s_barrier
	s_waitcnt lgkmcnt(0)
	s_setprio 1
	s_waitcnt lgkmcnt(0)
	v_mfma_f32_16x16x32_bf16 v[60:63], v[64:67], v[130:133], v[60:63]
	v_mfma_f32_16x16x32_bf16 v[56:59], v[64:67], v[154:157], v[56:59]
	v_mfma_f32_16x16x32_bf16 v[44:47], v[88:91], v[130:133], v[44:47]
	v_mfma_f32_16x16x32_bf16 v[40:43], v[88:91], v[154:157], v[40:43]
	v_mfma_f32_16x16x32_bf16 v[60:63], v[68:71], v[150:153], v[60:63]
	v_mfma_f32_16x16x32_bf16 v[56:59], v[68:71], v[164:167], v[56:59]
	v_mfma_f32_16x16x32_bf16 v[52:55], v[72:75], v[130:133], v[52:55]
	v_mfma_f32_16x16x32_bf16 v[48:51], v[72:75], v[154:157], v[48:51]
	v_mfma_f32_16x16x32_bf16 v[44:47], v[92:95], v[150:153], v[44:47]
	v_mfma_f32_16x16x32_bf16 v[40:43], v[92:95], v[164:167], v[40:43]
	v_mfma_f32_16x16x32_bf16 v[36:39], v[194:197], v[130:133], v[36:39]
	v_mfma_f32_16x16x32_bf16 v[32:35], v[194:197], v[154:157], v[32:35]
	v_mfma_f32_16x16x32_bf16 v[208:211], v[76:79], v[150:153], v[52:55]
	v_mfma_f32_16x16x32_bf16 v[228:231], v[76:79], v[164:167], v[48:51]
	v_mfma_f32_16x16x32_bf16 v[128:131], v[202:205], v[150:153], v[36:39]
	v_mfma_f32_16x16x32_bf16 v[150:153], v[202:205], v[164:167], v[32:35]
	s_setprio 0
	s_setprio 1
	v_mfma_f32_16x16x32_bf16 v[28:31], v[64:67], v[112:115], v[28:31]
	v_mfma_f32_16x16x32_bf16 v[24:27], v[64:67], v[216:219], v[24:27]
	v_mfma_f32_16x16x32_bf16 v[12:15], v[88:91], v[112:115], v[12:15]
	v_mfma_f32_16x16x32_bf16 v[8:11], v[88:91], v[216:219], v[8:11]
	v_mfma_f32_16x16x32_bf16 v[28:31], v[68:71], v[212:215], v[28:31]
	v_mfma_f32_16x16x32_bf16 v[24:27], v[68:71], v[220:223], v[24:27]
	v_mfma_f32_16x16x32_bf16 v[20:23], v[72:75], v[112:115], v[20:23]
	v_mfma_f32_16x16x32_bf16 v[16:19], v[72:75], v[216:219], v[16:19]
	v_mfma_f32_16x16x32_bf16 v[12:15], v[92:95], v[212:215], v[12:15]
	v_mfma_f32_16x16x32_bf16 v[8:11], v[92:95], v[220:223], v[8:11]
	v_mfma_f32_16x16x32_bf16 v[4:7], v[194:197], v[112:115], v[4:7]
	v_mfma_f32_16x16x32_bf16 v[0:3], v[194:197], v[216:219], v[0:3]
	v_mfma_f32_16x16x32_bf16 v[154:157], v[76:79], v[212:215], v[20:23]
	v_mfma_f32_16x16x32_bf16 v[164:167], v[76:79], v[220:223], v[16:19]
	v_mfma_f32_16x16x32_bf16 v[212:215], v[202:205], v[212:215], v[4:7]
	v_mfma_f32_16x16x32_bf16 v[194:197], v[202:205], v[220:223], v[0:3]
	s_setprio 0
	s_barrier
	s_nop 1
	ds_read_b128 v[0:3], v149
	ds_read_b128 v[4:7], v149 offset:1024
	ds_read_b128 v[202:205], v149 offset:2048
	ds_read_b128 v[216:219], v149 offset:3072
	ds_read_b128 v[16:19], v148 offset:32768
	ds_read_b128 v[20:23], v148 offset:33792
	ds_read_b128 v[32:35], v147 offset:32768
	ds_read_b128 v[36:39], v147 offset:33792
	ds_read_b128 v[48:51], v146 offset:32768
	ds_read_b128 v[52:55], v146 offset:33792
	ds_read_b128 v[220:223], v145 offset:32768
	ds_read_b128 v[232:235], v145 offset:33792
	s_waitcnt vmcnt(2)
	s_barrier
	s_waitcnt lgkmcnt(0)
	s_setprio 1
	s_waitcnt lgkmcnt(0)
	v_mfma_f32_16x16x32_bf16 v[64:67], v[16:19], v[0:3], v[124:127]
	v_mfma_f32_16x16x32_bf16 v[132:135], v[20:23], v[4:7], v[64:67]
	v_mfma_f32_16x16x32_bf16 v[64:67], v[16:19], v[202:205], v[120:123]
	v_mfma_f32_16x16x32_bf16 v[112:115], v[20:23], v[216:219], v[64:67]
	v_mfma_f32_16x16x32_bf16 v[64:67], v[32:35], v[0:3], v[116:119]
	v_mfma_f32_16x16x32_bf16 v[88:91], v[36:39], v[4:7], v[64:67]
	v_mfma_f32_16x16x32_bf16 v[64:67], v[32:35], v[202:205], v[160:163]
	v_mfma_f32_16x16x32_bf16 v[92:95], v[36:39], v[216:219], v[64:67]
	v_mfma_f32_16x16x32_bf16 v[64:67], v[48:51], v[0:3], v[108:111]
	v_mfma_f32_16x16x32_bf16 v[72:75], v[52:55], v[4:7], v[64:67]
	v_mfma_f32_16x16x32_bf16 v[64:67], v[48:51], v[202:205], v[104:107]
	v_mfma_f32_16x16x32_bf16 v[76:79], v[52:55], v[216:219], v[64:67]
	v_mfma_f32_16x16x32_bf16 v[64:67], v[220:223], v[0:3], v[100:103]
	v_mfma_f32_16x16x32_bf16 v[68:71], v[220:223], v[202:205], v[96:99]
	v_mfma_f32_16x16x32_bf16 v[64:67], v[232:235], v[4:7], v[64:67]
	v_mfma_f32_16x16x32_bf16 v[68:71], v[232:235], v[216:219], v[68:71]
	s_setprio 0
	s_barrier
; #define LDA(dst, b, h) for (int m = 0; m < 4; ++m) for (int k = 0; k < 2; ++k) \
;     dst[m][k] = *reinterpret_cast<const bf16x8*>((char*)SA(b, h) + lds_byte(wr * 64 + m * 16 + fr, k * 32 + fq * 8))
; #define LDB(dst, b, h) for (int n = 0; n < 2; ++n) for (int k = 0; k < 2; ++k) \
;     dst[n][k] = *reinterpret_cast<const bf16x8*>((char*)SB(b, h) + lds_byte(wc * 32 + n * 16 + fr, k * 32 + fq * 8))
; #define MMA(ai, bj, At, Bt_) do { __builtin_amdgcn_s_setprio(1); \
;     for (int m = 0; m < 4; ++m) for (int n = 0; n < 2; ++n) for (int k = 0; k < 2; ++k) \
;       acc[ai][bj][m][n] = __builtin_amdgcn_mfma_f32_16x16x32_bf16(At[m][k], Bt_[n][k], acc[ai][bj][m][n], 0, 0, 0); \
;     __builtin_amdgcn_s_setprio(0); } while (0)
; #define WAIT_V(n) asm volatile("s_waitcnt vmcnt(" #n ")" ::: "memory")
; #define WAIT_L(n) asm volatile("s_waitcnt lgkmcnt(" #n ")" ::: "memory")
; #define BAR __builtin_amdgcn_s_barrier()
; template <bool ABLK, class Epi>
; __device__ __forceinline__ void gemm_tile(const bf16* __restrict__ A, int lda, const bf16* __restrict__ Bt, int ldb, int K,
;                                           int brow, int bcol, bf16* shm, const Epi& epi, int wv) {
;     ...
;     LDB(B1, 1, 1); WAIT_V(0); BAR; WAIT_L(0); MMA(0, 1, At, B1); BAR;
;     LDA(At, 1, 1); BAR; WAIT_L(0); MMA(1, 0, At, B0); MMA(1, 1, At, B1); BAR; }
;   if (wr == 0) BAR;
	ds_read_b128 v[120:123], v140
	ds_read_b128 v[124:127], v140 offset:1024
	ds_read_b128 v[158:161], v140 offset:2048
	ds_read_b128 v[236:239], v140 offset:3072
	s_waitcnt vmcnt(0)
	s_barrier
	s_waitcnt lgkmcnt(0)
	s_setprio 1
	s_waitcnt lgkmcnt(0)
	v_mfma_f32_16x16x32_bf16 v[96:99], v[16:19], v[120:123], v[224:227]
	v_mfma_f32_16x16x32_bf16 v[16:19], v[16:19], v[158:161], v[168:171]
	v_mfma_f32_16x16x32_bf16 v[116:119], v[20:23], v[236:239], v[16:19]
	v_mfma_f32_16x16x32_bf16 v[16:19], v[32:35], v[120:123], v[84:87]
	v_mfma_f32_16x16x32_bf16 v[104:107], v[36:39], v[124:127], v[16:19]
	v_mfma_f32_16x16x32_bf16 v[16:19], v[32:35], v[158:161], v[80:83]
	v_mfma_f32_16x16x32_bf16 v[108:111], v[36:39], v[236:239], v[16:19]
	v_mfma_f32_16x16x32_bf16 v[16:19], v[48:51], v[120:123], v[172:175]
	v_mfma_f32_16x16x32_bf16 v[140:143], v[20:23], v[124:127], v[96:99]
	v_mfma_f32_16x16x32_bf16 v[96:99], v[52:55], v[124:127], v[16:19]
	v_mfma_f32_16x16x32_bf16 v[16:19], v[48:51], v[158:161], v[176:179]
	v_mfma_f32_16x16x32_bf16 v[100:103], v[52:55], v[236:239], v[16:19]
	v_mfma_f32_16x16x32_bf16 v[16:19], v[220:223], v[120:123], v[180:183]
	v_mfma_f32_16x16x32_bf16 v[80:83], v[232:235], v[124:127], v[16:19]
	v_mfma_f32_16x16x32_bf16 v[16:19], v[220:223], v[158:161], v[184:187]
	v_mfma_f32_16x16x32_bf16 v[84:87], v[232:235], v[236:239], v[16:19]
	s_setprio 0
	s_barrier
	ds_read_b128 v[168:171], v148 offset:49152
	ds_read_b128 v[172:175], v148 offset:50176
	ds_read_b128 v[176:179], v147 offset:49152
	ds_read_b128 v[180:183], v147 offset:50176
	ds_read_b128 v[184:187], v146 offset:49152
	ds_read_b128 v[146:149], v146 offset:50176
	ds_read_b128 v[220:223], v145 offset:49152
	ds_read_b128 v[224:227], v145 offset:50176
	s_barrier
	s_waitcnt lgkmcnt(0)
	s_setprio 1
	s_waitcnt lgkmcnt(0)
	v_mfma_f32_16x16x32_bf16 v[16:19], v[168:171], v[0:3], v[60:63]
	v_mfma_f32_16x16x32_bf16 v[48:51], v[172:175], v[4:7], v[16:19]
	v_mfma_f32_16x16x32_bf16 v[16:19], v[168:171], v[202:205], v[56:59]
	v_mfma_f32_16x16x32_bf16 v[52:55], v[172:175], v[216:219], v[16:19]
	v_mfma_f32_16x16x32_bf16 v[16:19], v[176:179], v[0:3], v[208:211]
	v_mfma_f32_16x16x32_bf16 v[32:35], v[180:183], v[4:7], v[16:19]
	v_mfma_f32_16x16x32_bf16 v[16:19], v[176:179], v[202:205], v[228:231]
	v_mfma_f32_16x16x32_bf16 v[36:39], v[180:183], v[216:219], v[16:19]
	v_mfma_f32_16x16x32_bf16 v[16:19], v[184:187], v[0:3], v[44:47]
	v_mfma_f32_16x16x32_bf16 v[0:3], v[220:223], v[0:3], v[128:131]
	v_mfma_f32_16x16x32_bf16 v[16:19], v[146:149], v[4:7], v[16:19]
	v_mfma_f32_16x16x32_bf16 v[20:23], v[184:187], v[202:205], v[40:43]
	v_mfma_f32_16x16x32_bf16 v[0:3], v[224:227], v[4:7], v[0:3]
	v_mfma_f32_16x16x32_bf16 v[4:7], v[220:223], v[202:205], v[150:153]
	v_mfma_f32_16x16x32_bf16 v[20:23], v[146:149], v[216:219], v[20:23]
	v_mfma_f32_16x16x32_bf16 v[4:7], v[224:227], v[216:219], v[4:7]
	s_setprio 0
	s_setprio 1
	v_mfma_f32_16x16x32_bf16 v[24:27], v[168:171], v[158:161], v[24:27]
	v_mfma_f32_16x16x32_bf16 v[28:31], v[168:171], v[120:123], v[28:31]
	v_mfma_f32_16x16x32_bf16 v[60:63], v[172:175], v[236:239], v[24:27]
	v_mfma_f32_16x16x32_bf16 v[24:27], v[176:179], v[120:123], v[154:157]
	v_mfma_f32_16x16x32_bf16 v[8:11], v[184:187], v[158:161], v[8:11]
	v_mfma_f32_16x16x32_bf16 v[56:59], v[172:175], v[124:127], v[28:31]
	v_mfma_f32_16x16x32_bf16 v[40:43], v[180:183], v[124:127], v[24:27]
	v_mfma_f32_16x16x32_bf16 v[24:27], v[176:179], v[158:161], v[164:167]
	v_mfma_f32_16x16x32_bf16 v[12:15], v[184:187], v[120:123], v[12:15]
	v_mfma_f32_16x16x32_bf16 v[28:31], v[146:149], v[236:239], v[8:11]
	v_mfma_f32_16x16x32_bf16 v[8:11], v[220:223], v[120:123], v[212:215]
	v_mfma_f32_16x16x32_bf16 v[44:47], v[180:183], v[236:239], v[24:27]
	v_mfma_f32_16x16x32_bf16 v[24:27], v[146:149], v[124:127], v[12:15]
	v_mfma_f32_16x16x32_bf16 v[12:15], v[224:227], v[124:127], v[8:11]
	v_mfma_f32_16x16x32_bf16 v[8:11], v[220:223], v[158:161], v[194:197]
	v_mfma_f32_16x16x32_bf16 v[8:11], v[224:227], v[236:239], v[8:11]
	s_setprio 0
	v_cmp_gt_u32_e32 vcc, s77, v136
	s_barrier
	s_and_saveexec_b64 s[62:63], vcc
	s_cbranch_execz .LBB0_628
	s_barrier
	s_branch .LBB0_628

; __device__ __forceinline__ int mytid(int wv) { return (wv << 6) | (int)__builtin_amdgcn_mbcnt_hi(~0u, __builtin_amdgcn_mbcnt_lo(~0u, 0u)); }
; template <bool ABLK, class Epi>
; __device__ __forceinline__ void gemm_tile(const bf16* __restrict__ A, int lda, const bf16* __restrict__ Bt, int ldb, int K,
;                                           int brow, int bcol, bf16* shm, const Epi& epi, int wv) {
;     ...
;   int tid = mytid(wv); asm volatile("" : "+v"(tid));
;   const int wid = tid >> 6, lane = tid & 63, wr = wid >> 2, wc = wid & 3, fr = lane & 15, fq = lane >> 4;
;   f32x4 acc[2][2][4][2] = {};
;   bf16x8 At[4][2], B0[2][2], B1[2][2];
;   const int nt = K / BK;
;   int offA, offB;
;   { int r_, c_; stage_rc(tid * 16, r_, c_); offA = ABLK ? r_ * 64 + c_ : r_ * lda + c_;
;     offB = ((r_ >> 5) * 64 + (r_ & 15) * 4 + ((r_ >> 4) & 1)) * ldb + c_; }
; template <bool ABLK, class Epi>
; __device__ __forceinline__ void gemm_phase(const bf16* A, int lda, const bf16* Bt, int ldb, int M, int N, int K, char* smem, const Epi& epi, int wv) {
;     ...
;   for (int w = blockIdx.x; w < nwg; w += gridDim.x) {
;     int wgid = w;
;     { int q = nwg / NXCD, r = nwg % NXCD, xcd = wgid % NXCD, off = wgid / NXCD;
;       wgid = (xcd < r ? xcd * (q + 1) : r * (q + 1) + (xcd - r) * q) + off; }
;     const int nig = WGM * nN, gid = wgid / nig, fm = gid * WGM, gsz = min(nM - fm, WGM);
;     const int pm = fm + ((wgid % nig) % gsz), pn = (wgid % nig) / gsz;
;     gemm_tile<ABLK>(A, lda, Bt, ldb, K, pm * BM, pn * BM, (bf16*)smem, epi, wv);
.LBB0_713:
	s_or_b64 exec, exec, s[6:7]
	s_mov_b64 s[6:7], s[90:91]
	s_mov_b64 s[8:9], s[90:91]
	s_mov_b64 s[10:11], s[90:91]
	s_cmpk_gt_i32 s89, 0x2ff
	s_barrier
	s_barrier
	s_cbranch_scc1 .LBB0_723
	s_load_dwordx2 s[12:13], s[6:7], 0xa8
	s_load_dwordx2 s[14:15], s[8:9], 0xa8
	s_load_dwordx2 s[16:17], s[10:11], 0xa8
	s_mov_b32 s24, 0xffff2000
	s_mov_b32 s26, 0xffff4000
	s_waitcnt lgkmcnt(0)
	s_add_u32 s1, s12, 0xba40000
	s_addc_u32 s3, s13, 0
	s_add_u32 s72, s14, 0x2000000
	s_addc_u32 s73, s15, 0
	s_add_u32 s6, s16, 0x2be40000
	s_addc_u32 s7, s17, 0
	s_add_u32 s74, s12, 0xba5a000
	s_addc_u32 s75, s13, 0
	s_add_u32 s76, s14, 0x2082180
	s_mov_b32 s30, 0xfff7df80
	s_movk_i32 s34, 0xdf80
	s_mov_b32 s36, 0xffff6000
	s_movk_i32 s38, 0x8000
	s_mov_b32 s40, 0xfff7ff80
	s_movk_i32 s42, 0xff80
	s_movk_i32 s44, 0xa000
	s_movk_i32 s46, 0xc000
	s_mov_b32 s48, 0xfff7e000
	s_movk_i32 s50, 0xe000
	s_mov_b32 s52, 0xfff80000
	s_movk_i32 s0, 0x61
	s_addc_u32 s77, s15, 0
	s_add_i32 s78, 0, 0x10000
	s_mov_b64 s[8:9], 0x80000
	s_mov_b64 s[10:11], 0x2000
	s_add_i32 s79, 0, 0x14000
	s_mov_b64 s[12:13], 0x4000
	s_mov_b64 s[14:15], 0x6000
	s_mov_b64 s[16:17], 0x80
	s_add_i32 s80, 0, 0x18000
	s_mov_b64 s[18:19], 0x80080
	s_mov_b64 s[20:21], 0x8000
	s_mov_b64 s[22:23], 0xa000
	s_add_i32 s81, 0, 0x1c000
	s_movk_i32 s82, 0x3c0
	s_mov_b32 s25, -1
	s_mov_b32 s27, -1
	s_mov_b32 s31, -1
	s_mov_b32 s35, -1
	s_mov_b32 s37, -1
	s_mov_b32 s39, -1
	s_mov_b32 s41, -1
	s_mov_b32 s43, -1
	s_mov_b32 s45, -1
	s_mov_b32 s47, -1
	s_mov_b32 s49, -1
	s_mov_b32 s51, -1
	s_mov_b32 s53, -1
	s_mov_b64 s[54:55], 0x10000
	s_mov_b64 s[56:57], 0x100
	s_mov_b64 s[58:59], 0xfc000
	s_mov_b64 s[60:61], 0xfe000
	s_movk_i32 s83, 0x100
	v_mov_b32_e32 v134, 1
	s_mov_b32 s84, s89
	v_lshlrev_b32_e32 v254, 4, v192
	s_nop 0
	v_readfirstlane_b32 s99, v254
	s_branch .LBB0_716

; #define STAGE_A(P, hf, kt) do { if constexpr (ABLK) { const bf16* _gp = A + ((long)(brow >> 8) * nt + (kt)) * 16384 + (hf) * 8192; GLDS2(_gp, 4096, offA, P); } \
;     else { const bf16* _gp = A + (long)(brow + (hf) * HALF) * lda + (long)(kt) * BK; GLDS2(_gp, 64 * (long)lda, offA, P); } } while (0)
; #define STAGE_B(P, hf, kt) do { const bf16* _gp = Bt + (long)(bcol + (hf) * 2) * ldb + (long)(kt) * BK; GLDS2(_gp, 128 * (long)ldb, offB, P); } while (0)
; #define LDA(dst, b, h) for (int m = 0; m < 4; ++m) for (int k = 0; k < 2; ++k) \
;     dst[m][k] = *reinterpret_cast<const bf16x8*>((char*)SA(b, h) + lds_byte(wr * 64 + m * 16 + fr, k * 32 + fq * 8))
; #define LDB(dst, b, h) for (int n = 0; n < 2; ++n) for (int k = 0; k < 2; ++k) \
;     dst[n][k] = *reinterpret_cast<const bf16x8*>((char*)SB(b, h) + lds_byte(wc * 32 + n * 16 + fr, k * 32 + fq * 8))
; #define MMA(ai, bj, At, Bt_) do { __builtin_amdgcn_s_setprio(1); \
;     for (int m = 0; m < 4; ++m) for (int n = 0; n < 2; ++n) for (int k = 0; k < 2; ++k) \
;       acc[ai][bj][m][n] = __builtin_amdgcn_mfma_f32_16x16x32_bf16(At[m][k], Bt_[n][k], acc[ai][bj][m][n], 0, 0, 0); \
;     __builtin_amdgcn_s_setprio(0); } while (0)
; #define WAIT_V(n) asm volatile("s_waitcnt vmcnt(" #n ")" ::: "memory")
; #define WAIT_L(n) asm volatile("s_waitcnt lgkmcnt(" #n ")" ::: "memory")
; #define BAR __builtin_amdgcn_s_barrier()
; #define SCHED __builtin_amdgcn_sched_barrier(0)
; template <bool ABLK, class Epi>
; __device__ __forceinline__ void gemm_tile(const bf16* __restrict__ A, int lda, const bf16* __restrict__ Bt, int ldb, int K,
;                                           int brow, int bcol, bf16* shm, const Epi& epi, int wv) {
;     ...
;     LDB(B0, 0, 0); SCHED; LDA(At, 0, 0); STAGE_A(SA(1, 1), 1, t + 1);
;     WAIT_L(8); BAR; MMA(0, 0, At, B0); BAR; SCHED;
;     LDB(B1, 0, 1); STAGE_B(SB(0, 0), 0, t + 2);
;     BAR; MMA(0, 1, At, B1); BAR;
;     LDA(At, 0, 1); STAGE_A(SA(0, 0), 0, t + 2);
;     BAR; MMA(1, 0, At, B0); BAR; SCHED;
;     STAGE_B(SB(0, 1), 1, t + 2);
;     WAIT_V(6); BAR; MMA(1, 1, At, B1); BAR;
.LBB0_719:
	ds_read_b128 v[164:167], v161
	ds_read_b128 v[168:171], v161 offset:1024
	ds_read_b128 v[172:175], v161 offset:2048
	ds_read_b128 v[176:179], v161 offset:3072
	v_add_u32_e32 v162, 0xc000, v147
	v_add_u32_e32 v163, 0xe000, v147
	v_lshl_add_u64 v[198:199], v[130:131], 0, s[24:25]
	s_add_i32 m0, s99, 0xc000
	ds_read_b128 v[180:183], v143
	ds_read_b128 v[184:187], v143 offset:1024
	ds_read_b128 v[188:191], v142
	ds_read_b128 v[194:197], v142 offset:1024
	ds_read_b128 v[202:205], v141
	ds_read_b128 v[208:211], v141 offset:1024
	ds_read_b128 v[212:215], v140
	ds_read_b128 v[216:219], v140 offset:1024
	global_load_lds_dwordx4 v[198:199], off
	s_add_i32 m0, s99, 0xe000
	v_lshl_add_u64 v[198:199], v[130:131], 0, s[26:27]
	global_load_lds_dwordx4 v[198:199], off
	s_waitcnt lgkmcnt(8)
	s_barrier
	s_setprio 1
	s_waitcnt lgkmcnt(0)
	v_mfma_f32_16x16x32_bf16 v[124:127], v[180:183], v[164:167], v[124:127]
	v_mfma_f32_16x16x32_bf16 v[120:123], v[180:183], v[172:175], v[120:123]
	v_mfma_f32_16x16x32_bf16 v[116:119], v[188:191], v[164:167], v[116:119]
	v_mfma_f32_16x16x32_bf16 v[112:115], v[188:191], v[172:175], v[112:115]
	v_mfma_f32_16x16x32_bf16 v[108:111], v[202:205], v[164:167], v[108:111]
	v_mfma_f32_16x16x32_bf16 v[104:107], v[202:205], v[172:175], v[104:107]
	v_mfma_f32_16x16x32_bf16 v[100:103], v[212:215], v[164:167], v[100:103]
	v_mfma_f32_16x16x32_bf16 v[96:99], v[212:215], v[172:175], v[96:99]
	v_mfma_f32_16x16x32_bf16 v[124:127], v[184:187], v[168:171], v[124:127]
	v_mfma_f32_16x16x32_bf16 v[120:123], v[184:187], v[176:179], v[120:123]
	v_mfma_f32_16x16x32_bf16 v[116:119], v[194:197], v[168:171], v[116:119]
	v_mfma_f32_16x16x32_bf16 v[112:115], v[194:197], v[176:179], v[112:115]
	v_mfma_f32_16x16x32_bf16 v[108:111], v[208:211], v[168:171], v[108:111]
	v_mfma_f32_16x16x32_bf16 v[104:107], v[208:211], v[176:179], v[104:107]
	v_mfma_f32_16x16x32_bf16 v[100:103], v[216:219], v[168:171], v[100:103]
	v_mfma_f32_16x16x32_bf16 v[96:99], v[216:219], v[176:179], v[96:99]
	s_setprio 0
	s_barrier
	v_lshl_add_u64 v[198:199], v[132:133], 0, s[30:31]
	s_add_i32 m0, s99, 0x10000
	ds_read_b128 v[220:223], v160
	ds_read_b128 v[224:227], v160 offset:1024
	ds_read_b128 v[228:231], v160 offset:2048
	ds_read_b128 v[232:235], v160 offset:3072
	global_load_lds_dwordx4 v[198:199], off
	s_add_i32 m0, s99, 0x12000
	v_lshl_add_u64 v[198:199], v[132:133], 0, s[34:35]
	global_load_lds_dwordx4 v[198:199], off
	s_barrier
	s_setprio 1
	s_waitcnt lgkmcnt(0)
	v_mfma_f32_16x16x32_bf16 v[92:95], v[180:183], v[220:223], v[92:95]
	v_mfma_f32_16x16x32_bf16 v[88:91], v[180:183], v[228:231], v[88:91]
	v_mfma_f32_16x16x32_bf16 v[84:87], v[188:191], v[220:223], v[84:87]
	v_mfma_f32_16x16x32_bf16 v[80:83], v[188:191], v[228:231], v[80:83]
	v_mfma_f32_16x16x32_bf16 v[76:79], v[202:205], v[220:223], v[76:79]
	v_mfma_f32_16x16x32_bf16 v[72:75], v[202:205], v[228:231], v[72:75]
	v_mfma_f32_16x16x32_bf16 v[68:71], v[212:215], v[220:223], v[68:71]
	v_mfma_f32_16x16x32_bf16 v[64:67], v[212:215], v[228:231], v[64:67]
	v_mfma_f32_16x16x32_bf16 v[92:95], v[184:187], v[224:227], v[92:95]
	v_mfma_f32_16x16x32_bf16 v[88:91], v[184:187], v[232:235], v[88:91]
	v_mfma_f32_16x16x32_bf16 v[84:87], v[194:197], v[224:227], v[84:87]
	v_mfma_f32_16x16x32_bf16 v[80:83], v[194:197], v[232:235], v[80:83]
	v_mfma_f32_16x16x32_bf16 v[76:79], v[208:211], v[224:227], v[76:79]
	v_mfma_f32_16x16x32_bf16 v[72:75], v[208:211], v[232:235], v[72:75]
	v_mfma_f32_16x16x32_bf16 v[68:71], v[216:219], v[224:227], v[68:71]
	v_mfma_f32_16x16x32_bf16 v[64:67], v[216:219], v[232:235], v[64:67]
	s_setprio 0
	v_lshl_add_u64 v[198:199], v[130:131], 0, s[36:37]
	s_add_i32 m0, s99, 0x0
	s_barrier
	ds_read_b128 v[180:183], v143 offset:16384
	ds_read_b128 v[184:187], v143 offset:17408
	ds_read_b128 v[188:191], v142 offset:16384
	ds_read_b128 v[194:197], v142 offset:17408
	ds_read_b128 v[202:205], v141 offset:16384
	ds_read_b128 v[208:211], v141 offset:17408
	ds_read_b128 v[212:215], v140 offset:16384
	ds_read_b128 v[216:219], v140 offset:17408
	global_load_lds_dwordx4 v[198:199], off
	s_add_i32 m0, s99, 0x2000
	v_lshl_add_u64 v[198:199], v[130:131], 0, s[38:39]
	global_load_lds_dwordx4 v[198:199], off
	s_barrier
	s_setprio 1
	s_waitcnt lgkmcnt(0)
	v_mfma_f32_16x16x32_bf16 v[60:63], v[180:183], v[164:167], v[60:63]
	v_mfma_f32_16x16x32_bf16 v[56:59], v[180:183], v[172:175], v[56:59]
	v_mfma_f32_16x16x32_bf16 v[52:55], v[188:191], v[164:167], v[52:55]
	v_mfma_f32_16x16x32_bf16 v[48:51], v[188:191], v[172:175], v[48:51]
	v_mfma_f32_16x16x32_bf16 v[44:47], v[202:205], v[164:167], v[44:47]
	v_mfma_f32_16x16x32_bf16 v[40:43], v[202:205], v[172:175], v[40:43]
	v_mfma_f32_16x16x32_bf16 v[36:39], v[212:215], v[164:167], v[36:39]
	v_mfma_f32_16x16x32_bf16 v[32:35], v[212:215], v[172:175], v[32:35]
	v_mfma_f32_16x16x32_bf16 v[60:63], v[184:187], v[168:171], v[60:63]
	v_mfma_f32_16x16x32_bf16 v[56:59], v[184:187], v[176:179], v[56:59]
	v_mfma_f32_16x16x32_bf16 v[52:55], v[194:197], v[168:171], v[52:55]
	v_mfma_f32_16x16x32_bf16 v[48:51], v[194:197], v[176:179], v[48:51]
	v_mfma_f32_16x16x32_bf16 v[44:47], v[208:211], v[168:171], v[44:47]
	v_mfma_f32_16x16x32_bf16 v[40:43], v[208:211], v[176:179], v[40:43]
	v_mfma_f32_16x16x32_bf16 v[36:39], v[216:219], v[168:171], v[36:39]
	v_mfma_f32_16x16x32_bf16 v[32:35], v[216:219], v[176:179], v[32:35]
	s_setprio 0
	s_barrier
	s_add_i32 m0, s99, 0x14000
	v_lshl_add_u64 v[164:165], v[132:133], 0, s[40:41]
	global_load_lds_dwordx4 v[164:165], off
	s_add_i32 m0, s99, 0x16000
	v_lshl_add_u64 v[164:165], v[132:133], 0, s[42:43]
	global_load_lds_dwordx4 v[164:165], off
	s_waitcnt vmcnt(6)
	s_barrier
; #define STAGE_A(P, hf, kt) do { if constexpr (ABLK) { const bf16* _gp = A + ((long)(brow >> 8) * nt + (kt)) * 16384 + (hf) * 8192; GLDS2(_gp, 4096, offA, P); } \
;     else { const bf16* _gp = A + (long)(brow + (hf) * HALF) * lda + (long)(kt) * BK; GLDS2(_gp, 64 * (long)lda, offA, P); } } while (0)
; #define STAGE_B(P, hf, kt) do { const bf16* _gp = Bt + (long)(bcol + (hf) * 2) * ldb + (long)(kt) * BK; GLDS2(_gp, 128 * (long)ldb, offB, P); } while (0)
; #define LDA(dst, b, h) for (int m = 0; m < 4; ++m) for (int k = 0; k < 2; ++k) \
;     dst[m][k] = *reinterpret_cast<const bf16x8*>((char*)SA(b, h) + lds_byte(wr * 64 + m * 16 + fr, k * 32 + fq * 8))
; #define LDB(dst, b, h) for (int n = 0; n < 2; ++n) for (int k = 0; k < 2; ++k) \
;     dst[n][k] = *reinterpret_cast<const bf16x8*>((char*)SB(b, h) + lds_byte(wc * 32 + n * 16 + fr, k * 32 + fq * 8))
; #define MMA(ai, bj, At, Bt_) do { __builtin_amdgcn_s_setprio(1); \
;     for (int m = 0; m < 4; ++m) for (int n = 0; n < 2; ++n) for (int k = 0; k < 2; ++k) \
;       acc[ai][bj][m][n] = __builtin_amdgcn_mfma_f32_16x16x32_bf16(At[m][k], Bt_[n][k], acc[ai][bj][m][n], 0, 0, 0); \
;     __builtin_amdgcn_s_setprio(0); } while (0)
; #define WAIT_V(n) asm volatile("s_waitcnt vmcnt(" #n ")" ::: "memory")
; #define WAIT_L(n) asm volatile("s_waitcnt lgkmcnt(" #n ")" ::: "memory")
; #define BAR __builtin_amdgcn_s_barrier()
; #define SCHED __builtin_amdgcn_sched_barrier(0)
; template <bool ABLK, class Epi>
; __device__ __forceinline__ void gemm_tile(const bf16* __restrict__ A, int lda, const bf16* __restrict__ Bt, int ldb, int K,
;                                           int brow, int bcol, bf16* shm, const Epi& epi, int wv) {
;     ...
;     WAIT_V(6); BAR; MMA(1, 1, At, B1); BAR;
;     LDB(B0, 1, 0); SCHED; LDA(At, 1, 0); STAGE_A(SA(0, 1), 1, t + 2);
;     WAIT_L(8); BAR; MMA(0, 0, At, B0); BAR; SCHED;
;     LDB(B1, 1, 1); STAGE_B(SB(1, 0), 0, t + 3);
;     BAR; MMA(0, 1, At, B1); BAR;
;     LDA(At, 1, 1); STAGE_A(SA(1, 0), 0, t + 3);
;     BAR; MMA(1, 0, At, B0); BAR; SCHED;
	s_setprio 1
	v_mfma_f32_16x16x32_bf16 v[28:31], v[180:183], v[220:223], v[28:31]
	v_mfma_f32_16x16x32_bf16 v[24:27], v[180:183], v[228:231], v[24:27]
	v_mfma_f32_16x16x32_bf16 v[20:23], v[188:191], v[220:223], v[20:23]
	v_mfma_f32_16x16x32_bf16 v[16:19], v[188:191], v[228:231], v[16:19]
	v_mfma_f32_16x16x32_bf16 v[12:15], v[202:205], v[220:223], v[12:15]
	v_mfma_f32_16x16x32_bf16 v[8:11], v[202:205], v[228:231], v[8:11]
	v_mfma_f32_16x16x32_bf16 v[4:7], v[212:215], v[220:223], v[4:7]
	v_mfma_f32_16x16x32_bf16 v[0:3], v[212:215], v[228:231], v[0:3]
	v_mfma_f32_16x16x32_bf16 v[28:31], v[184:187], v[224:227], v[28:31]
	v_mfma_f32_16x16x32_bf16 v[24:27], v[184:187], v[232:235], v[24:27]
	v_mfma_f32_16x16x32_bf16 v[20:23], v[194:197], v[224:227], v[20:23]
	v_mfma_f32_16x16x32_bf16 v[16:19], v[194:197], v[232:235], v[16:19]
	v_mfma_f32_16x16x32_bf16 v[12:15], v[208:211], v[224:227], v[12:15]
	v_mfma_f32_16x16x32_bf16 v[8:11], v[208:211], v[232:235], v[8:11]
	v_mfma_f32_16x16x32_bf16 v[4:7], v[216:219], v[224:227], v[4:7]
	v_mfma_f32_16x16x32_bf16 v[0:3], v[216:219], v[232:235], v[0:3]
	s_setprio 0
	s_barrier
	ds_read_b128 v[164:167], v149
	ds_read_b128 v[168:171], v149 offset:1024
	ds_read_b128 v[172:175], v149 offset:2048
	ds_read_b128 v[176:179], v149 offset:3072
	v_lshl_add_u64 v[198:199], v[130:131], 0, s[44:45]
	s_add_i32 m0, s99, 0x4000
	ds_read_b128 v[180:183], v143 offset:32768
	ds_read_b128 v[184:187], v143 offset:33792
	ds_read_b128 v[188:191], v142 offset:32768
	ds_read_b128 v[194:197], v142 offset:33792
	ds_read_b128 v[202:205], v141 offset:32768
	ds_read_b128 v[208:211], v141 offset:33792
	ds_read_b128 v[212:215], v140 offset:32768
	ds_read_b128 v[216:219], v140 offset:33792
	global_load_lds_dwordx4 v[198:199], off
	s_add_i32 m0, s99, 0x6000
	v_lshl_add_u64 v[198:199], v[130:131], 0, s[46:47]
	global_load_lds_dwordx4 v[198:199], off
	s_waitcnt lgkmcnt(8)
	s_barrier
	s_setprio 1
	s_waitcnt lgkmcnt(0)
	v_mfma_f32_16x16x32_bf16 v[124:127], v[180:183], v[164:167], v[124:127]
	v_mfma_f32_16x16x32_bf16 v[120:123], v[180:183], v[172:175], v[120:123]
	v_mfma_f32_16x16x32_bf16 v[116:119], v[188:191], v[164:167], v[116:119]
	v_mfma_f32_16x16x32_bf16 v[112:115], v[188:191], v[172:175], v[112:115]
	v_mfma_f32_16x16x32_bf16 v[108:111], v[202:205], v[164:167], v[108:111]
	v_mfma_f32_16x16x32_bf16 v[104:107], v[202:205], v[172:175], v[104:107]
	v_mfma_f32_16x16x32_bf16 v[100:103], v[212:215], v[164:167], v[100:103]
	v_mfma_f32_16x16x32_bf16 v[96:99], v[212:215], v[172:175], v[96:99]
	v_mfma_f32_16x16x32_bf16 v[124:127], v[184:187], v[168:171], v[124:127]
	v_mfma_f32_16x16x32_bf16 v[120:123], v[184:187], v[176:179], v[120:123]
	v_mfma_f32_16x16x32_bf16 v[116:119], v[194:197], v[168:171], v[116:119]
	v_mfma_f32_16x16x32_bf16 v[112:115], v[194:197], v[176:179], v[112:115]
	v_mfma_f32_16x16x32_bf16 v[108:111], v[208:211], v[168:171], v[108:111]
	v_mfma_f32_16x16x32_bf16 v[104:107], v[208:211], v[176:179], v[104:107]
	v_mfma_f32_16x16x32_bf16 v[100:103], v[216:219], v[168:171], v[100:103]
	v_mfma_f32_16x16x32_bf16 v[96:99], v[216:219], v[176:179], v[96:99]
	s_setprio 0
	s_barrier
	v_lshl_add_u64 v[198:199], v[132:133], 0, s[48:49]
	s_add_i32 m0, s99, 0x18000
	ds_read_b128 v[220:223], v146
	ds_read_b128 v[224:227], v146 offset:1024
	ds_read_b128 v[228:231], v146 offset:2048
	ds_read_b128 v[232:235], v146 offset:3072
	global_load_lds_dwordx4 v[198:199], off
	s_add_i32 m0, s99, 0x1a000
	v_lshl_add_u64 v[198:199], v[132:133], 0, s[50:51]
	global_load_lds_dwordx4 v[198:199], off
	s_barrier
	s_setprio 1
	s_waitcnt lgkmcnt(0)
	v_mfma_f32_16x16x32_bf16 v[92:95], v[180:183], v[220:223], v[92:95]
	v_mfma_f32_16x16x32_bf16 v[88:91], v[180:183], v[228:231], v[88:91]
	v_mfma_f32_16x16x32_bf16 v[84:87], v[188:191], v[220:223], v[84:87]
	v_mfma_f32_16x16x32_bf16 v[80:83], v[188:191], v[228:231], v[80:83]
	v_mfma_f32_16x16x32_bf16 v[76:79], v[202:205], v[220:223], v[76:79]
	v_mfma_f32_16x16x32_bf16 v[72:75], v[202:205], v[228:231], v[72:75]
	v_mfma_f32_16x16x32_bf16 v[68:71], v[212:215], v[220:223], v[68:71]
	v_mfma_f32_16x16x32_bf16 v[64:67], v[212:215], v[228:231], v[64:67]
	v_mfma_f32_16x16x32_bf16 v[92:95], v[184:187], v[224:227], v[92:95]
	v_mfma_f32_16x16x32_bf16 v[88:91], v[184:187], v[232:235], v[88:91]
	v_mfma_f32_16x16x32_bf16 v[84:87], v[194:197], v[224:227], v[84:87]
	v_mfma_f32_16x16x32_bf16 v[80:83], v[194:197], v[232:235], v[80:83]
	v_mfma_f32_16x16x32_bf16 v[76:79], v[208:211], v[224:227], v[76:79]
	v_mfma_f32_16x16x32_bf16 v[72:75], v[208:211], v[232:235], v[72:75]
	v_mfma_f32_16x16x32_bf16 v[68:71], v[216:219], v[224:227], v[68:71]
	v_mfma_f32_16x16x32_bf16 v[64:67], v[216:219], v[232:235], v[64:67]
	s_setprio 0
	v_lshl_add_u64 v[198:199], v[130:131], 0, s[50:51]
	s_add_i32 m0, s99, 0x8000
	s_barrier
	ds_read_b128 v[180:183], v143 offset:49152
	ds_read_b128 v[184:187], v143 offset:50176
	ds_read_b128 v[188:191], v142 offset:49152
	ds_read_b128 v[194:197], v142 offset:50176
	ds_read_b128 v[202:205], v141 offset:49152
	ds_read_b128 v[208:211], v141 offset:50176
	ds_read_b128 v[212:215], v140 offset:49152
	ds_read_b128 v[216:219], v140 offset:50176
	global_load_lds_dwordx4 v[198:199], off
	s_add_i32 m0, s99, 0xa000
	s_nop 0
	global_load_lds_dwordx4 v[130:131], off
	s_barrier
; #define STAGE_A(P, hf, kt) do { if constexpr (ABLK) { const bf16* _gp = A + ((long)(brow >> 8) * nt + (kt)) * 16384 + (hf) * 8192; GLDS2(_gp, 4096, offA, P); } \
;     else { const bf16* _gp = A + (long)(brow + (hf) * HALF) * lda + (long)(kt) * BK; GLDS2(_gp, 64 * (long)lda, offA, P); } } while (0)
; #define STAGE_B(P, hf, kt) do { const bf16* _gp = Bt + (long)(bcol + (hf) * 2) * ldb + (long)(kt) * BK; GLDS2(_gp, 128 * (long)ldb, offB, P); } while (0)
; #define LDA(dst, b, h) for (int m = 0; m < 4; ++m) for (int k = 0; k < 2; ++k) \
;     dst[m][k] = *reinterpret_cast<const bf16x8*>((char*)SA(b, h) + lds_byte(wr * 64 + m * 16 + fr, k * 32 + fq * 8))
; #define LDB(dst, b, h) for (int n = 0; n < 2; ++n) for (int k = 0; k < 2; ++k) \
;     dst[n][k] = *reinterpret_cast<const bf16x8*>((char*)SB(b, h) + lds_byte(wc * 32 + n * 16 + fr, k * 32 + fq * 8))
; #define MMA(ai, bj, At, Bt_) do { __builtin_amdgcn_s_setprio(1); \
;     for (int m = 0; m < 4; ++m) for (int n = 0; n < 2; ++n) for (int k = 0; k < 2; ++k) \
;       acc[ai][bj][m][n] = __builtin_amdgcn_mfma_f32_16x16x32_bf16(At[m][k], Bt_[n][k], acc[ai][bj][m][n], 0, 0, 0); \
;     __builtin_amdgcn_s_setprio(0); } while (0)
; #define WAIT_V(n) asm volatile("s_waitcnt vmcnt(" #n ")" ::: "memory")
; #define WAIT_L(n) asm volatile("s_waitcnt lgkmcnt(" #n ")" ::: "memory")
; #define BAR __builtin_amdgcn_s_barrier()
; #define SCHED __builtin_amdgcn_sched_barrier(0)
; template <bool ABLK, class Epi>
; __device__ __forceinline__ void gemm_tile(const bf16* __restrict__ A, int lda, const bf16* __restrict__ Bt, int ldb, int K,
;                                           int brow, int bcol, bf16* shm, const Epi& epi, int wv) {
;     ...
;     BAR; MMA(1, 0, At, B0); BAR; SCHED;
;     STAGE_B(SB(1, 1), 1, t + 3);
;     WAIT_V(6); BAR; MMA(1, 1, At, B1); BAR;
;   }
;   { LDB(B0, 0, 0); LDA(At, 0, 0); STAGE_A(SA(1, 1), 1, nt - 1);
;     BAR; WAIT_L(0); MMA(0, 0, At, B0); BAR;
;     LDB(B1, 0, 1); BAR; WAIT_L(0); MMA(0, 1, At, B1); BAR;
;     LDA(At, 0, 1); WAIT_V(4); BAR; WAIT_L(0); MMA(1, 0, At, B0); MMA(1, 1, At, B1); BAR; }
	s_setprio 1
	s_waitcnt lgkmcnt(0)
	v_mfma_f32_16x16x32_bf16 v[60:63], v[180:183], v[164:167], v[60:63]
	v_mfma_f32_16x16x32_bf16 v[56:59], v[180:183], v[172:175], v[56:59]
	v_mfma_f32_16x16x32_bf16 v[52:55], v[188:191], v[164:167], v[52:55]
	v_mfma_f32_16x16x32_bf16 v[48:51], v[188:191], v[172:175], v[48:51]
	v_mfma_f32_16x16x32_bf16 v[44:47], v[202:205], v[164:167], v[44:47]
	v_mfma_f32_16x16x32_bf16 v[40:43], v[202:205], v[172:175], v[40:43]
	v_mfma_f32_16x16x32_bf16 v[36:39], v[212:215], v[164:167], v[36:39]
	v_mfma_f32_16x16x32_bf16 v[32:35], v[212:215], v[172:175], v[32:35]
	v_mfma_f32_16x16x32_bf16 v[60:63], v[184:187], v[168:171], v[60:63]
	v_mfma_f32_16x16x32_bf16 v[56:59], v[184:187], v[176:179], v[56:59]
	v_mfma_f32_16x16x32_bf16 v[52:55], v[194:197], v[168:171], v[52:55]
	v_mfma_f32_16x16x32_bf16 v[48:51], v[194:197], v[176:179], v[48:51]
	v_mfma_f32_16x16x32_bf16 v[44:47], v[208:211], v[168:171], v[44:47]
	v_mfma_f32_16x16x32_bf16 v[40:43], v[208:211], v[176:179], v[40:43]
	v_mfma_f32_16x16x32_bf16 v[36:39], v[216:219], v[168:171], v[36:39]
	v_mfma_f32_16x16x32_bf16 v[32:35], v[216:219], v[176:179], v[32:35]
	s_setprio 0
	s_barrier
	s_add_i32 m0, s99, 0x1c000
	v_lshl_add_u64 v[164:165], v[132:133], 0, s[52:53]
	global_load_lds_dwordx4 v[164:165], off
	s_add_i32 m0, s99, 0x1e000
	s_nop 0
	global_load_lds_dwordx4 v[132:133], off
	s_waitcnt vmcnt(6)
	s_barrier
	s_setprio 1
	v_mfma_f32_16x16x32_bf16 v[28:31], v[180:183], v[220:223], v[28:31]
	v_mfma_f32_16x16x32_bf16 v[24:27], v[180:183], v[228:231], v[24:27]
	v_mfma_f32_16x16x32_bf16 v[20:23], v[188:191], v[220:223], v[20:23]
	v_mfma_f32_16x16x32_bf16 v[16:19], v[188:191], v[228:231], v[16:19]
	v_mfma_f32_16x16x32_bf16 v[12:15], v[202:205], v[220:223], v[12:15]
	v_mfma_f32_16x16x32_bf16 v[8:11], v[202:205], v[228:231], v[8:11]
	v_mfma_f32_16x16x32_bf16 v[4:7], v[212:215], v[220:223], v[4:7]
	v_mfma_f32_16x16x32_bf16 v[0:3], v[212:215], v[228:231], v[0:3]
	v_mfma_f32_16x16x32_bf16 v[28:31], v[184:187], v[224:227], v[28:31]
	v_mfma_f32_16x16x32_bf16 v[24:27], v[184:187], v[232:235], v[24:27]
	v_mfma_f32_16x16x32_bf16 v[20:23], v[194:197], v[224:227], v[20:23]
	v_mfma_f32_16x16x32_bf16 v[16:19], v[194:197], v[232:235], v[16:19]
	v_mfma_f32_16x16x32_bf16 v[12:15], v[208:211], v[224:227], v[12:15]
	v_mfma_f32_16x16x32_bf16 v[8:11], v[208:211], v[232:235], v[8:11]
	v_mfma_f32_16x16x32_bf16 v[4:7], v[216:219], v[224:227], v[4:7]
	v_mfma_f32_16x16x32_bf16 v[0:3], v[216:219], v[232:235], v[0:3]
	s_setprio 0
	s_add_i32 s33, s33, 2
	v_lshl_add_u64 v[130:131], v[130:131], 0, s[54:55]
	s_cmp_lt_u32 s33, 28
	v_lshl_add_u64 v[132:133], v[132:133], 0, s[56:57]
	s_barrier
	s_cbranch_scc1 .LBB0_719
	v_readfirstlane_b32 s2, v162
	v_lshl_add_u64 v[144:145], v[128:129], 0, s[58:59]
	s_mov_b32 m0, s2
	v_readfirstlane_b32 s2, v163
	ds_read_b128 v[130:133], v161
	ds_read_b128 v[150:153], v161 offset:1024
	ds_read_b128 v[154:157], v161 offset:2048
	ds_read_b128 v[164:167], v161 offset:3072
	ds_read_b128 v[168:171], v143
	ds_read_b128 v[172:175], v143 offset:1024
	ds_read_b128 v[176:179], v142
	ds_read_b128 v[180:183], v142 offset:1024
	ds_read_b128 v[184:187], v141
	ds_read_b128 v[188:191], v141 offset:1024
	ds_read_b128 v[194:197], v140
	ds_read_b128 v[202:205], v140 offset:1024
	global_load_lds_dwordx4 v[144:145], off
	v_lshl_add_u64 v[128:129], v[128:129], 0, s[60:61]
	s_mov_b32 m0, s2
	s_nop 0
	global_load_lds_dwordx4 v[128:129], off
	s_barrier
	s_waitcnt lgkmcnt(0)
	s_setprio 1
	s_waitcnt lgkmcnt(0)
	v_mfma_f32_16x16x32_bf16 v[124:127], v[168:171], v[130:133], v[124:127]
	v_mfma_f32_16x16x32_bf16 v[120:123], v[168:171], v[154:157], v[120:123]
	v_mfma_f32_16x16x32_bf16 v[108:111], v[184:187], v[130:133], v[108:111]
	v_mfma_f32_16x16x32_bf16 v[104:107], v[184:187], v[154:157], v[104:107]
	v_mfma_f32_16x16x32_bf16 v[124:127], v[172:175], v[150:153], v[124:127]
	v_mfma_f32_16x16x32_bf16 v[120:123], v[172:175], v[164:167], v[120:123]
	v_mfma_f32_16x16x32_bf16 v[116:119], v[176:179], v[130:133], v[116:119]
	v_mfma_f32_16x16x32_bf16 v[112:115], v[176:179], v[154:157], v[112:115]
	v_mfma_f32_16x16x32_bf16 v[108:111], v[188:191], v[150:153], v[108:111]
	v_mfma_f32_16x16x32_bf16 v[104:107], v[188:191], v[164:167], v[104:107]
	v_mfma_f32_16x16x32_bf16 v[100:103], v[194:197], v[130:133], v[100:103]
	v_mfma_f32_16x16x32_bf16 v[96:99], v[194:197], v[154:157], v[96:99]
	v_mfma_f32_16x16x32_bf16 v[208:211], v[180:183], v[150:153], v[116:119]
	v_mfma_f32_16x16x32_bf16 v[212:215], v[180:183], v[164:167], v[112:115]
	v_mfma_f32_16x16x32_bf16 v[216:219], v[202:205], v[150:153], v[100:103]
	v_mfma_f32_16x16x32_bf16 v[220:223], v[202:205], v[164:167], v[96:99]
	s_setprio 0
	s_barrier
	s_nop 1
	ds_read_b128 v[96:99], v160
	ds_read_b128 v[100:103], v160 offset:1024
	ds_read_b128 v[112:115], v160 offset:2048
	ds_read_b128 v[116:119], v160 offset:3072
	s_barrier
	s_waitcnt lgkmcnt(0)
	s_setprio 1
	s_waitcnt lgkmcnt(0)
	v_mfma_f32_16x16x32_bf16 v[92:95], v[168:171], v[96:99], v[92:95]
	v_mfma_f32_16x16x32_bf16 v[88:91], v[168:171], v[112:115], v[88:91]
	v_mfma_f32_16x16x32_bf16 v[76:79], v[184:187], v[96:99], v[76:79]
	v_mfma_f32_16x16x32_bf16 v[72:75], v[184:187], v[112:115], v[72:75]
	v_mfma_f32_16x16x32_bf16 v[68:71], v[194:197], v[96:99], v[68:71]
	v_mfma_f32_16x16x32_bf16 v[64:67], v[194:197], v[112:115], v[64:67]
	v_mfma_f32_16x16x32_bf16 v[92:95], v[172:175], v[100:103], v[92:95]
	v_mfma_f32_16x16x32_bf16 v[88:91], v[172:175], v[116:119], v[88:91]
	v_mfma_f32_16x16x32_bf16 v[84:87], v[176:179], v[96:99], v[84:87]
	v_mfma_f32_16x16x32_bf16 v[80:83], v[176:179], v[112:115], v[80:83]
	v_mfma_f32_16x16x32_bf16 v[76:79], v[188:191], v[100:103], v[76:79]
	v_mfma_f32_16x16x32_bf16 v[72:75], v[188:191], v[116:119], v[72:75]
	v_mfma_f32_16x16x32_bf16 v[68:71], v[202:205], v[100:103], v[68:71]
	v_mfma_f32_16x16x32_bf16 v[64:67], v[202:205], v[116:119], v[64:67]
	v_mfma_f32_16x16x32_bf16 v[158:161], v[180:183], v[100:103], v[84:87]
	v_mfma_f32_16x16x32_bf16 v[168:171], v[180:183], v[116:119], v[80:83]
	s_setprio 0
	s_barrier
; #define LDA(dst, b, h) for (int m = 0; m < 4; ++m) for (int k = 0; k < 2; ++k) \
;     dst[m][k] = *reinterpret_cast<const bf16x8*>((char*)SA(b, h) + lds_byte(wr * 64 + m * 16 + fr, k * 32 + fq * 8))
; #define LDB(dst, b, h) for (int n = 0; n < 2; ++n) for (int k = 0; k < 2; ++k) \
;     dst[n][k] = *reinterpret_cast<const bf16x8*>((char*)SB(b, h) + lds_byte(wc * 32 + n * 16 + fr, k * 32 + fq * 8))
; #define MMA(ai, bj, At, Bt_) do { __builtin_amdgcn_s_setprio(1); \
;     for (int m = 0; m < 4; ++m) for (int n = 0; n < 2; ++n) for (int k = 0; k < 2; ++k) \
;       acc[ai][bj][m][n] = __builtin_amdgcn_mfma_f32_16x16x32_bf16(At[m][k], Bt_[n][k], acc[ai][bj][m][n], 0, 0, 0); \
;     __builtin_amdgcn_s_setprio(0); } while (0)
; #define WAIT_V(n) asm volatile("s_waitcnt vmcnt(" #n ")" ::: "memory")
; #define WAIT_L(n) asm volatile("s_waitcnt lgkmcnt(" #n ")" ::: "memory")
; #define BAR __builtin_amdgcn_s_barrier()
; template <bool ABLK, class Epi>
; __device__ __forceinline__ void gemm_tile(const bf16* __restrict__ A, int lda, const bf16* __restrict__ Bt, int ldb, int K,
;                                           int brow, int bcol, bf16* shm, const Epi& epi, int wv) {
;     ...
;     LDB(B1, 0, 1); BAR; WAIT_L(0); MMA(0, 1, At, B1); BAR;
;     LDA(At, 0, 1); WAIT_V(4); BAR; WAIT_L(0); MMA(1, 0, At, B0); MMA(1, 1, At, B1); BAR; }
;   { LDB(B0, 1, 0); LDA(At, 1, 0); WAIT_V(2); BAR; WAIT_L(0); MMA(0, 0, At, B0); BAR;
	s_nop 0
	ds_read_b128 v[80:83], v143 offset:16384
	ds_read_b128 v[84:87], v143 offset:17408
	ds_read_b128 v[172:175], v142 offset:16384
	ds_read_b128 v[176:179], v142 offset:17408
	ds_read_b128 v[180:183], v141 offset:16384
	ds_read_b128 v[184:187], v141 offset:17408
	ds_read_b128 v[188:191], v140 offset:16384
	ds_read_b128 v[194:197], v140 offset:17408
	s_waitcnt vmcnt(4)
	s_barrier
	s_waitcnt lgkmcnt(0)
	s_setprio 1
	s_waitcnt lgkmcnt(0)
	v_mfma_f32_16x16x32_bf16 v[44:47], v[180:183], v[130:133], v[44:47]
	v_mfma_f32_16x16x32_bf16 v[40:43], v[180:183], v[154:157], v[40:43]
	v_mfma_f32_16x16x32_bf16 v[60:63], v[80:83], v[130:133], v[60:63]
	v_mfma_f32_16x16x32_bf16 v[56:59], v[80:83], v[154:157], v[56:59]
	v_mfma_f32_16x16x32_bf16 v[52:55], v[172:175], v[130:133], v[52:55]
	v_mfma_f32_16x16x32_bf16 v[48:51], v[172:175], v[154:157], v[48:51]
	v_mfma_f32_16x16x32_bf16 v[44:47], v[184:187], v[150:153], v[44:47]
	v_mfma_f32_16x16x32_bf16 v[40:43], v[184:187], v[164:167], v[40:43]
	v_mfma_f32_16x16x32_bf16 v[36:39], v[188:191], v[130:133], v[36:39]
	v_mfma_f32_16x16x32_bf16 v[32:35], v[188:191], v[154:157], v[32:35]
	v_mfma_f32_16x16x32_bf16 v[202:205], v[84:87], v[150:153], v[60:63]
	v_mfma_f32_16x16x32_bf16 v[224:227], v[84:87], v[164:167], v[56:59]
	v_mfma_f32_16x16x32_bf16 v[228:231], v[176:179], v[150:153], v[52:55]
	v_mfma_f32_16x16x32_bf16 v[232:235], v[176:179], v[164:167], v[48:51]
	v_mfma_f32_16x16x32_bf16 v[128:131], v[194:197], v[150:153], v[36:39]
	v_mfma_f32_16x16x32_bf16 v[150:153], v[194:197], v[164:167], v[32:35]
	s_setprio 0
	s_setprio 1
	v_mfma_f32_16x16x32_bf16 v[28:31], v[80:83], v[96:99], v[28:31]
	v_mfma_f32_16x16x32_bf16 v[24:27], v[80:83], v[112:115], v[24:27]
	v_mfma_f32_16x16x32_bf16 v[12:15], v[180:183], v[96:99], v[12:15]
	v_mfma_f32_16x16x32_bf16 v[8:11], v[180:183], v[112:115], v[8:11]
	v_mfma_f32_16x16x32_bf16 v[28:31], v[84:87], v[100:103], v[28:31]
	v_mfma_f32_16x16x32_bf16 v[24:27], v[84:87], v[116:119], v[24:27]
	v_mfma_f32_16x16x32_bf16 v[20:23], v[172:175], v[96:99], v[20:23]
	v_mfma_f32_16x16x32_bf16 v[16:19], v[172:175], v[112:115], v[16:19]
	v_mfma_f32_16x16x32_bf16 v[12:15], v[184:187], v[100:103], v[12:15]
	v_mfma_f32_16x16x32_bf16 v[8:11], v[184:187], v[116:119], v[8:11]
	v_mfma_f32_16x16x32_bf16 v[4:7], v[188:191], v[96:99], v[4:7]
	v_mfma_f32_16x16x32_bf16 v[0:3], v[188:191], v[112:115], v[0:3]
	v_mfma_f32_16x16x32_bf16 v[154:157], v[176:179], v[100:103], v[20:23]
	v_mfma_f32_16x16x32_bf16 v[162:165], v[176:179], v[116:119], v[16:19]
	v_mfma_f32_16x16x32_bf16 v[172:175], v[194:197], v[100:103], v[4:7]
	v_mfma_f32_16x16x32_bf16 v[176:179], v[194:197], v[116:119], v[0:3]
	s_setprio 0
	s_barrier
	s_nop 1
	ds_read_b128 v[0:3], v149
	ds_read_b128 v[4:7], v149 offset:1024
	ds_read_b128 v[180:183], v149 offset:2048
	ds_read_b128 v[184:187], v149 offset:3072
	ds_read_b128 v[16:19], v143 offset:32768
	ds_read_b128 v[20:23], v143 offset:33792
	ds_read_b128 v[32:35], v142 offset:32768
	ds_read_b128 v[36:39], v142 offset:33792
	ds_read_b128 v[48:51], v141 offset:32768
	ds_read_b128 v[52:55], v141 offset:33792
	ds_read_b128 v[188:191], v140 offset:32768
	ds_read_b128 v[194:197], v140 offset:33792
	s_waitcnt vmcnt(2)
	s_barrier
	s_waitcnt lgkmcnt(0)
	s_setprio 1
	s_waitcnt lgkmcnt(0)
	v_mfma_f32_16x16x32_bf16 v[56:59], v[16:19], v[0:3], v[124:127]
	v_mfma_f32_16x16x32_bf16 v[112:115], v[20:23], v[4:7], v[56:59]
	v_mfma_f32_16x16x32_bf16 v[56:59], v[16:19], v[180:183], v[120:123]
	v_mfma_f32_16x16x32_bf16 v[116:119], v[20:23], v[184:187], v[56:59]
	v_mfma_f32_16x16x32_bf16 v[56:59], v[32:35], v[0:3], v[208:211]
	v_mfma_f32_16x16x32_bf16 v[96:99], v[36:39], v[4:7], v[56:59]
	v_mfma_f32_16x16x32_bf16 v[56:59], v[32:35], v[180:183], v[212:215]
	v_mfma_f32_16x16x32_bf16 v[100:103], v[36:39], v[184:187], v[56:59]
	v_mfma_f32_16x16x32_bf16 v[56:59], v[48:51], v[0:3], v[108:111]
	v_mfma_f32_16x16x32_bf16 v[80:83], v[52:55], v[4:7], v[56:59]
	v_mfma_f32_16x16x32_bf16 v[56:59], v[48:51], v[180:183], v[104:107]
	v_mfma_f32_16x16x32_bf16 v[84:87], v[52:55], v[184:187], v[56:59]
	v_mfma_f32_16x16x32_bf16 v[56:59], v[188:191], v[0:3], v[216:219]
	v_mfma_f32_16x16x32_bf16 v[60:63], v[188:191], v[180:183], v[220:223]
	v_mfma_f32_16x16x32_bf16 v[56:59], v[194:197], v[4:7], v[56:59]
	v_mfma_f32_16x16x32_bf16 v[60:63], v[194:197], v[184:187], v[60:63]
	s_setprio 0
	s_barrier
; #define LDA(dst, b, h) for (int m = 0; m < 4; ++m) for (int k = 0; k < 2; ++k) \
;     dst[m][k] = *reinterpret_cast<const bf16x8*>((char*)SA(b, h) + lds_byte(wr * 64 + m * 16 + fr, k * 32 + fq * 8))
; #define LDB(dst, b, h) for (int n = 0; n < 2; ++n) for (int k = 0; k < 2; ++k) \
;     dst[n][k] = *reinterpret_cast<const bf16x8*>((char*)SB(b, h) + lds_byte(wc * 32 + n * 16 + fr, k * 32 + fq * 8))
; #define MMA(ai, bj, At, Bt_) do { __builtin_amdgcn_s_setprio(1); \
;     for (int m = 0; m < 4; ++m) for (int n = 0; n < 2; ++n) for (int k = 0; k < 2; ++k) \
;       acc[ai][bj][m][n] = __builtin_amdgcn_mfma_f32_16x16x32_bf16(At[m][k], Bt_[n][k], acc[ai][bj][m][n], 0, 0, 0); \
;     __builtin_amdgcn_s_setprio(0); } while (0)
; #define WAIT_V(n) asm volatile("s_waitcnt vmcnt(" #n ")" ::: "memory")
; #define WAIT_L(n) asm volatile("s_waitcnt lgkmcnt(" #n ")" ::: "memory")
; #define BAR __builtin_amdgcn_s_barrier()
; template <bool ABLK, class Epi>
; __device__ __forceinline__ void gemm_tile(const bf16* __restrict__ A, int lda, const bf16* __restrict__ Bt, int ldb, int K,
;                                           int brow, int bcol, bf16* shm, const Epi& epi, int wv) {
;     ...
;     LDB(B1, 1, 1); WAIT_V(0); BAR; WAIT_L(0); MMA(0, 1, At, B1); BAR;
;     LDA(At, 1, 1); BAR; WAIT_L(0); MMA(1, 0, At, B0); MMA(1, 1, At, B1); BAR; }
;   if (wr == 0) BAR;
	ds_read_b128 v[208:211], v146
	ds_read_b128 v[212:215], v146 offset:1024
	ds_read_b128 v[216:219], v146 offset:2048
	ds_read_b128 v[144:147], v146 offset:3072
	s_waitcnt vmcnt(0)
	s_barrier
	s_waitcnt lgkmcnt(0)
	s_setprio 1
	s_waitcnt lgkmcnt(0)
	v_mfma_f32_16x16x32_bf16 v[92:95], v[16:19], v[208:211], v[92:95]
	v_mfma_f32_16x16x32_bf16 v[16:19], v[16:19], v[216:219], v[88:91]
	v_mfma_f32_16x16x32_bf16 v[124:127], v[20:23], v[144:147], v[16:19]
	v_mfma_f32_16x16x32_bf16 v[16:19], v[32:35], v[208:211], v[158:161]
	v_mfma_f32_16x16x32_bf16 v[104:107], v[36:39], v[212:215], v[16:19]
	v_mfma_f32_16x16x32_bf16 v[16:19], v[32:35], v[216:219], v[168:171]
	v_mfma_f32_16x16x32_bf16 v[108:111], v[36:39], v[144:147], v[16:19]
	v_mfma_f32_16x16x32_bf16 v[16:19], v[48:51], v[208:211], v[76:79]
	v_mfma_f32_16x16x32_bf16 v[88:91], v[52:55], v[212:215], v[16:19]
	v_mfma_f32_16x16x32_bf16 v[16:19], v[48:51], v[216:219], v[72:75]
	v_mfma_f32_16x16x32_bf16 v[120:123], v[20:23], v[212:215], v[92:95]
	v_mfma_f32_16x16x32_bf16 v[92:95], v[52:55], v[144:147], v[16:19]
	v_mfma_f32_16x16x32_bf16 v[16:19], v[188:191], v[208:211], v[68:71]
	v_mfma_f32_16x16x32_bf16 v[72:75], v[194:197], v[212:215], v[16:19]
	v_mfma_f32_16x16x32_bf16 v[16:19], v[188:191], v[216:219], v[64:67]
	v_mfma_f32_16x16x32_bf16 v[76:79], v[194:197], v[144:147], v[16:19]
	s_setprio 0
	s_barrier
	ds_read_b128 v[68:71], v143 offset:49152
	ds_read_b128 v[158:161], v143 offset:50176
	ds_read_b128 v[166:169], v142 offset:49152
	ds_read_b128 v[188:191], v142 offset:50176
	ds_read_b128 v[194:197], v141 offset:49152
	ds_read_b128 v[220:223], v141 offset:50176
	ds_read_b128 v[236:239], v140 offset:49152
	ds_read_b128 v[140:143], v140 offset:50176
	s_barrier
	s_waitcnt lgkmcnt(0)
	s_setprio 1
	s_waitcnt lgkmcnt(0)
	v_mfma_f32_16x16x32_bf16 v[16:19], v[68:71], v[0:3], v[202:205]
	v_mfma_f32_16x16x32_bf16 v[48:51], v[158:161], v[4:7], v[16:19]
	v_mfma_f32_16x16x32_bf16 v[16:19], v[68:71], v[180:183], v[224:227]
	v_mfma_f32_16x16x32_bf16 v[52:55], v[158:161], v[184:187], v[16:19]
	v_mfma_f32_16x16x32_bf16 v[16:19], v[166:169], v[0:3], v[228:231]
	v_mfma_f32_16x16x32_bf16 v[32:35], v[188:191], v[4:7], v[16:19]
	v_mfma_f32_16x16x32_bf16 v[16:19], v[166:169], v[180:183], v[232:235]
	v_mfma_f32_16x16x32_bf16 v[36:39], v[188:191], v[184:187], v[16:19]
	v_mfma_f32_16x16x32_bf16 v[16:19], v[194:197], v[0:3], v[44:47]
	v_mfma_f32_16x16x32_bf16 v[0:3], v[236:239], v[0:3], v[128:131]
	v_mfma_f32_16x16x32_bf16 v[16:19], v[220:223], v[4:7], v[16:19]
	v_mfma_f32_16x16x32_bf16 v[20:23], v[194:197], v[180:183], v[40:43]
	v_mfma_f32_16x16x32_bf16 v[0:3], v[140:143], v[4:7], v[0:3]
	v_mfma_f32_16x16x32_bf16 v[4:7], v[236:239], v[180:183], v[150:153]
	v_mfma_f32_16x16x32_bf16 v[20:23], v[220:223], v[184:187], v[20:23]
	v_mfma_f32_16x16x32_bf16 v[4:7], v[140:143], v[184:187], v[4:7]
	s_setprio 0
	s_setprio 1
	v_mfma_f32_16x16x32_bf16 v[24:27], v[68:71], v[216:219], v[24:27]
	v_mfma_f32_16x16x32_bf16 v[28:31], v[68:71], v[208:211], v[28:31]
	v_mfma_f32_16x16x32_bf16 v[68:71], v[158:161], v[144:147], v[24:27]
	v_mfma_f32_16x16x32_bf16 v[24:27], v[166:169], v[208:211], v[154:157]
	v_mfma_f32_16x16x32_bf16 v[8:11], v[194:197], v[216:219], v[8:11]
	v_mfma_f32_16x16x32_bf16 v[64:67], v[158:161], v[212:215], v[28:31]
	v_mfma_f32_16x16x32_bf16 v[40:43], v[188:191], v[212:215], v[24:27]
	v_mfma_f32_16x16x32_bf16 v[24:27], v[166:169], v[216:219], v[162:165]
	v_mfma_f32_16x16x32_bf16 v[12:15], v[194:197], v[208:211], v[12:15]
	v_mfma_f32_16x16x32_bf16 v[28:31], v[220:223], v[144:147], v[8:11]
	v_mfma_f32_16x16x32_bf16 v[8:11], v[236:239], v[208:211], v[172:175]
	v_mfma_f32_16x16x32_bf16 v[44:47], v[188:191], v[144:147], v[24:27]
	v_mfma_f32_16x16x32_bf16 v[24:27], v[220:223], v[212:215], v[12:15]
	v_mfma_f32_16x16x32_bf16 v[12:15], v[140:143], v[212:215], v[8:11]
	v_mfma_f32_16x16x32_bf16 v[8:11], v[236:239], v[216:219], v[176:179]
	v_mfma_f32_16x16x32_bf16 v[8:11], v[140:143], v[144:147], v[8:11]
	s_setprio 0
	v_cmp_gt_u32_e32 vcc, s83, v135
	s_barrier
	s_and_saveexec_b64 s[66:67], vcc
	s_cbranch_execz .LBB0_715
	s_barrier
	s_branch .LBB0_715

; __device__ __forceinline__ int mytid(int wv) { return (wv << 6) | (int)__builtin_amdgcn_mbcnt_hi(~0u, __builtin_amdgcn_mbcnt_lo(~0u, 0u)); }
; template <bool ABLK, class Epi>
; __device__ __forceinline__ void gemm_tile(const bf16* __restrict__ A, int lda, const bf16* __restrict__ Bt, int ldb, int K,
;                                           int brow, int bcol, bf16* shm, const Epi& epi, int wv) {
;     ...
;   int tid = mytid(wv); asm volatile("" : "+v"(tid));
;   const int wid = tid >> 6, lane = tid & 63, wr = wid >> 2, wc = wid & 3, fr = lane & 15, fq = lane >> 4;
;   f32x4 acc[2][2][4][2] = {};
;   bf16x8 At[4][2], B0[2][2], B1[2][2];
;   const int nt = K / BK;
;   int offA, offB;
;   { int r_, c_; stage_rc(tid * 16, r_, c_); offA = ABLK ? r_ * 64 + c_ : r_ * lda + c_;
;     offB = ((r_ >> 5) * 64 + (r_ & 15) * 4 + ((r_ >> 4) & 1)) * ldb + c_; }
; template <bool ABLK, class Epi>
; __device__ __forceinline__ void gemm_phase(const bf16* A, int lda, const bf16* Bt, int ldb, int M, int N, int K, char* smem, const Epi& epi, int wv) {
;     ...
;   for (int w = blockIdx.x; w < nwg; w += gridDim.x) {
;     int wgid = w;
;     { int q = nwg / NXCD, r = nwg % NXCD, xcd = wgid % NXCD, off = wgid / NXCD;
;       wgid = (xcd < r ? xcd * (q + 1) : r * (q + 1) + (xcd - r) * q) + off; }
;     const int nig = WGM * nN, gid = wgid / nig, fm = gid * WGM, gsz = min(nM - fm, WGM);
;     const int pm = fm + ((wgid % nig) % gsz), pn = (wgid % nig) / gsz;
;     gemm_tile<ABLK>(A, lda, Bt, ldb, K, pm * BM, pn * BM, (bf16*)smem, epi, wv);
.LBB0_808:
	v_readlane_b32 s0, v255, 13
	v_readlane_b32 s1, v255, 14
	s_mov_b64 s[8:9], s[90:91]
	s_mov_b64 s[14:15], s[90:91]
	v_cndmask_b32_e64 v0, 0, 1, s[0:1]
	s_mov_b64 s[16:17], s[90:91]
	s_mov_b64 s[18:19], s[90:91]
	v_cmp_ne_u32_e64 s[6:7], 1, v0
	s_andn2_b64 vcc, exec, s[0:1]
	s_waitcnt vmcnt(0)
	s_barrier
	s_cbranch_vccnz .LBB0_850
	s_load_dwordx2 s[10:11], s[8:9], 0xa8
	s_load_dwordx2 s[12:13], s[14:15], 0xa8
	s_load_dwordx2 s[20:21], s[16:17], 0xa8
	s_load_dwordx2 s[22:23], s[18:19], 0xa8
	s_mov_b64 s[18:19], 0x20000
	s_waitcnt lgkmcnt(0)
	s_add_u32 s0, s10, 0x22e40000
	s_addc_u32 s1, s11, 0
	s_add_u32 s3, s12, 0x2640000
	s_addc_u32 s74, s13, 0
	s_add_u32 s14, s20, 0x17a40000
	s_addc_u32 s15, s21, 0
	s_add_u32 s16, s22, 0x25e40000
	s_addc_u32 s17, s23, 0
	s_add_i32 s75, 0, 0x10000
	s_mov_b64 s[20:21], 0x10000
	s_add_i32 s76, 0, 0x14000
	s_mov_b64 s[22:23], 0x80
	s_add_i32 s77, 0, 0x18000
	s_mov_b64 s[24:25], 0x20080
	s_add_i32 s78, 0, 0x1c000
	s_mov_b64 s[26:27], 0x22e70080
	s_mov_b64 s[30:31], 0x2640100
	s_mov_b64 s[34:35], 0x2660100
	s_mov_b64 s[36:37], 0x22e40100
	s_mov_b64 s[38:39], 0x22e50100
	s_mov_b64 s[40:41], 0x2640900
	s_mov_b64 s[42:43], 0x2660900
	s_mov_b64 s[44:45], 0x22e60100
	s_mov_b64 s[46:47], 0x22e70100
	s_mov_b64 s[48:49], 0x2640180
	s_mov_b64 s[50:51], 0x2660180
	s_mov_b64 s[52:53], 0x22e40180
	s_mov_b64 s[54:55], 0x22e50180
	s_mov_b64 s[56:57], 0x2640980
	s_mov_b64 s[58:59], 0x2660980
	s_mov_b64 s[60:61], 0x380
	s_mov_b64 s[62:63], 0x10380
	s_movk_i32 s79, 0x100
	v_mov_b32_e32 v129, 0
	s_movk_i32 s80, 0xff
	s_movk_i32 s81, 0xc00
	v_mov_b32_e32 v138, 1
	s_mov_b32 s82, s89
	v_lshlrev_b32_e32 v254, 4, v192
	s_nop 0
	v_readfirstlane_b32 s99, v254
	s_branch .LBB0_811

; #define STAGE_A(P, hf, kt) do { if constexpr (ABLK) { const bf16* _gp = A + ((long)(brow >> 8) * nt + (kt)) * 16384 + (hf) * 8192; GLDS2(_gp, 4096, offA, P); } \
;     else { const bf16* _gp = A + (long)(brow + (hf) * HALF) * lda + (long)(kt) * BK; GLDS2(_gp, 64 * (long)lda, offA, P); } } while (0)
; #define STAGE_B(P, hf, kt) do { const bf16* _gp = Bt + (long)(bcol + (hf) * 2) * ldb + (long)(kt) * BK; GLDS2(_gp, 128 * (long)ldb, offB, P); } while (0)
; #define LDA(dst, b, h) for (int m = 0; m < 4; ++m) for (int k = 0; k < 2; ++k) \
;     dst[m][k] = *reinterpret_cast<const bf16x8*>((char*)SA(b, h) + lds_byte(wr * 64 + m * 16 + fr, k * 32 + fq * 8))
; #define LDB(dst, b, h) for (int n = 0; n < 2; ++n) for (int k = 0; k < 2; ++k) \
;     dst[n][k] = *reinterpret_cast<const bf16x8*>((char*)SB(b, h) + lds_byte(wc * 32 + n * 16 + fr, k * 32 + fq * 8))
; #define MMA(ai, bj, At, Bt_) do { __builtin_amdgcn_s_setprio(1); \
;     for (int m = 0; m < 4; ++m) for (int n = 0; n < 2; ++n) for (int k = 0; k < 2; ++k) \
;       acc[ai][bj][m][n] = __builtin_amdgcn_mfma_f32_16x16x32_bf16(At[m][k], Bt_[n][k], acc[ai][bj][m][n], 0, 0, 0); \
;     __builtin_amdgcn_s_setprio(0); } while (0)
; #define WAIT_V(n) asm volatile("s_waitcnt vmcnt(" #n ")" ::: "memory")
; #define WAIT_L(n) asm volatile("s_waitcnt lgkmcnt(" #n ")" ::: "memory")
; #define BAR __builtin_amdgcn_s_barrier()
; #define SCHED __builtin_amdgcn_sched_barrier(0)
; template <bool ABLK, class Epi>
; __device__ __forceinline__ void gemm_tile(const bf16* __restrict__ A, int lda, const bf16* __restrict__ Bt, int ldb, int K,
;                                           int brow, int bcol, bf16* shm, const Epi& epi, int wv) {
;     ...
;     LDB(B0, 0, 0); SCHED; LDA(At, 0, 0); STAGE_A(SA(1, 1), 1, t + 1);
;     WAIT_L(8); BAR; MMA(0, 0, At, B0); BAR; SCHED;
;     LDB(B1, 0, 1); STAGE_B(SB(0, 0), 0, t + 2);
;     BAR; MMA(0, 1, At, B1); BAR;
;     LDA(At, 0, 1); STAGE_A(SA(0, 0), 0, t + 2);
;     BAR; MMA(1, 0, At, B0); BAR; SCHED;
;     STAGE_B(SB(0, 1), 1, t + 2);
;     WAIT_V(6); BAR; MMA(1, 1, At, B1); BAR;
.LBB0_814:
	ds_read_b128 v[168:171], v165
	ds_read_b128 v[172:175], v165 offset:1024
	ds_read_b128 v[176:179], v165 offset:2048
	ds_read_b128 v[180:183], v165 offset:3072
	v_add_u32_e32 v166, 0xc000, v150
	v_lshl_add_u64 v[198:199], v[136:137], 0, s[66:67]
	s_mov_b64 s[68:69], 0x22e60080
	v_add_u32_e32 v167, 0xe000, v150
	v_lshl_add_u64 v[224:225], v[198:199], 0, s[68:69]
	s_add_i32 m0, s99, 0xc000
	ds_read_b128 v[184:187], v147
	ds_read_b128 v[188:191], v147 offset:1024
	ds_read_b128 v[194:197], v146
	ds_read_b128 v[202:205], v146 offset:1024
	ds_read_b128 v[208:211], v145
	ds_read_b128 v[212:215], v145 offset:1024
	ds_read_b128 v[216:219], v144
	ds_read_b128 v[220:223], v144 offset:1024
	global_load_lds_dwordx4 v[224:225], off
	s_add_i32 m0, s99, 0xe000
	v_lshl_add_u64 v[224:225], v[198:199], 0, s[26:27]
	global_load_lds_dwordx4 v[224:225], off
	s_waitcnt lgkmcnt(8)
	s_barrier
	s_setprio 1
	s_waitcnt lgkmcnt(0)
	v_mfma_f32_16x16x32_bf16 v[124:127], v[184:187], v[168:171], v[124:127]
	v_mfma_f32_16x16x32_bf16 v[120:123], v[184:187], v[176:179], v[120:123]
	v_mfma_f32_16x16x32_bf16 v[116:119], v[194:197], v[168:171], v[116:119]
	v_mfma_f32_16x16x32_bf16 v[112:115], v[194:197], v[176:179], v[112:115]
	v_mfma_f32_16x16x32_bf16 v[108:111], v[208:211], v[168:171], v[108:111]
	v_mfma_f32_16x16x32_bf16 v[104:107], v[208:211], v[176:179], v[104:107]
	v_mfma_f32_16x16x32_bf16 v[100:103], v[216:219], v[168:171], v[100:103]
	v_mfma_f32_16x16x32_bf16 v[96:99], v[216:219], v[176:179], v[96:99]
	v_mfma_f32_16x16x32_bf16 v[124:127], v[188:191], v[172:175], v[124:127]
	v_mfma_f32_16x16x32_bf16 v[120:123], v[188:191], v[180:183], v[120:123]
	v_mfma_f32_16x16x32_bf16 v[116:119], v[202:205], v[172:175], v[116:119]
	v_mfma_f32_16x16x32_bf16 v[112:115], v[202:205], v[180:183], v[112:115]
	v_mfma_f32_16x16x32_bf16 v[108:111], v[212:215], v[172:175], v[108:111]
	v_mfma_f32_16x16x32_bf16 v[104:107], v[212:215], v[180:183], v[104:107]
	v_mfma_f32_16x16x32_bf16 v[100:103], v[220:223], v[172:175], v[100:103]
	v_mfma_f32_16x16x32_bf16 v[96:99], v[220:223], v[180:183], v[96:99]
	s_setprio 0
	s_barrier
	v_lshl_add_u64 v[240:241], v[134:135], 0, s[66:67]
	v_lshl_add_u64 v[242:243], v[240:241], 0, s[30:31]
	s_add_i32 m0, s99, 0x10000
	ds_read_b128 v[224:227], v164
	ds_read_b128 v[228:231], v164 offset:1024
	ds_read_b128 v[232:235], v164 offset:2048
	ds_read_b128 v[236:239], v164 offset:3072
	global_load_lds_dwordx4 v[242:243], off
	s_add_i32 m0, s99, 0x12000
	v_lshl_add_u64 v[242:243], v[240:241], 0, s[34:35]
	global_load_lds_dwordx4 v[242:243], off
	s_barrier
	s_setprio 1
	s_waitcnt lgkmcnt(0)
	v_mfma_f32_16x16x32_bf16 v[92:95], v[184:187], v[224:227], v[92:95]
	v_mfma_f32_16x16x32_bf16 v[88:91], v[184:187], v[232:235], v[88:91]
	v_mfma_f32_16x16x32_bf16 v[84:87], v[194:197], v[224:227], v[84:87]
	v_mfma_f32_16x16x32_bf16 v[80:83], v[194:197], v[232:235], v[80:83]
	v_mfma_f32_16x16x32_bf16 v[76:79], v[208:211], v[224:227], v[76:79]
	v_mfma_f32_16x16x32_bf16 v[72:75], v[208:211], v[232:235], v[72:75]
	v_mfma_f32_16x16x32_bf16 v[68:71], v[216:219], v[224:227], v[68:71]
	v_mfma_f32_16x16x32_bf16 v[64:67], v[216:219], v[232:235], v[64:67]
	v_mfma_f32_16x16x32_bf16 v[92:95], v[188:191], v[228:231], v[92:95]
	v_mfma_f32_16x16x32_bf16 v[88:91], v[188:191], v[236:239], v[88:91]
	v_mfma_f32_16x16x32_bf16 v[84:87], v[202:205], v[228:231], v[84:87]
	v_mfma_f32_16x16x32_bf16 v[80:83], v[202:205], v[236:239], v[80:83]
	v_mfma_f32_16x16x32_bf16 v[76:79], v[212:215], v[228:231], v[76:79]
	v_mfma_f32_16x16x32_bf16 v[72:75], v[212:215], v[236:239], v[72:75]
	v_mfma_f32_16x16x32_bf16 v[68:71], v[220:223], v[228:231], v[68:71]
	v_mfma_f32_16x16x32_bf16 v[64:67], v[220:223], v[236:239], v[64:67]
	s_setprio 0
	v_lshl_add_u64 v[242:243], v[198:199], 0, s[36:37]
	s_add_i32 m0, s99, 0x0
	s_barrier
	ds_read_b128 v[184:187], v147 offset:16384
	ds_read_b128 v[188:191], v147 offset:17408
	ds_read_b128 v[194:197], v146 offset:16384
	ds_read_b128 v[202:205], v146 offset:17408
	ds_read_b128 v[208:211], v145 offset:16384
	ds_read_b128 v[212:215], v145 offset:17408
	ds_read_b128 v[216:219], v144 offset:16384
	ds_read_b128 v[220:223], v144 offset:17408
	global_load_lds_dwordx4 v[242:243], off
	s_add_i32 m0, s99, 0x2000
	v_lshl_add_u64 v[242:243], v[198:199], 0, s[38:39]
	global_load_lds_dwordx4 v[242:243], off
	s_barrier
	s_setprio 1
	s_waitcnt lgkmcnt(0)
	v_mfma_f32_16x16x32_bf16 v[60:63], v[184:187], v[168:171], v[60:63]
	v_mfma_f32_16x16x32_bf16 v[56:59], v[184:187], v[176:179], v[56:59]
	v_mfma_f32_16x16x32_bf16 v[52:55], v[194:197], v[168:171], v[52:55]
	v_mfma_f32_16x16x32_bf16 v[48:51], v[194:197], v[176:179], v[48:51]
	v_mfma_f32_16x16x32_bf16 v[44:47], v[208:211], v[168:171], v[44:47]
	v_mfma_f32_16x16x32_bf16 v[40:43], v[208:211], v[176:179], v[40:43]
	v_mfma_f32_16x16x32_bf16 v[36:39], v[216:219], v[168:171], v[36:39]
	v_mfma_f32_16x16x32_bf16 v[32:35], v[216:219], v[176:179], v[32:35]
	v_mfma_f32_16x16x32_bf16 v[60:63], v[188:191], v[172:175], v[60:63]
	v_mfma_f32_16x16x32_bf16 v[56:59], v[188:191], v[180:183], v[56:59]
	v_mfma_f32_16x16x32_bf16 v[52:55], v[202:205], v[172:175], v[52:55]
	v_mfma_f32_16x16x32_bf16 v[48:51], v[202:205], v[180:183], v[48:51]
	v_mfma_f32_16x16x32_bf16 v[44:47], v[212:215], v[172:175], v[44:47]
	v_mfma_f32_16x16x32_bf16 v[40:43], v[212:215], v[180:183], v[40:43]
	v_mfma_f32_16x16x32_bf16 v[36:39], v[220:223], v[172:175], v[36:39]
	v_mfma_f32_16x16x32_bf16 v[32:35], v[220:223], v[180:183], v[32:35]
	s_setprio 0
	s_barrier
	s_add_i32 m0, s99, 0x14000
	v_lshl_add_u64 v[168:169], v[240:241], 0, s[40:41]
	global_load_lds_dwordx4 v[168:169], off
	s_add_i32 m0, s99, 0x16000
	v_lshl_add_u64 v[168:169], v[240:241], 0, s[42:43]
	global_load_lds_dwordx4 v[168:169], off
	s_waitcnt vmcnt(6)
	s_barrier
; #define STAGE_A(P, hf, kt) do { if constexpr (ABLK) { const bf16* _gp = A + ((long)(brow >> 8) * nt + (kt)) * 16384 + (hf) * 8192; GLDS2(_gp, 4096, offA, P); } \
;     else { const bf16* _gp = A + (long)(brow + (hf) * HALF) * lda + (long)(kt) * BK; GLDS2(_gp, 64 * (long)lda, offA, P); } } while (0)
; #define STAGE_B(P, hf, kt) do { const bf16* _gp = Bt + (long)(bcol + (hf) * 2) * ldb + (long)(kt) * BK; GLDS2(_gp, 128 * (long)ldb, offB, P); } while (0)
; #define LDA(dst, b, h) for (int m = 0; m < 4; ++m) for (int k = 0; k < 2; ++k) \
;     dst[m][k] = *reinterpret_cast<const bf16x8*>((char*)SA(b, h) + lds_byte(wr * 64 + m * 16 + fr, k * 32 + fq * 8))
; #define LDB(dst, b, h) for (int n = 0; n < 2; ++n) for (int k = 0; k < 2; ++k) \
;     dst[n][k] = *reinterpret_cast<const bf16x8*>((char*)SB(b, h) + lds_byte(wc * 32 + n * 16 + fr, k * 32 + fq * 8))
; #define MMA(ai, bj, At, Bt_) do { __builtin_amdgcn_s_setprio(1); \
;     for (int m = 0; m < 4; ++m) for (int n = 0; n < 2; ++n) for (int k = 0; k < 2; ++k) \
;       acc[ai][bj][m][n] = __builtin_amdgcn_mfma_f32_16x16x32_bf16(At[m][k], Bt_[n][k], acc[ai][bj][m][n], 0, 0, 0); \
;     __builtin_amdgcn_s_setprio(0); } while (0)
; #define WAIT_V(n) asm volatile("s_waitcnt vmcnt(" #n ")" ::: "memory")
; #define WAIT_L(n) asm volatile("s_waitcnt lgkmcnt(" #n ")" ::: "memory")
; #define BAR __builtin_amdgcn_s_barrier()
; #define SCHED __builtin_amdgcn_sched_barrier(0)
; template <bool ABLK, class Epi>
; __device__ __forceinline__ void gemm_tile(const bf16* __restrict__ A, int lda, const bf16* __restrict__ Bt, int ldb, int K,
;                                           int brow, int bcol, bf16* shm, const Epi& epi, int wv) {
;     ...
;     WAIT_V(6); BAR; MMA(1, 1, At, B1); BAR;
;     LDB(B0, 1, 0); SCHED; LDA(At, 1, 0); STAGE_A(SA(0, 1), 1, t + 2);
;     WAIT_L(8); BAR; MMA(0, 0, At, B0); BAR; SCHED;
;     LDB(B1, 1, 1); STAGE_B(SB(1, 0), 0, t + 3);
;     BAR; MMA(0, 1, At, B1); BAR;
;     LDA(At, 1, 1); STAGE_A(SA(1, 0), 0, t + 3);
;     BAR; MMA(1, 0, At, B0); BAR; SCHED;
	s_setprio 1
	v_mfma_f32_16x16x32_bf16 v[28:31], v[184:187], v[224:227], v[28:31]
	v_mfma_f32_16x16x32_bf16 v[24:27], v[184:187], v[232:235], v[24:27]
	v_mfma_f32_16x16x32_bf16 v[20:23], v[194:197], v[224:227], v[20:23]
	v_mfma_f32_16x16x32_bf16 v[16:19], v[194:197], v[232:235], v[16:19]
	v_mfma_f32_16x16x32_bf16 v[12:15], v[208:211], v[224:227], v[12:15]
	v_mfma_f32_16x16x32_bf16 v[8:11], v[208:211], v[232:235], v[8:11]
	v_mfma_f32_16x16x32_bf16 v[4:7], v[216:219], v[224:227], v[4:7]
	v_mfma_f32_16x16x32_bf16 v[0:3], v[216:219], v[232:235], v[0:3]
	v_mfma_f32_16x16x32_bf16 v[28:31], v[188:191], v[228:231], v[28:31]
	v_mfma_f32_16x16x32_bf16 v[24:27], v[188:191], v[236:239], v[24:27]
	v_mfma_f32_16x16x32_bf16 v[20:23], v[202:205], v[228:231], v[20:23]
	v_mfma_f32_16x16x32_bf16 v[16:19], v[202:205], v[236:239], v[16:19]
	v_mfma_f32_16x16x32_bf16 v[12:15], v[212:215], v[228:231], v[12:15]
	v_mfma_f32_16x16x32_bf16 v[8:11], v[212:215], v[236:239], v[8:11]
	v_mfma_f32_16x16x32_bf16 v[4:7], v[220:223], v[228:231], v[4:7]
	v_mfma_f32_16x16x32_bf16 v[0:3], v[220:223], v[236:239], v[0:3]
	s_setprio 0
	s_barrier
	ds_read_b128 v[168:171], v155
	ds_read_b128 v[172:175], v155 offset:1024
	ds_read_b128 v[176:179], v155 offset:2048
	ds_read_b128 v[180:183], v155 offset:3072
	v_lshl_add_u64 v[224:225], v[198:199], 0, s[44:45]
	s_add_i32 m0, s99, 0x4000
	ds_read_b128 v[184:187], v147 offset:32768
	ds_read_b128 v[188:191], v147 offset:33792
	ds_read_b128 v[194:197], v146 offset:32768
	ds_read_b128 v[202:205], v146 offset:33792
	ds_read_b128 v[208:211], v145 offset:32768
	ds_read_b128 v[212:215], v145 offset:33792
	ds_read_b128 v[216:219], v144 offset:32768
	ds_read_b128 v[220:223], v144 offset:33792
	global_load_lds_dwordx4 v[224:225], off
	s_add_i32 m0, s99, 0x6000
	v_lshl_add_u64 v[224:225], v[198:199], 0, s[46:47]
	global_load_lds_dwordx4 v[224:225], off
	s_waitcnt lgkmcnt(8)
	s_barrier
	s_setprio 1
	s_waitcnt lgkmcnt(0)
	v_mfma_f32_16x16x32_bf16 v[124:127], v[184:187], v[168:171], v[124:127]
	v_mfma_f32_16x16x32_bf16 v[120:123], v[184:187], v[176:179], v[120:123]
	v_mfma_f32_16x16x32_bf16 v[116:119], v[194:197], v[168:171], v[116:119]
	v_mfma_f32_16x16x32_bf16 v[112:115], v[194:197], v[176:179], v[112:115]
	v_mfma_f32_16x16x32_bf16 v[108:111], v[208:211], v[168:171], v[108:111]
	v_mfma_f32_16x16x32_bf16 v[104:107], v[208:211], v[176:179], v[104:107]
	v_mfma_f32_16x16x32_bf16 v[100:103], v[216:219], v[168:171], v[100:103]
	v_mfma_f32_16x16x32_bf16 v[96:99], v[216:219], v[176:179], v[96:99]
	v_mfma_f32_16x16x32_bf16 v[124:127], v[188:191], v[172:175], v[124:127]
	v_mfma_f32_16x16x32_bf16 v[120:123], v[188:191], v[180:183], v[120:123]
	v_mfma_f32_16x16x32_bf16 v[116:119], v[202:205], v[172:175], v[116:119]
	v_mfma_f32_16x16x32_bf16 v[112:115], v[202:205], v[180:183], v[112:115]
	v_mfma_f32_16x16x32_bf16 v[108:111], v[212:215], v[172:175], v[108:111]
	v_mfma_f32_16x16x32_bf16 v[104:107], v[212:215], v[180:183], v[104:107]
	v_mfma_f32_16x16x32_bf16 v[100:103], v[220:223], v[172:175], v[100:103]
	v_mfma_f32_16x16x32_bf16 v[96:99], v[220:223], v[180:183], v[96:99]
	s_setprio 0
	s_barrier
	v_lshl_add_u64 v[242:243], v[240:241], 0, s[48:49]
	s_add_i32 m0, s99, 0x18000
	ds_read_b128 v[224:227], v151
	ds_read_b128 v[228:231], v151 offset:1024
	ds_read_b128 v[232:235], v151 offset:2048
	ds_read_b128 v[236:239], v151 offset:3072
	global_load_lds_dwordx4 v[242:243], off
	s_add_i32 m0, s99, 0x1a000
	v_lshl_add_u64 v[242:243], v[240:241], 0, s[50:51]
	global_load_lds_dwordx4 v[242:243], off
	s_barrier
	s_setprio 1
	s_waitcnt lgkmcnt(0)
	v_mfma_f32_16x16x32_bf16 v[92:95], v[184:187], v[224:227], v[92:95]
	v_mfma_f32_16x16x32_bf16 v[88:91], v[184:187], v[232:235], v[88:91]
	v_mfma_f32_16x16x32_bf16 v[84:87], v[194:197], v[224:227], v[84:87]
	v_mfma_f32_16x16x32_bf16 v[80:83], v[194:197], v[232:235], v[80:83]
	v_mfma_f32_16x16x32_bf16 v[76:79], v[208:211], v[224:227], v[76:79]
	v_mfma_f32_16x16x32_bf16 v[72:75], v[208:211], v[232:235], v[72:75]
	v_mfma_f32_16x16x32_bf16 v[68:71], v[216:219], v[224:227], v[68:71]
	v_mfma_f32_16x16x32_bf16 v[64:67], v[216:219], v[232:235], v[64:67]
	v_mfma_f32_16x16x32_bf16 v[92:95], v[188:191], v[228:231], v[92:95]
	v_mfma_f32_16x16x32_bf16 v[88:91], v[188:191], v[236:239], v[88:91]
	v_mfma_f32_16x16x32_bf16 v[84:87], v[202:205], v[228:231], v[84:87]
	v_mfma_f32_16x16x32_bf16 v[80:83], v[202:205], v[236:239], v[80:83]
	v_mfma_f32_16x16x32_bf16 v[76:79], v[212:215], v[228:231], v[76:79]
	v_mfma_f32_16x16x32_bf16 v[72:75], v[212:215], v[236:239], v[72:75]
	v_mfma_f32_16x16x32_bf16 v[68:71], v[220:223], v[228:231], v[68:71]
	v_mfma_f32_16x16x32_bf16 v[64:67], v[220:223], v[236:239], v[64:67]
	s_setprio 0
	v_lshl_add_u64 v[242:243], v[198:199], 0, s[52:53]
	s_add_i32 m0, s99, 0x8000
	s_barrier
	ds_read_b128 v[184:187], v147 offset:49152
	ds_read_b128 v[188:191], v147 offset:50176
	ds_read_b128 v[194:197], v146 offset:49152
	ds_read_b128 v[202:205], v146 offset:50176
	ds_read_b128 v[208:211], v145 offset:49152
	ds_read_b128 v[212:215], v145 offset:50176
	ds_read_b128 v[216:219], v144 offset:49152
	ds_read_b128 v[220:223], v144 offset:50176
	global_load_lds_dwordx4 v[242:243], off
	s_add_i32 m0, s99, 0xa000
	v_lshl_add_u64 v[198:199], v[198:199], 0, s[54:55]
	global_load_lds_dwordx4 v[198:199], off
	s_barrier
; #define STAGE_A(P, hf, kt) do { if constexpr (ABLK) { const bf16* _gp = A + ((long)(brow >> 8) * nt + (kt)) * 16384 + (hf) * 8192; GLDS2(_gp, 4096, offA, P); } \
;     else { const bf16* _gp = A + (long)(brow + (hf) * HALF) * lda + (long)(kt) * BK; GLDS2(_gp, 64 * (long)lda, offA, P); } } while (0)
; #define STAGE_B(P, hf, kt) do { const bf16* _gp = Bt + (long)(bcol + (hf) * 2) * ldb + (long)(kt) * BK; GLDS2(_gp, 128 * (long)ldb, offB, P); } while (0)
; #define LDA(dst, b, h) for (int m = 0; m < 4; ++m) for (int k = 0; k < 2; ++k) \
;     dst[m][k] = *reinterpret_cast<const bf16x8*>((char*)SA(b, h) + lds_byte(wr * 64 + m * 16 + fr, k * 32 + fq * 8))
; #define LDB(dst, b, h) for (int n = 0; n < 2; ++n) for (int k = 0; k < 2; ++k) \
;     dst[n][k] = *reinterpret_cast<const bf16x8*>((char*)SB(b, h) + lds_byte(wc * 32 + n * 16 + fr, k * 32 + fq * 8))
; #define MMA(ai, bj, At, Bt_) do { __builtin_amdgcn_s_setprio(1); \
;     for (int m = 0; m < 4; ++m) for (int n = 0; n < 2; ++n) for (int k = 0; k < 2; ++k) \
;       acc[ai][bj][m][n] = __builtin_amdgcn_mfma_f32_16x16x32_bf16(At[m][k], Bt_[n][k], acc[ai][bj][m][n], 0, 0, 0); \
;     __builtin_amdgcn_s_setprio(0); } while (0)
; #define WAIT_V(n) asm volatile("s_waitcnt vmcnt(" #n ")" ::: "memory")
; #define WAIT_L(n) asm volatile("s_waitcnt lgkmcnt(" #n ")" ::: "memory")
; #define BAR __builtin_amdgcn_s_barrier()
; #define SCHED __builtin_amdgcn_sched_barrier(0)
; template <bool ABLK, class Epi>
; __device__ __forceinline__ void gemm_tile(const bf16* __restrict__ A, int lda, const bf16* __restrict__ Bt, int ldb, int K,
;                                           int brow, int bcol, bf16* shm, const Epi& epi, int wv) {
;     ...
;     BAR; MMA(1, 0, At, B0); BAR; SCHED;
;     STAGE_B(SB(1, 1), 1, t + 3);
;     WAIT_V(6); BAR; MMA(1, 1, At, B1); BAR;
;   }
;   { LDB(B0, 0, 0); LDA(At, 0, 0); STAGE_A(SA(1, 1), 1, nt - 1);
;     BAR; WAIT_L(0); MMA(0, 0, At, B0); BAR;
;     LDB(B1, 0, 1); BAR; WAIT_L(0); MMA(0, 1, At, B1); BAR;
;     LDA(At, 0, 1); WAIT_V(4); BAR; WAIT_L(0); MMA(1, 0, At, B0); MMA(1, 1, At, B1); BAR; }
	s_setprio 1
	s_waitcnt lgkmcnt(0)
	v_mfma_f32_16x16x32_bf16 v[60:63], v[184:187], v[168:171], v[60:63]
	v_mfma_f32_16x16x32_bf16 v[56:59], v[184:187], v[176:179], v[56:59]
	v_mfma_f32_16x16x32_bf16 v[52:55], v[194:197], v[168:171], v[52:55]
	v_mfma_f32_16x16x32_bf16 v[48:51], v[194:197], v[176:179], v[48:51]
	v_mfma_f32_16x16x32_bf16 v[44:47], v[208:211], v[168:171], v[44:47]
	v_mfma_f32_16x16x32_bf16 v[40:43], v[208:211], v[176:179], v[40:43]
	v_mfma_f32_16x16x32_bf16 v[36:39], v[216:219], v[168:171], v[36:39]
	v_mfma_f32_16x16x32_bf16 v[32:35], v[216:219], v[176:179], v[32:35]
	v_mfma_f32_16x16x32_bf16 v[60:63], v[188:191], v[172:175], v[60:63]
	v_mfma_f32_16x16x32_bf16 v[56:59], v[188:191], v[180:183], v[56:59]
	v_mfma_f32_16x16x32_bf16 v[52:55], v[202:205], v[172:175], v[52:55]
	v_mfma_f32_16x16x32_bf16 v[48:51], v[202:205], v[180:183], v[48:51]
	v_mfma_f32_16x16x32_bf16 v[44:47], v[212:215], v[172:175], v[44:47]
	v_mfma_f32_16x16x32_bf16 v[40:43], v[212:215], v[180:183], v[40:43]
	v_mfma_f32_16x16x32_bf16 v[36:39], v[220:223], v[172:175], v[36:39]
	v_mfma_f32_16x16x32_bf16 v[32:35], v[220:223], v[180:183], v[32:35]
	s_setprio 0
	s_barrier
	s_add_i32 m0, s99, 0x1c000
	v_lshl_add_u64 v[168:169], v[240:241], 0, s[56:57]
	global_load_lds_dwordx4 v[168:169], off
	s_add_i32 m0, s99, 0x1e000
	v_lshl_add_u64 v[168:169], v[240:241], 0, s[58:59]
	global_load_lds_dwordx4 v[168:169], off
	s_waitcnt vmcnt(6)
	s_barrier
	s_setprio 1
	v_mfma_f32_16x16x32_bf16 v[28:31], v[184:187], v[224:227], v[28:31]
	v_mfma_f32_16x16x32_bf16 v[24:27], v[184:187], v[232:235], v[24:27]
	v_mfma_f32_16x16x32_bf16 v[20:23], v[194:197], v[224:227], v[20:23]
	v_mfma_f32_16x16x32_bf16 v[16:19], v[194:197], v[232:235], v[16:19]
	v_mfma_f32_16x16x32_bf16 v[12:15], v[208:211], v[224:227], v[12:15]
	v_mfma_f32_16x16x32_bf16 v[8:11], v[208:211], v[232:235], v[8:11]
	v_mfma_f32_16x16x32_bf16 v[4:7], v[216:219], v[224:227], v[4:7]
	v_mfma_f32_16x16x32_bf16 v[0:3], v[216:219], v[232:235], v[0:3]
	v_mfma_f32_16x16x32_bf16 v[28:31], v[188:191], v[228:231], v[28:31]
	v_mfma_f32_16x16x32_bf16 v[24:27], v[188:191], v[236:239], v[24:27]
	v_mfma_f32_16x16x32_bf16 v[20:23], v[202:205], v[228:231], v[20:23]
	v_mfma_f32_16x16x32_bf16 v[16:19], v[202:205], v[236:239], v[16:19]
	v_mfma_f32_16x16x32_bf16 v[12:15], v[212:215], v[228:231], v[12:15]
	v_mfma_f32_16x16x32_bf16 v[8:11], v[212:215], v[236:239], v[8:11]
	v_mfma_f32_16x16x32_bf16 v[4:7], v[220:223], v[228:231], v[4:7]
	v_mfma_f32_16x16x32_bf16 v[0:3], v[220:223], v[236:239], v[0:3]
	s_setprio 0
	s_add_i32 s9, s9, 2
	s_add_u32 s66, s66, 0x100
	s_addc_u32 s67, s67, 0
	s_cmp_lt_u32 s9, 4
	s_barrier
	s_cbranch_scc1 .LBB0_814
	v_readfirstlane_b32 s2, v166
	v_lshl_add_u64 v[132:133], v[132:133], 0, s[60:61]
	s_mov_b32 m0, s2
	v_lshl_add_u64 v[130:131], v[130:131], 1, s[64:65]
	v_readfirstlane_b32 s2, v167
	ds_read_b128 v[134:137], v165
	ds_read_b128 v[156:159], v165 offset:1024
	ds_read_b128 v[160:163], v165 offset:2048
	ds_read_b128 v[168:171], v165 offset:3072
	ds_read_b128 v[172:175], v147
	ds_read_b128 v[176:179], v147 offset:1024
	ds_read_b128 v[180:183], v146
	ds_read_b128 v[184:187], v146 offset:1024
	ds_read_b128 v[188:191], v145
	ds_read_b128 v[194:197], v145 offset:1024
	ds_read_b128 v[202:205], v144
	ds_read_b128 v[208:211], v144 offset:1024
	global_load_lds_dwordx4 v[132:133], off
	v_lshl_add_u64 v[130:131], v[130:131], 0, s[62:63]
	s_mov_b32 m0, s2
	s_nop 0
	global_load_lds_dwordx4 v[130:131], off
	s_barrier
	s_waitcnt lgkmcnt(0)
	s_setprio 1
	s_waitcnt lgkmcnt(0)
	v_mfma_f32_16x16x32_bf16 v[124:127], v[172:175], v[134:137], v[124:127]
	v_mfma_f32_16x16x32_bf16 v[120:123], v[172:175], v[160:163], v[120:123]
	v_mfma_f32_16x16x32_bf16 v[108:111], v[188:191], v[134:137], v[108:111]
	v_mfma_f32_16x16x32_bf16 v[104:107], v[188:191], v[160:163], v[104:107]
	v_mfma_f32_16x16x32_bf16 v[124:127], v[176:179], v[156:159], v[124:127]
	v_mfma_f32_16x16x32_bf16 v[120:123], v[176:179], v[168:171], v[120:123]
	v_mfma_f32_16x16x32_bf16 v[116:119], v[180:183], v[134:137], v[116:119]
	v_mfma_f32_16x16x32_bf16 v[112:115], v[180:183], v[160:163], v[112:115]
	v_mfma_f32_16x16x32_bf16 v[108:111], v[194:197], v[156:159], v[108:111]
	v_mfma_f32_16x16x32_bf16 v[104:107], v[194:197], v[168:171], v[104:107]
	v_mfma_f32_16x16x32_bf16 v[100:103], v[202:205], v[134:137], v[100:103]
	v_mfma_f32_16x16x32_bf16 v[96:99], v[202:205], v[160:163], v[96:99]
	v_mfma_f32_16x16x32_bf16 v[130:133], v[184:187], v[156:159], v[116:119]
	v_mfma_f32_16x16x32_bf16 v[212:215], v[184:187], v[168:171], v[112:115]
	v_mfma_f32_16x16x32_bf16 v[216:219], v[208:211], v[156:159], v[100:103]
	v_mfma_f32_16x16x32_bf16 v[220:223], v[208:211], v[168:171], v[96:99]
	s_setprio 0
	s_barrier
	s_nop 1
	ds_read_b128 v[96:99], v164
	ds_read_b128 v[100:103], v164 offset:1024
	ds_read_b128 v[112:115], v164 offset:2048
	ds_read_b128 v[116:119], v164 offset:3072
	s_barrier
	s_waitcnt lgkmcnt(0)
	s_setprio 1
	s_waitcnt lgkmcnt(0)
	v_mfma_f32_16x16x32_bf16 v[92:95], v[172:175], v[96:99], v[92:95]
	v_mfma_f32_16x16x32_bf16 v[88:91], v[172:175], v[112:115], v[88:91]
	v_mfma_f32_16x16x32_bf16 v[76:79], v[188:191], v[96:99], v[76:79]
	v_mfma_f32_16x16x32_bf16 v[72:75], v[188:191], v[112:115], v[72:75]
	v_mfma_f32_16x16x32_bf16 v[92:95], v[176:179], v[100:103], v[92:95]
	v_mfma_f32_16x16x32_bf16 v[88:91], v[176:179], v[116:119], v[88:91]
	v_mfma_f32_16x16x32_bf16 v[84:87], v[180:183], v[96:99], v[84:87]
	v_mfma_f32_16x16x32_bf16 v[80:83], v[180:183], v[112:115], v[80:83]
	v_mfma_f32_16x16x32_bf16 v[76:79], v[194:197], v[100:103], v[76:79]
	v_mfma_f32_16x16x32_bf16 v[72:75], v[194:197], v[116:119], v[72:75]
	v_mfma_f32_16x16x32_bf16 v[68:71], v[202:205], v[96:99], v[68:71]
	v_mfma_f32_16x16x32_bf16 v[64:67], v[202:205], v[112:115], v[64:67]
	v_mfma_f32_16x16x32_bf16 v[164:167], v[184:187], v[100:103], v[84:87]
	v_mfma_f32_16x16x32_bf16 v[172:175], v[184:187], v[116:119], v[80:83]
	v_mfma_f32_16x16x32_bf16 v[176:179], v[208:211], v[100:103], v[68:71]
	v_mfma_f32_16x16x32_bf16 v[180:183], v[208:211], v[116:119], v[64:67]
	s_setprio 0
	s_barrier
; #define LDA(dst, b, h) for (int m = 0; m < 4; ++m) for (int k = 0; k < 2; ++k) \
;     dst[m][k] = *reinterpret_cast<const bf16x8*>((char*)SA(b, h) + lds_byte(wr * 64 + m * 16 + fr, k * 32 + fq * 8))
; #define LDB(dst, b, h) for (int n = 0; n < 2; ++n) for (int k = 0; k < 2; ++k) \
;     dst[n][k] = *reinterpret_cast<const bf16x8*>((char*)SB(b, h) + lds_byte(wc * 32 + n * 16 + fr, k * 32 + fq * 8))
; #define MMA(ai, bj, At, Bt_) do { __builtin_amdgcn_s_setprio(1); \
;     for (int m = 0; m < 4; ++m) for (int n = 0; n < 2; ++n) for (int k = 0; k < 2; ++k) \
;       acc[ai][bj][m][n] = __builtin_amdgcn_mfma_f32_16x16x32_bf16(At[m][k], Bt_[n][k], acc[ai][bj][m][n], 0, 0, 0); \
;     __builtin_amdgcn_s_setprio(0); } while (0)
; #define WAIT_V(n) asm volatile("s_waitcnt vmcnt(" #n ")" ::: "memory")
; #define WAIT_L(n) asm volatile("s_waitcnt lgkmcnt(" #n ")" ::: "memory")
; #define BAR __builtin_amdgcn_s_barrier()
; template <bool ABLK, class Epi>
; __device__ __forceinline__ void gemm_tile(const bf16* __restrict__ A, int lda, const bf16* __restrict__ Bt, int ldb, int K,
;                                           int brow, int bcol, bf16* shm, const Epi& epi, int wv) {
;     ...
;     LDB(B1, 0, 1); BAR; WAIT_L(0); MMA(0, 1, At, B1); BAR;
;     LDA(At, 0, 1); WAIT_V(4); BAR; WAIT_L(0); MMA(1, 0, At, B0); MMA(1, 1, At, B1); BAR; }
;   { LDB(B0, 1, 0); LDA(At, 1, 0); WAIT_V(2); BAR; WAIT_L(0); MMA(0, 0, At, B0); BAR;
	s_nop 1
	ds_read_b128 v[64:67], v147 offset:16384
	ds_read_b128 v[68:71], v147 offset:17408
	ds_read_b128 v[80:83], v146 offset:16384
	ds_read_b128 v[84:87], v146 offset:17408
	ds_read_b128 v[184:187], v145 offset:16384
	ds_read_b128 v[188:191], v145 offset:17408
	ds_read_b128 v[194:197], v144 offset:16384
	ds_read_b128 v[202:205], v144 offset:17408
	s_waitcnt vmcnt(4)
	s_barrier
	s_waitcnt lgkmcnt(0)
	s_setprio 1
	s_waitcnt lgkmcnt(0)
	v_mfma_f32_16x16x32_bf16 v[60:63], v[64:67], v[134:137], v[60:63]
	v_mfma_f32_16x16x32_bf16 v[56:59], v[64:67], v[160:163], v[56:59]
	v_mfma_f32_16x16x32_bf16 v[44:47], v[184:187], v[134:137], v[44:47]
	v_mfma_f32_16x16x32_bf16 v[40:43], v[184:187], v[160:163], v[40:43]
	v_mfma_f32_16x16x32_bf16 v[60:63], v[68:71], v[156:159], v[60:63]
	v_mfma_f32_16x16x32_bf16 v[56:59], v[68:71], v[168:171], v[56:59]
	v_mfma_f32_16x16x32_bf16 v[52:55], v[80:83], v[134:137], v[52:55]
	v_mfma_f32_16x16x32_bf16 v[48:51], v[80:83], v[160:163], v[48:51]
	v_mfma_f32_16x16x32_bf16 v[44:47], v[188:191], v[156:159], v[44:47]
	v_mfma_f32_16x16x32_bf16 v[40:43], v[188:191], v[168:171], v[40:43]
	v_mfma_f32_16x16x32_bf16 v[36:39], v[194:197], v[134:137], v[36:39]
	v_mfma_f32_16x16x32_bf16 v[32:35], v[194:197], v[160:163], v[32:35]
	v_mfma_f32_16x16x32_bf16 v[208:211], v[84:87], v[156:159], v[52:55]
	v_mfma_f32_16x16x32_bf16 v[224:227], v[84:87], v[168:171], v[48:51]
	v_mfma_f32_16x16x32_bf16 v[134:137], v[202:205], v[156:159], v[36:39]
	v_mfma_f32_16x16x32_bf16 v[156:159], v[202:205], v[168:171], v[32:35]
	s_setprio 0
	s_setprio 1
	v_mfma_f32_16x16x32_bf16 v[28:31], v[64:67], v[96:99], v[28:31]
	v_mfma_f32_16x16x32_bf16 v[24:27], v[64:67], v[112:115], v[24:27]
	v_mfma_f32_16x16x32_bf16 v[12:15], v[184:187], v[96:99], v[12:15]
	v_mfma_f32_16x16x32_bf16 v[8:11], v[184:187], v[112:115], v[8:11]
	v_mfma_f32_16x16x32_bf16 v[28:31], v[68:71], v[100:103], v[28:31]
	v_mfma_f32_16x16x32_bf16 v[24:27], v[68:71], v[116:119], v[24:27]
	v_mfma_f32_16x16x32_bf16 v[20:23], v[80:83], v[96:99], v[20:23]
	v_mfma_f32_16x16x32_bf16 v[16:19], v[80:83], v[112:115], v[16:19]
	v_mfma_f32_16x16x32_bf16 v[12:15], v[188:191], v[100:103], v[12:15]
	v_mfma_f32_16x16x32_bf16 v[8:11], v[188:191], v[116:119], v[8:11]
	v_mfma_f32_16x16x32_bf16 v[4:7], v[194:197], v[96:99], v[4:7]
	v_mfma_f32_16x16x32_bf16 v[0:3], v[194:197], v[112:115], v[0:3]
	v_mfma_f32_16x16x32_bf16 v[160:163], v[84:87], v[100:103], v[20:23]
	v_mfma_f32_16x16x32_bf16 v[168:171], v[84:87], v[116:119], v[16:19]
	v_mfma_f32_16x16x32_bf16 v[184:187], v[202:205], v[100:103], v[4:7]
	v_mfma_f32_16x16x32_bf16 v[188:191], v[202:205], v[116:119], v[0:3]
	s_setprio 0
	s_barrier
	s_nop 1
	ds_read_b128 v[0:3], v155
	ds_read_b128 v[4:7], v155 offset:1024
	ds_read_b128 v[194:197], v155 offset:2048
	ds_read_b128 v[152:155], v155 offset:3072
	ds_read_b128 v[16:19], v147 offset:32768
	ds_read_b128 v[20:23], v147 offset:33792
	ds_read_b128 v[32:35], v146 offset:32768
	ds_read_b128 v[36:39], v146 offset:33792
	ds_read_b128 v[48:51], v145 offset:32768
	ds_read_b128 v[52:55], v145 offset:33792
	ds_read_b128 v[202:205], v144 offset:32768
	ds_read_b128 v[228:231], v144 offset:33792
	s_waitcnt vmcnt(2)
	s_barrier
	s_waitcnt lgkmcnt(0)
	s_setprio 1
	s_waitcnt lgkmcnt(0)
	v_mfma_f32_16x16x32_bf16 v[64:67], v[16:19], v[0:3], v[124:127]
	v_mfma_f32_16x16x32_bf16 v[112:115], v[20:23], v[4:7], v[64:67]
	v_mfma_f32_16x16x32_bf16 v[64:67], v[16:19], v[194:197], v[120:123]
	v_mfma_f32_16x16x32_bf16 v[116:119], v[20:23], v[152:155], v[64:67]
	v_mfma_f32_16x16x32_bf16 v[64:67], v[32:35], v[0:3], v[130:133]
	v_mfma_f32_16x16x32_bf16 v[96:99], v[36:39], v[4:7], v[64:67]
	v_mfma_f32_16x16x32_bf16 v[64:67], v[32:35], v[194:197], v[212:215]
	v_mfma_f32_16x16x32_bf16 v[100:103], v[36:39], v[152:155], v[64:67]
	v_mfma_f32_16x16x32_bf16 v[64:67], v[48:51], v[0:3], v[108:111]
	v_mfma_f32_16x16x32_bf16 v[80:83], v[52:55], v[4:7], v[64:67]
	v_mfma_f32_16x16x32_bf16 v[64:67], v[48:51], v[194:197], v[104:107]
	v_mfma_f32_16x16x32_bf16 v[84:87], v[52:55], v[152:155], v[64:67]
	v_mfma_f32_16x16x32_bf16 v[64:67], v[202:205], v[0:3], v[216:219]
	v_mfma_f32_16x16x32_bf16 v[68:71], v[202:205], v[194:197], v[220:223]
	v_mfma_f32_16x16x32_bf16 v[64:67], v[228:231], v[4:7], v[64:67]
	v_mfma_f32_16x16x32_bf16 v[68:71], v[228:231], v[152:155], v[68:71]
	s_setprio 0
	s_barrier
; #define LDA(dst, b, h) for (int m = 0; m < 4; ++m) for (int k = 0; k < 2; ++k) \
;     dst[m][k] = *reinterpret_cast<const bf16x8*>((char*)SA(b, h) + lds_byte(wr * 64 + m * 16 + fr, k * 32 + fq * 8))
; #define LDB(dst, b, h) for (int n = 0; n < 2; ++n) for (int k = 0; k < 2; ++k) \
;     dst[n][k] = *reinterpret_cast<const bf16x8*>((char*)SB(b, h) + lds_byte(wc * 32 + n * 16 + fr, k * 32 + fq * 8))
; #define MMA(ai, bj, At, Bt_) do { __builtin_amdgcn_s_setprio(1); \
;     for (int m = 0; m < 4; ++m) for (int n = 0; n < 2; ++n) for (int k = 0; k < 2; ++k) \
;       acc[ai][bj][m][n] = __builtin_amdgcn_mfma_f32_16x16x32_bf16(At[m][k], Bt_[n][k], acc[ai][bj][m][n], 0, 0, 0); \
;     __builtin_amdgcn_s_setprio(0); } while (0)
; #define WAIT_V(n) asm volatile("s_waitcnt vmcnt(" #n ")" ::: "memory")
; #define WAIT_L(n) asm volatile("s_waitcnt lgkmcnt(" #n ")" ::: "memory")
; #define BAR __builtin_amdgcn_s_barrier()
; template <bool ABLK, class Epi>
; __device__ __forceinline__ void gemm_tile(const bf16* __restrict__ A, int lda, const bf16* __restrict__ Bt, int ldb, int K,
;                                           int brow, int bcol, bf16* shm, const Epi& epi, int wv) {
;     ...
;     LDB(B1, 1, 1); WAIT_V(0); BAR; WAIT_L(0); MMA(0, 1, At, B1); BAR;
;     LDA(At, 1, 1); BAR; WAIT_L(0); MMA(1, 0, At, B0); MMA(1, 1, At, B1); BAR; }
;   if (wr == 0) BAR;
	ds_read_b128 v[130:133], v151
	ds_read_b128 v[212:215], v151 offset:1024
	ds_read_b128 v[216:219], v151 offset:2048
	ds_read_b128 v[148:151], v151 offset:3072
	s_waitcnt vmcnt(0)
	s_barrier
	s_waitcnt lgkmcnt(0)
	s_setprio 1
	s_waitcnt lgkmcnt(0)
	v_mfma_f32_16x16x32_bf16 v[92:95], v[16:19], v[130:133], v[92:95]
	v_mfma_f32_16x16x32_bf16 v[16:19], v[16:19], v[216:219], v[88:91]
	v_mfma_f32_16x16x32_bf16 v[124:127], v[20:23], v[148:151], v[16:19]
	v_mfma_f32_16x16x32_bf16 v[16:19], v[32:35], v[130:133], v[164:167]
	v_mfma_f32_16x16x32_bf16 v[104:107], v[36:39], v[212:215], v[16:19]
	v_mfma_f32_16x16x32_bf16 v[16:19], v[32:35], v[216:219], v[172:175]
	v_mfma_f32_16x16x32_bf16 v[108:111], v[36:39], v[148:151], v[16:19]
	v_mfma_f32_16x16x32_bf16 v[16:19], v[48:51], v[130:133], v[76:79]
	v_mfma_f32_16x16x32_bf16 v[88:91], v[52:55], v[212:215], v[16:19]
	v_mfma_f32_16x16x32_bf16 v[16:19], v[48:51], v[216:219], v[72:75]
	v_mfma_f32_16x16x32_bf16 v[120:123], v[20:23], v[212:215], v[92:95]
	v_mfma_f32_16x16x32_bf16 v[92:95], v[52:55], v[148:151], v[16:19]
	v_mfma_f32_16x16x32_bf16 v[16:19], v[202:205], v[130:133], v[176:179]
	v_mfma_f32_16x16x32_bf16 v[72:75], v[228:231], v[212:215], v[16:19]
	v_mfma_f32_16x16x32_bf16 v[16:19], v[202:205], v[216:219], v[180:183]
	v_mfma_f32_16x16x32_bf16 v[76:79], v[228:231], v[148:151], v[16:19]
	s_setprio 0
	s_barrier
	ds_read_b128 v[164:167], v147 offset:49152
	ds_read_b128 v[172:175], v147 offset:50176
	ds_read_b128 v[176:179], v146 offset:49152
	ds_read_b128 v[180:183], v146 offset:50176
	ds_read_b128 v[202:205], v145 offset:49152
	ds_read_b128 v[220:223], v145 offset:50176
	ds_read_b128 v[228:231], v144 offset:49152
	ds_read_b128 v[144:147], v144 offset:50176
	s_barrier
	s_waitcnt lgkmcnt(0)
	s_setprio 1
	s_waitcnt lgkmcnt(0)
	v_mfma_f32_16x16x32_bf16 v[16:19], v[164:167], v[0:3], v[60:63]
	v_mfma_f32_16x16x32_bf16 v[48:51], v[172:175], v[4:7], v[16:19]
	v_mfma_f32_16x16x32_bf16 v[16:19], v[164:167], v[194:197], v[56:59]
	v_mfma_f32_16x16x32_bf16 v[52:55], v[172:175], v[152:155], v[16:19]
	v_mfma_f32_16x16x32_bf16 v[16:19], v[176:179], v[0:3], v[208:211]
	v_mfma_f32_16x16x32_bf16 v[32:35], v[180:183], v[4:7], v[16:19]
	v_mfma_f32_16x16x32_bf16 v[16:19], v[176:179], v[194:197], v[224:227]
	v_mfma_f32_16x16x32_bf16 v[36:39], v[180:183], v[152:155], v[16:19]
	v_mfma_f32_16x16x32_bf16 v[16:19], v[202:205], v[0:3], v[44:47]
	v_mfma_f32_16x16x32_bf16 v[0:3], v[228:231], v[0:3], v[134:137]
	v_mfma_f32_16x16x32_bf16 v[16:19], v[220:223], v[4:7], v[16:19]
	v_mfma_f32_16x16x32_bf16 v[20:23], v[202:205], v[194:197], v[40:43]
	v_mfma_f32_16x16x32_bf16 v[0:3], v[144:147], v[4:7], v[0:3]
	v_mfma_f32_16x16x32_bf16 v[4:7], v[228:231], v[194:197], v[156:159]
	v_mfma_f32_16x16x32_bf16 v[20:23], v[220:223], v[152:155], v[20:23]
	v_mfma_f32_16x16x32_bf16 v[4:7], v[144:147], v[152:155], v[4:7]
	s_setprio 0
	s_setprio 1
	v_mfma_f32_16x16x32_bf16 v[24:27], v[164:167], v[216:219], v[24:27]
	v_mfma_f32_16x16x32_bf16 v[60:63], v[172:175], v[148:151], v[24:27]
	v_mfma_f32_16x16x32_bf16 v[24:27], v[176:179], v[130:133], v[160:163]
	v_mfma_f32_16x16x32_bf16 v[28:31], v[164:167], v[130:133], v[28:31]
	v_mfma_f32_16x16x32_bf16 v[40:43], v[180:183], v[212:215], v[24:27]
	v_mfma_f32_16x16x32_bf16 v[24:27], v[176:179], v[216:219], v[168:171]
	v_mfma_f32_16x16x32_bf16 v[12:15], v[202:205], v[130:133], v[12:15]
	v_mfma_f32_16x16x32_bf16 v[8:11], v[202:205], v[216:219], v[8:11]
	v_mfma_f32_16x16x32_bf16 v[56:59], v[172:175], v[212:215], v[28:31]
	v_mfma_f32_16x16x32_bf16 v[44:47], v[180:183], v[148:151], v[24:27]
	v_mfma_f32_16x16x32_bf16 v[24:27], v[220:223], v[212:215], v[12:15]
	v_mfma_f32_16x16x32_bf16 v[28:31], v[220:223], v[148:151], v[8:11]
	v_mfma_f32_16x16x32_bf16 v[8:11], v[228:231], v[130:133], v[184:187]
	v_mfma_f32_16x16x32_bf16 v[12:15], v[228:231], v[216:219], v[188:191]
	v_mfma_f32_16x16x32_bf16 v[8:11], v[144:147], v[212:215], v[8:11]
	v_mfma_f32_16x16x32_bf16 v[12:15], v[144:147], v[148:151], v[12:15]
	s_setprio 0
	v_cmp_gt_u32_e32 vcc, s79, v128
	s_barrier
	s_and_saveexec_b64 s[64:65], vcc
	s_cbranch_execz .LBB0_817
	s_barrier

; __device__ __forceinline__ int mytid(int wv) { return (wv << 6) | (int)__builtin_amdgcn_mbcnt_hi(~0u, __builtin_amdgcn_mbcnt_lo(~0u, 0u)); }
; template <bool ABLK, class Epi>
; __device__ __forceinline__ void gemm_tile(const bf16* __restrict__ A, int lda, const bf16* __restrict__ Bt, int ldb, int K,
;                                           int brow, int bcol, bf16* shm, const Epi& epi, int wv) {
;     ...
;   int tid = mytid(wv); asm volatile("" : "+v"(tid));
;   const int wid = tid >> 6, lane = tid & 63, wr = wid >> 2, wc = wid & 3, fr = lane & 15, fq = lane >> 4;
;   f32x4 acc[2][2][4][2] = {};
;   bf16x8 At[4][2], B0[2][2], B1[2][2];
;   const int nt = K / BK;
;   int offA, offB;
;   { int r_, c_; stage_rc(tid * 16, r_, c_); offA = ABLK ? r_ * 64 + c_ : r_ * lda + c_;
;     offB = ((r_ >> 5) * 64 + (r_ & 15) * 4 + ((r_ >> 4) & 1)) * ldb + c_; }
; template <bool ABLK, class Epi>
; __device__ __forceinline__ void gemm_phase(const bf16* A, int lda, const bf16* Bt, int ldb, int M, int N, int K, char* smem, const Epi& epi, int wv) {
;     ...
;   for (int w = blockIdx.x; w < nwg; w += gridDim.x) {
;     int wgid = w;
;     { int q = nwg / NXCD, r = nwg % NXCD, xcd = wgid % NXCD, off = wgid / NXCD;
;       wgid = (xcd < r ? xcd * (q + 1) : r * (q + 1) + (xcd - r) * q) + off; }
;     const int nig = WGM * nN, gid = wgid / nig, fm = gid * WGM, gsz = min(nM - fm, WGM);
;     const int pm = fm + ((wgid % nig) % gsz), pn = (wgid % nig) / gsz;
;     gemm_tile<ABLK>(A, lda, Bt, ldb, K, pm * BM, pn * BM, (bf16*)smem, epi, wv);
.LBB0_971:
	s_or_b64 exec, exec, s[6:7]
	s_mov_b64 s[8:9], s[90:91]
	s_mov_b64 s[10:11], s[90:91]
	s_mov_b64 s[12:13], s[90:91]
	s_and_b64 vcc, exec, s[4:5]
	s_barrier
	s_barrier
	s_cbranch_vccnz .LBB0_981
	s_load_dwordx2 s[14:15], s[8:9], 0xa8
	s_load_dwordx2 s[16:17], s[10:11], 0xa8
	s_load_dwordx2 s[6:7], s[12:13], 0xa0
	s_mov_b32 s24, 0xffff2000
	s_mov_b32 s26, 0xffff4000
	s_waitcnt lgkmcnt(0)
	s_add_u32 s1, s14, 0xba40000
	s_addc_u32 s3, s15, 0
	s_add_u32 s72, s16, 0x2a40000
	s_addc_u32 s73, s17, 0
	s_add_u32 s74, s14, 0xba5a000
	s_addc_u32 s75, s15, 0
	s_add_u32 s76, s16, 0x2ac2180
	s_mov_b32 s30, 0xfff7df80
	s_movk_i32 s34, 0xdf80
	s_mov_b32 s36, 0xffff6000
	s_movk_i32 s38, 0x8000
	s_mov_b32 s40, 0xfff7ff80
	s_movk_i32 s42, 0xff80
	s_movk_i32 s44, 0xa000
	s_movk_i32 s46, 0xc000
	s_mov_b32 s48, 0xfff7e000
	s_movk_i32 s50, 0xe000
	s_mov_b32 s52, 0xfff80000
	s_movk_i32 s0, 0xc1
	s_addc_u32 s77, s17, 0
	s_add_i32 s78, 0, 0x10000
	s_mov_b64 s[8:9], 0x80000
	s_mov_b64 s[10:11], 0x2000
	s_add_i32 s79, 0, 0x14000
	s_mov_b64 s[12:13], 0x4000
	s_mov_b64 s[14:15], 0x6000
	s_mov_b64 s[16:17], 0x80
	s_add_i32 s80, 0, 0x18000
	s_mov_b64 s[18:19], 0x80080
	s_mov_b64 s[20:21], 0x8000
	s_mov_b64 s[22:23], 0xa000
	s_add_i32 s81, 0, 0x1c000
	s_movk_i32 s82, 0x3c0
	s_mov_b32 s25, -1
	s_mov_b32 s27, -1
	s_mov_b32 s31, -1
	s_mov_b32 s35, -1
	s_mov_b32 s37, -1
	s_mov_b32 s39, -1
	s_mov_b32 s41, -1
	s_mov_b32 s43, -1
	s_mov_b32 s45, -1
	s_mov_b32 s47, -1
	s_mov_b32 s49, -1
	s_mov_b32 s51, -1
	s_mov_b32 s53, -1
	s_mov_b64 s[54:55], 0x10000
	s_mov_b64 s[56:57], 0x100
	s_mov_b64 s[58:59], 0xfc000
	s_mov_b64 s[60:61], 0xfe000
	s_movk_i32 s83, 0x100
	v_mov_b32_e32 v134, 1
	s_mov_b32 s84, s89
	v_lshlrev_b32_e32 v254, 4, v192
	s_nop 0
	v_readfirstlane_b32 s99, v254
	s_branch .LBB0_974

; #define STAGE_A(P, hf, kt) do { if constexpr (ABLK) { const bf16* _gp = A + ((long)(brow >> 8) * nt + (kt)) * 16384 + (hf) * 8192; GLDS2(_gp, 4096, offA, P); } \
;     else { const bf16* _gp = A + (long)(brow + (hf) * HALF) * lda + (long)(kt) * BK; GLDS2(_gp, 64 * (long)lda, offA, P); } } while (0)
; #define STAGE_B(P, hf, kt) do { const bf16* _gp = Bt + (long)(bcol + (hf) * 2) * ldb + (long)(kt) * BK; GLDS2(_gp, 128 * (long)ldb, offB, P); } while (0)
; #define LDA(dst, b, h) for (int m = 0; m < 4; ++m) for (int k = 0; k < 2; ++k) \
;     dst[m][k] = *reinterpret_cast<const bf16x8*>((char*)SA(b, h) + lds_byte(wr * 64 + m * 16 + fr, k * 32 + fq * 8))
; #define LDB(dst, b, h) for (int n = 0; n < 2; ++n) for (int k = 0; k < 2; ++k) \
;     dst[n][k] = *reinterpret_cast<const bf16x8*>((char*)SB(b, h) + lds_byte(wc * 32 + n * 16 + fr, k * 32 + fq * 8))
; #define MMA(ai, bj, At, Bt_) do { __builtin_amdgcn_s_setprio(1); \
;     for (int m = 0; m < 4; ++m) for (int n = 0; n < 2; ++n) for (int k = 0; k < 2; ++k) \
;       acc[ai][bj][m][n] = __builtin_amdgcn_mfma_f32_16x16x32_bf16(At[m][k], Bt_[n][k], acc[ai][bj][m][n], 0, 0, 0); \
;     __builtin_amdgcn_s_setprio(0); } while (0)
; #define WAIT_V(n) asm volatile("s_waitcnt vmcnt(" #n ")" ::: "memory")
; #define WAIT_L(n) asm volatile("s_waitcnt lgkmcnt(" #n ")" ::: "memory")
; #define BAR __builtin_amdgcn_s_barrier()
; #define SCHED __builtin_amdgcn_sched_barrier(0)
; template <bool ABLK, class Epi>
; __device__ __forceinline__ void gemm_tile(const bf16* __restrict__ A, int lda, const bf16* __restrict__ Bt, int ldb, int K,
;                                           int brow, int bcol, bf16* shm, const Epi& epi, int wv) {
;     ...
;   for (int t = 0; t < nt - 2; t += 2) {
;     LDB(B0, 0, 0); SCHED; LDA(At, 0, 0); STAGE_A(SA(1, 1), 1, t + 1);
;     WAIT_L(8); BAR; MMA(0, 0, At, B0); BAR; SCHED;
;     LDB(B1, 0, 1); STAGE_B(SB(0, 0), 0, t + 2);
;     BAR; MMA(0, 1, At, B1); BAR;
;     LDA(At, 0, 1); STAGE_A(SA(0, 0), 0, t + 2);
;     BAR; MMA(1, 0, At, B0); BAR; SCHED;
;     STAGE_B(SB(0, 1), 1, t + 2);
;     WAIT_V(6); BAR; MMA(1, 1, At, B1); BAR;
.LBB0_977:
	ds_read_b128 v[164:167], v161
	ds_read_b128 v[168:171], v161 offset:1024
	ds_read_b128 v[172:175], v161 offset:2048
	ds_read_b128 v[176:179], v161 offset:3072
	v_add_u32_e32 v162, 0xc000, v147
	v_add_u32_e32 v163, 0xe000, v147
	v_lshl_add_u64 v[198:199], v[130:131], 0, s[24:25]
	s_add_i32 m0, s99, 0xc000
	ds_read_b128 v[180:183], v143
	ds_read_b128 v[184:187], v143 offset:1024
	ds_read_b128 v[188:191], v142
	ds_read_b128 v[194:197], v142 offset:1024
	ds_read_b128 v[202:205], v141
	ds_read_b128 v[208:211], v141 offset:1024
	ds_read_b128 v[212:215], v140
	ds_read_b128 v[216:219], v140 offset:1024
	global_load_lds_dwordx4 v[198:199], off
	s_add_i32 m0, s99, 0xe000
	v_lshl_add_u64 v[198:199], v[130:131], 0, s[26:27]
	global_load_lds_dwordx4 v[198:199], off
	s_waitcnt lgkmcnt(8)
	s_barrier
	s_setprio 1
	s_waitcnt lgkmcnt(0)
	v_mfma_f32_16x16x32_bf16 v[124:127], v[180:183], v[164:167], v[124:127]
	v_mfma_f32_16x16x32_bf16 v[120:123], v[180:183], v[172:175], v[120:123]
	v_mfma_f32_16x16x32_bf16 v[116:119], v[188:191], v[164:167], v[116:119]
	v_mfma_f32_16x16x32_bf16 v[112:115], v[188:191], v[172:175], v[112:115]
	v_mfma_f32_16x16x32_bf16 v[108:111], v[202:205], v[164:167], v[108:111]
	v_mfma_f32_16x16x32_bf16 v[104:107], v[202:205], v[172:175], v[104:107]
	v_mfma_f32_16x16x32_bf16 v[100:103], v[212:215], v[164:167], v[100:103]
	v_mfma_f32_16x16x32_bf16 v[96:99], v[212:215], v[172:175], v[96:99]
	v_mfma_f32_16x16x32_bf16 v[124:127], v[184:187], v[168:171], v[124:127]
	v_mfma_f32_16x16x32_bf16 v[120:123], v[184:187], v[176:179], v[120:123]
	v_mfma_f32_16x16x32_bf16 v[116:119], v[194:197], v[168:171], v[116:119]
	v_mfma_f32_16x16x32_bf16 v[112:115], v[194:197], v[176:179], v[112:115]
	v_mfma_f32_16x16x32_bf16 v[108:111], v[208:211], v[168:171], v[108:111]
	v_mfma_f32_16x16x32_bf16 v[104:107], v[208:211], v[176:179], v[104:107]
	v_mfma_f32_16x16x32_bf16 v[100:103], v[216:219], v[168:171], v[100:103]
	v_mfma_f32_16x16x32_bf16 v[96:99], v[216:219], v[176:179], v[96:99]
	s_setprio 0
	s_barrier
	v_lshl_add_u64 v[198:199], v[132:133], 0, s[30:31]
	s_add_i32 m0, s99, 0x10000
	ds_read_b128 v[220:223], v160
	ds_read_b128 v[224:227], v160 offset:1024
	ds_read_b128 v[228:231], v160 offset:2048
	ds_read_b128 v[232:235], v160 offset:3072
	global_load_lds_dwordx4 v[198:199], off
	s_add_i32 m0, s99, 0x12000
	v_lshl_add_u64 v[198:199], v[132:133], 0, s[34:35]
	global_load_lds_dwordx4 v[198:199], off
	s_barrier
	s_setprio 1
	s_waitcnt lgkmcnt(0)
	v_mfma_f32_16x16x32_bf16 v[92:95], v[180:183], v[220:223], v[92:95]
	v_mfma_f32_16x16x32_bf16 v[88:91], v[180:183], v[228:231], v[88:91]
	v_mfma_f32_16x16x32_bf16 v[84:87], v[188:191], v[220:223], v[84:87]
	v_mfma_f32_16x16x32_bf16 v[80:83], v[188:191], v[228:231], v[80:83]
	v_mfma_f32_16x16x32_bf16 v[76:79], v[202:205], v[220:223], v[76:79]
	v_mfma_f32_16x16x32_bf16 v[72:75], v[202:205], v[228:231], v[72:75]
	v_mfma_f32_16x16x32_bf16 v[68:71], v[212:215], v[220:223], v[68:71]
	v_mfma_f32_16x16x32_bf16 v[64:67], v[212:215], v[228:231], v[64:67]
	v_mfma_f32_16x16x32_bf16 v[92:95], v[184:187], v[224:227], v[92:95]
	v_mfma_f32_16x16x32_bf16 v[88:91], v[184:187], v[232:235], v[88:91]
	v_mfma_f32_16x16x32_bf16 v[84:87], v[194:197], v[224:227], v[84:87]
	v_mfma_f32_16x16x32_bf16 v[80:83], v[194:197], v[232:235], v[80:83]
	v_mfma_f32_16x16x32_bf16 v[76:79], v[208:211], v[224:227], v[76:79]
	v_mfma_f32_16x16x32_bf16 v[72:75], v[208:211], v[232:235], v[72:75]
	v_mfma_f32_16x16x32_bf16 v[68:71], v[216:219], v[224:227], v[68:71]
	v_mfma_f32_16x16x32_bf16 v[64:67], v[216:219], v[232:235], v[64:67]
	s_setprio 0
	v_lshl_add_u64 v[198:199], v[130:131], 0, s[36:37]
	s_add_i32 m0, s99, 0x0
	s_barrier
	ds_read_b128 v[180:183], v143 offset:16384
	ds_read_b128 v[184:187], v143 offset:17408
	ds_read_b128 v[188:191], v142 offset:16384
	ds_read_b128 v[194:197], v142 offset:17408
	ds_read_b128 v[202:205], v141 offset:16384
	ds_read_b128 v[208:211], v141 offset:17408
	ds_read_b128 v[212:215], v140 offset:16384
	ds_read_b128 v[216:219], v140 offset:17408
	global_load_lds_dwordx4 v[198:199], off
	s_add_i32 m0, s99, 0x2000
	v_lshl_add_u64 v[198:199], v[130:131], 0, s[38:39]
	global_load_lds_dwordx4 v[198:199], off
	s_barrier
	s_setprio 1
	s_waitcnt lgkmcnt(0)
	v_mfma_f32_16x16x32_bf16 v[60:63], v[180:183], v[164:167], v[60:63]
	v_mfma_f32_16x16x32_bf16 v[56:59], v[180:183], v[172:175], v[56:59]
	v_mfma_f32_16x16x32_bf16 v[52:55], v[188:191], v[164:167], v[52:55]
	v_mfma_f32_16x16x32_bf16 v[48:51], v[188:191], v[172:175], v[48:51]
	v_mfma_f32_16x16x32_bf16 v[44:47], v[202:205], v[164:167], v[44:47]
	v_mfma_f32_16x16x32_bf16 v[40:43], v[202:205], v[172:175], v[40:43]
	v_mfma_f32_16x16x32_bf16 v[36:39], v[212:215], v[164:167], v[36:39]
	v_mfma_f32_16x16x32_bf16 v[32:35], v[212:215], v[172:175], v[32:35]
	v_mfma_f32_16x16x32_bf16 v[60:63], v[184:187], v[168:171], v[60:63]
	v_mfma_f32_16x16x32_bf16 v[56:59], v[184:187], v[176:179], v[56:59]
	v_mfma_f32_16x16x32_bf16 v[52:55], v[194:197], v[168:171], v[52:55]
	v_mfma_f32_16x16x32_bf16 v[48:51], v[194:197], v[176:179], v[48:51]
	v_mfma_f32_16x16x32_bf16 v[44:47], v[208:211], v[168:171], v[44:47]
	v_mfma_f32_16x16x32_bf16 v[40:43], v[208:211], v[176:179], v[40:43]
	v_mfma_f32_16x16x32_bf16 v[36:39], v[216:219], v[168:171], v[36:39]
	v_mfma_f32_16x16x32_bf16 v[32:35], v[216:219], v[176:179], v[32:35]
	s_setprio 0
	s_barrier
	s_add_i32 m0, s99, 0x14000
	v_lshl_add_u64 v[164:165], v[132:133], 0, s[40:41]
	global_load_lds_dwordx4 v[164:165], off
	s_add_i32 m0, s99, 0x16000
	v_lshl_add_u64 v[164:165], v[132:133], 0, s[42:43]
	global_load_lds_dwordx4 v[164:165], off
	s_waitcnt vmcnt(6)
	s_barrier
; #define STAGE_A(P, hf, kt) do { if constexpr (ABLK) { const bf16* _gp = A + ((long)(brow >> 8) * nt + (kt)) * 16384 + (hf) * 8192; GLDS2(_gp, 4096, offA, P); } \
;     else { const bf16* _gp = A + (long)(brow + (hf) * HALF) * lda + (long)(kt) * BK; GLDS2(_gp, 64 * (long)lda, offA, P); } } while (0)
; #define STAGE_B(P, hf, kt) do { const bf16* _gp = Bt + (long)(bcol + (hf) * 2) * ldb + (long)(kt) * BK; GLDS2(_gp, 128 * (long)ldb, offB, P); } while (0)
; #define LDA(dst, b, h) for (int m = 0; m < 4; ++m) for (int k = 0; k < 2; ++k) \
;     dst[m][k] = *reinterpret_cast<const bf16x8*>((char*)SA(b, h) + lds_byte(wr * 64 + m * 16 + fr, k * 32 + fq * 8))
; #define LDB(dst, b, h) for (int n = 0; n < 2; ++n) for (int k = 0; k < 2; ++k) \
;     dst[n][k] = *reinterpret_cast<const bf16x8*>((char*)SB(b, h) + lds_byte(wc * 32 + n * 16 + fr, k * 32 + fq * 8))
; #define MMA(ai, bj, At, Bt_) do { __builtin_amdgcn_s_setprio(1); \
;     for (int m = 0; m < 4; ++m) for (int n = 0; n < 2; ++n) for (int k = 0; k < 2; ++k) \
;       acc[ai][bj][m][n] = __builtin_amdgcn_mfma_f32_16x16x32_bf16(At[m][k], Bt_[n][k], acc[ai][bj][m][n], 0, 0, 0); \
;     __builtin_amdgcn_s_setprio(0); } while (0)
; #define WAIT_V(n) asm volatile("s_waitcnt vmcnt(" #n ")" ::: "memory")
; #define WAIT_L(n) asm volatile("s_waitcnt lgkmcnt(" #n ")" ::: "memory")
; #define BAR __builtin_amdgcn_s_barrier()
; #define SCHED __builtin_amdgcn_sched_barrier(0)
; template <bool ABLK, class Epi>
; __device__ __forceinline__ void gemm_tile(const bf16* __restrict__ A, int lda, const bf16* __restrict__ Bt, int ldb, int K,
;                                           int brow, int bcol, bf16* shm, const Epi& epi, int wv) {
;     ...
;     WAIT_V(6); BAR; MMA(1, 1, At, B1); BAR;
;     LDB(B0, 1, 0); SCHED; LDA(At, 1, 0); STAGE_A(SA(0, 1), 1, t + 2);
;     WAIT_L(8); BAR; MMA(0, 0, At, B0); BAR; SCHED;
;     LDB(B1, 1, 1); STAGE_B(SB(1, 0), 0, t + 3);
;     BAR; MMA(0, 1, At, B1); BAR;
;     LDA(At, 1, 1); STAGE_A(SA(1, 0), 0, t + 3);
;     BAR; MMA(1, 0, At, B0); BAR; SCHED;
	s_setprio 1
	v_mfma_f32_16x16x32_bf16 v[28:31], v[180:183], v[220:223], v[28:31]
	v_mfma_f32_16x16x32_bf16 v[24:27], v[180:183], v[228:231], v[24:27]
	v_mfma_f32_16x16x32_bf16 v[20:23], v[188:191], v[220:223], v[20:23]
	v_mfma_f32_16x16x32_bf16 v[16:19], v[188:191], v[228:231], v[16:19]
	v_mfma_f32_16x16x32_bf16 v[12:15], v[202:205], v[220:223], v[12:15]
	v_mfma_f32_16x16x32_bf16 v[8:11], v[202:205], v[228:231], v[8:11]
	v_mfma_f32_16x16x32_bf16 v[4:7], v[212:215], v[220:223], v[4:7]
	v_mfma_f32_16x16x32_bf16 v[0:3], v[212:215], v[228:231], v[0:3]
	v_mfma_f32_16x16x32_bf16 v[28:31], v[184:187], v[224:227], v[28:31]
	v_mfma_f32_16x16x32_bf16 v[24:27], v[184:187], v[232:235], v[24:27]
	v_mfma_f32_16x16x32_bf16 v[20:23], v[194:197], v[224:227], v[20:23]
	v_mfma_f32_16x16x32_bf16 v[16:19], v[194:197], v[232:235], v[16:19]
	v_mfma_f32_16x16x32_bf16 v[12:15], v[208:211], v[224:227], v[12:15]
	v_mfma_f32_16x16x32_bf16 v[8:11], v[208:211], v[232:235], v[8:11]
	v_mfma_f32_16x16x32_bf16 v[4:7], v[216:219], v[224:227], v[4:7]
	v_mfma_f32_16x16x32_bf16 v[0:3], v[216:219], v[232:235], v[0:3]
	s_setprio 0
	s_barrier
	ds_read_b128 v[164:167], v149
	ds_read_b128 v[168:171], v149 offset:1024
	ds_read_b128 v[172:175], v149 offset:2048
	ds_read_b128 v[176:179], v149 offset:3072
	v_lshl_add_u64 v[198:199], v[130:131], 0, s[44:45]
	s_add_i32 m0, s99, 0x4000
	ds_read_b128 v[180:183], v143 offset:32768
	ds_read_b128 v[184:187], v143 offset:33792
	ds_read_b128 v[188:191], v142 offset:32768
	ds_read_b128 v[194:197], v142 offset:33792
	ds_read_b128 v[202:205], v141 offset:32768
	ds_read_b128 v[208:211], v141 offset:33792
	ds_read_b128 v[212:215], v140 offset:32768
	ds_read_b128 v[216:219], v140 offset:33792
	global_load_lds_dwordx4 v[198:199], off
	s_add_i32 m0, s99, 0x6000
	v_lshl_add_u64 v[198:199], v[130:131], 0, s[46:47]
	global_load_lds_dwordx4 v[198:199], off
	s_waitcnt lgkmcnt(8)
	s_barrier
	s_setprio 1
	s_waitcnt lgkmcnt(0)
	v_mfma_f32_16x16x32_bf16 v[124:127], v[180:183], v[164:167], v[124:127]
	v_mfma_f32_16x16x32_bf16 v[120:123], v[180:183], v[172:175], v[120:123]
	v_mfma_f32_16x16x32_bf16 v[116:119], v[188:191], v[164:167], v[116:119]
	v_mfma_f32_16x16x32_bf16 v[112:115], v[188:191], v[172:175], v[112:115]
	v_mfma_f32_16x16x32_bf16 v[108:111], v[202:205], v[164:167], v[108:111]
	v_mfma_f32_16x16x32_bf16 v[104:107], v[202:205], v[172:175], v[104:107]
	v_mfma_f32_16x16x32_bf16 v[100:103], v[212:215], v[164:167], v[100:103]
	v_mfma_f32_16x16x32_bf16 v[96:99], v[212:215], v[172:175], v[96:99]
	v_mfma_f32_16x16x32_bf16 v[124:127], v[184:187], v[168:171], v[124:127]
	v_mfma_f32_16x16x32_bf16 v[120:123], v[184:187], v[176:179], v[120:123]
	v_mfma_f32_16x16x32_bf16 v[116:119], v[194:197], v[168:171], v[116:119]
	v_mfma_f32_16x16x32_bf16 v[112:115], v[194:197], v[176:179], v[112:115]
	v_mfma_f32_16x16x32_bf16 v[108:111], v[208:211], v[168:171], v[108:111]
	v_mfma_f32_16x16x32_bf16 v[104:107], v[208:211], v[176:179], v[104:107]
	v_mfma_f32_16x16x32_bf16 v[100:103], v[216:219], v[168:171], v[100:103]
	v_mfma_f32_16x16x32_bf16 v[96:99], v[216:219], v[176:179], v[96:99]
	s_setprio 0
	s_barrier
	v_lshl_add_u64 v[198:199], v[132:133], 0, s[48:49]
	s_add_i32 m0, s99, 0x18000
	ds_read_b128 v[220:223], v146
	ds_read_b128 v[224:227], v146 offset:1024
	ds_read_b128 v[228:231], v146 offset:2048
	ds_read_b128 v[232:235], v146 offset:3072
	global_load_lds_dwordx4 v[198:199], off
	s_add_i32 m0, s99, 0x1a000
	v_lshl_add_u64 v[198:199], v[132:133], 0, s[50:51]
	global_load_lds_dwordx4 v[198:199], off
	s_barrier
	s_setprio 1
	s_waitcnt lgkmcnt(0)
	v_mfma_f32_16x16x32_bf16 v[92:95], v[180:183], v[220:223], v[92:95]
	v_mfma_f32_16x16x32_bf16 v[88:91], v[180:183], v[228:231], v[88:91]
	v_mfma_f32_16x16x32_bf16 v[84:87], v[188:191], v[220:223], v[84:87]
	v_mfma_f32_16x16x32_bf16 v[80:83], v[188:191], v[228:231], v[80:83]
	v_mfma_f32_16x16x32_bf16 v[76:79], v[202:205], v[220:223], v[76:79]
	v_mfma_f32_16x16x32_bf16 v[72:75], v[202:205], v[228:231], v[72:75]
	v_mfma_f32_16x16x32_bf16 v[68:71], v[212:215], v[220:223], v[68:71]
	v_mfma_f32_16x16x32_bf16 v[64:67], v[212:215], v[228:231], v[64:67]
	v_mfma_f32_16x16x32_bf16 v[92:95], v[184:187], v[224:227], v[92:95]
	v_mfma_f32_16x16x32_bf16 v[88:91], v[184:187], v[232:235], v[88:91]
	v_mfma_f32_16x16x32_bf16 v[84:87], v[194:197], v[224:227], v[84:87]
	v_mfma_f32_16x16x32_bf16 v[80:83], v[194:197], v[232:235], v[80:83]
	v_mfma_f32_16x16x32_bf16 v[76:79], v[208:211], v[224:227], v[76:79]
	v_mfma_f32_16x16x32_bf16 v[72:75], v[208:211], v[232:235], v[72:75]
	v_mfma_f32_16x16x32_bf16 v[68:71], v[216:219], v[224:227], v[68:71]
	v_mfma_f32_16x16x32_bf16 v[64:67], v[216:219], v[232:235], v[64:67]
	s_setprio 0
	v_lshl_add_u64 v[198:199], v[130:131], 0, s[50:51]
	s_add_i32 m0, s99, 0x8000
	s_barrier
	ds_read_b128 v[180:183], v143 offset:49152
	ds_read_b128 v[184:187], v143 offset:50176
	ds_read_b128 v[188:191], v142 offset:49152
	ds_read_b128 v[194:197], v142 offset:50176
	ds_read_b128 v[202:205], v141 offset:49152
	ds_read_b128 v[208:211], v141 offset:50176
	ds_read_b128 v[212:215], v140 offset:49152
	ds_read_b128 v[216:219], v140 offset:50176
	global_load_lds_dwordx4 v[198:199], off
	s_add_i32 m0, s99, 0xa000
	s_nop 0
	global_load_lds_dwordx4 v[130:131], off
	s_barrier
; #define STAGE_A(P, hf, kt) do { if constexpr (ABLK) { const bf16* _gp = A + ((long)(brow >> 8) * nt + (kt)) * 16384 + (hf) * 8192; GLDS2(_gp, 4096, offA, P); } \
;     else { const bf16* _gp = A + (long)(brow + (hf) * HALF) * lda + (long)(kt) * BK; GLDS2(_gp, 64 * (long)lda, offA, P); } } while (0)
; #define STAGE_B(P, hf, kt) do { const bf16* _gp = Bt + (long)(bcol + (hf) * 2) * ldb + (long)(kt) * BK; GLDS2(_gp, 128 * (long)ldb, offB, P); } while (0)
; #define LDA(dst, b, h) for (int m = 0; m < 4; ++m) for (int k = 0; k < 2; ++k) \
;     dst[m][k] = *reinterpret_cast<const bf16x8*>((char*)SA(b, h) + lds_byte(wr * 64 + m * 16 + fr, k * 32 + fq * 8))
; #define LDB(dst, b, h) for (int n = 0; n < 2; ++n) for (int k = 0; k < 2; ++k) \
;     dst[n][k] = *reinterpret_cast<const bf16x8*>((char*)SB(b, h) + lds_byte(wc * 32 + n * 16 + fr, k * 32 + fq * 8))
; #define MMA(ai, bj, At, Bt_) do { __builtin_amdgcn_s_setprio(1); \
;     for (int m = 0; m < 4; ++m) for (int n = 0; n < 2; ++n) for (int k = 0; k < 2; ++k) \
;       acc[ai][bj][m][n] = __builtin_amdgcn_mfma_f32_16x16x32_bf16(At[m][k], Bt_[n][k], acc[ai][bj][m][n], 0, 0, 0); \
;     __builtin_amdgcn_s_setprio(0); } while (0)
; #define WAIT_V(n) asm volatile("s_waitcnt vmcnt(" #n ")" ::: "memory")
; #define WAIT_L(n) asm volatile("s_waitcnt lgkmcnt(" #n ")" ::: "memory")
; #define BAR __builtin_amdgcn_s_barrier()
; #define SCHED __builtin_amdgcn_sched_barrier(0)
; template <bool ABLK, class Epi>
; __device__ __forceinline__ void gemm_tile(const bf16* __restrict__ A, int lda, const bf16* __restrict__ Bt, int ldb, int K,
;                                           int brow, int bcol, bf16* shm, const Epi& epi, int wv) {
;     ...
;     BAR; MMA(1, 0, At, B0); BAR; SCHED;
;     STAGE_B(SB(1, 1), 1, t + 3);
;     WAIT_V(6); BAR; MMA(1, 1, At, B1); BAR;
;   }
;   { LDB(B0, 0, 0); LDA(At, 0, 0); STAGE_A(SA(1, 1), 1, nt - 1);
;     BAR; WAIT_L(0); MMA(0, 0, At, B0); BAR;
;     LDB(B1, 0, 1); BAR; WAIT_L(0); MMA(0, 1, At, B1); BAR;
;     LDA(At, 0, 1); WAIT_V(4); BAR; WAIT_L(0); MMA(1, 0, At, B0); MMA(1, 1, At, B1); BAR; }
	s_setprio 1
	s_waitcnt lgkmcnt(0)
	v_mfma_f32_16x16x32_bf16 v[60:63], v[180:183], v[164:167], v[60:63]
	v_mfma_f32_16x16x32_bf16 v[56:59], v[180:183], v[172:175], v[56:59]
	v_mfma_f32_16x16x32_bf16 v[52:55], v[188:191], v[164:167], v[52:55]
	v_mfma_f32_16x16x32_bf16 v[48:51], v[188:191], v[172:175], v[48:51]
	v_mfma_f32_16x16x32_bf16 v[44:47], v[202:205], v[164:167], v[44:47]
	v_mfma_f32_16x16x32_bf16 v[40:43], v[202:205], v[172:175], v[40:43]
	v_mfma_f32_16x16x32_bf16 v[36:39], v[212:215], v[164:167], v[36:39]
	v_mfma_f32_16x16x32_bf16 v[32:35], v[212:215], v[172:175], v[32:35]
	v_mfma_f32_16x16x32_bf16 v[60:63], v[184:187], v[168:171], v[60:63]
	v_mfma_f32_16x16x32_bf16 v[56:59], v[184:187], v[176:179], v[56:59]
	v_mfma_f32_16x16x32_bf16 v[52:55], v[194:197], v[168:171], v[52:55]
	v_mfma_f32_16x16x32_bf16 v[48:51], v[194:197], v[176:179], v[48:51]
	v_mfma_f32_16x16x32_bf16 v[44:47], v[208:211], v[168:171], v[44:47]
	v_mfma_f32_16x16x32_bf16 v[40:43], v[208:211], v[176:179], v[40:43]
	v_mfma_f32_16x16x32_bf16 v[36:39], v[216:219], v[168:171], v[36:39]
	v_mfma_f32_16x16x32_bf16 v[32:35], v[216:219], v[176:179], v[32:35]
	s_setprio 0
	s_barrier
	s_add_i32 m0, s99, 0x1c000
	v_lshl_add_u64 v[164:165], v[132:133], 0, s[52:53]
	global_load_lds_dwordx4 v[164:165], off
	s_add_i32 m0, s99, 0x1e000
	s_nop 0
	global_load_lds_dwordx4 v[132:133], off
	s_waitcnt vmcnt(6)
	s_barrier
	s_setprio 1
	v_mfma_f32_16x16x32_bf16 v[28:31], v[180:183], v[220:223], v[28:31]
	v_mfma_f32_16x16x32_bf16 v[24:27], v[180:183], v[228:231], v[24:27]
	v_mfma_f32_16x16x32_bf16 v[20:23], v[188:191], v[220:223], v[20:23]
	v_mfma_f32_16x16x32_bf16 v[16:19], v[188:191], v[228:231], v[16:19]
	v_mfma_f32_16x16x32_bf16 v[12:15], v[202:205], v[220:223], v[12:15]
	v_mfma_f32_16x16x32_bf16 v[8:11], v[202:205], v[228:231], v[8:11]
	v_mfma_f32_16x16x32_bf16 v[4:7], v[212:215], v[220:223], v[4:7]
	v_mfma_f32_16x16x32_bf16 v[0:3], v[212:215], v[228:231], v[0:3]
	v_mfma_f32_16x16x32_bf16 v[28:31], v[184:187], v[224:227], v[28:31]
	v_mfma_f32_16x16x32_bf16 v[24:27], v[184:187], v[232:235], v[24:27]
	v_mfma_f32_16x16x32_bf16 v[20:23], v[194:197], v[224:227], v[20:23]
	v_mfma_f32_16x16x32_bf16 v[16:19], v[194:197], v[232:235], v[16:19]
	v_mfma_f32_16x16x32_bf16 v[12:15], v[208:211], v[224:227], v[12:15]
	v_mfma_f32_16x16x32_bf16 v[8:11], v[208:211], v[232:235], v[8:11]
	v_mfma_f32_16x16x32_bf16 v[4:7], v[216:219], v[224:227], v[4:7]
	v_mfma_f32_16x16x32_bf16 v[0:3], v[216:219], v[232:235], v[0:3]
	s_setprio 0
	s_add_i32 s33, s33, 2
	v_lshl_add_u64 v[130:131], v[130:131], 0, s[54:55]
	s_cmp_lt_u32 s33, 28
	v_lshl_add_u64 v[132:133], v[132:133], 0, s[56:57]
	s_barrier
	s_cbranch_scc1 .LBB0_977
	v_readfirstlane_b32 s2, v162
	v_lshl_add_u64 v[144:145], v[128:129], 0, s[58:59]
	s_mov_b32 m0, s2
	v_readfirstlane_b32 s2, v163
	ds_read_b128 v[130:133], v161
	ds_read_b128 v[150:153], v161 offset:1024
	ds_read_b128 v[154:157], v161 offset:2048
	ds_read_b128 v[164:167], v161 offset:3072
	ds_read_b128 v[168:171], v143
	ds_read_b128 v[172:175], v143 offset:1024
	ds_read_b128 v[176:179], v142
	ds_read_b128 v[180:183], v142 offset:1024
	ds_read_b128 v[184:187], v141
	ds_read_b128 v[188:191], v141 offset:1024
	ds_read_b128 v[194:197], v140
	ds_read_b128 v[202:205], v140 offset:1024
	global_load_lds_dwordx4 v[144:145], off
	v_lshl_add_u64 v[128:129], v[128:129], 0, s[60:61]
	s_mov_b32 m0, s2
	s_nop 0
	global_load_lds_dwordx4 v[128:129], off
	s_barrier
	s_waitcnt lgkmcnt(0)
	s_setprio 1
	s_waitcnt lgkmcnt(0)
	v_mfma_f32_16x16x32_bf16 v[124:127], v[168:171], v[130:133], v[124:127]
	v_mfma_f32_16x16x32_bf16 v[116:119], v[176:179], v[130:133], v[116:119]
	v_mfma_f32_16x16x32_bf16 v[108:111], v[184:187], v[130:133], v[108:111]
	v_mfma_f32_16x16x32_bf16 v[104:107], v[184:187], v[154:157], v[104:107]
	v_mfma_f32_16x16x32_bf16 v[100:103], v[194:197], v[130:133], v[100:103]
	v_mfma_f32_16x16x32_bf16 v[96:99], v[194:197], v[154:157], v[96:99]
	v_mfma_f32_16x16x32_bf16 v[124:127], v[172:175], v[150:153], v[124:127]
	v_mfma_f32_16x16x32_bf16 v[120:123], v[168:171], v[154:157], v[120:123]
	v_mfma_f32_16x16x32_bf16 v[116:119], v[180:183], v[150:153], v[116:119]
	v_mfma_f32_16x16x32_bf16 v[112:115], v[176:179], v[154:157], v[112:115]
	v_mfma_f32_16x16x32_bf16 v[108:111], v[188:191], v[150:153], v[108:111]
	v_mfma_f32_16x16x32_bf16 v[104:107], v[188:191], v[164:167], v[104:107]
	v_mfma_f32_16x16x32_bf16 v[100:103], v[202:205], v[150:153], v[100:103]
	v_mfma_f32_16x16x32_bf16 v[96:99], v[202:205], v[164:167], v[96:99]
	v_mfma_f32_16x16x32_bf16 v[208:211], v[172:175], v[164:167], v[120:123]
	v_mfma_f32_16x16x32_bf16 v[212:215], v[180:183], v[164:167], v[112:115]
	s_setprio 0
	s_barrier
	s_nop 0
	ds_read_b128 v[112:115], v160
	ds_read_b128 v[120:123], v160 offset:1024
	ds_read_b128 v[216:219], v160 offset:2048
	ds_read_b128 v[158:161], v160 offset:3072
	s_barrier
	s_waitcnt lgkmcnt(0)
	s_setprio 1
	s_waitcnt lgkmcnt(0)
	v_mfma_f32_16x16x32_bf16 v[84:87], v[176:179], v[112:115], v[84:87]
	v_mfma_f32_16x16x32_bf16 v[80:83], v[176:179], v[216:219], v[80:83]
	v_mfma_f32_16x16x32_bf16 v[92:95], v[168:171], v[112:115], v[92:95]
	v_mfma_f32_16x16x32_bf16 v[88:91], v[168:171], v[216:219], v[88:91]
	v_mfma_f32_16x16x32_bf16 v[84:87], v[180:183], v[120:123], v[84:87]
	v_mfma_f32_16x16x32_bf16 v[80:83], v[180:183], v[158:161], v[80:83]
	v_mfma_f32_16x16x32_bf16 v[76:79], v[184:187], v[112:115], v[76:79]
	v_mfma_f32_16x16x32_bf16 v[72:75], v[184:187], v[216:219], v[72:75]
	v_mfma_f32_16x16x32_bf16 v[68:71], v[194:197], v[112:115], v[68:71]
	v_mfma_f32_16x16x32_bf16 v[64:67], v[194:197], v[216:219], v[64:67]
	v_mfma_f32_16x16x32_bf16 v[220:223], v[172:175], v[120:123], v[92:95]
	v_mfma_f32_16x16x32_bf16 v[168:171], v[172:175], v[158:161], v[88:91]
	v_mfma_f32_16x16x32_bf16 v[172:175], v[188:191], v[120:123], v[76:79]
	v_mfma_f32_16x16x32_bf16 v[176:179], v[188:191], v[158:161], v[72:75]
	v_mfma_f32_16x16x32_bf16 v[180:183], v[202:205], v[120:123], v[68:71]
	v_mfma_f32_16x16x32_bf16 v[184:187], v[202:205], v[158:161], v[64:67]
	s_setprio 0
	s_barrier
; #define LDA(dst, b, h) for (int m = 0; m < 4; ++m) for (int k = 0; k < 2; ++k) \
;     dst[m][k] = *reinterpret_cast<const bf16x8*>((char*)SA(b, h) + lds_byte(wr * 64 + m * 16 + fr, k * 32 + fq * 8))
; #define LDB(dst, b, h) for (int n = 0; n < 2; ++n) for (int k = 0; k < 2; ++k) \
;     dst[n][k] = *reinterpret_cast<const bf16x8*>((char*)SB(b, h) + lds_byte(wc * 32 + n * 16 + fr, k * 32 + fq * 8))
; #define MMA(ai, bj, At, Bt_) do { __builtin_amdgcn_s_setprio(1); \
;     for (int m = 0; m < 4; ++m) for (int n = 0; n < 2; ++n) for (int k = 0; k < 2; ++k) \
;       acc[ai][bj][m][n] = __builtin_amdgcn_mfma_f32_16x16x32_bf16(At[m][k], Bt_[n][k], acc[ai][bj][m][n], 0, 0, 0); \
;     __builtin_amdgcn_s_setprio(0); } while (0)
; #define WAIT_V(n) asm volatile("s_waitcnt vmcnt(" #n ")" ::: "memory")
; #define WAIT_L(n) asm volatile("s_waitcnt lgkmcnt(" #n ")" ::: "memory")
; #define BAR __builtin_amdgcn_s_barrier()
; template <bool ABLK, class Epi>
; __device__ __forceinline__ void gemm_tile(const bf16* __restrict__ A, int lda, const bf16* __restrict__ Bt, int ldb, int K,
;                                           int brow, int bcol, bf16* shm, const Epi& epi, int wv) {
;     ...
;     LDB(B1, 0, 1); BAR; WAIT_L(0); MMA(0, 1, At, B1); BAR;
;     LDA(At, 0, 1); WAIT_V(4); BAR; WAIT_L(0); MMA(1, 0, At, B0); MMA(1, 1, At, B1); BAR; }
;   { LDB(B0, 1, 0); LDA(At, 1, 0); WAIT_V(2); BAR; WAIT_L(0); MMA(0, 0, At, B0); BAR;
	s_nop 0
	ds_read_b128 v[64:67], v143 offset:16384
	ds_read_b128 v[68:71], v143 offset:17408
	ds_read_b128 v[72:75], v142 offset:16384
	ds_read_b128 v[76:79], v142 offset:17408
	ds_read_b128 v[88:91], v141 offset:16384
	ds_read_b128 v[92:95], v141 offset:17408
	ds_read_b128 v[188:191], v140 offset:16384
	ds_read_b128 v[194:197], v140 offset:17408
	s_waitcnt vmcnt(4)
	s_barrier
	s_waitcnt lgkmcnt(0)
	s_setprio 1
	s_waitcnt lgkmcnt(0)
	v_mfma_f32_16x16x32_bf16 v[60:63], v[64:67], v[130:133], v[60:63]
	v_mfma_f32_16x16x32_bf16 v[56:59], v[64:67], v[154:157], v[56:59]
	v_mfma_f32_16x16x32_bf16 v[44:47], v[88:91], v[130:133], v[44:47]
	v_mfma_f32_16x16x32_bf16 v[40:43], v[88:91], v[154:157], v[40:43]
	v_mfma_f32_16x16x32_bf16 v[60:63], v[68:71], v[150:153], v[60:63]
	v_mfma_f32_16x16x32_bf16 v[56:59], v[68:71], v[164:167], v[56:59]
	v_mfma_f32_16x16x32_bf16 v[52:55], v[72:75], v[130:133], v[52:55]
	v_mfma_f32_16x16x32_bf16 v[48:51], v[72:75], v[154:157], v[48:51]
	v_mfma_f32_16x16x32_bf16 v[44:47], v[92:95], v[150:153], v[44:47]
	v_mfma_f32_16x16x32_bf16 v[40:43], v[92:95], v[164:167], v[40:43]
	v_mfma_f32_16x16x32_bf16 v[36:39], v[188:191], v[130:133], v[36:39]
	v_mfma_f32_16x16x32_bf16 v[32:35], v[188:191], v[154:157], v[32:35]
	v_mfma_f32_16x16x32_bf16 v[202:205], v[76:79], v[150:153], v[52:55]
	v_mfma_f32_16x16x32_bf16 v[224:227], v[76:79], v[164:167], v[48:51]
	v_mfma_f32_16x16x32_bf16 v[128:131], v[194:197], v[150:153], v[36:39]
	v_mfma_f32_16x16x32_bf16 v[150:153], v[194:197], v[164:167], v[32:35]
	s_setprio 0
	s_setprio 1
	v_mfma_f32_16x16x32_bf16 v[28:31], v[64:67], v[112:115], v[28:31]
	v_mfma_f32_16x16x32_bf16 v[24:27], v[64:67], v[216:219], v[24:27]
	v_mfma_f32_16x16x32_bf16 v[12:15], v[88:91], v[112:115], v[12:15]
	v_mfma_f32_16x16x32_bf16 v[8:11], v[88:91], v[216:219], v[8:11]
	v_mfma_f32_16x16x32_bf16 v[28:31], v[68:71], v[120:123], v[28:31]
	v_mfma_f32_16x16x32_bf16 v[24:27], v[68:71], v[158:161], v[24:27]
	v_mfma_f32_16x16x32_bf16 v[20:23], v[72:75], v[112:115], v[20:23]
	v_mfma_f32_16x16x32_bf16 v[16:19], v[72:75], v[216:219], v[16:19]
	v_mfma_f32_16x16x32_bf16 v[12:15], v[92:95], v[120:123], v[12:15]
	v_mfma_f32_16x16x32_bf16 v[8:11], v[92:95], v[158:161], v[8:11]
	v_mfma_f32_16x16x32_bf16 v[4:7], v[188:191], v[112:115], v[4:7]
	v_mfma_f32_16x16x32_bf16 v[0:3], v[188:191], v[216:219], v[0:3]
	v_mfma_f32_16x16x32_bf16 v[154:157], v[76:79], v[120:123], v[20:23]
	v_mfma_f32_16x16x32_bf16 v[162:165], v[76:79], v[158:161], v[16:19]
	v_mfma_f32_16x16x32_bf16 v[228:231], v[194:197], v[120:123], v[4:7]
	v_mfma_f32_16x16x32_bf16 v[158:161], v[194:197], v[158:161], v[0:3]
	s_setprio 0
	s_barrier
	s_nop 1
	ds_read_b128 v[0:3], v149
	ds_read_b128 v[4:7], v149 offset:1024
	ds_read_b128 v[188:191], v149 offset:2048
	ds_read_b128 v[194:197], v149 offset:3072
	ds_read_b128 v[16:19], v143 offset:32768
	ds_read_b128 v[20:23], v143 offset:33792
	ds_read_b128 v[32:35], v142 offset:32768
	ds_read_b128 v[36:39], v142 offset:33792
	ds_read_b128 v[48:51], v141 offset:32768
	ds_read_b128 v[52:55], v141 offset:33792
	ds_read_b128 v[216:219], v140 offset:32768
	ds_read_b128 v[232:235], v140 offset:33792
	s_waitcnt vmcnt(2)
	s_barrier
	s_waitcnt lgkmcnt(0)
	s_setprio 1
	s_waitcnt lgkmcnt(0)
	v_mfma_f32_16x16x32_bf16 v[64:67], v[16:19], v[0:3], v[124:127]
	v_mfma_f32_16x16x32_bf16 v[120:123], v[20:23], v[4:7], v[64:67]
	v_mfma_f32_16x16x32_bf16 v[64:67], v[16:19], v[188:191], v[208:211]
	v_mfma_f32_16x16x32_bf16 v[112:115], v[20:23], v[194:197], v[64:67]
	v_mfma_f32_16x16x32_bf16 v[64:67], v[32:35], v[0:3], v[116:119]
	v_mfma_f32_16x16x32_bf16 v[88:91], v[36:39], v[4:7], v[64:67]
	v_mfma_f32_16x16x32_bf16 v[64:67], v[32:35], v[188:191], v[212:215]
	v_mfma_f32_16x16x32_bf16 v[92:95], v[36:39], v[194:197], v[64:67]
	v_mfma_f32_16x16x32_bf16 v[64:67], v[48:51], v[0:3], v[108:111]
	v_mfma_f32_16x16x32_bf16 v[72:75], v[52:55], v[4:7], v[64:67]
	v_mfma_f32_16x16x32_bf16 v[64:67], v[48:51], v[188:191], v[104:107]
	v_mfma_f32_16x16x32_bf16 v[76:79], v[52:55], v[194:197], v[64:67]
	v_mfma_f32_16x16x32_bf16 v[64:67], v[216:219], v[0:3], v[100:103]
	v_mfma_f32_16x16x32_bf16 v[68:71], v[216:219], v[188:191], v[96:99]
	v_mfma_f32_16x16x32_bf16 v[64:67], v[232:235], v[4:7], v[64:67]
	v_mfma_f32_16x16x32_bf16 v[68:71], v[232:235], v[194:197], v[68:71]
	s_setprio 0
	s_barrier
; #define LDA(dst, b, h) for (int m = 0; m < 4; ++m) for (int k = 0; k < 2; ++k) \
;     dst[m][k] = *reinterpret_cast<const bf16x8*>((char*)SA(b, h) + lds_byte(wr * 64 + m * 16 + fr, k * 32 + fq * 8))
; #define LDB(dst, b, h) for (int n = 0; n < 2; ++n) for (int k = 0; k < 2; ++k) \
;     dst[n][k] = *reinterpret_cast<const bf16x8*>((char*)SB(b, h) + lds_byte(wc * 32 + n * 16 + fr, k * 32 + fq * 8))
; #define MMA(ai, bj, At, Bt_) do { __builtin_amdgcn_s_setprio(1); \
;     for (int m = 0; m < 4; ++m) for (int n = 0; n < 2; ++n) for (int k = 0; k < 2; ++k) \
;       acc[ai][bj][m][n] = __builtin_amdgcn_mfma_f32_16x16x32_bf16(At[m][k], Bt_[n][k], acc[ai][bj][m][n], 0, 0, 0); \
;     __builtin_amdgcn_s_setprio(0); } while (0)
; #define WAIT_V(n) asm volatile("s_waitcnt vmcnt(" #n ")" ::: "memory")
; #define WAIT_L(n) asm volatile("s_waitcnt lgkmcnt(" #n ")" ::: "memory")
; #define BAR __builtin_amdgcn_s_barrier()
; template <bool ABLK, class Epi>
; __device__ __forceinline__ void gemm_tile(const bf16* __restrict__ A, int lda, const bf16* __restrict__ Bt, int ldb, int K,
;                                           int brow, int bcol, bf16* shm, const Epi& epi, int wv) {
;     ...
;   { LDB(B0, 1, 0); LDA(At, 1, 0); WAIT_V(2); BAR; WAIT_L(0); MMA(0, 0, At, B0); BAR;
;     LDB(B1, 1, 1); WAIT_V(0); BAR; WAIT_L(0); MMA(0, 1, At, B1); BAR;
;     LDA(At, 1, 1); BAR; WAIT_L(0); MMA(1, 0, At, B0); MMA(1, 1, At, B1); BAR; }
;   if (wr == 0) BAR;
	ds_read_b128 v[208:211], v146
	ds_read_b128 v[212:215], v146 offset:1024
	ds_read_b128 v[236:239], v146 offset:2048
	ds_read_b128 v[144:147], v146 offset:3072
	s_waitcnt vmcnt(0)
	s_barrier
	s_waitcnt lgkmcnt(0)
	s_setprio 1
	s_waitcnt lgkmcnt(0)
	v_mfma_f32_16x16x32_bf16 v[96:99], v[16:19], v[208:211], v[220:223]
	v_mfma_f32_16x16x32_bf16 v[16:19], v[16:19], v[236:239], v[168:171]
	v_mfma_f32_16x16x32_bf16 v[116:119], v[20:23], v[144:147], v[16:19]
	v_mfma_f32_16x16x32_bf16 v[16:19], v[32:35], v[208:211], v[84:87]
	v_mfma_f32_16x16x32_bf16 v[104:107], v[36:39], v[212:215], v[16:19]
	v_mfma_f32_16x16x32_bf16 v[16:19], v[32:35], v[236:239], v[80:83]
	v_mfma_f32_16x16x32_bf16 v[108:111], v[36:39], v[144:147], v[16:19]
	v_mfma_f32_16x16x32_bf16 v[16:19], v[48:51], v[208:211], v[172:175]
	v_mfma_f32_16x16x32_bf16 v[124:127], v[20:23], v[212:215], v[96:99]
	v_mfma_f32_16x16x32_bf16 v[96:99], v[52:55], v[212:215], v[16:19]
	v_mfma_f32_16x16x32_bf16 v[16:19], v[48:51], v[236:239], v[176:179]
	v_mfma_f32_16x16x32_bf16 v[100:103], v[52:55], v[144:147], v[16:19]
	v_mfma_f32_16x16x32_bf16 v[16:19], v[216:219], v[208:211], v[180:183]
	v_mfma_f32_16x16x32_bf16 v[80:83], v[232:235], v[212:215], v[16:19]
	v_mfma_f32_16x16x32_bf16 v[16:19], v[216:219], v[236:239], v[184:187]
	v_mfma_f32_16x16x32_bf16 v[84:87], v[232:235], v[144:147], v[16:19]
	s_setprio 0
	s_barrier
	ds_read_b128 v[166:169], v143 offset:49152
	ds_read_b128 v[170:173], v143 offset:50176
	ds_read_b128 v[174:177], v142 offset:49152
	ds_read_b128 v[178:181], v142 offset:50176
	ds_read_b128 v[182:185], v141 offset:49152
	ds_read_b128 v[216:219], v141 offset:50176
	ds_read_b128 v[220:223], v140 offset:49152
	ds_read_b128 v[140:143], v140 offset:50176
	s_barrier
	s_waitcnt lgkmcnt(0)
	s_setprio 1
	s_waitcnt lgkmcnt(0)
	v_mfma_f32_16x16x32_bf16 v[16:19], v[166:169], v[0:3], v[60:63]
	v_mfma_f32_16x16x32_bf16 v[48:51], v[170:173], v[4:7], v[16:19]
	v_mfma_f32_16x16x32_bf16 v[16:19], v[166:169], v[188:191], v[56:59]
	v_mfma_f32_16x16x32_bf16 v[52:55], v[170:173], v[194:197], v[16:19]
	v_mfma_f32_16x16x32_bf16 v[16:19], v[174:177], v[0:3], v[202:205]
	v_mfma_f32_16x16x32_bf16 v[32:35], v[178:181], v[4:7], v[16:19]
	v_mfma_f32_16x16x32_bf16 v[16:19], v[174:177], v[188:191], v[224:227]
	v_mfma_f32_16x16x32_bf16 v[36:39], v[178:181], v[194:197], v[16:19]
	v_mfma_f32_16x16x32_bf16 v[16:19], v[182:185], v[0:3], v[44:47]
	v_mfma_f32_16x16x32_bf16 v[0:3], v[220:223], v[0:3], v[128:131]
	v_mfma_f32_16x16x32_bf16 v[16:19], v[216:219], v[4:7], v[16:19]
	v_mfma_f32_16x16x32_bf16 v[20:23], v[182:185], v[188:191], v[40:43]
	v_mfma_f32_16x16x32_bf16 v[0:3], v[140:143], v[4:7], v[0:3]
	v_mfma_f32_16x16x32_bf16 v[4:7], v[220:223], v[188:191], v[150:153]
	v_mfma_f32_16x16x32_bf16 v[20:23], v[216:219], v[194:197], v[20:23]
	v_mfma_f32_16x16x32_bf16 v[4:7], v[140:143], v[194:197], v[4:7]
	s_setprio 0
	s_setprio 1
	v_mfma_f32_16x16x32_bf16 v[24:27], v[166:169], v[236:239], v[24:27]
	v_mfma_f32_16x16x32_bf16 v[28:31], v[166:169], v[208:211], v[28:31]
	v_mfma_f32_16x16x32_bf16 v[60:63], v[170:173], v[144:147], v[24:27]
	v_mfma_f32_16x16x32_bf16 v[24:27], v[174:177], v[208:211], v[154:157]
	v_mfma_f32_16x16x32_bf16 v[8:11], v[182:185], v[236:239], v[8:11]
	v_mfma_f32_16x16x32_bf16 v[56:59], v[170:173], v[212:215], v[28:31]
	v_mfma_f32_16x16x32_bf16 v[40:43], v[178:181], v[212:215], v[24:27]
	v_mfma_f32_16x16x32_bf16 v[24:27], v[174:177], v[236:239], v[162:165]
	v_mfma_f32_16x16x32_bf16 v[12:15], v[182:185], v[208:211], v[12:15]
	v_mfma_f32_16x16x32_bf16 v[28:31], v[216:219], v[144:147], v[8:11]
	v_mfma_f32_16x16x32_bf16 v[8:11], v[220:223], v[208:211], v[228:231]
	v_mfma_f32_16x16x32_bf16 v[44:47], v[178:181], v[144:147], v[24:27]
	v_mfma_f32_16x16x32_bf16 v[24:27], v[216:219], v[212:215], v[12:15]
	v_mfma_f32_16x16x32_bf16 v[12:15], v[140:143], v[212:215], v[8:11]
	v_mfma_f32_16x16x32_bf16 v[8:11], v[220:223], v[236:239], v[158:161]
	v_mfma_f32_16x16x32_bf16 v[8:11], v[140:143], v[144:147], v[8:11]
	s_setprio 0
	v_cmp_gt_u32_e32 vcc, s83, v135
	s_barrier
	s_and_saveexec_b64 s[66:67], vcc
	s_cbranch_execz .LBB0_973
	s_barrier
	s_branch .LBB0_973

; __device__ __forceinline__ int mytid(int wv) { return (wv << 6) | (int)__builtin_amdgcn_mbcnt_hi(~0u, __builtin_amdgcn_mbcnt_lo(~0u, 0u)); }
; #define STAGE_A(P, hf, kt) do { if constexpr (ABLK) { const bf16* _gp = A + ((long)(brow >> 8) * nt + (kt)) * 16384 + (hf) * 8192; GLDS2(_gp, 4096, offA, P); } \
;     else { const bf16* _gp = A + (long)(brow + (hf) * HALF) * lda + (long)(kt) * BK; GLDS2(_gp, 64 * (long)lda, offA, P); } } while (0)
; #define STAGE_B(P, hf, kt) do { const bf16* _gp = Bt + (long)(bcol + (hf) * 2) * ldb + (long)(kt) * BK; GLDS2(_gp, 128 * (long)ldb, offB, P); } while (0)
; #define WAIT_V(n) asm volatile("s_waitcnt vmcnt(" #n ")" ::: "memory")
; #define BAR __builtin_amdgcn_s_barrier()
; template <bool ABLK, class Epi>
; __device__ __forceinline__ void gemm_tile(const bf16* __restrict__ A, int lda, const bf16* __restrict__ Bt, int ldb, int K,
;                                           int brow, int bcol, bf16* shm, const Epi& epi, int wv) {
;     ...
;   int tid = mytid(wv); asm volatile("" : "+v"(tid));
;   const int wid = tid >> 6, lane = tid & 63, wr = wid >> 2, wc = wid & 3, fr = lane & 15, fq = lane >> 4;
;   f32x4 acc[2][2][4][2] = {};
;   bf16x8 At[4][2], B0[2][2], B1[2][2];
;   const int nt = K / BK;
;   int offA, offB;
;   { int r_, c_; stage_rc(tid * 16, r_, c_); offA = ABLK ? r_ * 64 + c_ : r_ * lda + c_;
;     offB = ((r_ >> 5) * 64 + (r_ & 15) * 4 + ((r_ >> 4) & 1)) * ldb + c_; }
;   STAGE_B(SB(0, 0), 0, 0); STAGE_A(SA(0, 0), 0, 0);
;   STAGE_B(SB(0, 1), 1, 0); STAGE_A(SA(0, 1), 1, 0);
;   if (wr == 1) BAR;
;   WAIT_V(4); BAR;
;   STAGE_B(SB(1, 0), 0, 1); STAGE_A(SA(1, 0), 0, 1); STAGE_B(SB(1, 1), 1, 1);
;   WAIT_V(6); BAR;
; __global__ __launch_bounds__(NTHR, 2) void mega(Params p_unused) {
;     ...
;   gemm_phase<true>(P_H, DM, P_Wgu1, DM, TOK, 2 * DFF, DM, smem, EpiSwiglu{ACT}, wv);
.LBB0_1058:
	s_or_b64 exec, exec, s[6:7]
	s_mov_b64 s[6:7], s[90:91]
	s_mov_b64 s[8:9], s[90:91]
	s_mov_b64 s[10:11], s[90:91]
	s_andn2_b64 vcc, exec, s[28:29]
	s_barrier
	s_barrier
	s_cbranch_vccnz .LBB0_1068
	s_load_dwordx2 s[12:13], s[6:7], 0xa8
	s_load_dwordx2 s[14:15], s[8:9], 0xa8
	s_load_dwordx2 s[16:17], s[10:11], 0xa8
	s_mov_b32 s24, 0xffff2000
	s_mov_b32 s26, 0xffff4000
	s_waitcnt lgkmcnt(0)
	s_add_u32 s1, s12, 0xba40000
	s_addc_u32 s3, s13, 0
	s_add_u32 s70, s14, 0x5e40000
	s_addc_u32 s71, s15, 0
	s_add_u32 s6, s16, 0x17a40000
	s_addc_u32 s7, s17, 0
	s_add_u32 s72, s12, 0xba5a000
	s_addc_u32 s73, s13, 0
	s_add_u32 s74, s14, 0x5ec2180
	s_mov_b32 s28, 0xfff7df80
	s_movk_i32 s30, 0xdf80
	s_mov_b32 s34, 0xffff6000
	s_movk_i32 s36, 0x8000
	s_mov_b32 s38, 0xfff7ff80
	s_movk_i32 s40, 0xff80
	s_movk_i32 s42, 0xa000
	s_movk_i32 s44, 0xc000
	s_mov_b32 s46, 0xfff7e000
	s_movk_i32 s48, 0xe000
	s_mov_b32 s50, 0xfff80000
	s_movk_i32 s0, 0x421
	s_addc_u32 s75, s15, 0
	s_add_i32 s76, 0, 0x10000
	s_mov_b64 s[8:9], 0x80000
	s_mov_b64 s[10:11], 0x2000
	s_add_i32 s77, 0, 0x14000
	s_mov_b64 s[12:13], 0x4000
	s_mov_b64 s[14:15], 0x6000
	s_mov_b64 s[16:17], 0x80
	s_add_i32 s78, 0, 0x18000
	s_mov_b64 s[18:19], 0x80080
	s_mov_b64 s[20:21], 0x8000
	s_mov_b64 s[22:23], 0xa000
	s_add_i32 s79, 0, 0x1c000
	s_movk_i32 s80, 0x3c0
	s_movk_i32 s81, 0x1000
	s_mov_b32 s25, -1
	s_mov_b32 s27, -1
	s_mov_b32 s29, -1
	s_mov_b32 s31, -1
	s_mov_b32 s35, -1
	s_mov_b32 s37, -1
	s_mov_b32 s39, -1
	s_mov_b32 s41, -1
	s_mov_b32 s43, -1
	s_mov_b32 s45, -1
	s_mov_b32 s47, -1
	s_mov_b32 s49, -1
	s_mov_b32 s51, -1
	s_mov_b64 s[52:53], 0x10000
	s_mov_b64 s[54:55], 0x100
	s_mov_b64 s[56:57], 0xfc000
	s_mov_b64 s[58:59], 0xfe000
	s_movk_i32 s82, 0x100
	v_mov_b32_e32 v129, 0
	s_movk_i32 s83, 0x7c
	v_mov_b32_e32 v136, 1
	s_mov_b32 s84, s89
	v_lshlrev_b32_e32 v254, 4, v192
	s_nop 0
	v_readfirstlane_b32 s99, v254
	s_branch .LBB0_1061

; #define STAGE_A(P, hf, kt) do { if constexpr (ABLK) { const bf16* _gp = A + ((long)(brow >> 8) * nt + (kt)) * 16384 + (hf) * 8192; GLDS2(_gp, 4096, offA, P); } \
;     else { const bf16* _gp = A + (long)(brow + (hf) * HALF) * lda + (long)(kt) * BK; GLDS2(_gp, 64 * (long)lda, offA, P); } } while (0)
; #define STAGE_B(P, hf, kt) do { const bf16* _gp = Bt + (long)(bcol + (hf) * 2) * ldb + (long)(kt) * BK; GLDS2(_gp, 128 * (long)ldb, offB, P); } while (0)
; #define LDA(dst, b, h) for (int m = 0; m < 4; ++m) for (int k = 0; k < 2; ++k) \
;     dst[m][k] = *reinterpret_cast<const bf16x8*>((char*)SA(b, h) + lds_byte(wr * 64 + m * 16 + fr, k * 32 + fq * 8))
; #define LDB(dst, b, h) for (int n = 0; n < 2; ++n) for (int k = 0; k < 2; ++k) \
;     dst[n][k] = *reinterpret_cast<const bf16x8*>((char*)SB(b, h) + lds_byte(wc * 32 + n * 16 + fr, k * 32 + fq * 8))
; #define MMA(ai, bj, At, Bt_) do { __builtin_amdgcn_s_setprio(1); \
;     for (int m = 0; m < 4; ++m) for (int n = 0; n < 2; ++n) for (int k = 0; k < 2; ++k) \
;       acc[ai][bj][m][n] = __builtin_amdgcn_mfma_f32_16x16x32_bf16(At[m][k], Bt_[n][k], acc[ai][bj][m][n], 0, 0, 0); \
;     __builtin_amdgcn_s_setprio(0); } while (0)
; #define WAIT_V(n) asm volatile("s_waitcnt vmcnt(" #n ")" ::: "memory")
; #define WAIT_L(n) asm volatile("s_waitcnt lgkmcnt(" #n ")" ::: "memory")
; #define BAR __builtin_amdgcn_s_barrier()
; #define SCHED __builtin_amdgcn_sched_barrier(0)
; template <bool ABLK, class Epi>
; __device__ __forceinline__ void gemm_tile(const bf16* __restrict__ A, int lda, const bf16* __restrict__ Bt, int ldb, int K,
;                                           int brow, int bcol, bf16* shm, const Epi& epi, int wv) {
;     ...
;   for (int t = 0; t < nt - 2; t += 2) {
;     LDB(B0, 0, 0); SCHED; LDA(At, 0, 0); STAGE_A(SA(1, 1), 1, t + 1);
;     WAIT_L(8); BAR; MMA(0, 0, At, B0); BAR; SCHED;
;     LDB(B1, 0, 1); STAGE_B(SB(0, 0), 0, t + 2);
;     BAR; MMA(0, 1, At, B1); BAR;
;     LDA(At, 0, 1); STAGE_A(SA(0, 0), 0, t + 2);
;     BAR; MMA(1, 0, At, B0); BAR; SCHED;
;     STAGE_B(SB(0, 1), 1, t + 2);
;     WAIT_V(6); BAR; MMA(1, 1, At, B1); BAR;
.LBB0_1064:
	ds_read_b128 v[166:169], v162
	ds_read_b128 v[170:173], v162 offset:1024
	ds_read_b128 v[174:177], v162 offset:2048
	ds_read_b128 v[178:181], v162 offset:3072
	v_add_u32_e32 v163, 0xc000, v148
	v_lshl_add_u64 v[164:165], v[132:133], 0, s[24:25]
	s_add_i32 m0, s99, 0xc000
	ds_read_b128 v[182:185], v144
	ds_read_b128 v[186:189], v144 offset:1024
	ds_read_b128 v[194:197], v143
	ds_read_b128 v[202:205], v143 offset:1024
	ds_read_b128 v[208:211], v142
	ds_read_b128 v[212:215], v142 offset:1024
	ds_read_b128 v[216:219], v141
	ds_read_b128 v[220:223], v141 offset:1024
	global_load_lds_dwordx4 v[164:165], off
	v_add_u32_e32 v164, 0xe000, v148
	s_add_i32 m0, s99, 0xe000
	v_lshl_add_u64 v[190:191], v[132:133], 0, s[26:27]
	global_load_lds_dwordx4 v[190:191], off
	s_waitcnt lgkmcnt(8)
	s_barrier
	s_setprio 1
	s_waitcnt lgkmcnt(0)
	v_mfma_f32_16x16x32_bf16 v[124:127], v[182:185], v[166:169], v[124:127]
	v_mfma_f32_16x16x32_bf16 v[120:123], v[182:185], v[174:177], v[120:123]
	v_mfma_f32_16x16x32_bf16 v[116:119], v[194:197], v[166:169], v[116:119]
	v_mfma_f32_16x16x32_bf16 v[112:115], v[194:197], v[174:177], v[112:115]
	v_mfma_f32_16x16x32_bf16 v[108:111], v[208:211], v[166:169], v[108:111]
	v_mfma_f32_16x16x32_bf16 v[104:107], v[208:211], v[174:177], v[104:107]
	v_mfma_f32_16x16x32_bf16 v[100:103], v[216:219], v[166:169], v[100:103]
	v_mfma_f32_16x16x32_bf16 v[96:99], v[216:219], v[174:177], v[96:99]
	v_mfma_f32_16x16x32_bf16 v[124:127], v[186:189], v[170:173], v[124:127]
	v_mfma_f32_16x16x32_bf16 v[120:123], v[186:189], v[178:181], v[120:123]
	v_mfma_f32_16x16x32_bf16 v[116:119], v[202:205], v[170:173], v[116:119]
	v_mfma_f32_16x16x32_bf16 v[112:115], v[202:205], v[178:181], v[112:115]
	v_mfma_f32_16x16x32_bf16 v[108:111], v[212:215], v[170:173], v[108:111]
	v_mfma_f32_16x16x32_bf16 v[104:107], v[212:215], v[178:181], v[104:107]
	v_mfma_f32_16x16x32_bf16 v[100:103], v[220:223], v[170:173], v[100:103]
	v_mfma_f32_16x16x32_bf16 v[96:99], v[220:223], v[178:181], v[96:99]
	s_setprio 0
	s_barrier
	v_lshl_add_u64 v[190:191], v[134:135], 0, s[28:29]
	s_add_i32 m0, s99, 0x10000
	ds_read_b128 v[224:227], v161
	ds_read_b128 v[228:231], v161 offset:1024
	ds_read_b128 v[232:235], v161 offset:2048
	ds_read_b128 v[236:239], v161 offset:3072
	global_load_lds_dwordx4 v[190:191], off
	s_add_i32 m0, s99, 0x12000
	v_lshl_add_u64 v[190:191], v[134:135], 0, s[30:31]
	global_load_lds_dwordx4 v[190:191], off
	s_barrier
	s_setprio 1
	s_waitcnt lgkmcnt(0)
	v_mfma_f32_16x16x32_bf16 v[92:95], v[182:185], v[224:227], v[92:95]
	v_mfma_f32_16x16x32_bf16 v[88:91], v[182:185], v[232:235], v[88:91]
	v_mfma_f32_16x16x32_bf16 v[84:87], v[194:197], v[224:227], v[84:87]
	v_mfma_f32_16x16x32_bf16 v[80:83], v[194:197], v[232:235], v[80:83]
	v_mfma_f32_16x16x32_bf16 v[76:79], v[208:211], v[224:227], v[76:79]
	v_mfma_f32_16x16x32_bf16 v[72:75], v[208:211], v[232:235], v[72:75]
	v_mfma_f32_16x16x32_bf16 v[68:71], v[216:219], v[224:227], v[68:71]
	v_mfma_f32_16x16x32_bf16 v[64:67], v[216:219], v[232:235], v[64:67]
	v_mfma_f32_16x16x32_bf16 v[92:95], v[186:189], v[228:231], v[92:95]
	v_mfma_f32_16x16x32_bf16 v[88:91], v[186:189], v[236:239], v[88:91]
	v_mfma_f32_16x16x32_bf16 v[84:87], v[202:205], v[228:231], v[84:87]
	v_mfma_f32_16x16x32_bf16 v[80:83], v[202:205], v[236:239], v[80:83]
	v_mfma_f32_16x16x32_bf16 v[76:79], v[212:215], v[228:231], v[76:79]
	v_mfma_f32_16x16x32_bf16 v[72:75], v[212:215], v[236:239], v[72:75]
	v_mfma_f32_16x16x32_bf16 v[68:71], v[220:223], v[228:231], v[68:71]
	v_mfma_f32_16x16x32_bf16 v[64:67], v[220:223], v[236:239], v[64:67]
	s_setprio 0
	v_lshl_add_u64 v[190:191], v[132:133], 0, s[34:35]
	s_add_i32 m0, s99, 0x0
	s_barrier
	ds_read_b128 v[182:185], v144 offset:16384
	ds_read_b128 v[186:189], v144 offset:17408
	ds_read_b128 v[194:197], v143 offset:16384
	ds_read_b128 v[202:205], v143 offset:17408
	ds_read_b128 v[208:211], v142 offset:16384
	ds_read_b128 v[212:215], v142 offset:17408
	ds_read_b128 v[216:219], v141 offset:16384
	ds_read_b128 v[220:223], v141 offset:17408
	global_load_lds_dwordx4 v[190:191], off
	s_add_i32 m0, s99, 0x2000
	v_lshl_add_u64 v[190:191], v[132:133], 0, s[36:37]
	global_load_lds_dwordx4 v[190:191], off
	s_barrier
	s_setprio 1
	s_waitcnt lgkmcnt(0)
	v_mfma_f32_16x16x32_bf16 v[60:63], v[182:185], v[166:169], v[60:63]
	v_mfma_f32_16x16x32_bf16 v[56:59], v[182:185], v[174:177], v[56:59]
	v_mfma_f32_16x16x32_bf16 v[52:55], v[194:197], v[166:169], v[52:55]
	v_mfma_f32_16x16x32_bf16 v[48:51], v[194:197], v[174:177], v[48:51]
	v_mfma_f32_16x16x32_bf16 v[44:47], v[208:211], v[166:169], v[44:47]
	v_mfma_f32_16x16x32_bf16 v[40:43], v[208:211], v[174:177], v[40:43]
	v_mfma_f32_16x16x32_bf16 v[36:39], v[216:219], v[166:169], v[36:39]
	v_mfma_f32_16x16x32_bf16 v[32:35], v[216:219], v[174:177], v[32:35]
	v_mfma_f32_16x16x32_bf16 v[60:63], v[186:189], v[170:173], v[60:63]
	v_mfma_f32_16x16x32_bf16 v[56:59], v[186:189], v[178:181], v[56:59]
	v_mfma_f32_16x16x32_bf16 v[52:55], v[202:205], v[170:173], v[52:55]
	v_mfma_f32_16x16x32_bf16 v[48:51], v[202:205], v[178:181], v[48:51]
	v_mfma_f32_16x16x32_bf16 v[44:47], v[212:215], v[170:173], v[44:47]
	v_mfma_f32_16x16x32_bf16 v[40:43], v[212:215], v[178:181], v[40:43]
	v_mfma_f32_16x16x32_bf16 v[36:39], v[220:223], v[170:173], v[36:39]
	v_mfma_f32_16x16x32_bf16 v[32:35], v[220:223], v[178:181], v[32:35]
	s_setprio 0
	s_barrier
	s_add_i32 m0, s99, 0x14000
	v_lshl_add_u64 v[166:167], v[134:135], 0, s[38:39]
	global_load_lds_dwordx4 v[166:167], off
	s_add_i32 m0, s99, 0x16000
	v_lshl_add_u64 v[166:167], v[134:135], 0, s[40:41]
	global_load_lds_dwordx4 v[166:167], off
	s_waitcnt vmcnt(6)
	s_barrier
; #define STAGE_A(P, hf, kt) do { if constexpr (ABLK) { const bf16* _gp = A + ((long)(brow >> 8) * nt + (kt)) * 16384 + (hf) * 8192; GLDS2(_gp, 4096, offA, P); } \
;     else { const bf16* _gp = A + (long)(brow + (hf) * HALF) * lda + (long)(kt) * BK; GLDS2(_gp, 64 * (long)lda, offA, P); } } while (0)
; #define STAGE_B(P, hf, kt) do { const bf16* _gp = Bt + (long)(bcol + (hf) * 2) * ldb + (long)(kt) * BK; GLDS2(_gp, 128 * (long)ldb, offB, P); } while (0)
; #define LDA(dst, b, h) for (int m = 0; m < 4; ++m) for (int k = 0; k < 2; ++k) \
;     dst[m][k] = *reinterpret_cast<const bf16x8*>((char*)SA(b, h) + lds_byte(wr * 64 + m * 16 + fr, k * 32 + fq * 8))
; #define LDB(dst, b, h) for (int n = 0; n < 2; ++n) for (int k = 0; k < 2; ++k) \
;     dst[n][k] = *reinterpret_cast<const bf16x8*>((char*)SB(b, h) + lds_byte(wc * 32 + n * 16 + fr, k * 32 + fq * 8))
; #define MMA(ai, bj, At, Bt_) do { __builtin_amdgcn_s_setprio(1); \
;     for (int m = 0; m < 4; ++m) for (int n = 0; n < 2; ++n) for (int k = 0; k < 2; ++k) \
;       acc[ai][bj][m][n] = __builtin_amdgcn_mfma_f32_16x16x32_bf16(At[m][k], Bt_[n][k], acc[ai][bj][m][n], 0, 0, 0); \
;     __builtin_amdgcn_s_setprio(0); } while (0)
; #define WAIT_V(n) asm volatile("s_waitcnt vmcnt(" #n ")" ::: "memory")
; #define WAIT_L(n) asm volatile("s_waitcnt lgkmcnt(" #n ")" ::: "memory")
; #define BAR __builtin_amdgcn_s_barrier()
; #define SCHED __builtin_amdgcn_sched_barrier(0)
; template <bool ABLK, class Epi>
; __device__ __forceinline__ void gemm_tile(const bf16* __restrict__ A, int lda, const bf16* __restrict__ Bt, int ldb, int K,
;                                           int brow, int bcol, bf16* shm, const Epi& epi, int wv) {
;     ...
;     WAIT_V(6); BAR; MMA(1, 1, At, B1); BAR;
;     LDB(B0, 1, 0); SCHED; LDA(At, 1, 0); STAGE_A(SA(0, 1), 1, t + 2);
;     WAIT_L(8); BAR; MMA(0, 0, At, B0); BAR; SCHED;
;     LDB(B1, 1, 1); STAGE_B(SB(1, 0), 0, t + 3);
;     BAR; MMA(0, 1, At, B1); BAR;
;     LDA(At, 1, 1); STAGE_A(SA(1, 0), 0, t + 3);
;     BAR; MMA(1, 0, At, B0); BAR; SCHED;
	s_setprio 1
	v_mfma_f32_16x16x32_bf16 v[28:31], v[182:185], v[224:227], v[28:31]
	v_mfma_f32_16x16x32_bf16 v[24:27], v[182:185], v[232:235], v[24:27]
	v_mfma_f32_16x16x32_bf16 v[20:23], v[194:197], v[224:227], v[20:23]
	v_mfma_f32_16x16x32_bf16 v[16:19], v[194:197], v[232:235], v[16:19]
	v_mfma_f32_16x16x32_bf16 v[12:15], v[208:211], v[224:227], v[12:15]
	v_mfma_f32_16x16x32_bf16 v[8:11], v[208:211], v[232:235], v[8:11]
	v_mfma_f32_16x16x32_bf16 v[4:7], v[216:219], v[224:227], v[4:7]
	v_mfma_f32_16x16x32_bf16 v[0:3], v[216:219], v[232:235], v[0:3]
	v_mfma_f32_16x16x32_bf16 v[28:31], v[186:189], v[228:231], v[28:31]
	v_mfma_f32_16x16x32_bf16 v[24:27], v[186:189], v[236:239], v[24:27]
	v_mfma_f32_16x16x32_bf16 v[20:23], v[202:205], v[228:231], v[20:23]
	v_mfma_f32_16x16x32_bf16 v[16:19], v[202:205], v[236:239], v[16:19]
	v_mfma_f32_16x16x32_bf16 v[12:15], v[212:215], v[228:231], v[12:15]
	v_mfma_f32_16x16x32_bf16 v[8:11], v[212:215], v[236:239], v[8:11]
	v_mfma_f32_16x16x32_bf16 v[4:7], v[220:223], v[228:231], v[4:7]
	v_mfma_f32_16x16x32_bf16 v[0:3], v[220:223], v[236:239], v[0:3]
	s_setprio 0
	s_barrier
	ds_read_b128 v[166:169], v150
	ds_read_b128 v[170:173], v150 offset:1024
	ds_read_b128 v[174:177], v150 offset:2048
	ds_read_b128 v[178:181], v150 offset:3072
	v_lshl_add_u64 v[190:191], v[132:133], 0, s[42:43]
	s_add_i32 m0, s99, 0x4000
	ds_read_b128 v[182:185], v144 offset:32768
	ds_read_b128 v[186:189], v144 offset:33792
	ds_read_b128 v[194:197], v143 offset:32768
	ds_read_b128 v[202:205], v143 offset:33792
	ds_read_b128 v[208:211], v142 offset:32768
	ds_read_b128 v[212:215], v142 offset:33792
	ds_read_b128 v[216:219], v141 offset:32768
	ds_read_b128 v[220:223], v141 offset:33792
	global_load_lds_dwordx4 v[190:191], off
	s_add_i32 m0, s99, 0x6000
	v_lshl_add_u64 v[190:191], v[132:133], 0, s[44:45]
	global_load_lds_dwordx4 v[190:191], off
	s_waitcnt lgkmcnt(8)
	s_barrier
	s_setprio 1
	s_waitcnt lgkmcnt(0)
	v_mfma_f32_16x16x32_bf16 v[124:127], v[182:185], v[166:169], v[124:127]
	v_mfma_f32_16x16x32_bf16 v[120:123], v[182:185], v[174:177], v[120:123]
	v_mfma_f32_16x16x32_bf16 v[116:119], v[194:197], v[166:169], v[116:119]
	v_mfma_f32_16x16x32_bf16 v[112:115], v[194:197], v[174:177], v[112:115]
	v_mfma_f32_16x16x32_bf16 v[108:111], v[208:211], v[166:169], v[108:111]
	v_mfma_f32_16x16x32_bf16 v[104:107], v[208:211], v[174:177], v[104:107]
	v_mfma_f32_16x16x32_bf16 v[100:103], v[216:219], v[166:169], v[100:103]
	v_mfma_f32_16x16x32_bf16 v[96:99], v[216:219], v[174:177], v[96:99]
	v_mfma_f32_16x16x32_bf16 v[124:127], v[186:189], v[170:173], v[124:127]
	v_mfma_f32_16x16x32_bf16 v[120:123], v[186:189], v[178:181], v[120:123]
	v_mfma_f32_16x16x32_bf16 v[116:119], v[202:205], v[170:173], v[116:119]
	v_mfma_f32_16x16x32_bf16 v[112:115], v[202:205], v[178:181], v[112:115]
	v_mfma_f32_16x16x32_bf16 v[108:111], v[212:215], v[170:173], v[108:111]
	v_mfma_f32_16x16x32_bf16 v[104:107], v[212:215], v[178:181], v[104:107]
	v_mfma_f32_16x16x32_bf16 v[100:103], v[220:223], v[170:173], v[100:103]
	v_mfma_f32_16x16x32_bf16 v[96:99], v[220:223], v[178:181], v[96:99]
	s_setprio 0
	s_barrier
	v_lshl_add_u64 v[190:191], v[134:135], 0, s[46:47]
	s_add_i32 m0, s99, 0x18000
	ds_read_b128 v[224:227], v147
	ds_read_b128 v[228:231], v147 offset:1024
	ds_read_b128 v[232:235], v147 offset:2048
	ds_read_b128 v[236:239], v147 offset:3072
	global_load_lds_dwordx4 v[190:191], off
	s_add_i32 m0, s99, 0x1a000
	v_lshl_add_u64 v[190:191], v[134:135], 0, s[48:49]
	global_load_lds_dwordx4 v[190:191], off
	s_barrier
	s_setprio 1
	s_waitcnt lgkmcnt(0)
	v_mfma_f32_16x16x32_bf16 v[92:95], v[182:185], v[224:227], v[92:95]
	v_mfma_f32_16x16x32_bf16 v[88:91], v[182:185], v[232:235], v[88:91]
	v_mfma_f32_16x16x32_bf16 v[84:87], v[194:197], v[224:227], v[84:87]
	v_mfma_f32_16x16x32_bf16 v[80:83], v[194:197], v[232:235], v[80:83]
	v_mfma_f32_16x16x32_bf16 v[76:79], v[208:211], v[224:227], v[76:79]
	v_mfma_f32_16x16x32_bf16 v[72:75], v[208:211], v[232:235], v[72:75]
	v_mfma_f32_16x16x32_bf16 v[68:71], v[216:219], v[224:227], v[68:71]
	v_mfma_f32_16x16x32_bf16 v[64:67], v[216:219], v[232:235], v[64:67]
	v_mfma_f32_16x16x32_bf16 v[92:95], v[186:189], v[228:231], v[92:95]
	v_mfma_f32_16x16x32_bf16 v[88:91], v[186:189], v[236:239], v[88:91]
	v_mfma_f32_16x16x32_bf16 v[84:87], v[202:205], v[228:231], v[84:87]
	v_mfma_f32_16x16x32_bf16 v[80:83], v[202:205], v[236:239], v[80:83]
	v_mfma_f32_16x16x32_bf16 v[76:79], v[212:215], v[228:231], v[76:79]
	v_mfma_f32_16x16x32_bf16 v[72:75], v[212:215], v[236:239], v[72:75]
	v_mfma_f32_16x16x32_bf16 v[68:71], v[220:223], v[228:231], v[68:71]
	v_mfma_f32_16x16x32_bf16 v[64:67], v[220:223], v[236:239], v[64:67]
	s_setprio 0
	v_lshl_add_u64 v[190:191], v[132:133], 0, s[48:49]
	s_add_i32 m0, s99, 0x8000
	s_barrier
	ds_read_b128 v[182:185], v144 offset:49152
	ds_read_b128 v[186:189], v144 offset:50176
	ds_read_b128 v[194:197], v143 offset:49152
	ds_read_b128 v[202:205], v143 offset:50176
	ds_read_b128 v[208:211], v142 offset:49152
	ds_read_b128 v[212:215], v142 offset:50176
	ds_read_b128 v[216:219], v141 offset:49152
	ds_read_b128 v[220:223], v141 offset:50176
	global_load_lds_dwordx4 v[190:191], off
	s_add_i32 m0, s99, 0xa000
	s_nop 0
	global_load_lds_dwordx4 v[132:133], off
	s_barrier
; #define STAGE_A(P, hf, kt) do { if constexpr (ABLK) { const bf16* _gp = A + ((long)(brow >> 8) * nt + (kt)) * 16384 + (hf) * 8192; GLDS2(_gp, 4096, offA, P); } \
;     else { const bf16* _gp = A + (long)(brow + (hf) * HALF) * lda + (long)(kt) * BK; GLDS2(_gp, 64 * (long)lda, offA, P); } } while (0)
; #define STAGE_B(P, hf, kt) do { const bf16* _gp = Bt + (long)(bcol + (hf) * 2) * ldb + (long)(kt) * BK; GLDS2(_gp, 128 * (long)ldb, offB, P); } while (0)
; #define LDA(dst, b, h) for (int m = 0; m < 4; ++m) for (int k = 0; k < 2; ++k) \
;     dst[m][k] = *reinterpret_cast<const bf16x8*>((char*)SA(b, h) + lds_byte(wr * 64 + m * 16 + fr, k * 32 + fq * 8))
; #define LDB(dst, b, h) for (int n = 0; n < 2; ++n) for (int k = 0; k < 2; ++k) \
;     dst[n][k] = *reinterpret_cast<const bf16x8*>((char*)SB(b, h) + lds_byte(wc * 32 + n * 16 + fr, k * 32 + fq * 8))
; #define MMA(ai, bj, At, Bt_) do { __builtin_amdgcn_s_setprio(1); \
;     for (int m = 0; m < 4; ++m) for (int n = 0; n < 2; ++n) for (int k = 0; k < 2; ++k) \
;       acc[ai][bj][m][n] = __builtin_amdgcn_mfma_f32_16x16x32_bf16(At[m][k], Bt_[n][k], acc[ai][bj][m][n], 0, 0, 0); \
;     __builtin_amdgcn_s_setprio(0); } while (0)
; #define WAIT_V(n) asm volatile("s_waitcnt vmcnt(" #n ")" ::: "memory")
; #define WAIT_L(n) asm volatile("s_waitcnt lgkmcnt(" #n ")" ::: "memory")
; #define BAR __builtin_amdgcn_s_barrier()
; #define SCHED __builtin_amdgcn_sched_barrier(0)
; template <bool ABLK, class Epi>
; __device__ __forceinline__ void gemm_tile(const bf16* __restrict__ A, int lda, const bf16* __restrict__ Bt, int ldb, int K,
;                                           int brow, int bcol, bf16* shm, const Epi& epi, int wv) {
;     ...
;     BAR; MMA(1, 0, At, B0); BAR; SCHED;
;     STAGE_B(SB(1, 1), 1, t + 3);
;     WAIT_V(6); BAR; MMA(1, 1, At, B1); BAR;
;   }
;   { LDB(B0, 0, 0); LDA(At, 0, 0); STAGE_A(SA(1, 1), 1, nt - 1);
;     BAR; WAIT_L(0); MMA(0, 0, At, B0); BAR;
;     LDB(B1, 0, 1); BAR; WAIT_L(0); MMA(0, 1, At, B1); BAR;
;     LDA(At, 0, 1); WAIT_V(4); BAR; WAIT_L(0); MMA(1, 0, At, B0); MMA(1, 1, At, B1); BAR; }
	s_setprio 1
	s_waitcnt lgkmcnt(0)
	v_mfma_f32_16x16x32_bf16 v[60:63], v[182:185], v[166:169], v[60:63]
	v_mfma_f32_16x16x32_bf16 v[56:59], v[182:185], v[174:177], v[56:59]
	v_mfma_f32_16x16x32_bf16 v[52:55], v[194:197], v[166:169], v[52:55]
	v_mfma_f32_16x16x32_bf16 v[48:51], v[194:197], v[174:177], v[48:51]
	v_mfma_f32_16x16x32_bf16 v[44:47], v[208:211], v[166:169], v[44:47]
	v_mfma_f32_16x16x32_bf16 v[40:43], v[208:211], v[174:177], v[40:43]
	v_mfma_f32_16x16x32_bf16 v[36:39], v[216:219], v[166:169], v[36:39]
	v_mfma_f32_16x16x32_bf16 v[32:35], v[216:219], v[174:177], v[32:35]
	v_mfma_f32_16x16x32_bf16 v[60:63], v[186:189], v[170:173], v[60:63]
	v_mfma_f32_16x16x32_bf16 v[56:59], v[186:189], v[178:181], v[56:59]
	v_mfma_f32_16x16x32_bf16 v[52:55], v[202:205], v[170:173], v[52:55]
	v_mfma_f32_16x16x32_bf16 v[48:51], v[202:205], v[178:181], v[48:51]
	v_mfma_f32_16x16x32_bf16 v[44:47], v[212:215], v[170:173], v[44:47]
	v_mfma_f32_16x16x32_bf16 v[40:43], v[212:215], v[178:181], v[40:43]
	v_mfma_f32_16x16x32_bf16 v[36:39], v[220:223], v[170:173], v[36:39]
	v_mfma_f32_16x16x32_bf16 v[32:35], v[220:223], v[178:181], v[32:35]
	s_setprio 0
	s_barrier
	s_add_i32 m0, s99, 0x1c000
	v_lshl_add_u64 v[166:167], v[134:135], 0, s[50:51]
	global_load_lds_dwordx4 v[166:167], off
	s_add_i32 m0, s99, 0x1e000
	s_nop 0
	global_load_lds_dwordx4 v[134:135], off
	s_waitcnt vmcnt(6)
	s_barrier
	s_setprio 1
	v_mfma_f32_16x16x32_bf16 v[28:31], v[182:185], v[224:227], v[28:31]
	v_mfma_f32_16x16x32_bf16 v[24:27], v[182:185], v[232:235], v[24:27]
	v_mfma_f32_16x16x32_bf16 v[20:23], v[194:197], v[224:227], v[20:23]
	v_mfma_f32_16x16x32_bf16 v[16:19], v[194:197], v[232:235], v[16:19]
	v_mfma_f32_16x16x32_bf16 v[12:15], v[208:211], v[224:227], v[12:15]
	v_mfma_f32_16x16x32_bf16 v[8:11], v[208:211], v[232:235], v[8:11]
	v_mfma_f32_16x16x32_bf16 v[4:7], v[216:219], v[224:227], v[4:7]
	v_mfma_f32_16x16x32_bf16 v[0:3], v[216:219], v[232:235], v[0:3]
	v_mfma_f32_16x16x32_bf16 v[28:31], v[186:189], v[228:231], v[28:31]
	v_mfma_f32_16x16x32_bf16 v[24:27], v[186:189], v[236:239], v[24:27]
	v_mfma_f32_16x16x32_bf16 v[20:23], v[202:205], v[228:231], v[20:23]
	v_mfma_f32_16x16x32_bf16 v[16:19], v[202:205], v[236:239], v[16:19]
	v_mfma_f32_16x16x32_bf16 v[12:15], v[212:215], v[228:231], v[12:15]
	v_mfma_f32_16x16x32_bf16 v[8:11], v[212:215], v[236:239], v[8:11]
	v_mfma_f32_16x16x32_bf16 v[4:7], v[220:223], v[228:231], v[4:7]
	v_mfma_f32_16x16x32_bf16 v[0:3], v[220:223], v[236:239], v[0:3]
	s_setprio 0
	s_add_i32 s33, s33, 2
	v_lshl_add_u64 v[132:133], v[132:133], 0, s[52:53]
	s_cmp_lt_u32 s33, 28
	v_lshl_add_u64 v[134:135], v[134:135], 0, s[54:55]
	s_barrier
	s_cbranch_scc1 .LBB0_1064
	v_readfirstlane_b32 s2, v163
	v_lshl_add_u64 v[148:149], v[130:131], 0, s[56:57]
	s_mov_b32 m0, s2
	v_readfirstlane_b32 s2, v164
	ds_read_b128 v[132:135], v162
	ds_read_b128 v[152:155], v162 offset:1024
	ds_read_b128 v[156:159], v162 offset:2048
	ds_read_b128 v[166:169], v162 offset:3072
	ds_read_b128 v[170:173], v144
	ds_read_b128 v[174:177], v144 offset:1024
	ds_read_b128 v[178:181], v143
	ds_read_b128 v[182:185], v143 offset:1024
	ds_read_b128 v[186:189], v142
	ds_read_b128 v[194:197], v142 offset:1024
	ds_read_b128 v[202:205], v141
	ds_read_b128 v[208:211], v141 offset:1024
	global_load_lds_dwordx4 v[148:149], off
	v_lshl_add_u64 v[130:131], v[130:131], 0, s[58:59]
	s_mov_b32 m0, s2
	s_nop 0
	global_load_lds_dwordx4 v[130:131], off
	s_barrier
	s_waitcnt lgkmcnt(0)
	s_setprio 1
	s_waitcnt lgkmcnt(0)
	v_mfma_f32_16x16x32_bf16 v[124:127], v[170:173], v[132:135], v[124:127]
	v_mfma_f32_16x16x32_bf16 v[120:123], v[170:173], v[156:159], v[120:123]
	v_mfma_f32_16x16x32_bf16 v[108:111], v[186:189], v[132:135], v[108:111]
	v_mfma_f32_16x16x32_bf16 v[104:107], v[186:189], v[156:159], v[104:107]
	v_mfma_f32_16x16x32_bf16 v[124:127], v[174:177], v[152:155], v[124:127]
	v_mfma_f32_16x16x32_bf16 v[120:123], v[174:177], v[166:169], v[120:123]
	v_mfma_f32_16x16x32_bf16 v[116:119], v[178:181], v[132:135], v[116:119]
	v_mfma_f32_16x16x32_bf16 v[112:115], v[178:181], v[156:159], v[112:115]
	v_mfma_f32_16x16x32_bf16 v[108:111], v[194:197], v[152:155], v[108:111]
	v_mfma_f32_16x16x32_bf16 v[104:107], v[194:197], v[166:169], v[104:107]
	v_mfma_f32_16x16x32_bf16 v[100:103], v[202:205], v[132:135], v[100:103]
	v_mfma_f32_16x16x32_bf16 v[96:99], v[202:205], v[156:159], v[96:99]
	v_mfma_f32_16x16x32_bf16 v[162:165], v[182:185], v[152:155], v[116:119]
	v_mfma_f32_16x16x32_bf16 v[212:215], v[182:185], v[166:169], v[112:115]
	v_mfma_f32_16x16x32_bf16 v[216:219], v[208:211], v[152:155], v[100:103]
	v_mfma_f32_16x16x32_bf16 v[220:223], v[208:211], v[166:169], v[96:99]
	s_setprio 0
	s_barrier
	s_nop 1
	ds_read_b128 v[96:99], v161
	ds_read_b128 v[100:103], v161 offset:1024
	ds_read_b128 v[112:115], v161 offset:2048
	ds_read_b128 v[116:119], v161 offset:3072
	s_barrier
	s_waitcnt lgkmcnt(0)
	s_setprio 1
	s_waitcnt lgkmcnt(0)
	v_mfma_f32_16x16x32_bf16 v[92:95], v[170:173], v[96:99], v[92:95]
	v_mfma_f32_16x16x32_bf16 v[88:91], v[170:173], v[112:115], v[88:91]
	v_mfma_f32_16x16x32_bf16 v[76:79], v[186:189], v[96:99], v[76:79]
	v_mfma_f32_16x16x32_bf16 v[72:75], v[186:189], v[112:115], v[72:75]
	v_mfma_f32_16x16x32_bf16 v[92:95], v[174:177], v[100:103], v[92:95]
	v_mfma_f32_16x16x32_bf16 v[88:91], v[174:177], v[116:119], v[88:91]
	v_mfma_f32_16x16x32_bf16 v[84:87], v[178:181], v[96:99], v[84:87]
	v_mfma_f32_16x16x32_bf16 v[80:83], v[178:181], v[112:115], v[80:83]
	v_mfma_f32_16x16x32_bf16 v[76:79], v[194:197], v[100:103], v[76:79]
	v_mfma_f32_16x16x32_bf16 v[72:75], v[194:197], v[116:119], v[72:75]
	v_mfma_f32_16x16x32_bf16 v[68:71], v[202:205], v[96:99], v[68:71]
	v_mfma_f32_16x16x32_bf16 v[64:67], v[202:205], v[112:115], v[64:67]
	v_mfma_f32_16x16x32_bf16 v[170:173], v[182:185], v[100:103], v[84:87]
	v_mfma_f32_16x16x32_bf16 v[174:177], v[182:185], v[116:119], v[80:83]
	v_mfma_f32_16x16x32_bf16 v[178:181], v[208:211], v[100:103], v[68:71]
	v_mfma_f32_16x16x32_bf16 v[182:185], v[208:211], v[116:119], v[64:67]
	s_setprio 0
	s_barrier
; #define LDA(dst, b, h) for (int m = 0; m < 4; ++m) for (int k = 0; k < 2; ++k) \
;     dst[m][k] = *reinterpret_cast<const bf16x8*>((char*)SA(b, h) + lds_byte(wr * 64 + m * 16 + fr, k * 32 + fq * 8))
; #define LDB(dst, b, h) for (int n = 0; n < 2; ++n) for (int k = 0; k < 2; ++k) \
;     dst[n][k] = *reinterpret_cast<const bf16x8*>((char*)SB(b, h) + lds_byte(wc * 32 + n * 16 + fr, k * 32 + fq * 8))
; #define MMA(ai, bj, At, Bt_) do { __builtin_amdgcn_s_setprio(1); \
;     for (int m = 0; m < 4; ++m) for (int n = 0; n < 2; ++n) for (int k = 0; k < 2; ++k) \
;       acc[ai][bj][m][n] = __builtin_amdgcn_mfma_f32_16x16x32_bf16(At[m][k], Bt_[n][k], acc[ai][bj][m][n], 0, 0, 0); \
;     __builtin_amdgcn_s_setprio(0); } while (0)
; #define WAIT_V(n) asm volatile("s_waitcnt vmcnt(" #n ")" ::: "memory")
; #define WAIT_L(n) asm volatile("s_waitcnt lgkmcnt(" #n ")" ::: "memory")
; #define BAR __builtin_amdgcn_s_barrier()
; template <bool ABLK, class Epi>
; __device__ __forceinline__ void gemm_tile(const bf16* __restrict__ A, int lda, const bf16* __restrict__ Bt, int ldb, int K,
;                                           int brow, int bcol, bf16* shm, const Epi& epi, int wv) {
;     ...
;     LDB(B1, 0, 1); BAR; WAIT_L(0); MMA(0, 1, At, B1); BAR;
;     LDA(At, 0, 1); WAIT_V(4); BAR; WAIT_L(0); MMA(1, 0, At, B0); MMA(1, 1, At, B1); BAR; }
;   { LDB(B0, 1, 0); LDA(At, 1, 0); WAIT_V(2); BAR; WAIT_L(0); MMA(0, 0, At, B0); BAR;
	s_nop 1
	ds_read_b128 v[64:67], v144 offset:16384
	ds_read_b128 v[68:71], v144 offset:17408
	ds_read_b128 v[80:83], v143 offset:16384
	ds_read_b128 v[84:87], v143 offset:17408
	ds_read_b128 v[186:189], v142 offset:16384
	ds_read_b128 v[194:197], v142 offset:17408
	ds_read_b128 v[202:205], v141 offset:16384
	ds_read_b128 v[208:211], v141 offset:17408
	s_waitcnt vmcnt(4)
	s_barrier
	s_waitcnt lgkmcnt(0)
	s_setprio 1
	s_waitcnt lgkmcnt(0)
	v_mfma_f32_16x16x32_bf16 v[60:63], v[64:67], v[132:135], v[60:63]
	v_mfma_f32_16x16x32_bf16 v[56:59], v[64:67], v[156:159], v[56:59]
	v_mfma_f32_16x16x32_bf16 v[44:47], v[186:189], v[132:135], v[44:47]
	v_mfma_f32_16x16x32_bf16 v[40:43], v[186:189], v[156:159], v[40:43]
	v_mfma_f32_16x16x32_bf16 v[60:63], v[68:71], v[152:155], v[60:63]
	v_mfma_f32_16x16x32_bf16 v[56:59], v[68:71], v[166:169], v[56:59]
	v_mfma_f32_16x16x32_bf16 v[52:55], v[80:83], v[132:135], v[52:55]
	v_mfma_f32_16x16x32_bf16 v[48:51], v[80:83], v[156:159], v[48:51]
	v_mfma_f32_16x16x32_bf16 v[44:47], v[194:197], v[152:155], v[44:47]
	v_mfma_f32_16x16x32_bf16 v[40:43], v[194:197], v[166:169], v[40:43]
	v_mfma_f32_16x16x32_bf16 v[36:39], v[202:205], v[132:135], v[36:39]
	v_mfma_f32_16x16x32_bf16 v[32:35], v[202:205], v[156:159], v[32:35]
	v_mfma_f32_16x16x32_bf16 v[224:227], v[84:87], v[152:155], v[52:55]
	v_mfma_f32_16x16x32_bf16 v[228:231], v[84:87], v[166:169], v[48:51]
	v_mfma_f32_16x16x32_bf16 v[130:133], v[208:211], v[152:155], v[36:39]
	v_mfma_f32_16x16x32_bf16 v[152:155], v[208:211], v[166:169], v[32:35]
	s_setprio 0
	s_setprio 1
	v_mfma_f32_16x16x32_bf16 v[28:31], v[64:67], v[96:99], v[28:31]
	v_mfma_f32_16x16x32_bf16 v[24:27], v[64:67], v[112:115], v[24:27]
	v_mfma_f32_16x16x32_bf16 v[12:15], v[186:189], v[96:99], v[12:15]
	v_mfma_f32_16x16x32_bf16 v[8:11], v[186:189], v[112:115], v[8:11]
	v_mfma_f32_16x16x32_bf16 v[28:31], v[68:71], v[100:103], v[28:31]
	v_mfma_f32_16x16x32_bf16 v[24:27], v[68:71], v[116:119], v[24:27]
	v_mfma_f32_16x16x32_bf16 v[20:23], v[80:83], v[96:99], v[20:23]
	v_mfma_f32_16x16x32_bf16 v[16:19], v[80:83], v[112:115], v[16:19]
	v_mfma_f32_16x16x32_bf16 v[12:15], v[194:197], v[100:103], v[12:15]
	v_mfma_f32_16x16x32_bf16 v[8:11], v[194:197], v[116:119], v[8:11]
	v_mfma_f32_16x16x32_bf16 v[4:7], v[202:205], v[96:99], v[4:7]
	v_mfma_f32_16x16x32_bf16 v[0:3], v[202:205], v[112:115], v[0:3]
	v_mfma_f32_16x16x32_bf16 v[156:159], v[84:87], v[100:103], v[20:23]
	v_mfma_f32_16x16x32_bf16 v[166:169], v[84:87], v[116:119], v[16:19]
	v_mfma_f32_16x16x32_bf16 v[186:189], v[208:211], v[100:103], v[4:7]
	v_mfma_f32_16x16x32_bf16 v[194:197], v[208:211], v[116:119], v[0:3]
	s_setprio 0
	s_barrier
	s_nop 1
	ds_read_b128 v[0:3], v150
	ds_read_b128 v[4:7], v150 offset:1024
	ds_read_b128 v[202:205], v150 offset:2048
	ds_read_b128 v[148:151], v150 offset:3072
	ds_read_b128 v[16:19], v144 offset:32768
	ds_read_b128 v[20:23], v144 offset:33792
	ds_read_b128 v[32:35], v143 offset:32768
	ds_read_b128 v[36:39], v143 offset:33792
	ds_read_b128 v[48:51], v142 offset:32768
	ds_read_b128 v[52:55], v142 offset:33792
	ds_read_b128 v[208:211], v141 offset:32768
	ds_read_b128 v[232:235], v141 offset:33792
	s_waitcnt vmcnt(2)
	s_barrier
	s_waitcnt lgkmcnt(0)
	s_setprio 1
	s_waitcnt lgkmcnt(0)
	v_mfma_f32_16x16x32_bf16 v[64:67], v[16:19], v[0:3], v[124:127]
	v_mfma_f32_16x16x32_bf16 v[112:115], v[20:23], v[4:7], v[64:67]
	v_mfma_f32_16x16x32_bf16 v[64:67], v[16:19], v[202:205], v[120:123]
	v_mfma_f32_16x16x32_bf16 v[116:119], v[20:23], v[148:151], v[64:67]
	v_mfma_f32_16x16x32_bf16 v[64:67], v[32:35], v[0:3], v[162:165]
	v_mfma_f32_16x16x32_bf16 v[96:99], v[36:39], v[4:7], v[64:67]
	v_mfma_f32_16x16x32_bf16 v[64:67], v[32:35], v[202:205], v[212:215]
	v_mfma_f32_16x16x32_bf16 v[100:103], v[36:39], v[148:151], v[64:67]
	v_mfma_f32_16x16x32_bf16 v[64:67], v[48:51], v[0:3], v[108:111]
	v_mfma_f32_16x16x32_bf16 v[80:83], v[52:55], v[4:7], v[64:67]
	v_mfma_f32_16x16x32_bf16 v[64:67], v[48:51], v[202:205], v[104:107]
	v_mfma_f32_16x16x32_bf16 v[84:87], v[52:55], v[148:151], v[64:67]
	v_mfma_f32_16x16x32_bf16 v[64:67], v[208:211], v[0:3], v[216:219]
	v_mfma_f32_16x16x32_bf16 v[68:71], v[208:211], v[202:205], v[220:223]
	v_mfma_f32_16x16x32_bf16 v[64:67], v[232:235], v[4:7], v[64:67]
	v_mfma_f32_16x16x32_bf16 v[68:71], v[232:235], v[148:151], v[68:71]
	s_setprio 0
	s_barrier
; #define LDA(dst, b, h) for (int m = 0; m < 4; ++m) for (int k = 0; k < 2; ++k) \
;     dst[m][k] = *reinterpret_cast<const bf16x8*>((char*)SA(b, h) + lds_byte(wr * 64 + m * 16 + fr, k * 32 + fq * 8))
; #define LDB(dst, b, h) for (int n = 0; n < 2; ++n) for (int k = 0; k < 2; ++k) \
;     dst[n][k] = *reinterpret_cast<const bf16x8*>((char*)SB(b, h) + lds_byte(wc * 32 + n * 16 + fr, k * 32 + fq * 8))
; #define MMA(ai, bj, At, Bt_) do { __builtin_amdgcn_s_setprio(1); \
;     for (int m = 0; m < 4; ++m) for (int n = 0; n < 2; ++n) for (int k = 0; k < 2; ++k) \
;       acc[ai][bj][m][n] = __builtin_amdgcn_mfma_f32_16x16x32_bf16(At[m][k], Bt_[n][k], acc[ai][bj][m][n], 0, 0, 0); \
;     __builtin_amdgcn_s_setprio(0); } while (0)
; #define WAIT_V(n) asm volatile("s_waitcnt vmcnt(" #n ")" ::: "memory")
; #define WAIT_L(n) asm volatile("s_waitcnt lgkmcnt(" #n ")" ::: "memory")
; #define BAR __builtin_amdgcn_s_barrier()
; template <bool ABLK, class Epi>
; __device__ __forceinline__ void gemm_tile(const bf16* __restrict__ A, int lda, const bf16* __restrict__ Bt, int ldb, int K,
;                                           int brow, int bcol, bf16* shm, const Epi& epi, int wv) {
;     ...
;   { LDB(B0, 1, 0); LDA(At, 1, 0); WAIT_V(2); BAR; WAIT_L(0); MMA(0, 0, At, B0); BAR;
;     LDB(B1, 1, 1); WAIT_V(0); BAR; WAIT_L(0); MMA(0, 1, At, B1); BAR;
;     LDA(At, 1, 1); BAR; WAIT_L(0); MMA(1, 0, At, B0); MMA(1, 1, At, B1); BAR; }
;   if (wr == 0) BAR;
	ds_read_b128 v[160:163], v147
	ds_read_b128 v[212:215], v147 offset:1024
	ds_read_b128 v[216:219], v147 offset:2048
	ds_read_b128 v[220:223], v147 offset:3072
	s_waitcnt vmcnt(0)
	s_barrier
	s_waitcnt lgkmcnt(0)
	s_setprio 1
	s_waitcnt lgkmcnt(0)
	v_mfma_f32_16x16x32_bf16 v[92:95], v[16:19], v[160:163], v[92:95]
	v_mfma_f32_16x16x32_bf16 v[16:19], v[16:19], v[216:219], v[88:91]
	v_mfma_f32_16x16x32_bf16 v[124:127], v[20:23], v[220:223], v[16:19]
	v_mfma_f32_16x16x32_bf16 v[16:19], v[32:35], v[160:163], v[170:173]
	v_mfma_f32_16x16x32_bf16 v[104:107], v[36:39], v[212:215], v[16:19]
	v_mfma_f32_16x16x32_bf16 v[16:19], v[32:35], v[216:219], v[174:177]
	v_mfma_f32_16x16x32_bf16 v[108:111], v[36:39], v[220:223], v[16:19]
	v_mfma_f32_16x16x32_bf16 v[16:19], v[48:51], v[160:163], v[76:79]
	v_mfma_f32_16x16x32_bf16 v[88:91], v[52:55], v[212:215], v[16:19]
	v_mfma_f32_16x16x32_bf16 v[16:19], v[48:51], v[216:219], v[72:75]
	v_mfma_f32_16x16x32_bf16 v[120:123], v[20:23], v[212:215], v[92:95]
	v_mfma_f32_16x16x32_bf16 v[92:95], v[52:55], v[220:223], v[16:19]
	v_mfma_f32_16x16x32_bf16 v[16:19], v[208:211], v[160:163], v[178:181]
	v_mfma_f32_16x16x32_bf16 v[72:75], v[232:235], v[212:215], v[16:19]
	v_mfma_f32_16x16x32_bf16 v[16:19], v[208:211], v[216:219], v[182:185]
	v_mfma_f32_16x16x32_bf16 v[76:79], v[232:235], v[220:223], v[16:19]
	s_setprio 0
	s_barrier
	ds_read_b128 v[170:173], v144 offset:49152
	ds_read_b128 v[144:147], v144 offset:50176
	ds_read_b128 v[174:177], v143 offset:49152
	ds_read_b128 v[178:181], v143 offset:50176
	ds_read_b128 v[182:185], v142 offset:49152
	ds_read_b128 v[208:211], v142 offset:50176
	ds_read_b128 v[232:235], v141 offset:49152
	ds_read_b128 v[236:239], v141 offset:50176
	s_barrier
	s_waitcnt lgkmcnt(0)
	s_setprio 1
	s_waitcnt lgkmcnt(0)
	v_mfma_f32_16x16x32_bf16 v[16:19], v[170:173], v[0:3], v[60:63]
	v_mfma_f32_16x16x32_bf16 v[48:51], v[144:147], v[4:7], v[16:19]
	v_mfma_f32_16x16x32_bf16 v[16:19], v[170:173], v[202:205], v[56:59]
	v_mfma_f32_16x16x32_bf16 v[52:55], v[144:147], v[148:151], v[16:19]
	v_mfma_f32_16x16x32_bf16 v[16:19], v[174:177], v[0:3], v[224:227]
	v_mfma_f32_16x16x32_bf16 v[32:35], v[178:181], v[4:7], v[16:19]
	v_mfma_f32_16x16x32_bf16 v[16:19], v[174:177], v[202:205], v[228:231]
	v_mfma_f32_16x16x32_bf16 v[36:39], v[178:181], v[148:151], v[16:19]
	v_mfma_f32_16x16x32_bf16 v[16:19], v[182:185], v[0:3], v[44:47]
	v_mfma_f32_16x16x32_bf16 v[0:3], v[232:235], v[0:3], v[130:133]
	v_mfma_f32_16x16x32_bf16 v[16:19], v[208:211], v[4:7], v[16:19]
	v_mfma_f32_16x16x32_bf16 v[20:23], v[182:185], v[202:205], v[40:43]
	v_mfma_f32_16x16x32_bf16 v[0:3], v[236:239], v[4:7], v[0:3]
	v_mfma_f32_16x16x32_bf16 v[4:7], v[232:235], v[202:205], v[152:155]
	v_mfma_f32_16x16x32_bf16 v[20:23], v[208:211], v[148:151], v[20:23]
	v_mfma_f32_16x16x32_bf16 v[4:7], v[236:239], v[148:151], v[4:7]
	s_setprio 0
	s_setprio 1
	v_mfma_f32_16x16x32_bf16 v[24:27], v[170:173], v[216:219], v[24:27]
	v_mfma_f32_16x16x32_bf16 v[60:63], v[144:147], v[220:223], v[24:27]
	v_mfma_f32_16x16x32_bf16 v[24:27], v[174:177], v[160:163], v[156:159]
	v_mfma_f32_16x16x32_bf16 v[28:31], v[170:173], v[160:163], v[28:31]
	v_mfma_f32_16x16x32_bf16 v[40:43], v[178:181], v[212:215], v[24:27]
	v_mfma_f32_16x16x32_bf16 v[24:27], v[174:177], v[216:219], v[166:169]
	v_mfma_f32_16x16x32_bf16 v[12:15], v[182:185], v[160:163], v[12:15]
	v_mfma_f32_16x16x32_bf16 v[8:11], v[182:185], v[216:219], v[8:11]
	v_mfma_f32_16x16x32_bf16 v[56:59], v[144:147], v[212:215], v[28:31]
	v_mfma_f32_16x16x32_bf16 v[44:47], v[178:181], v[220:223], v[24:27]
	v_mfma_f32_16x16x32_bf16 v[24:27], v[208:211], v[212:215], v[12:15]
	v_mfma_f32_16x16x32_bf16 v[28:31], v[208:211], v[220:223], v[8:11]
	v_mfma_f32_16x16x32_bf16 v[8:11], v[232:235], v[160:163], v[186:189]
	v_mfma_f32_16x16x32_bf16 v[12:15], v[232:235], v[216:219], v[194:197]
	v_mfma_f32_16x16x32_bf16 v[8:11], v[236:239], v[212:215], v[8:11]
	v_mfma_f32_16x16x32_bf16 v[12:15], v[236:239], v[220:223], v[12:15]
	s_setprio 0
	v_cmp_gt_u32_e32 vcc, s82, v128
	s_barrier
	s_and_saveexec_b64 s[64:65], vcc
	s_cbranch_execz .LBB0_1060
	s_barrier
	s_branch .LBB0_1060

; __device__ __forceinline__ KP getp() { KP k = (KP)__builtin_amdgcn_kernarg_segment_ptr(); asm volatile("" : "+s"(k)); return k; }
; __device__ __forceinline__ int mytid(int wv) { return (wv << 6) | (int)__builtin_amdgcn_mbcnt_hi(~0u, __builtin_amdgcn_mbcnt_lo(~0u, 0u)); }
; #define STAGE_A(P, hf, kt) do { if constexpr (ABLK) { const bf16* _gp = A + ((long)(brow >> 8) * nt + (kt)) * 16384 + (hf) * 8192; GLDS2(_gp, 4096, offA, P); } \
;     else { const bf16* _gp = A + (long)(brow + (hf) * HALF) * lda + (long)(kt) * BK; GLDS2(_gp, 64 * (long)lda, offA, P); } } while (0)
; #define STAGE_B(P, hf, kt) do { const bf16* _gp = Bt + (long)(bcol + (hf) * 2) * ldb + (long)(kt) * BK; GLDS2(_gp, 128 * (long)ldb, offB, P); } while (0)
; #define WAIT_V(n) asm volatile("s_waitcnt vmcnt(" #n ")" ::: "memory")
; #define BAR __builtin_amdgcn_s_barrier()
; template <bool ABLK, class Epi>
; __device__ __forceinline__ void gemm_tile(const bf16* __restrict__ A, int lda, const bf16* __restrict__ Bt, int ldb, int K,
;                                           int brow, int bcol, bf16* shm, const Epi& epi, int wv) {
;     ...
;   int tid = mytid(wv); asm volatile("" : "+v"(tid));
;   const int wid = tid >> 6, lane = tid & 63, wr = wid >> 2, wc = wid & 3, fr = lane & 15, fq = lane >> 4;
;   f32x4 acc[2][2][4][2] = {};
;   bf16x8 At[4][2], B0[2][2], B1[2][2];
;   const int nt = K / BK;
;   int offA, offB;
;   { int r_, c_; stage_rc(tid * 16, r_, c_); offA = ABLK ? r_ * 64 + c_ : r_ * lda + c_;
;     offB = ((r_ >> 5) * 64 + (r_ & 15) * 4 + ((r_ >> 4) & 1)) * ldb + c_; }
;   STAGE_B(SB(0, 0), 0, 0); STAGE_A(SA(0, 0), 0, 0);
;   STAGE_B(SB(0, 1), 1, 0); STAGE_A(SA(0, 1), 1, 0);
;   if (wr == 1) BAR;
;   WAIT_V(4); BAR;
;   STAGE_B(SB(1, 0), 0, 1); STAGE_A(SA(1, 0), 0, 1); STAGE_B(SB(1, 1), 1, 1);
;   WAIT_V(6); BAR;
; __global__ __launch_bounds__(NTHR, 2) void mega(Params p_unused) {
;     ...
;   gemm_phase<true>(ACT, DFF, P_Wd1, DFF, TOK, DM, DFF, smem, EpiResid{getp()->X}, wv);
.LBB0_1105:
	s_or_b64 exec, exec, s[6:7]
	s_mov_b64 s[6:7], s[90:91]
	s_mov_b64 s[8:9], s[90:91]
	s_mov_b64 s[10:11], s[90:91]
	s_and_b64 vcc, exec, s[4:5]
	s_barrier
	s_barrier
	s_cbranch_vccnz .LBB0_1115
	s_load_dwordx2 s[12:13], s[6:7], 0xa8
	s_load_dwordx2 s[14:15], s[8:9], 0xa8
	s_load_dwordx2 s[4:5], s[10:11], 0xa0
	s_mov_b32 s28, 0xffff2000
	s_mov_b32 s30, 0xffff4000
	s_waitcnt lgkmcnt(0)
	s_add_u32 s1, s12, 0x17a40000
	s_addc_u32 s3, s13, 0
	s_add_u32 s70, s14, 0xa040000
	s_addc_u32 s71, s15, 0
	s_add_u32 s72, s12, 0x17a5a000
	s_addc_u32 s73, s13, 0
	s_add_u32 s74, s14, 0xa1a5980
	s_mov_b32 s34, 0xffe9a780
	s_movk_i32 s36, 0xa780
	s_mov_b32 s38, 0xffff6000
	s_movk_i32 s40, 0x8000
	s_mov_b32 s42, 0xffe9ff80
	s_movk_i32 s44, 0xff80
	s_movk_i32 s46, 0xa000
	s_movk_i32 s48, 0xc000
	s_mov_b32 s50, 0xffe9a800
	s_movk_i32 s52, 0xa800
	s_movk_i32 s54, 0xe000
	s_mov_b32 s56, 0xffea0000
	s_movk_i32 s0, 0x1600
	s_addc_u32 s75, s15, 0
	s_add_i32 s76, 0, 0x10000
	s_mov_b64 s[6:7], 0x2000
	s_mov_b64 s[8:9], 0x5800
	s_add_i32 s77, 0, 0x14000
	s_mov_b64 s[10:11], 0x165800
	s_mov_b64 s[12:13], 0x4000
	s_mov_b64 s[14:15], 0x6000
	s_mov_b64 s[16:17], 0x80
	s_add_i32 s78, 0, 0x18000
	s_mov_b64 s[18:19], 0x160080
	s_mov_b64 s[20:21], 0x8000
	s_mov_b64 s[22:23], 0xa000
	s_mov_b64 s[24:25], 0x5880
	s_add_i32 s79, 0, 0x1c000
	s_mov_b64 s[26:27], 0x165880
	s_movk_i32 s80, 0x3c0
	s_mov_b32 s29, -1
	s_mov_b32 s31, -1
	s_mov_b32 s35, -1
	s_mov_b32 s37, -1
	s_mov_b32 s39, -1
	s_mov_b32 s41, -1
	s_mov_b32 s43, -1
	s_mov_b32 s45, -1
	s_mov_b32 s47, -1
	s_mov_b32 s49, -1
	s_mov_b32 s51, -1
	s_mov_b32 s53, -1
	s_mov_b32 s55, -1
	s_mov_b32 s57, -1
	s_mov_b64 s[58:59], 0x10000
	s_mov_b64 s[60:61], 0x100
	s_mov_b64 s[62:63], 0x2bc000
	s_mov_b64 s[64:65], 0x2be000
	s_movk_i32 s81, 0x100
	v_mov_b32_e32 v134, 1
	v_lshlrev_b32_e32 v254, 4, v192
	s_nop 0
	v_readfirstlane_b32 s99, v254
	s_branch .LBB0_1108

; #define STAGE_A(P, hf, kt) do { if constexpr (ABLK) { const bf16* _gp = A + ((long)(brow >> 8) * nt + (kt)) * 16384 + (hf) * 8192; GLDS2(_gp, 4096, offA, P); } \
;     else { const bf16* _gp = A + (long)(brow + (hf) * HALF) * lda + (long)(kt) * BK; GLDS2(_gp, 64 * (long)lda, offA, P); } } while (0)
; #define STAGE_B(P, hf, kt) do { const bf16* _gp = Bt + (long)(bcol + (hf) * 2) * ldb + (long)(kt) * BK; GLDS2(_gp, 128 * (long)ldb, offB, P); } while (0)
; #define LDA(dst, b, h) for (int m = 0; m < 4; ++m) for (int k = 0; k < 2; ++k) \
;     dst[m][k] = *reinterpret_cast<const bf16x8*>((char*)SA(b, h) + lds_byte(wr * 64 + m * 16 + fr, k * 32 + fq * 8))
; #define LDB(dst, b, h) for (int n = 0; n < 2; ++n) for (int k = 0; k < 2; ++k) \
;     dst[n][k] = *reinterpret_cast<const bf16x8*>((char*)SB(b, h) + lds_byte(wc * 32 + n * 16 + fr, k * 32 + fq * 8))
; #define MMA(ai, bj, At, Bt_) do { __builtin_amdgcn_s_setprio(1); \
;     for (int m = 0; m < 4; ++m) for (int n = 0; n < 2; ++n) for (int k = 0; k < 2; ++k) \
;       acc[ai][bj][m][n] = __builtin_amdgcn_mfma_f32_16x16x32_bf16(At[m][k], Bt_[n][k], acc[ai][bj][m][n], 0, 0, 0); \
;     __builtin_amdgcn_s_setprio(0); } while (0)
; #define WAIT_V(n) asm volatile("s_waitcnt vmcnt(" #n ")" ::: "memory")
; #define WAIT_L(n) asm volatile("s_waitcnt lgkmcnt(" #n ")" ::: "memory")
; #define BAR __builtin_amdgcn_s_barrier()
; #define SCHED __builtin_amdgcn_sched_barrier(0)
; template <bool ABLK, class Epi>
; __device__ __forceinline__ void gemm_tile(const bf16* __restrict__ A, int lda, const bf16* __restrict__ Bt, int ldb, int K,
;                                           int brow, int bcol, bf16* shm, const Epi& epi, int wv) {
;     ...
;   for (int t = 0; t < nt - 2; t += 2) {
;     LDB(B0, 0, 0); SCHED; LDA(At, 0, 0); STAGE_A(SA(1, 1), 1, t + 1);
;     WAIT_L(8); BAR; MMA(0, 0, At, B0); BAR; SCHED;
;     LDB(B1, 0, 1); STAGE_B(SB(0, 0), 0, t + 2);
;     BAR; MMA(0, 1, At, B1); BAR;
;     LDA(At, 0, 1); STAGE_A(SA(0, 0), 0, t + 2);
;     BAR; MMA(1, 0, At, B0); BAR; SCHED;
;     STAGE_B(SB(0, 1), 1, t + 2);
;     WAIT_V(6); BAR; MMA(1, 1, At, B1); BAR;
.LBB0_1111:
	ds_read_b128 v[164:167], v161
	ds_read_b128 v[168:171], v161 offset:1024
	ds_read_b128 v[172:175], v161 offset:2048
	ds_read_b128 v[176:179], v161 offset:3072
	v_add_u32_e32 v162, 0xc000, v147
	v_add_u32_e32 v163, 0xe000, v147
	v_lshl_add_u64 v[198:199], v[130:131], 0, s[28:29]
	s_add_i32 m0, s99, 0xc000
	ds_read_b128 v[180:183], v143
	ds_read_b128 v[184:187], v143 offset:1024
	ds_read_b128 v[188:191], v142
	ds_read_b128 v[194:197], v142 offset:1024
	ds_read_b128 v[202:205], v141
	ds_read_b128 v[208:211], v141 offset:1024
	ds_read_b128 v[212:215], v140
	ds_read_b128 v[216:219], v140 offset:1024
	global_load_lds_dwordx4 v[198:199], off
	s_add_i32 m0, s99, 0xe000
	v_lshl_add_u64 v[198:199], v[130:131], 0, s[30:31]
	global_load_lds_dwordx4 v[198:199], off
	s_waitcnt lgkmcnt(8)
	s_barrier
	s_setprio 1
	s_waitcnt lgkmcnt(0)
	v_mfma_f32_16x16x32_bf16 v[124:127], v[180:183], v[164:167], v[124:127]
	v_mfma_f32_16x16x32_bf16 v[120:123], v[180:183], v[172:175], v[120:123]
	v_mfma_f32_16x16x32_bf16 v[116:119], v[188:191], v[164:167], v[116:119]
	v_mfma_f32_16x16x32_bf16 v[112:115], v[188:191], v[172:175], v[112:115]
	v_mfma_f32_16x16x32_bf16 v[108:111], v[202:205], v[164:167], v[108:111]
	v_mfma_f32_16x16x32_bf16 v[104:107], v[202:205], v[172:175], v[104:107]
	v_mfma_f32_16x16x32_bf16 v[100:103], v[212:215], v[164:167], v[100:103]
	v_mfma_f32_16x16x32_bf16 v[96:99], v[212:215], v[172:175], v[96:99]
	v_mfma_f32_16x16x32_bf16 v[124:127], v[184:187], v[168:171], v[124:127]
	v_mfma_f32_16x16x32_bf16 v[120:123], v[184:187], v[176:179], v[120:123]
	v_mfma_f32_16x16x32_bf16 v[116:119], v[194:197], v[168:171], v[116:119]
	v_mfma_f32_16x16x32_bf16 v[112:115], v[194:197], v[176:179], v[112:115]
	v_mfma_f32_16x16x32_bf16 v[108:111], v[208:211], v[168:171], v[108:111]
	v_mfma_f32_16x16x32_bf16 v[104:107], v[208:211], v[176:179], v[104:107]
	v_mfma_f32_16x16x32_bf16 v[100:103], v[216:219], v[168:171], v[100:103]
	v_mfma_f32_16x16x32_bf16 v[96:99], v[216:219], v[176:179], v[96:99]
	s_setprio 0
	s_barrier
	v_lshl_add_u64 v[198:199], v[132:133], 0, s[34:35]
	s_add_i32 m0, s99, 0x10000
	ds_read_b128 v[220:223], v160
	ds_read_b128 v[224:227], v160 offset:1024
	ds_read_b128 v[228:231], v160 offset:2048
	ds_read_b128 v[232:235], v160 offset:3072
	global_load_lds_dwordx4 v[198:199], off
	s_add_i32 m0, s99, 0x12000
	v_lshl_add_u64 v[198:199], v[132:133], 0, s[36:37]
	global_load_lds_dwordx4 v[198:199], off
	s_barrier
	s_setprio 1
	s_waitcnt lgkmcnt(0)
	v_mfma_f32_16x16x32_bf16 v[92:95], v[180:183], v[220:223], v[92:95]
	v_mfma_f32_16x16x32_bf16 v[88:91], v[180:183], v[228:231], v[88:91]
	v_mfma_f32_16x16x32_bf16 v[84:87], v[188:191], v[220:223], v[84:87]
	v_mfma_f32_16x16x32_bf16 v[80:83], v[188:191], v[228:231], v[80:83]
	v_mfma_f32_16x16x32_bf16 v[76:79], v[202:205], v[220:223], v[76:79]
	v_mfma_f32_16x16x32_bf16 v[72:75], v[202:205], v[228:231], v[72:75]
	v_mfma_f32_16x16x32_bf16 v[68:71], v[212:215], v[220:223], v[68:71]
	v_mfma_f32_16x16x32_bf16 v[64:67], v[212:215], v[228:231], v[64:67]
	v_mfma_f32_16x16x32_bf16 v[92:95], v[184:187], v[224:227], v[92:95]
	v_mfma_f32_16x16x32_bf16 v[88:91], v[184:187], v[232:235], v[88:91]
	v_mfma_f32_16x16x32_bf16 v[84:87], v[194:197], v[224:227], v[84:87]
	v_mfma_f32_16x16x32_bf16 v[80:83], v[194:197], v[232:235], v[80:83]
	v_mfma_f32_16x16x32_bf16 v[76:79], v[208:211], v[224:227], v[76:79]
	v_mfma_f32_16x16x32_bf16 v[72:75], v[208:211], v[232:235], v[72:75]
	v_mfma_f32_16x16x32_bf16 v[68:71], v[216:219], v[224:227], v[68:71]
	v_mfma_f32_16x16x32_bf16 v[64:67], v[216:219], v[232:235], v[64:67]
	s_setprio 0
	v_lshl_add_u64 v[198:199], v[130:131], 0, s[38:39]
	s_add_i32 m0, s99, 0x0
	s_barrier
	ds_read_b128 v[180:183], v143 offset:16384
	ds_read_b128 v[184:187], v143 offset:17408
	ds_read_b128 v[188:191], v142 offset:16384
	ds_read_b128 v[194:197], v142 offset:17408
	ds_read_b128 v[202:205], v141 offset:16384
	ds_read_b128 v[208:211], v141 offset:17408
	ds_read_b128 v[212:215], v140 offset:16384
	ds_read_b128 v[216:219], v140 offset:17408
	global_load_lds_dwordx4 v[198:199], off
	s_add_i32 m0, s99, 0x2000
	v_lshl_add_u64 v[198:199], v[130:131], 0, s[40:41]
	global_load_lds_dwordx4 v[198:199], off
	s_barrier
	s_setprio 1
	s_waitcnt lgkmcnt(0)
	v_mfma_f32_16x16x32_bf16 v[60:63], v[180:183], v[164:167], v[60:63]
	v_mfma_f32_16x16x32_bf16 v[56:59], v[180:183], v[172:175], v[56:59]
	v_mfma_f32_16x16x32_bf16 v[52:55], v[188:191], v[164:167], v[52:55]
	v_mfma_f32_16x16x32_bf16 v[48:51], v[188:191], v[172:175], v[48:51]
	v_mfma_f32_16x16x32_bf16 v[44:47], v[202:205], v[164:167], v[44:47]
	v_mfma_f32_16x16x32_bf16 v[40:43], v[202:205], v[172:175], v[40:43]
	v_mfma_f32_16x16x32_bf16 v[36:39], v[212:215], v[164:167], v[36:39]
	v_mfma_f32_16x16x32_bf16 v[32:35], v[212:215], v[172:175], v[32:35]
	v_mfma_f32_16x16x32_bf16 v[60:63], v[184:187], v[168:171], v[60:63]
	v_mfma_f32_16x16x32_bf16 v[56:59], v[184:187], v[176:179], v[56:59]
	v_mfma_f32_16x16x32_bf16 v[52:55], v[194:197], v[168:171], v[52:55]
	v_mfma_f32_16x16x32_bf16 v[48:51], v[194:197], v[176:179], v[48:51]
	v_mfma_f32_16x16x32_bf16 v[44:47], v[208:211], v[168:171], v[44:47]
	v_mfma_f32_16x16x32_bf16 v[40:43], v[208:211], v[176:179], v[40:43]
	v_mfma_f32_16x16x32_bf16 v[36:39], v[216:219], v[168:171], v[36:39]
	v_mfma_f32_16x16x32_bf16 v[32:35], v[216:219], v[176:179], v[32:35]
	s_setprio 0
	s_barrier
	s_add_i32 m0, s99, 0x14000
	v_lshl_add_u64 v[164:165], v[132:133], 0, s[42:43]
	global_load_lds_dwordx4 v[164:165], off
	s_add_i32 m0, s99, 0x16000
	v_lshl_add_u64 v[164:165], v[132:133], 0, s[44:45]
	global_load_lds_dwordx4 v[164:165], off
	s_waitcnt vmcnt(6)
	s_barrier
; #define STAGE_A(P, hf, kt) do { if constexpr (ABLK) { const bf16* _gp = A + ((long)(brow >> 8) * nt + (kt)) * 16384 + (hf) * 8192; GLDS2(_gp, 4096, offA, P); } \
;     else { const bf16* _gp = A + (long)(brow + (hf) * HALF) * lda + (long)(kt) * BK; GLDS2(_gp, 64 * (long)lda, offA, P); } } while (0)
; #define STAGE_B(P, hf, kt) do { const bf16* _gp = Bt + (long)(bcol + (hf) * 2) * ldb + (long)(kt) * BK; GLDS2(_gp, 128 * (long)ldb, offB, P); } while (0)
; #define LDA(dst, b, h) for (int m = 0; m < 4; ++m) for (int k = 0; k < 2; ++k) \
;     dst[m][k] = *reinterpret_cast<const bf16x8*>((char*)SA(b, h) + lds_byte(wr * 64 + m * 16 + fr, k * 32 + fq * 8))
; #define LDB(dst, b, h) for (int n = 0; n < 2; ++n) for (int k = 0; k < 2; ++k) \
;     dst[n][k] = *reinterpret_cast<const bf16x8*>((char*)SB(b, h) + lds_byte(wc * 32 + n * 16 + fr, k * 32 + fq * 8))
; #define MMA(ai, bj, At, Bt_) do { __builtin_amdgcn_s_setprio(1); \
;     for (int m = 0; m < 4; ++m) for (int n = 0; n < 2; ++n) for (int k = 0; k < 2; ++k) \
;       acc[ai][bj][m][n] = __builtin_amdgcn_mfma_f32_16x16x32_bf16(At[m][k], Bt_[n][k], acc[ai][bj][m][n], 0, 0, 0); \
;     __builtin_amdgcn_s_setprio(0); } while (0)
; #define WAIT_V(n) asm volatile("s_waitcnt vmcnt(" #n ")" ::: "memory")
; #define WAIT_L(n) asm volatile("s_waitcnt lgkmcnt(" #n ")" ::: "memory")
; #define BAR __builtin_amdgcn_s_barrier()
; #define SCHED __builtin_amdgcn_sched_barrier(0)
; template <bool ABLK, class Epi>
; __device__ __forceinline__ void gemm_tile(const bf16* __restrict__ A, int lda, const bf16* __restrict__ Bt, int ldb, int K,
;                                           int brow, int bcol, bf16* shm, const Epi& epi, int wv) {
;     ...
;     WAIT_V(6); BAR; MMA(1, 1, At, B1); BAR;
;     LDB(B0, 1, 0); SCHED; LDA(At, 1, 0); STAGE_A(SA(0, 1), 1, t + 2);
;     WAIT_L(8); BAR; MMA(0, 0, At, B0); BAR; SCHED;
;     LDB(B1, 1, 1); STAGE_B(SB(1, 0), 0, t + 3);
;     BAR; MMA(0, 1, At, B1); BAR;
;     LDA(At, 1, 1); STAGE_A(SA(1, 0), 0, t + 3);
;     BAR; MMA(1, 0, At, B0); BAR; SCHED;
	s_setprio 1
	v_mfma_f32_16x16x32_bf16 v[28:31], v[180:183], v[220:223], v[28:31]
	v_mfma_f32_16x16x32_bf16 v[24:27], v[180:183], v[228:231], v[24:27]
	v_mfma_f32_16x16x32_bf16 v[20:23], v[188:191], v[220:223], v[20:23]
	v_mfma_f32_16x16x32_bf16 v[16:19], v[188:191], v[228:231], v[16:19]
	v_mfma_f32_16x16x32_bf16 v[12:15], v[202:205], v[220:223], v[12:15]
	v_mfma_f32_16x16x32_bf16 v[8:11], v[202:205], v[228:231], v[8:11]
	v_mfma_f32_16x16x32_bf16 v[4:7], v[212:215], v[220:223], v[4:7]
	v_mfma_f32_16x16x32_bf16 v[0:3], v[212:215], v[228:231], v[0:3]
	v_mfma_f32_16x16x32_bf16 v[28:31], v[184:187], v[224:227], v[28:31]
	v_mfma_f32_16x16x32_bf16 v[24:27], v[184:187], v[232:235], v[24:27]
	v_mfma_f32_16x16x32_bf16 v[20:23], v[194:197], v[224:227], v[20:23]
	v_mfma_f32_16x16x32_bf16 v[16:19], v[194:197], v[232:235], v[16:19]
	v_mfma_f32_16x16x32_bf16 v[12:15], v[208:211], v[224:227], v[12:15]
	v_mfma_f32_16x16x32_bf16 v[8:11], v[208:211], v[232:235], v[8:11]
	v_mfma_f32_16x16x32_bf16 v[4:7], v[216:219], v[224:227], v[4:7]
	v_mfma_f32_16x16x32_bf16 v[0:3], v[216:219], v[232:235], v[0:3]
	s_setprio 0
	s_barrier
	ds_read_b128 v[164:167], v149
	ds_read_b128 v[168:171], v149 offset:1024
	ds_read_b128 v[172:175], v149 offset:2048
	ds_read_b128 v[176:179], v149 offset:3072
	v_lshl_add_u64 v[198:199], v[130:131], 0, s[46:47]
	s_add_i32 m0, s99, 0x4000
	ds_read_b128 v[180:183], v143 offset:32768
	ds_read_b128 v[184:187], v143 offset:33792
	ds_read_b128 v[188:191], v142 offset:32768
	ds_read_b128 v[194:197], v142 offset:33792
	ds_read_b128 v[202:205], v141 offset:32768
	ds_read_b128 v[208:211], v141 offset:33792
	ds_read_b128 v[212:215], v140 offset:32768
	ds_read_b128 v[216:219], v140 offset:33792
	global_load_lds_dwordx4 v[198:199], off
	s_add_i32 m0, s99, 0x6000
	v_lshl_add_u64 v[198:199], v[130:131], 0, s[48:49]
	global_load_lds_dwordx4 v[198:199], off
	s_waitcnt lgkmcnt(8)
	s_barrier
	s_setprio 1
	s_waitcnt lgkmcnt(0)
	v_mfma_f32_16x16x32_bf16 v[124:127], v[180:183], v[164:167], v[124:127]
	v_mfma_f32_16x16x32_bf16 v[120:123], v[180:183], v[172:175], v[120:123]
	v_mfma_f32_16x16x32_bf16 v[116:119], v[188:191], v[164:167], v[116:119]
	v_mfma_f32_16x16x32_bf16 v[112:115], v[188:191], v[172:175], v[112:115]
	v_mfma_f32_16x16x32_bf16 v[108:111], v[202:205], v[164:167], v[108:111]
	v_mfma_f32_16x16x32_bf16 v[104:107], v[202:205], v[172:175], v[104:107]
	v_mfma_f32_16x16x32_bf16 v[100:103], v[212:215], v[164:167], v[100:103]
	v_mfma_f32_16x16x32_bf16 v[96:99], v[212:215], v[172:175], v[96:99]
	v_mfma_f32_16x16x32_bf16 v[124:127], v[184:187], v[168:171], v[124:127]
	v_mfma_f32_16x16x32_bf16 v[120:123], v[184:187], v[176:179], v[120:123]
	v_mfma_f32_16x16x32_bf16 v[116:119], v[194:197], v[168:171], v[116:119]
	v_mfma_f32_16x16x32_bf16 v[112:115], v[194:197], v[176:179], v[112:115]
	v_mfma_f32_16x16x32_bf16 v[108:111], v[208:211], v[168:171], v[108:111]
	v_mfma_f32_16x16x32_bf16 v[104:107], v[208:211], v[176:179], v[104:107]
	v_mfma_f32_16x16x32_bf16 v[100:103], v[216:219], v[168:171], v[100:103]
	v_mfma_f32_16x16x32_bf16 v[96:99], v[216:219], v[176:179], v[96:99]
	s_setprio 0
	s_barrier
	v_lshl_add_u64 v[198:199], v[132:133], 0, s[50:51]
	s_add_i32 m0, s99, 0x18000
	ds_read_b128 v[220:223], v144
	ds_read_b128 v[224:227], v144 offset:1024
	ds_read_b128 v[228:231], v144 offset:2048
	ds_read_b128 v[232:235], v144 offset:3072
	global_load_lds_dwordx4 v[198:199], off
	s_add_i32 m0, s99, 0x1a000
	v_lshl_add_u64 v[198:199], v[132:133], 0, s[52:53]
	global_load_lds_dwordx4 v[198:199], off
	s_barrier
	s_setprio 1
	s_waitcnt lgkmcnt(0)
	v_mfma_f32_16x16x32_bf16 v[92:95], v[180:183], v[220:223], v[92:95]
	v_mfma_f32_16x16x32_bf16 v[88:91], v[180:183], v[228:231], v[88:91]
	v_mfma_f32_16x16x32_bf16 v[84:87], v[188:191], v[220:223], v[84:87]
	v_mfma_f32_16x16x32_bf16 v[80:83], v[188:191], v[228:231], v[80:83]
	v_mfma_f32_16x16x32_bf16 v[76:79], v[202:205], v[220:223], v[76:79]
	v_mfma_f32_16x16x32_bf16 v[72:75], v[202:205], v[228:231], v[72:75]
	v_mfma_f32_16x16x32_bf16 v[68:71], v[212:215], v[220:223], v[68:71]
	v_mfma_f32_16x16x32_bf16 v[64:67], v[212:215], v[228:231], v[64:67]
	v_mfma_f32_16x16x32_bf16 v[92:95], v[184:187], v[224:227], v[92:95]
	v_mfma_f32_16x16x32_bf16 v[88:91], v[184:187], v[232:235], v[88:91]
	v_mfma_f32_16x16x32_bf16 v[84:87], v[194:197], v[224:227], v[84:87]
	v_mfma_f32_16x16x32_bf16 v[80:83], v[194:197], v[232:235], v[80:83]
	v_mfma_f32_16x16x32_bf16 v[76:79], v[208:211], v[224:227], v[76:79]
	v_mfma_f32_16x16x32_bf16 v[72:75], v[208:211], v[232:235], v[72:75]
	v_mfma_f32_16x16x32_bf16 v[68:71], v[216:219], v[224:227], v[68:71]
	v_mfma_f32_16x16x32_bf16 v[64:67], v[216:219], v[232:235], v[64:67]
	s_setprio 0
	v_lshl_add_u64 v[198:199], v[130:131], 0, s[54:55]
	s_add_i32 m0, s99, 0x8000
	s_barrier
	ds_read_b128 v[180:183], v143 offset:49152
	ds_read_b128 v[184:187], v143 offset:50176
	ds_read_b128 v[188:191], v142 offset:49152
	ds_read_b128 v[194:197], v142 offset:50176
	ds_read_b128 v[202:205], v141 offset:49152
	ds_read_b128 v[208:211], v141 offset:50176
	ds_read_b128 v[212:215], v140 offset:49152
	ds_read_b128 v[216:219], v140 offset:50176
	global_load_lds_dwordx4 v[198:199], off
	s_add_i32 m0, s99, 0xa000
	s_nop 0
	global_load_lds_dwordx4 v[130:131], off
	s_barrier
; #define STAGE_A(P, hf, kt) do { if constexpr (ABLK) { const bf16* _gp = A + ((long)(brow >> 8) * nt + (kt)) * 16384 + (hf) * 8192; GLDS2(_gp, 4096, offA, P); } \
;     else { const bf16* _gp = A + (long)(brow + (hf) * HALF) * lda + (long)(kt) * BK; GLDS2(_gp, 64 * (long)lda, offA, P); } } while (0)
; #define STAGE_B(P, hf, kt) do { const bf16* _gp = Bt + (long)(bcol + (hf) * 2) * ldb + (long)(kt) * BK; GLDS2(_gp, 128 * (long)ldb, offB, P); } while (0)
; #define LDA(dst, b, h) for (int m = 0; m < 4; ++m) for (int k = 0; k < 2; ++k) \
;     dst[m][k] = *reinterpret_cast<const bf16x8*>((char*)SA(b, h) + lds_byte(wr * 64 + m * 16 + fr, k * 32 + fq * 8))
; #define LDB(dst, b, h) for (int n = 0; n < 2; ++n) for (int k = 0; k < 2; ++k) \
;     dst[n][k] = *reinterpret_cast<const bf16x8*>((char*)SB(b, h) + lds_byte(wc * 32 + n * 16 + fr, k * 32 + fq * 8))
; #define MMA(ai, bj, At, Bt_) do { __builtin_amdgcn_s_setprio(1); \
;     for (int m = 0; m < 4; ++m) for (int n = 0; n < 2; ++n) for (int k = 0; k < 2; ++k) \
;       acc[ai][bj][m][n] = __builtin_amdgcn_mfma_f32_16x16x32_bf16(At[m][k], Bt_[n][k], acc[ai][bj][m][n], 0, 0, 0); \
;     __builtin_amdgcn_s_setprio(0); } while (0)
; #define WAIT_V(n) asm volatile("s_waitcnt vmcnt(" #n ")" ::: "memory")
; #define WAIT_L(n) asm volatile("s_waitcnt lgkmcnt(" #n ")" ::: "memory")
; #define BAR __builtin_amdgcn_s_barrier()
; #define SCHED __builtin_amdgcn_sched_barrier(0)
; template <bool ABLK, class Epi>
; __device__ __forceinline__ void gemm_tile(const bf16* __restrict__ A, int lda, const bf16* __restrict__ Bt, int ldb, int K,
;                                           int brow, int bcol, bf16* shm, const Epi& epi, int wv) {
;     ...
;     BAR; MMA(1, 0, At, B0); BAR; SCHED;
;     STAGE_B(SB(1, 1), 1, t + 3);
;     WAIT_V(6); BAR; MMA(1, 1, At, B1); BAR;
;   }
;   { LDB(B0, 0, 0); LDA(At, 0, 0); STAGE_A(SA(1, 1), 1, nt - 1);
;     BAR; WAIT_L(0); MMA(0, 0, At, B0); BAR;
;     LDB(B1, 0, 1); BAR; WAIT_L(0); MMA(0, 1, At, B1); BAR;
;     LDA(At, 0, 1); WAIT_V(4); BAR; WAIT_L(0); MMA(1, 0, At, B0); MMA(1, 1, At, B1); BAR; }
	s_setprio 1
	s_waitcnt lgkmcnt(0)
	v_mfma_f32_16x16x32_bf16 v[60:63], v[180:183], v[164:167], v[60:63]
	v_mfma_f32_16x16x32_bf16 v[56:59], v[180:183], v[172:175], v[56:59]
	v_mfma_f32_16x16x32_bf16 v[52:55], v[188:191], v[164:167], v[52:55]
	v_mfma_f32_16x16x32_bf16 v[48:51], v[188:191], v[172:175], v[48:51]
	v_mfma_f32_16x16x32_bf16 v[44:47], v[202:205], v[164:167], v[44:47]
	v_mfma_f32_16x16x32_bf16 v[40:43], v[202:205], v[172:175], v[40:43]
	v_mfma_f32_16x16x32_bf16 v[36:39], v[212:215], v[164:167], v[36:39]
	v_mfma_f32_16x16x32_bf16 v[32:35], v[212:215], v[172:175], v[32:35]
	v_mfma_f32_16x16x32_bf16 v[60:63], v[184:187], v[168:171], v[60:63]
	v_mfma_f32_16x16x32_bf16 v[56:59], v[184:187], v[176:179], v[56:59]
	v_mfma_f32_16x16x32_bf16 v[52:55], v[194:197], v[168:171], v[52:55]
	v_mfma_f32_16x16x32_bf16 v[48:51], v[194:197], v[176:179], v[48:51]
	v_mfma_f32_16x16x32_bf16 v[44:47], v[208:211], v[168:171], v[44:47]
	v_mfma_f32_16x16x32_bf16 v[40:43], v[208:211], v[176:179], v[40:43]
	v_mfma_f32_16x16x32_bf16 v[36:39], v[216:219], v[168:171], v[36:39]
	v_mfma_f32_16x16x32_bf16 v[32:35], v[216:219], v[176:179], v[32:35]
	s_setprio 0
	s_barrier
	s_add_i32 m0, s99, 0x1c000
	v_lshl_add_u64 v[164:165], v[132:133], 0, s[56:57]
	global_load_lds_dwordx4 v[164:165], off
	s_add_i32 m0, s99, 0x1e000
	s_nop 0
	global_load_lds_dwordx4 v[132:133], off
	s_waitcnt vmcnt(6)
	s_barrier
	s_setprio 1
	v_mfma_f32_16x16x32_bf16 v[28:31], v[180:183], v[220:223], v[28:31]
	v_mfma_f32_16x16x32_bf16 v[24:27], v[180:183], v[228:231], v[24:27]
	v_mfma_f32_16x16x32_bf16 v[20:23], v[188:191], v[220:223], v[20:23]
	v_mfma_f32_16x16x32_bf16 v[16:19], v[188:191], v[228:231], v[16:19]
	v_mfma_f32_16x16x32_bf16 v[12:15], v[202:205], v[220:223], v[12:15]
	v_mfma_f32_16x16x32_bf16 v[8:11], v[202:205], v[228:231], v[8:11]
	v_mfma_f32_16x16x32_bf16 v[4:7], v[212:215], v[220:223], v[4:7]
	v_mfma_f32_16x16x32_bf16 v[0:3], v[212:215], v[228:231], v[0:3]
	v_mfma_f32_16x16x32_bf16 v[28:31], v[184:187], v[224:227], v[28:31]
	v_mfma_f32_16x16x32_bf16 v[24:27], v[184:187], v[232:235], v[24:27]
	v_mfma_f32_16x16x32_bf16 v[20:23], v[194:197], v[224:227], v[20:23]
	v_mfma_f32_16x16x32_bf16 v[16:19], v[194:197], v[232:235], v[16:19]
	v_mfma_f32_16x16x32_bf16 v[12:15], v[208:211], v[224:227], v[12:15]
	v_mfma_f32_16x16x32_bf16 v[8:11], v[208:211], v[232:235], v[8:11]
	v_mfma_f32_16x16x32_bf16 v[4:7], v[216:219], v[224:227], v[4:7]
	v_mfma_f32_16x16x32_bf16 v[0:3], v[216:219], v[232:235], v[0:3]
	s_setprio 0
	s_add_i32 s33, s33, 2
	v_lshl_add_u64 v[130:131], v[130:131], 0, s[58:59]
	s_cmpk_lt_u32 s33, 0x54
	v_lshl_add_u64 v[132:133], v[132:133], 0, s[60:61]
	s_barrier
	s_cbranch_scc1 .LBB0_1111
	v_readfirstlane_b32 s2, v162
	v_lshl_add_u64 v[146:147], v[128:129], 0, s[62:63]
	s_mov_b32 m0, s2
	v_readfirstlane_b32 s2, v163
	ds_read_b128 v[130:133], v161
	ds_read_b128 v[150:153], v161 offset:1024
	ds_read_b128 v[154:157], v161 offset:2048
	ds_read_b128 v[164:167], v161 offset:3072
	ds_read_b128 v[168:171], v143
	ds_read_b128 v[172:175], v143 offset:1024
	ds_read_b128 v[176:179], v142
	ds_read_b128 v[180:183], v142 offset:1024
	ds_read_b128 v[184:187], v141
	ds_read_b128 v[188:191], v141 offset:1024
	ds_read_b128 v[194:197], v140
	ds_read_b128 v[202:205], v140 offset:1024
	global_load_lds_dwordx4 v[146:147], off
	v_lshl_add_u64 v[128:129], v[128:129], 0, s[64:65]
	s_mov_b32 m0, s2
	s_nop 0
	global_load_lds_dwordx4 v[128:129], off
	s_barrier
	s_waitcnt lgkmcnt(0)
	s_setprio 1
	s_waitcnt lgkmcnt(0)
	v_mfma_f32_16x16x32_bf16 v[124:127], v[168:171], v[130:133], v[124:127]
	v_mfma_f32_16x16x32_bf16 v[116:119], v[176:179], v[130:133], v[116:119]
	v_mfma_f32_16x16x32_bf16 v[108:111], v[184:187], v[130:133], v[108:111]
	v_mfma_f32_16x16x32_bf16 v[104:107], v[184:187], v[154:157], v[104:107]
	v_mfma_f32_16x16x32_bf16 v[100:103], v[194:197], v[130:133], v[100:103]
	v_mfma_f32_16x16x32_bf16 v[96:99], v[194:197], v[154:157], v[96:99]
	v_mfma_f32_16x16x32_bf16 v[124:127], v[172:175], v[150:153], v[124:127]
	v_mfma_f32_16x16x32_bf16 v[120:123], v[168:171], v[154:157], v[120:123]
	v_mfma_f32_16x16x32_bf16 v[116:119], v[180:183], v[150:153], v[116:119]
	v_mfma_f32_16x16x32_bf16 v[112:115], v[176:179], v[154:157], v[112:115]
	v_mfma_f32_16x16x32_bf16 v[108:111], v[188:191], v[150:153], v[108:111]
	v_mfma_f32_16x16x32_bf16 v[104:107], v[188:191], v[164:167], v[104:107]
	v_mfma_f32_16x16x32_bf16 v[100:103], v[202:205], v[150:153], v[100:103]
	v_mfma_f32_16x16x32_bf16 v[96:99], v[202:205], v[164:167], v[96:99]
	v_mfma_f32_16x16x32_bf16 v[208:211], v[172:175], v[164:167], v[120:123]
	v_mfma_f32_16x16x32_bf16 v[212:215], v[180:183], v[164:167], v[112:115]
	s_setprio 0
	s_barrier
	s_nop 0
	ds_read_b128 v[112:115], v160
	ds_read_b128 v[120:123], v160 offset:1024
	ds_read_b128 v[216:219], v160 offset:2048
	ds_read_b128 v[158:161], v160 offset:3072
	s_barrier
	s_waitcnt lgkmcnt(0)
	s_setprio 1
	s_waitcnt lgkmcnt(0)
	v_mfma_f32_16x16x32_bf16 v[84:87], v[176:179], v[112:115], v[84:87]
	v_mfma_f32_16x16x32_bf16 v[80:83], v[176:179], v[216:219], v[80:83]
	v_mfma_f32_16x16x32_bf16 v[92:95], v[168:171], v[112:115], v[92:95]
	v_mfma_f32_16x16x32_bf16 v[88:91], v[168:171], v[216:219], v[88:91]
	v_mfma_f32_16x16x32_bf16 v[84:87], v[180:183], v[120:123], v[84:87]
	v_mfma_f32_16x16x32_bf16 v[80:83], v[180:183], v[158:161], v[80:83]
	v_mfma_f32_16x16x32_bf16 v[76:79], v[184:187], v[112:115], v[76:79]
	v_mfma_f32_16x16x32_bf16 v[72:75], v[184:187], v[216:219], v[72:75]
	v_mfma_f32_16x16x32_bf16 v[68:71], v[194:197], v[112:115], v[68:71]
	v_mfma_f32_16x16x32_bf16 v[64:67], v[194:197], v[216:219], v[64:67]
	v_mfma_f32_16x16x32_bf16 v[220:223], v[172:175], v[120:123], v[92:95]
	v_mfma_f32_16x16x32_bf16 v[168:171], v[172:175], v[158:161], v[88:91]
	v_mfma_f32_16x16x32_bf16 v[172:175], v[188:191], v[120:123], v[76:79]
	v_mfma_f32_16x16x32_bf16 v[176:179], v[188:191], v[158:161], v[72:75]
	v_mfma_f32_16x16x32_bf16 v[180:183], v[202:205], v[120:123], v[68:71]
	v_mfma_f32_16x16x32_bf16 v[184:187], v[202:205], v[158:161], v[64:67]
	s_setprio 0
	s_barrier
; #define LDA(dst, b, h) for (int m = 0; m < 4; ++m) for (int k = 0; k < 2; ++k) \
;     dst[m][k] = *reinterpret_cast<const bf16x8*>((char*)SA(b, h) + lds_byte(wr * 64 + m * 16 + fr, k * 32 + fq * 8))
; #define LDB(dst, b, h) for (int n = 0; n < 2; ++n) for (int k = 0; k < 2; ++k) \
;     dst[n][k] = *reinterpret_cast<const bf16x8*>((char*)SB(b, h) + lds_byte(wc * 32 + n * 16 + fr, k * 32 + fq * 8))
; #define MMA(ai, bj, At, Bt_) do { __builtin_amdgcn_s_setprio(1); \
;     for (int m = 0; m < 4; ++m) for (int n = 0; n < 2; ++n) for (int k = 0; k < 2; ++k) \
;       acc[ai][bj][m][n] = __builtin_amdgcn_mfma_f32_16x16x32_bf16(At[m][k], Bt_[n][k], acc[ai][bj][m][n], 0, 0, 0); \
;     __builtin_amdgcn_s_setprio(0); } while (0)
; #define WAIT_V(n) asm volatile("s_waitcnt vmcnt(" #n ")" ::: "memory")
; #define WAIT_L(n) asm volatile("s_waitcnt lgkmcnt(" #n ")" ::: "memory")
; #define BAR __builtin_amdgcn_s_barrier()
; template <bool ABLK, class Epi>
; __device__ __forceinline__ void gemm_tile(const bf16* __restrict__ A, int lda, const bf16* __restrict__ Bt, int ldb, int K,
;                                           int brow, int bcol, bf16* shm, const Epi& epi, int wv) {
;     ...
;     LDB(B1, 0, 1); BAR; WAIT_L(0); MMA(0, 1, At, B1); BAR;
;     LDA(At, 0, 1); WAIT_V(4); BAR; WAIT_L(0); MMA(1, 0, At, B0); MMA(1, 1, At, B1); BAR; }
;   { LDB(B0, 1, 0); LDA(At, 1, 0); WAIT_V(2); BAR; WAIT_L(0); MMA(0, 0, At, B0); BAR;
	s_nop 0
	ds_read_b128 v[64:67], v143 offset:16384
	ds_read_b128 v[68:71], v143 offset:17408
	ds_read_b128 v[72:75], v142 offset:16384
	ds_read_b128 v[76:79], v142 offset:17408
	ds_read_b128 v[88:91], v141 offset:16384
	ds_read_b128 v[92:95], v141 offset:17408
	ds_read_b128 v[188:191], v140 offset:16384
	ds_read_b128 v[194:197], v140 offset:17408
	s_waitcnt vmcnt(4)
	s_barrier
	s_waitcnt lgkmcnt(0)
	s_setprio 1
	s_waitcnt lgkmcnt(0)
	v_mfma_f32_16x16x32_bf16 v[60:63], v[64:67], v[130:133], v[60:63]
	v_mfma_f32_16x16x32_bf16 v[56:59], v[64:67], v[154:157], v[56:59]
	v_mfma_f32_16x16x32_bf16 v[44:47], v[88:91], v[130:133], v[44:47]
	v_mfma_f32_16x16x32_bf16 v[40:43], v[88:91], v[154:157], v[40:43]
	v_mfma_f32_16x16x32_bf16 v[60:63], v[68:71], v[150:153], v[60:63]
	v_mfma_f32_16x16x32_bf16 v[56:59], v[68:71], v[164:167], v[56:59]
	v_mfma_f32_16x16x32_bf16 v[52:55], v[72:75], v[130:133], v[52:55]
	v_mfma_f32_16x16x32_bf16 v[48:51], v[72:75], v[154:157], v[48:51]
	v_mfma_f32_16x16x32_bf16 v[44:47], v[92:95], v[150:153], v[44:47]
	v_mfma_f32_16x16x32_bf16 v[40:43], v[92:95], v[164:167], v[40:43]
	v_mfma_f32_16x16x32_bf16 v[36:39], v[188:191], v[130:133], v[36:39]
	v_mfma_f32_16x16x32_bf16 v[32:35], v[188:191], v[154:157], v[32:35]
	v_mfma_f32_16x16x32_bf16 v[202:205], v[76:79], v[150:153], v[52:55]
	v_mfma_f32_16x16x32_bf16 v[224:227], v[76:79], v[164:167], v[48:51]
	v_mfma_f32_16x16x32_bf16 v[128:131], v[194:197], v[150:153], v[36:39]
	v_mfma_f32_16x16x32_bf16 v[150:153], v[194:197], v[164:167], v[32:35]
	s_setprio 0
	s_setprio 1
	v_mfma_f32_16x16x32_bf16 v[28:31], v[64:67], v[112:115], v[28:31]
	v_mfma_f32_16x16x32_bf16 v[24:27], v[64:67], v[216:219], v[24:27]
	v_mfma_f32_16x16x32_bf16 v[12:15], v[88:91], v[112:115], v[12:15]
	v_mfma_f32_16x16x32_bf16 v[8:11], v[88:91], v[216:219], v[8:11]
	v_mfma_f32_16x16x32_bf16 v[28:31], v[68:71], v[120:123], v[28:31]
	v_mfma_f32_16x16x32_bf16 v[24:27], v[68:71], v[158:161], v[24:27]
	v_mfma_f32_16x16x32_bf16 v[20:23], v[72:75], v[112:115], v[20:23]
	v_mfma_f32_16x16x32_bf16 v[16:19], v[72:75], v[216:219], v[16:19]
	v_mfma_f32_16x16x32_bf16 v[12:15], v[92:95], v[120:123], v[12:15]
	v_mfma_f32_16x16x32_bf16 v[8:11], v[92:95], v[158:161], v[8:11]
	v_mfma_f32_16x16x32_bf16 v[4:7], v[188:191], v[112:115], v[4:7]
	v_mfma_f32_16x16x32_bf16 v[0:3], v[188:191], v[216:219], v[0:3]
	v_mfma_f32_16x16x32_bf16 v[154:157], v[76:79], v[120:123], v[20:23]
	v_mfma_f32_16x16x32_bf16 v[162:165], v[76:79], v[158:161], v[16:19]
	v_mfma_f32_16x16x32_bf16 v[228:231], v[194:197], v[120:123], v[4:7]
	v_mfma_f32_16x16x32_bf16 v[158:161], v[194:197], v[158:161], v[0:3]
	s_setprio 0
	s_barrier
	s_nop 1
	ds_read_b128 v[0:3], v149
	ds_read_b128 v[4:7], v149 offset:1024
	ds_read_b128 v[188:191], v149 offset:2048
	ds_read_b128 v[146:149], v149 offset:3072
	ds_read_b128 v[16:19], v143 offset:32768
	ds_read_b128 v[20:23], v143 offset:33792
	ds_read_b128 v[32:35], v142 offset:32768
	ds_read_b128 v[36:39], v142 offset:33792
	ds_read_b128 v[48:51], v141 offset:32768
	ds_read_b128 v[52:55], v141 offset:33792
	ds_read_b128 v[194:197], v140 offset:32768
	ds_read_b128 v[216:219], v140 offset:33792
	s_waitcnt vmcnt(2)
	s_barrier
	s_waitcnt lgkmcnt(0)
	s_setprio 1
	s_waitcnt lgkmcnt(0)
	v_mfma_f32_16x16x32_bf16 v[64:67], v[16:19], v[0:3], v[124:127]
	v_mfma_f32_16x16x32_bf16 v[120:123], v[20:23], v[4:7], v[64:67]
	v_mfma_f32_16x16x32_bf16 v[64:67], v[16:19], v[188:191], v[208:211]
	v_mfma_f32_16x16x32_bf16 v[112:115], v[20:23], v[146:149], v[64:67]
	v_mfma_f32_16x16x32_bf16 v[64:67], v[32:35], v[0:3], v[116:119]
	v_mfma_f32_16x16x32_bf16 v[88:91], v[36:39], v[4:7], v[64:67]
	v_mfma_f32_16x16x32_bf16 v[64:67], v[32:35], v[188:191], v[212:215]
	v_mfma_f32_16x16x32_bf16 v[92:95], v[36:39], v[146:149], v[64:67]
	v_mfma_f32_16x16x32_bf16 v[64:67], v[48:51], v[0:3], v[108:111]
	v_mfma_f32_16x16x32_bf16 v[72:75], v[52:55], v[4:7], v[64:67]
	v_mfma_f32_16x16x32_bf16 v[64:67], v[48:51], v[188:191], v[104:107]
	v_mfma_f32_16x16x32_bf16 v[76:79], v[52:55], v[146:149], v[64:67]
	v_mfma_f32_16x16x32_bf16 v[64:67], v[194:197], v[0:3], v[100:103]
	v_mfma_f32_16x16x32_bf16 v[68:71], v[194:197], v[188:191], v[96:99]
	v_mfma_f32_16x16x32_bf16 v[64:67], v[216:219], v[4:7], v[64:67]
	v_mfma_f32_16x16x32_bf16 v[68:71], v[216:219], v[146:149], v[68:71]
	s_setprio 0
	s_barrier
; #define LDA(dst, b, h) for (int m = 0; m < 4; ++m) for (int k = 0; k < 2; ++k) \
;     dst[m][k] = *reinterpret_cast<const bf16x8*>((char*)SA(b, h) + lds_byte(wr * 64 + m * 16 + fr, k * 32 + fq * 8))
; #define LDB(dst, b, h) for (int n = 0; n < 2; ++n) for (int k = 0; k < 2; ++k) \
;     dst[n][k] = *reinterpret_cast<const bf16x8*>((char*)SB(b, h) + lds_byte(wc * 32 + n * 16 + fr, k * 32 + fq * 8))
; #define MMA(ai, bj, At, Bt_) do { __builtin_amdgcn_s_setprio(1); \
;     for (int m = 0; m < 4; ++m) for (int n = 0; n < 2; ++n) for (int k = 0; k < 2; ++k) \
;       acc[ai][bj][m][n] = __builtin_amdgcn_mfma_f32_16x16x32_bf16(At[m][k], Bt_[n][k], acc[ai][bj][m][n], 0, 0, 0); \
;     __builtin_amdgcn_s_setprio(0); } while (0)
; #define WAIT_V(n) asm volatile("s_waitcnt vmcnt(" #n ")" ::: "memory")
; #define WAIT_L(n) asm volatile("s_waitcnt lgkmcnt(" #n ")" ::: "memory")
; #define BAR __builtin_amdgcn_s_barrier()
; template <bool ABLK, class Epi>
; __device__ __forceinline__ void gemm_tile(const bf16* __restrict__ A, int lda, const bf16* __restrict__ Bt, int ldb, int K,
;                                           int brow, int bcol, bf16* shm, const Epi& epi, int wv) {
;     ...
;   { LDB(B0, 1, 0); LDA(At, 1, 0); WAIT_V(2); BAR; WAIT_L(0); MMA(0, 0, At, B0); BAR;
;     LDB(B1, 1, 1); WAIT_V(0); BAR; WAIT_L(0); MMA(0, 1, At, B1); BAR;
;     LDA(At, 1, 1); BAR; WAIT_L(0); MMA(1, 0, At, B0); MMA(1, 1, At, B1); BAR; }
;   if (wr == 0) BAR;
	ds_read_b128 v[208:211], v144
	ds_read_b128 v[212:215], v144 offset:1024
	ds_read_b128 v[232:235], v144 offset:2048
	ds_read_b128 v[236:239], v144 offset:3072
	s_waitcnt vmcnt(0)
	s_barrier
	s_waitcnt lgkmcnt(0)
	s_setprio 1
	s_waitcnt lgkmcnt(0)
	v_mfma_f32_16x16x32_bf16 v[96:99], v[16:19], v[208:211], v[220:223]
	v_mfma_f32_16x16x32_bf16 v[16:19], v[16:19], v[232:235], v[168:171]
	v_mfma_f32_16x16x32_bf16 v[116:119], v[20:23], v[236:239], v[16:19]
	v_mfma_f32_16x16x32_bf16 v[16:19], v[32:35], v[208:211], v[84:87]
	v_mfma_f32_16x16x32_bf16 v[104:107], v[36:39], v[212:215], v[16:19]
	v_mfma_f32_16x16x32_bf16 v[16:19], v[32:35], v[232:235], v[80:83]
	v_mfma_f32_16x16x32_bf16 v[108:111], v[36:39], v[236:239], v[16:19]
	v_mfma_f32_16x16x32_bf16 v[16:19], v[48:51], v[208:211], v[172:175]
	v_mfma_f32_16x16x32_bf16 v[124:127], v[20:23], v[212:215], v[96:99]
	v_mfma_f32_16x16x32_bf16 v[96:99], v[52:55], v[212:215], v[16:19]
	v_mfma_f32_16x16x32_bf16 v[16:19], v[48:51], v[232:235], v[176:179]
	v_mfma_f32_16x16x32_bf16 v[100:103], v[52:55], v[236:239], v[16:19]
	v_mfma_f32_16x16x32_bf16 v[16:19], v[194:197], v[208:211], v[180:183]
	v_mfma_f32_16x16x32_bf16 v[80:83], v[216:219], v[212:215], v[16:19]
	v_mfma_f32_16x16x32_bf16 v[16:19], v[194:197], v[232:235], v[184:187]
	v_mfma_f32_16x16x32_bf16 v[84:87], v[216:219], v[236:239], v[16:19]
	s_setprio 0
	s_barrier
	ds_read_b128 v[166:169], v143 offset:49152
	ds_read_b128 v[170:173], v143 offset:50176
	ds_read_b128 v[174:177], v142 offset:49152
	ds_read_b128 v[142:145], v142 offset:50176
	ds_read_b128 v[178:181], v141 offset:49152
	ds_read_b128 v[182:185], v141 offset:50176
	ds_read_b128 v[194:197], v140 offset:49152
	ds_read_b128 v[216:219], v140 offset:50176
	s_barrier
	s_waitcnt lgkmcnt(0)
	s_setprio 1
	s_waitcnt lgkmcnt(0)
	v_mfma_f32_16x16x32_bf16 v[16:19], v[166:169], v[0:3], v[60:63]
	v_mfma_f32_16x16x32_bf16 v[48:51], v[170:173], v[4:7], v[16:19]
	v_mfma_f32_16x16x32_bf16 v[16:19], v[166:169], v[188:191], v[56:59]
	v_mfma_f32_16x16x32_bf16 v[52:55], v[170:173], v[146:149], v[16:19]
	v_mfma_f32_16x16x32_bf16 v[16:19], v[174:177], v[0:3], v[202:205]
	v_mfma_f32_16x16x32_bf16 v[32:35], v[142:145], v[4:7], v[16:19]
	v_mfma_f32_16x16x32_bf16 v[16:19], v[174:177], v[188:191], v[224:227]
	v_mfma_f32_16x16x32_bf16 v[36:39], v[142:145], v[146:149], v[16:19]
	v_mfma_f32_16x16x32_bf16 v[16:19], v[178:181], v[0:3], v[44:47]
	v_mfma_f32_16x16x32_bf16 v[0:3], v[194:197], v[0:3], v[128:131]
	v_mfma_f32_16x16x32_bf16 v[16:19], v[182:185], v[4:7], v[16:19]
	v_mfma_f32_16x16x32_bf16 v[20:23], v[178:181], v[188:191], v[40:43]
	v_mfma_f32_16x16x32_bf16 v[0:3], v[216:219], v[4:7], v[0:3]
	v_mfma_f32_16x16x32_bf16 v[4:7], v[194:197], v[188:191], v[150:153]
	v_mfma_f32_16x16x32_bf16 v[20:23], v[182:185], v[146:149], v[20:23]
	v_mfma_f32_16x16x32_bf16 v[4:7], v[216:219], v[146:149], v[4:7]
	s_setprio 0
	s_setprio 1
	v_mfma_f32_16x16x32_bf16 v[24:27], v[166:169], v[232:235], v[24:27]
	v_mfma_f32_16x16x32_bf16 v[28:31], v[166:169], v[208:211], v[28:31]
	v_mfma_f32_16x16x32_bf16 v[60:63], v[170:173], v[236:239], v[24:27]
	v_mfma_f32_16x16x32_bf16 v[24:27], v[174:177], v[208:211], v[154:157]
	v_mfma_f32_16x16x32_bf16 v[8:11], v[178:181], v[232:235], v[8:11]
	v_mfma_f32_16x16x32_bf16 v[56:59], v[170:173], v[212:215], v[28:31]
	v_mfma_f32_16x16x32_bf16 v[40:43], v[142:145], v[212:215], v[24:27]
	v_mfma_f32_16x16x32_bf16 v[24:27], v[174:177], v[232:235], v[162:165]
	v_mfma_f32_16x16x32_bf16 v[12:15], v[178:181], v[208:211], v[12:15]
	v_mfma_f32_16x16x32_bf16 v[28:31], v[182:185], v[236:239], v[8:11]
	v_mfma_f32_16x16x32_bf16 v[8:11], v[194:197], v[208:211], v[228:231]
	v_mfma_f32_16x16x32_bf16 v[44:47], v[142:145], v[236:239], v[24:27]
	v_mfma_f32_16x16x32_bf16 v[24:27], v[182:185], v[212:215], v[12:15]
	v_mfma_f32_16x16x32_bf16 v[12:15], v[216:219], v[212:215], v[8:11]
	v_mfma_f32_16x16x32_bf16 v[8:11], v[194:197], v[232:235], v[158:161]
	v_mfma_f32_16x16x32_bf16 v[8:11], v[216:219], v[236:239], v[8:11]
	s_setprio 0
	v_cmp_gt_u32_e32 vcc, s81, v135
	s_barrier
	s_and_saveexec_b64 s[66:67], vcc
	s_cbranch_execz .LBB0_1107
	s_barrier
	s_branch .LBB0_1107
